# attention epilogues (diff + cross): all 64 gate values of an item requested at the start of the epilogue, hipcc arithmetic consumes them from registers; per-row load/store round trips removed
# speedup vs baseline: 1.1115x; 1.0026x over previous
.LBB0_449:
	s_or_b64 exec, exec, s[0:1]
	v_cmp_gt_u32_e32 vcc, s51, v174
	s_waitcnt lgkmcnt(0)
	s_barrier
	s_and_saveexec_b64 s[16:17], vcc
	s_cbranch_execz .LBB0_421
	v_lshl_or_b32 v204, v172, 2, v171
	v_or_b32_e32 v208, s65, v173
	v_lshlrev_b32_e32 v204, 10, v204
	v_lshl_or_b32 v204, v208, 1, v204
	v_add_u32_e32 v205, 0x2000, v204
	v_add_u32_e32 v206, 0x4000, v204
	v_add_u32_e32 v207, 0x6000, v204
	global_load_ushort v122, v204, s[8:9]
	global_load_ushort v123, v204, s[8:9] offset:64
	global_load_ushort v124, v204, s[8:9] offset:128
	global_load_ushort v125, v204, s[8:9] offset:192
	global_load_ushort v126, v204, s[8:9] offset:1024
	global_load_ushort v127, v204, s[8:9] offset:1088
	global_load_ushort v128, v204, s[8:9] offset:1152
	global_load_ushort v129, v204, s[8:9] offset:1216
	global_load_ushort v130, v204, s[8:9] offset:2048
	global_load_ushort v131, v204, s[8:9] offset:2112
	global_load_ushort v132, v204, s[8:9] offset:2176
	global_load_ushort v133, v204, s[8:9] offset:2240
	global_load_ushort v134, v204, s[8:9] offset:3072
	global_load_ushort v135, v204, s[8:9] offset:3136
	global_load_ushort v136, v204, s[8:9] offset:3200
	global_load_ushort v137, v204, s[8:9] offset:3264
	global_load_ushort v138, v205, s[8:9]
	global_load_ushort v139, v205, s[8:9] offset:64
	global_load_ushort v140, v205, s[8:9] offset:128
	global_load_ushort v141, v205, s[8:9] offset:192
	global_load_ushort v142, v205, s[8:9] offset:1024
	global_load_ushort v143, v205, s[8:9] offset:1088
	global_load_ushort v144, v205, s[8:9] offset:1152
	global_load_ushort v145, v205, s[8:9] offset:1216
	global_load_ushort v146, v205, s[8:9] offset:2048
	global_load_ushort v147, v205, s[8:9] offset:2112
	global_load_ushort v148, v205, s[8:9] offset:2176
	global_load_ushort v149, v205, s[8:9] offset:2240
	global_load_ushort v150, v205, s[8:9] offset:3072
	global_load_ushort v151, v205, s[8:9] offset:3136
	global_load_ushort v152, v205, s[8:9] offset:3200
	global_load_ushort v153, v205, s[8:9] offset:3264
	global_load_ushort v154, v206, s[8:9]
	global_load_ushort v155, v206, s[8:9] offset:64
	global_load_ushort v156, v206, s[8:9] offset:128
	global_load_ushort v157, v206, s[8:9] offset:192
	global_load_ushort v158, v206, s[8:9] offset:1024
	global_load_ushort v159, v206, s[8:9] offset:1088
	global_load_ushort v178, v206, s[8:9] offset:1152
	global_load_ushort v179, v206, s[8:9] offset:1216
	global_load_ushort v180, v206, s[8:9] offset:2048
	global_load_ushort v181, v206, s[8:9] offset:2112
	global_load_ushort v182, v206, s[8:9] offset:2176
	global_load_ushort v183, v206, s[8:9] offset:2240
	global_load_ushort v184, v206, s[8:9] offset:3072
	global_load_ushort v185, v206, s[8:9] offset:3136
	global_load_ushort v186, v206, s[8:9] offset:3200
	global_load_ushort v187, v206, s[8:9] offset:3264
	global_load_ushort v188, v207, s[8:9]
	global_load_ushort v189, v207, s[8:9] offset:64
	global_load_ushort v190, v207, s[8:9] offset:128
	global_load_ushort v191, v207, s[8:9] offset:192
	global_load_ushort v192, v207, s[8:9] offset:1024
	global_load_ushort v193, v207, s[8:9] offset:1088
	global_load_ushort v194, v207, s[8:9] offset:1152
	global_load_ushort v195, v207, s[8:9] offset:1216
	global_load_ushort v196, v207, s[8:9] offset:2048
	global_load_ushort v197, v207, s[8:9] offset:2112
	global_load_ushort v198, v207, s[8:9] offset:2176
	global_load_ushort v199, v207, s[8:9] offset:2240
	global_load_ushort v200, v207, s[8:9] offset:3072
	global_load_ushort v201, v207, s[8:9] offset:3136
	global_load_ushort v202, v207, s[8:9] offset:3200
	global_load_ushort v203, v207, s[8:9] offset:3264
	v_lshl_or_b32 v68, v172, 2, v171
	v_or_b32_e32 v65, s65, v173
	v_ashrrev_i32_e32 v69, 31, v68
	v_lshlrev_b64 v[98:99], 10, v[68:69]
	v_lshlrev_b32_e32 v65, 1, v65
	v_or_b32_e32 v98, v98, v65
	v_lshlrev_b32_e32 v73, 2, v173
	v_lshl_add_u64 v[100:101], s[8:9], 0, v[98:99]
	global_load_dword v75, v73, s[52:53]
	global_load_dword v77, v73, s[52:53] offset:128
	global_load_dword v79, v73, s[52:53] offset:256
	global_load_dword v81, v73, s[52:53] offset:384
	s_waitcnt vmcnt(0)
	v_mov_b32_e32 v83, v122
	v_or_b32_e32 v100, 64, v98
	v_mov_b32_e32 v101, v99
	v_lshl_add_u64 v[102:103], s[8:9], 0, v[100:101]
	v_or_b32_e32 v104, 0x80, v98
	v_mov_b32_e32 v105, v99
	v_lshl_add_u64 v[106:107], s[8:9], 0, v[104:105]
	v_mov_b32_e32 v85, v123
	v_mov_b32_e32 v87, v124
	v_lshl_add_u32 v67, v67, 14, 16
	v_lshl_add_u64 v[112:113], s[10:11], 0, v[98:99]
	v_or_b32_e32 v98, 0xc0, v98
	v_add3_u32 v71, v67, v71, v73
	v_lshl_add_u64 v[114:115], s[8:9], 0, v[98:99]
	v_mov_b32_e32 v102, v0
	v_mov_b32_e32 v103, v48
	v_mov_b32_e32 v106, v32
	v_mov_b32_e32 v107, v16
	v_mov_b32_e32 v48, v1
	v_mov_b32_e32 v16, v33
	ds_read2_b32 v[0:1], v71 offset1:32
	ds_read2_b32 v[32:33], v71 offset0:64 offset1:96
	ds_read2_b32 v[108:109], v71 offset0:128 offset1:160
	ds_read2_b32 v[110:111], v71 offset0:192 offset1:224
	v_mov_b32_e32 v73, v125
	s_waitcnt lgkmcnt(3)
	v_pk_mul_f32 v[0:1], v[164:165], v[0:1]
	s_waitcnt lgkmcnt(2)
	v_pk_mul_f32 v[32:33], v[164:165], v[32:33]
	v_pk_fma_f32 v[102:103], v[102:103], v[96:97], v[0:1] op_sel_hi:[1,0,1] neg_lo:[0,0,1] neg_hi:[0,0,1]
	s_waitcnt lgkmcnt(0)
	v_pk_mul_f32 v[110:111], v[164:165], v[110:111]
	v_pk_mul_f32 v[0:1], v[102:103], v[102:103]
	v_pk_fma_f32 v[16:17], v[16:17], v[94:95], v[110:111] op_sel_hi:[1,0,1] neg_lo:[0,0,1] neg_hi:[0,0,1]
	v_mov_b32_e32 v111, v0
	v_pk_mul_f32 v[108:109], v[164:165], v[108:109]
	v_pk_fma_f32 v[96:97], v[106:107], v[96:97], v[32:33] op_sel_hi:[1,0,1] neg_lo:[0,0,1] neg_hi:[0,0,1]
	v_pk_fma_f32 v[32:33], v[48:49], v[94:95], v[108:109] op_sel_hi:[1,0,1] neg_lo:[0,0,1] neg_hi:[0,0,1]
	v_pk_mul_f32 v[94:95], v[96:97], v[96:97]
	v_pk_mul_f32 v[106:107], v[32:33], v[32:33]
	v_pk_mul_f32 v[108:109], v[16:17], v[16:17]
	v_mov_b32_e32 v110, v106
	v_lshl_add_u64 v[100:101], s[10:11], 0, v[100:101]
	v_lshl_add_u64 v[104:105], s[10:11], 0, v[104:105]
	v_lshl_add_u64 v[98:99], s[10:11], 0, v[98:99]
	v_mul_f32_e32 v69, 0x3f4ccccd, v75
	v_mul_f32_e32 v67, 0x3f4ccccd, v77
	v_mul_f32_e32 v49, 0x3f4ccccd, v79
	v_mul_f32_e32 v48, 0x3f4ccccd, v81
	v_lshlrev_b32_e32 v0, 16, v83
	v_mul_f32_e32 v75, 0xbfb8aa3b, v0
	v_exp_f32_e32 v75, v75
	v_lshlrev_b32_e32 v77, 16, v85
	v_lshlrev_b32_e32 v79, 16, v87
	v_mul_f32_e32 v81, 0xbfb8aa3b, v77
	v_mul_f32_e32 v83, 0xbfb8aa3b, v79
	v_exp_f32_e32 v81, v81
	v_exp_f32_e32 v83, v83
	v_add_f32_e32 v75, 1.0, v75
	v_div_scale_f32 v85, s[0:1], v75, v75, v0
	v_add_f32_e32 v81, 1.0, v81
	v_add_f32_e32 v83, 1.0, v83
	v_rcp_f32_e32 v89, v85
	v_div_scale_f32 v91, s[0:1], v81, v81, v77
	v_div_scale_f32 v114, s[4:5], v83, v83, v79
	v_rcp_f32_e32 v106, v91
	v_rcp_f32_e32 v116, v114
	v_fma_f32 v117, -v85, v89, 1.0
	v_div_scale_f32 v87, vcc, v0, v75, v0
	v_fmac_f32_e32 v89, v117, v89
	v_fma_f32 v117, -v91, v106, 1.0
	v_div_scale_f32 v93, s[0:1], v77, v81, v77
	v_fma_f32 v118, -v114, v116, 1.0
	v_mul_f32_e32 v119, v87, v89
	v_fmac_f32_e32 v106, v117, v106
	v_fmac_f32_e32 v116, v118, v116
	v_fma_f32 v117, -v85, v119, v87
	v_mul_f32_e32 v118, v93, v106
	v_fmac_f32_e32 v119, v117, v89
	v_fma_f32 v117, -v91, v118, v93
	v_fma_f32 v85, -v85, v119, v87
	v_fmac_f32_e32 v118, v117, v106
	v_div_fmas_f32 v85, v85, v89, v119
	v_fma_f32 v87, -v91, v118, v93
	s_mov_b64 vcc, s[0:1]
	v_div_fixup_f32 v75, v85, v75, v0
	v_div_fmas_f32 v0, v87, v106, v118
	v_div_fixup_f32 v77, v0, v81, v77
	v_mov_b32_e32 v0, v107
	v_pk_add_f32 v[0:1], v[110:111], v[0:1]
	v_mov_b32_e32 v106, v108
	v_mov_b32_e32 v107, v94
	v_pk_add_f32 v[0:1], v[0:1], v[106:107]
	v_mov_b32_e32 v94, v109
	v_pk_add_f32 v[0:1], v[0:1], v[94:95]
	ds_bpermute_b32 v95, v216, v1
	ds_bpermute_b32 v94, v216, v0
	v_div_scale_f32 v115, s[4:5], v79, v83, v79
	v_mul_f32_e32 v120, v115, v116
	v_fma_f32 v121, -v114, v120, v115
	s_waitcnt lgkmcnt(0)
	v_pk_add_f32 v[0:1], v[0:1], v[94:95]
	ds_bpermute_b32 v95, v217, v1
	ds_bpermute_b32 v94, v217, v0
	v_fmac_f32_e32 v120, v121, v116
	v_fma_f32 v81, -v114, v120, v115
	s_mov_b64 vcc, s[4:5]
	v_div_fmas_f32 v81, v81, v116, v120
	s_waitcnt lgkmcnt(0)
	v_pk_add_f32 v[0:1], v[0:1], v[94:95]
	ds_bpermute_b32 v95, v218, v1
	ds_bpermute_b32 v94, v218, v0
	v_lshlrev_b32_e32 v73, 16, v73
	v_div_fixup_f32 v79, v81, v83, v79
	v_mul_f32_e32 v81, 0xbfb8aa3b, v73
	v_exp_f32_e32 v81, v81
	s_waitcnt lgkmcnt(0)
	v_pk_add_f32 v[0:1], v[0:1], v[94:95]
	ds_bpermute_b32 v95, v219, v1
	ds_bpermute_b32 v94, v219, v0
	v_add_f32_e32 v81, 1.0, v81
	v_div_scale_f32 v83, s[0:1], v81, v81, v73
	v_rcp_f32_e32 v85, v83
	s_waitcnt lgkmcnt(0)
	v_pk_add_f32 v[0:1], v[0:1], v[94:95]
	ds_bpermute_b32 v95, v220, v1
	ds_bpermute_b32 v94, v220, v0
	v_fma_f32 v87, -v83, v85, 1.0
	v_fmac_f32_e32 v85, v87, v85
	v_div_scale_f32 v87, vcc, v73, v81, v73
	v_mul_f32_e32 v89, v87, v85
	v_fma_f32 v91, -v83, v89, v87
	s_waitcnt lgkmcnt(0)
	v_pk_add_f32 v[94:95], v[0:1], v[94:95]
	v_mov_b64_e32 v[0:1], s[48:49]
	v_fmac_f32_e32 v89, v91, v85
	v_pk_fma_f32 v[94:95], v[94:95], s[46:47], v[0:1] op_sel_hi:[1,0,0]
	v_fma_f32 v83, -v83, v89, v87
	v_mul_f32_e32 v87, 0x4b800000, v95
	v_cmp_gt_f32_e64 s[0:1], s49, v95
	v_div_fmas_f32 v83, v83, v85, v89
	v_div_fixup_f32 v73, v83, v81, v73
	v_cndmask_b32_e64 v87, v95, v87, s[0:1]
	v_rsq_f32_e32 v87, v87
	v_cmp_gt_f32_e32 vcc, s49, v94
	v_mul_f32_e32 v81, 0x45800000, v87
	v_cndmask_b32_e64 v81, v87, v81, s[0:1]
	v_mul_f32_e32 v83, v102, v81
	v_mul_f32_e32 v83, v83, v69
	v_mul_f32_e32 v75, v83, v75
	v_cvt_pk_bf16_f32 v75, v75, s0
	global_store_short v[112:113], v75, off
	v_mul_f32_e32 v75, v103, v81
	v_mul_f32_e32 v75, v75, v67
	v_mul_f32_e32 v75, v75, v77
	v_cvt_pk_bf16_f32 v75, v75, s0
	global_store_short v[100:101], v75, off
	v_mul_f32_e32 v75, v96, v81
	v_mul_f32_e32 v75, v75, v49
	v_mul_f32_e32 v75, v75, v79
	v_cvt_pk_bf16_f32 v75, v75, s0
	global_store_short v[104:105], v75, off
	v_mul_f32_e32 v75, v97, v81
	v_or_b32_e32 v96, 1, v68
	v_mul_f32_e32 v75, v75, v48
	v_ashrrev_i32_e32 v97, 31, v96
	v_mul_f32_e32 v73, v75, v73
	v_lshlrev_b64 v[96:97], 10, v[96:97]
	v_cvt_pk_bf16_f32 v73, v73, s0
	v_or_b32_e32 v96, v96, v65
	global_store_short v[98:99], v73, off
	v_lshl_add_u64 v[98:99], s[8:9], 0, v[96:97]
	v_mov_b32_e32 v73, v126
	v_or_b32_e32 v98, 64, v96
	v_mov_b32_e32 v99, v97
	v_lshl_add_u64 v[100:101], s[8:9], 0, v[98:99]
	v_mov_b32_e32 v75, v127
	v_or_b32_e32 v100, 0x80, v96
	v_mov_b32_e32 v101, v97
	v_lshl_add_u64 v[102:103], s[8:9], 0, v[100:101]
	v_mov_b32_e32 v77, v128
	v_lshl_add_u64 v[102:103], s[10:11], 0, v[96:97]
	v_or_b32_e32 v96, 0xc0, v96
	v_lshl_add_u64 v[104:105], s[8:9], 0, v[96:97]
	v_mov_b32_e32 v79, v129
	v_mul_f32_e32 v81, 0x4b800000, v94
	v_cndmask_b32_e32 v81, v94, v81, vcc
	v_rsq_f32_e32 v81, v81
	v_lshlrev_b32_e32 v73, 16, v73
	v_mul_f32_e32 v83, 0xbfb8aa3b, v73
	v_exp_f32_e32 v83, v83
	v_mul_f32_e32 v85, 0x45800000, v81
	v_cndmask_b32_e32 v81, v81, v85, vcc
	v_lshlrev_b32_e32 v75, 16, v75
	v_add_f32_e32 v83, 1.0, v83
	v_div_scale_f32 v87, s[0:1], v83, v83, v73
	v_rcp_f32_e32 v89, v87
	v_mul_f32_e32 v32, v32, v81
	v_mul_f32_e32 v32, v32, v69
	v_mul_f32_e32 v16, v16, v81
	v_fma_f32 v85, -v87, v89, 1.0
	v_fmac_f32_e32 v89, v85, v89
	v_div_scale_f32 v85, vcc, v73, v83, v73
	v_mul_f32_e32 v91, v85, v89
	v_fma_f32 v93, -v87, v91, v85
	v_fmac_f32_e32 v91, v93, v89
	v_fma_f32 v85, -v87, v91, v85
	v_mul_f32_e32 v87, 0xbfb8aa3b, v75
	v_exp_f32_e32 v87, v87
	v_div_fmas_f32 v85, v85, v89, v91
	v_div_fixup_f32 v73, v85, v83, v73
	v_mul_f32_e32 v32, v32, v73
	v_add_f32_e32 v73, 1.0, v87
	v_cvt_pk_bf16_f32 v32, v32, s0
	v_div_scale_f32 v83, s[0:1], v73, v73, v75
	v_rcp_f32_e32 v85, v83
	global_store_short v[102:103], v32, off
	v_mul_f32_e32 v32, v33, v81
	v_mul_f32_e32 v32, v32, v67
	v_fma_f32 v33, -v83, v85, 1.0
	v_fmac_f32_e32 v85, v33, v85
	v_div_scale_f32 v33, vcc, v75, v73, v75
	v_mul_f32_e32 v87, v33, v85
	v_fma_f32 v89, -v83, v87, v33
	v_fmac_f32_e32 v87, v89, v85
	v_fma_f32 v33, -v83, v87, v33
	v_div_fmas_f32 v33, v33, v85, v87
	v_div_fixup_f32 v33, v33, v73, v75
	v_lshlrev_b32_e32 v73, 16, v77
	v_mul_f32_e32 v75, 0xbfb8aa3b, v73
	v_exp_f32_e32 v75, v75
	v_mul_f32_e32 v32, v32, v33
	v_cvt_pk_bf16_f32 v77, v32, s0
	v_lshl_add_u64 v[32:33], s[10:11], 0, v[98:99]
	v_add_f32_e32 v75, 1.0, v75
	v_div_scale_f32 v83, s[0:1], v75, v75, v73
	v_rcp_f32_e32 v85, v83
	global_store_short v[32:33], v77, off
	v_mul_f32_e32 v16, v16, v49
	v_mov_b32_e32 v98, v2
	v_fma_f32 v32, -v83, v85, 1.0
	v_fmac_f32_e32 v85, v32, v85
	v_div_scale_f32 v32, vcc, v73, v75, v73
	v_mul_f32_e32 v33, v32, v85
	v_fma_f32 v77, -v83, v33, v32
	v_fmac_f32_e32 v33, v77, v85
	v_fma_f32 v32, -v83, v33, v32
	v_div_fmas_f32 v32, v32, v85, v33
	v_div_fixup_f32 v32, v32, v75, v73
	v_lshlrev_b32_e32 v73, 16, v79
	v_mul_f32_e32 v33, 0xbfb8aa3b, v73
	v_exp_f32_e32 v75, v33
	v_mul_f32_e32 v16, v16, v32
	v_cvt_pk_bf16_f32 v16, v16, s0
	v_lshl_add_u64 v[32:33], s[10:11], 0, v[100:101]
	v_add_f32_e32 v75, 1.0, v75
	v_div_scale_f32 v77, s[0:1], v75, v75, v73
	v_rcp_f32_e32 v79, v77
	global_store_short v[32:33], v16, off
	v_mul_f32_e32 v16, v17, v81
	v_mul_f32_e32 v16, v16, v48
	v_fma_f32 v17, -v77, v79, 1.0
	v_fmac_f32_e32 v79, v17, v79
	v_div_scale_f32 v17, vcc, v73, v75, v73
	v_mul_f32_e32 v32, v17, v79
	v_fma_f32 v33, -v77, v32, v17
	v_fmac_f32_e32 v32, v33, v79
	v_fma_f32 v17, -v77, v32, v17
	v_div_fmas_f32 v17, v17, v79, v32
	v_div_fixup_f32 v17, v17, v75, v73
	v_mul_f32_e32 v16, v16, v17
	v_cvt_pk_bf16_f32 v32, v16, s0
	v_lshl_add_u64 v[16:17], s[10:11], 0, v[96:97]
	global_store_short v[16:17], v32, off
	v_or_b32_e32 v16, 2, v68
	v_ashrrev_i32_e32 v17, 31, v16
	v_lshlrev_b64 v[32:33], 10, v[16:17]
	v_or_b32_e32 v32, v32, v65
	v_lshl_add_u64 v[16:17], s[8:9], 0, v[32:33]
	v_mov_b32_e32 v73, v130
	v_or_b32_e32 v94, 64, v32
	v_or_b32_e32 v96, 0x80, v32
	v_lshl_add_u64 v[104:105], s[10:11], 0, v[32:33]
	v_or_b32_e32 v32, 0xc0, v32
	v_mov_b32_e32 v95, v33
	v_lshl_add_u64 v[106:107], s[8:9], 0, v[32:33]
	v_mov_b32_e32 v81, v133
	v_lshl_add_u64 v[16:17], s[8:9], 0, v[94:95]
	v_mov_b32_e32 v75, v131
	v_mov_b32_e32 v97, v33
	v_lshl_add_u64 v[16:17], s[8:9], 0, v[96:97]
	v_mov_b32_e32 v77, v132
	v_add_u32_e32 v79, 0x400, v71
	ds_read2_b32 v[16:17], v79 offset1:32
	ds_read2_b32 v[100:101], v79 offset0:64 offset1:96
	v_mov_b32_e32 v99, v50
	v_mov_b32_e32 v50, v3
	v_lshl_add_u64 v[32:33], s[10:11], 0, v[32:33]
	s_waitcnt lgkmcnt(1)
	v_pk_mul_f32 v[16:17], v[164:165], v[16:17]
	s_waitcnt lgkmcnt(0)
	v_pk_mul_f32 v[100:101], v[164:165], v[100:101]
	v_pk_fma_f32 v[98:99], v[98:99], v[92:93], v[16:17] op_sel_hi:[1,0,1] neg_lo:[0,0,1] neg_hi:[0,0,1]
	v_mov_b32_e32 v16, v34
	v_mov_b32_e32 v17, v18
	v_pk_fma_f32 v[92:93], v[16:17], v[92:93], v[100:101] op_sel_hi:[1,0,1] neg_lo:[0,0,1] neg_hi:[0,0,1]
	ds_read2_b32 v[16:17], v79 offset0:128 offset1:160
	v_mov_b32_e32 v18, v35
	v_pk_mul_f32 v[102:103], v[98:99], v[98:99]
	v_pk_mul_f32 v[100:101], v[92:93], v[92:93]
	s_waitcnt lgkmcnt(0)
	v_pk_mul_f32 v[2:3], v[164:165], v[16:17]
	s_nop 0
	v_pk_fma_f32 v[16:17], v[50:51], v[90:91], v[2:3] op_sel_hi:[1,0,1] neg_lo:[0,0,1] neg_hi:[0,0,1]
	v_lshlrev_b32_e32 v34, 16, v73
	v_mul_f32_e32 v2, 0xbfb8aa3b, v34
	v_exp_f32_e32 v73, v2
	ds_read2_b32 v[2:3], v79 offset0:192 offset1:224
	v_pk_mul_f32 v[50:51], v[16:17], v[16:17]
	v_add_f32_e32 v35, 1.0, v73
	v_div_scale_f32 v73, s[0:1], v35, v35, v34
	v_rcp_f32_e32 v79, v73
	v_lshlrev_b32_e32 v75, 16, v75
	v_mul_f32_e32 v87, 0xbfb8aa3b, v75
	v_exp_f32_e32 v87, v87
	v_fma_f32 v83, -v73, v79, 1.0
	v_fmac_f32_e32 v79, v83, v79
	v_div_scale_f32 v83, vcc, v34, v35, v34
	v_mul_f32_e32 v85, v83, v79
	v_fma_f32 v89, -v73, v85, v83
	v_fmac_f32_e32 v85, v89, v79
	v_fma_f32 v73, -v73, v85, v83
	v_add_f32_e32 v83, 1.0, v87
	v_div_scale_f32 v87, s[0:1], v83, v83, v75
	v_rcp_f32_e32 v89, v87
	v_lshlrev_b32_e32 v77, 16, v77
	v_div_fmas_f32 v73, v73, v79, v85
	v_mul_f32_e32 v79, 0xbfb8aa3b, v77
	v_exp_f32_e32 v79, v79
	v_div_fixup_f32 v73, v73, v35, v34
	v_fma_f32 v34, -v87, v89, 1.0
	v_fmac_f32_e32 v89, v34, v89
	v_div_scale_f32 v34, vcc, v75, v83, v75
	v_mul_f32_e32 v35, v34, v89
	v_fma_f32 v85, -v87, v35, v34
	v_add_f32_e32 v79, 1.0, v79
	v_fmac_f32_e32 v35, v85, v89
	v_div_scale_f32 v85, s[0:1], v79, v79, v77
	v_fma_f32 v34, -v87, v35, v34
	v_rcp_f32_e32 v87, v85
	v_div_fmas_f32 v34, v34, v89, v35
	v_div_fixup_f32 v75, v34, v83, v75
	s_waitcnt lgkmcnt(0)
	v_pk_mul_f32 v[2:3], v[164:165], v[2:3]
	v_fma_f32 v83, -v85, v87, 1.0
	v_fmac_f32_e32 v87, v83, v87
	v_div_scale_f32 v83, vcc, v77, v79, v77
	v_mul_f32_e32 v89, v83, v87
	v_pk_fma_f32 v[2:3], v[18:19], v[90:91], v[2:3] op_sel_hi:[1,0,1] neg_lo:[0,0,1] neg_hi:[0,0,1]
	v_fma_f32 v90, -v85, v89, v83
	v_pk_mul_f32 v[18:19], v[2:3], v[2:3]
	v_fmac_f32_e32 v89, v90, v87
	v_mov_b32_e32 v90, v50
	v_mov_b32_e32 v91, v102
	v_mov_b32_e32 v102, v51
	v_pk_add_f32 v[50:51], v[90:91], v[102:103]
	v_mov_b32_e32 v90, v18
	v_mov_b32_e32 v91, v100
	v_pk_add_f32 v[50:51], v[50:51], v[90:91]
	v_mov_b32_e32 v100, v19
	v_pk_add_f32 v[18:19], v[50:51], v[100:101]
	ds_bpermute_b32 v51, v216, v19
	ds_bpermute_b32 v50, v216, v18
	v_fma_f32 v83, -v85, v89, v83
	v_div_fmas_f32 v83, v83, v87, v89
	v_div_fixup_f32 v77, v83, v79, v77
	v_lshlrev_b32_e32 v79, 16, v81
	s_waitcnt lgkmcnt(0)
	v_pk_add_f32 v[18:19], v[18:19], v[50:51]
	ds_bpermute_b32 v51, v217, v19
	ds_bpermute_b32 v50, v217, v18
	v_mul_f32_e32 v81, 0xbfb8aa3b, v79
	v_exp_f32_e32 v81, v81
	v_lshl_add_u64 v[34:35], s[10:11], 0, v[94:95]
	v_lshl_add_u64 v[90:91], s[10:11], 0, v[96:97]
	s_waitcnt lgkmcnt(0)
	v_pk_add_f32 v[18:19], v[18:19], v[50:51]
	ds_bpermute_b32 v51, v218, v19
	ds_bpermute_b32 v50, v218, v18
	v_add_f32_e32 v81, 1.0, v81
	v_div_scale_f32 v83, s[0:1], v81, v81, v79
	v_rcp_f32_e32 v85, v83
	s_waitcnt lgkmcnt(0)
	v_pk_add_f32 v[18:19], v[18:19], v[50:51]
	ds_bpermute_b32 v51, v219, v19
	ds_bpermute_b32 v50, v219, v18
	v_fma_f32 v87, -v83, v85, 1.0
	v_fmac_f32_e32 v85, v87, v85
	v_div_scale_f32 v87, vcc, v79, v81, v79
	s_waitcnt lgkmcnt(0)
	v_pk_add_f32 v[18:19], v[18:19], v[50:51]
	ds_bpermute_b32 v51, v220, v19
	ds_bpermute_b32 v50, v220, v18
	v_mul_f32_e32 v89, v87, v85
	v_fma_f32 v94, -v83, v89, v87
	v_fmac_f32_e32 v89, v94, v85
	v_fma_f32 v83, -v83, v89, v87
	s_waitcnt lgkmcnt(0)
	v_pk_add_f32 v[18:19], v[18:19], v[50:51]
	s_nop 0
	v_pk_fma_f32 v[18:19], v[18:19], s[46:47], v[0:1] op_sel_hi:[1,0,0]
	s_nop 0
	v_mul_f32_e32 v50, 0x4b800000, v19
	v_cmp_gt_f32_e64 s[0:1], s49, v19
	s_nop 1
	v_cndmask_b32_e64 v19, v19, v50, s[0:1]
	v_rsq_f32_e32 v19, v19
	v_div_fmas_f32 v50, v83, v85, v89
	v_div_fixup_f32 v50, v50, v81, v79
	v_mul_f32_e32 v79, 0x4b800000, v18
	v_mul_f32_e32 v51, 0x45800000, v19
	v_cndmask_b32_e64 v19, v19, v51, s[0:1]
	v_mul_f32_e32 v51, v98, v19
	v_mul_f32_e32 v51, v51, v69
	v_mul_f32_e32 v51, v51, v73
	v_cvt_pk_bf16_f32 v51, v51, s0
	global_store_short v[104:105], v51, off
	v_mul_f32_e32 v51, v99, v19
	v_mul_f32_e32 v51, v51, v67
	v_mul_f32_e32 v51, v51, v75
	v_cvt_pk_bf16_f32 v51, v51, s0
	global_store_short v[34:35], v51, off
	v_mul_f32_e32 v34, v92, v19
	v_mul_f32_e32 v19, v93, v19
	v_mul_f32_e32 v19, v19, v48
	v_mul_f32_e32 v19, v19, v50
	v_cvt_pk_bf16_f32 v19, v19, s0
	global_store_short v[32:33], v19, off
	v_or_b32_e32 v32, 3, v68
	v_mul_f32_e32 v34, v34, v49
	v_ashrrev_i32_e32 v33, 31, v32
	v_mul_f32_e32 v34, v34, v77
	v_lshlrev_b64 v[32:33], 10, v[32:33]
	v_cvt_pk_bf16_f32 v34, v34, s0
	v_or_b32_e32 v32, v32, v65
	global_store_short v[90:91], v34, off
	v_lshl_add_u64 v[34:35], s[8:9], 0, v[32:33]
	v_mov_b32_e32 v19, v134
	v_or_b32_e32 v34, 64, v32
	v_mov_b32_e32 v35, v33
	v_lshl_add_u64 v[50:51], s[8:9], 0, v[34:35]
	v_mov_b32_e32 v73, v135
	v_or_b32_e32 v50, 0x80, v32
	v_mov_b32_e32 v51, v33
	v_lshl_add_u64 v[90:91], s[8:9], 0, v[50:51]
	v_mov_b32_e32 v75, v136
	v_lshl_add_u64 v[90:91], s[10:11], 0, v[32:33]
	v_or_b32_e32 v32, 0xc0, v32
	v_lshl_add_u64 v[92:93], s[8:9], 0, v[32:33]
	v_mov_b32_e32 v77, v137
	v_cmp_gt_f32_e32 vcc, s49, v18
	v_lshlrev_b32_e32 v19, 16, v19
	v_cndmask_b32_e32 v18, v18, v79, vcc
	v_mul_f32_e32 v79, 0xbfb8aa3b, v19
	v_exp_f32_e32 v79, v79
	v_rsq_f32_e32 v18, v18
	v_lshlrev_b32_e32 v73, 16, v73
	v_add_f32_e32 v79, 1.0, v79
	v_div_scale_f32 v83, s[0:1], v79, v79, v19
	v_rcp_f32_e32 v85, v83
	v_mul_f32_e32 v81, 0x45800000, v18
	v_cndmask_b32_e32 v18, v18, v81, vcc
	v_mul_f32_e32 v16, v16, v18
	v_fma_f32 v81, -v83, v85, 1.0
	v_fmac_f32_e32 v85, v81, v85
	v_div_scale_f32 v81, vcc, v19, v79, v19
	v_mul_f32_e32 v87, v81, v85
	v_fma_f32 v89, -v83, v87, v81
	v_fmac_f32_e32 v87, v89, v85
	v_fma_f32 v81, -v83, v87, v81
	v_mul_f32_e32 v83, 0xbfb8aa3b, v73
	v_exp_f32_e32 v83, v83
	v_div_fmas_f32 v81, v81, v85, v87
	v_mul_f32_e32 v16, v16, v69
	v_div_fixup_f32 v19, v81, v79, v19
	v_mul_f32_e32 v16, v16, v19
	v_add_f32_e32 v19, 1.0, v83
	v_cvt_pk_bf16_f32 v16, v16, s0
	v_div_scale_f32 v79, s[0:1], v19, v19, v73
	v_rcp_f32_e32 v81, v79
	global_store_short v[90:91], v16, off
	v_mul_f32_e32 v16, v17, v18
	v_mul_f32_e32 v16, v16, v67
	v_fma_f32 v17, -v79, v81, 1.0
	v_fmac_f32_e32 v81, v17, v81
	v_div_scale_f32 v17, vcc, v73, v19, v73
	v_mul_f32_e32 v83, v17, v81
	v_fma_f32 v85, -v79, v83, v17
	v_fmac_f32_e32 v83, v85, v81
	v_fma_f32 v17, -v79, v83, v17
	v_div_fmas_f32 v17, v17, v81, v83
	v_div_fixup_f32 v17, v17, v19, v73
	v_lshlrev_b32_e32 v19, 16, v75
	v_mul_f32_e32 v73, 0xbfb8aa3b, v19
	v_exp_f32_e32 v73, v73
	v_mul_f32_e32 v16, v16, v17
	v_cvt_pk_bf16_f32 v75, v16, s0
	v_lshl_add_u64 v[16:17], s[10:11], 0, v[34:35]
	v_add_f32_e32 v34, 1.0, v73
	v_div_scale_f32 v35, s[0:1], v34, v34, v19
	v_rcp_f32_e32 v73, v35
	global_store_short v[16:17], v75, off
	v_mul_f32_e32 v2, v2, v18
	v_mul_f32_e32 v2, v2, v49
	v_fma_f32 v16, -v35, v73, 1.0
	v_fmac_f32_e32 v73, v16, v73
	v_div_scale_f32 v16, vcc, v19, v34, v19
	v_mul_f32_e32 v17, v16, v73
	v_fma_f32 v75, -v35, v17, v16
	v_fmac_f32_e32 v17, v75, v73
	v_fma_f32 v16, -v35, v17, v16
	v_div_fmas_f32 v16, v16, v73, v17
	v_div_fixup_f32 v16, v16, v34, v19
	v_lshlrev_b32_e32 v19, 16, v77
	v_mul_f32_e32 v17, 0xbfb8aa3b, v19
	v_exp_f32_e32 v34, v17
	v_mul_f32_e32 v2, v2, v16
	v_cvt_pk_bf16_f32 v2, v2, s0
	v_lshl_add_u64 v[16:17], s[10:11], 0, v[50:51]
	v_add_f32_e32 v34, 1.0, v34
	v_div_scale_f32 v35, s[0:1], v34, v34, v19
	v_rcp_f32_e32 v50, v35
	global_store_short v[16:17], v2, off
	v_mul_f32_e32 v2, v3, v18
	v_mul_f32_e32 v2, v2, v48
	v_fma_f32 v3, -v35, v50, 1.0
	v_fmac_f32_e32 v50, v3, v50
	v_div_scale_f32 v3, vcc, v19, v34, v19
	v_mul_f32_e32 v16, v3, v50
	v_fma_f32 v17, -v35, v16, v3
	v_fmac_f32_e32 v16, v17, v50
	v_fma_f32 v3, -v35, v16, v3
	v_div_fmas_f32 v3, v3, v50, v16
	v_div_fixup_f32 v3, v3, v34, v19
	v_mul_f32_e32 v2, v2, v3
	v_cvt_pk_bf16_f32 v16, v2, s0
	v_lshl_add_u64 v[2:3], s[10:11], 0, v[32:33]
	global_store_short v[2:3], v16, off
	v_or_b32_e32 v2, 8, v68
	v_ashrrev_i32_e32 v3, 31, v2
	v_lshlrev_b64 v[16:17], 10, v[2:3]
	v_or_b32_e32 v16, v16, v65
	v_lshl_add_u64 v[2:3], s[8:9], 0, v[16:17]
	v_mov_b32_e32 v73, v138
	v_or_b32_e32 v18, 64, v16
	v_or_b32_e32 v32, 0x80, v16
	v_lshl_add_u64 v[92:93], s[10:11], 0, v[16:17]
	v_or_b32_e32 v16, 0xc0, v16
	v_mov_b32_e32 v19, v17
	v_lshl_add_u64 v[94:95], s[8:9], 0, v[16:17]
	v_mov_b32_e32 v81, v141
	v_lshl_add_u64 v[2:3], s[8:9], 0, v[18:19]
	v_mov_b32_e32 v75, v139
	v_mov_b32_e32 v33, v17
	v_lshl_add_u64 v[2:3], s[8:9], 0, v[32:33]
	v_mov_b32_e32 v77, v140
	v_add_u32_e32 v79, 0x1000, v71
	ds_read2_b32 v[2:3], v79 offset1:32
	ds_read2_b32 v[50:51], v79 offset0:64 offset1:96
	v_mov_b32_e32 v34, v4
	v_mov_b32_e32 v35, v52
	v_mov_b32_e32 v52, v5
	s_waitcnt lgkmcnt(1)
	v_pk_mul_f32 v[2:3], v[164:165], v[2:3]
	s_waitcnt lgkmcnt(0)
	v_pk_mul_f32 v[50:51], v[164:165], v[50:51]
	v_pk_fma_f32 v[34:35], v[34:35], v[88:89], v[2:3] op_sel_hi:[1,0,1] neg_lo:[0,0,1] neg_hi:[0,0,1]
	v_mov_b32_e32 v2, v36
	v_mov_b32_e32 v3, v20
	v_pk_fma_f32 v[50:51], v[2:3], v[88:89], v[50:51] op_sel_hi:[1,0,1] neg_lo:[0,0,1] neg_hi:[0,0,1]
	ds_read2_b32 v[2:3], v79 offset0:128 offset1:160
	v_mov_b32_e32 v20, v37
	v_pk_mul_f32 v[90:91], v[34:35], v[34:35]
	v_pk_mul_f32 v[88:89], v[50:51], v[50:51]
	v_lshl_add_u64 v[18:19], s[10:11], 0, v[18:19]
	s_waitcnt lgkmcnt(0)
	v_pk_mul_f32 v[2:3], v[164:165], v[2:3]
	v_lshl_add_u64 v[32:33], s[10:11], 0, v[32:33]
	v_pk_fma_f32 v[4:5], v[52:53], v[86:87], v[2:3] op_sel_hi:[1,0,1] neg_lo:[0,0,1] neg_hi:[0,0,1]
	v_lshl_add_u64 v[16:17], s[10:11], 0, v[16:17]
	v_pk_mul_f32 v[52:53], v[4:5], v[4:5]
	v_lshlrev_b32_e32 v36, 16, v73
	v_mul_f32_e32 v2, 0xbfb8aa3b, v36
	v_exp_f32_e32 v73, v2
	ds_read2_b32 v[2:3], v79 offset0:192 offset1:224
	v_add_f32_e32 v37, 1.0, v73
	v_div_scale_f32 v73, s[0:1], v37, v37, v36
	v_rcp_f32_e32 v79, v73
	s_waitcnt lgkmcnt(0)
	v_pk_mul_f32 v[2:3], v[164:165], v[2:3]
	v_lshlrev_b32_e32 v75, 16, v75
	v_pk_fma_f32 v[2:3], v[20:21], v[86:87], v[2:3] op_sel_hi:[1,0,1] neg_lo:[0,0,1] neg_hi:[0,0,1]
	v_fma_f32 v83, -v73, v79, 1.0
	v_mul_f32_e32 v86, 0xbfb8aa3b, v75
	v_fmac_f32_e32 v79, v83, v79
	v_div_scale_f32 v83, vcc, v36, v37, v36
	v_exp_f32_e32 v86, v86
	v_mul_f32_e32 v85, v83, v79
	v_fma_f32 v87, -v73, v85, v83
	v_fmac_f32_e32 v85, v87, v79
	v_fma_f32 v73, -v73, v85, v83
	v_add_f32_e32 v83, 1.0, v86
	v_div_scale_f32 v86, s[0:1], v83, v83, v75
	v_rcp_f32_e32 v87, v86
	v_lshlrev_b32_e32 v77, 16, v77
	v_div_fmas_f32 v73, v73, v79, v85
	v_mul_f32_e32 v79, 0xbfb8aa3b, v77
	v_exp_f32_e32 v79, v79
	v_div_fixup_f32 v73, v73, v37, v36
	v_fma_f32 v36, -v86, v87, 1.0
	v_fmac_f32_e32 v87, v36, v87
	v_div_scale_f32 v36, vcc, v75, v83, v75
	v_mul_f32_e32 v37, v36, v87
	v_fma_f32 v85, -v86, v37, v36
	v_add_f32_e32 v79, 1.0, v79
	v_fmac_f32_e32 v37, v85, v87
	v_div_scale_f32 v85, s[0:1], v79, v79, v77
	v_fma_f32 v36, -v86, v37, v36
	v_rcp_f32_e32 v86, v85
	v_div_fmas_f32 v36, v36, v87, v37
	v_div_fixup_f32 v75, v36, v83, v75
	v_div_scale_f32 v83, vcc, v77, v79, v77
	v_fma_f32 v36, -v85, v86, 1.0
	v_fmac_f32_e32 v86, v36, v86
	v_mul_f32_e32 v87, v83, v86
	v_fma_f32 v36, -v85, v87, v83
	v_pk_mul_f32 v[20:21], v[2:3], v[2:3]
	v_fmac_f32_e32 v87, v36, v86
	v_mov_b32_e32 v36, v52
	v_mov_b32_e32 v37, v90
	v_mov_b32_e32 v90, v53
	v_pk_add_f32 v[36:37], v[36:37], v[90:91]
	v_mov_b32_e32 v52, v20
	v_mov_b32_e32 v53, v88
	v_pk_add_f32 v[36:37], v[36:37], v[52:53]
	v_mov_b32_e32 v88, v21
	v_pk_add_f32 v[20:21], v[36:37], v[88:89]
	ds_bpermute_b32 v37, v216, v21
	ds_bpermute_b32 v36, v216, v20
	v_fma_f32 v52, -v85, v87, v83
	v_div_fmas_f32 v52, v52, v86, v87
	v_lshlrev_b32_e32 v53, 16, v81
	v_div_fixup_f32 v52, v52, v79, v77
	s_waitcnt lgkmcnt(0)
	v_pk_add_f32 v[20:21], v[20:21], v[36:37]
	ds_bpermute_b32 v37, v217, v21
	ds_bpermute_b32 v36, v217, v20
	v_mul_f32_e32 v77, 0xbfb8aa3b, v53
	v_exp_f32_e32 v77, v77
	s_waitcnt lgkmcnt(0)
	v_pk_add_f32 v[20:21], v[20:21], v[36:37]
	ds_bpermute_b32 v37, v218, v21
	ds_bpermute_b32 v36, v218, v20
	v_add_f32_e32 v77, 1.0, v77
	v_div_scale_f32 v79, s[0:1], v77, v77, v53
	v_rcp_f32_e32 v81, v79
	s_waitcnt lgkmcnt(0)
	v_pk_add_f32 v[20:21], v[20:21], v[36:37]
	ds_bpermute_b32 v37, v219, v21
	ds_bpermute_b32 v36, v219, v20
	v_fma_f32 v83, -v79, v81, 1.0
	v_fmac_f32_e32 v81, v83, v81
	v_div_scale_f32 v83, vcc, v53, v77, v53
	s_waitcnt lgkmcnt(0)
	v_pk_add_f32 v[20:21], v[20:21], v[36:37]
	ds_bpermute_b32 v37, v220, v21
	ds_bpermute_b32 v36, v220, v20
	v_mul_f32_e32 v85, v83, v81
	v_fma_f32 v86, -v79, v85, v83
	v_fmac_f32_e32 v85, v86, v81
	v_fma_f32 v79, -v79, v85, v83
	s_waitcnt lgkmcnt(0)
	v_pk_add_f32 v[20:21], v[20:21], v[36:37]
	s_nop 0
	v_pk_fma_f32 v[20:21], v[20:21], s[46:47], v[0:1] op_sel_hi:[1,0,0]
	s_nop 0
	v_mul_f32_e32 v36, 0x4b800000, v21
	v_cmp_gt_f32_e64 s[0:1], s49, v21
	s_nop 1
	v_cndmask_b32_e64 v21, v21, v36, s[0:1]
	v_rsq_f32_e32 v21, v21
	v_div_fmas_f32 v36, v79, v81, v85
	v_div_fixup_f32 v36, v36, v77, v53
	v_cmp_gt_f32_e32 vcc, s49, v20
	v_mul_f32_e32 v37, 0x45800000, v21
	v_cndmask_b32_e64 v21, v21, v37, s[0:1]
	v_mul_f32_e32 v34, v34, v21
	v_mul_f32_e32 v34, v34, v69
	v_mul_f32_e32 v34, v34, v73
	v_cvt_pk_bf16_f32 v34, v34, s0
	global_store_short v[92:93], v34, off
	v_mul_f32_e32 v34, v35, v21
	v_mul_f32_e32 v34, v34, v67
	v_mul_f32_e32 v34, v34, v75
	v_cvt_pk_bf16_f32 v34, v34, s0
	global_store_short v[18:19], v34, off
	v_mul_f32_e32 v18, v50, v21
	v_mul_f32_e32 v18, v18, v49
	v_mul_f32_e32 v18, v18, v52
	v_cvt_pk_bf16_f32 v18, v18, s0
	global_store_short v[32:33], v18, off
	v_mul_f32_e32 v18, v51, v21
	v_mul_f32_e32 v18, v18, v48
	v_mul_f32_e32 v18, v18, v36
	v_cvt_pk_bf16_f32 v18, v18, s0
	global_store_short v[16:17], v18, off
	v_or_b32_e32 v16, 9, v68
	v_ashrrev_i32_e32 v17, 31, v16
	v_lshlrev_b64 v[16:17], 10, v[16:17]
	v_or_b32_e32 v16, v16, v65
	v_lshl_add_u64 v[18:19], s[8:9], 0, v[16:17]
	v_mov_b32_e32 v21, v142
	v_or_b32_e32 v18, 64, v16
	v_mov_b32_e32 v19, v17
	v_lshl_add_u64 v[32:33], s[8:9], 0, v[18:19]
	v_mov_b32_e32 v50, v143
	v_or_b32_e32 v32, 0x80, v16
	v_mov_b32_e32 v33, v17
	v_lshl_add_u64 v[34:35], s[8:9], 0, v[32:33]
	v_mov_b32_e32 v51, v144
	v_lshl_add_u64 v[34:35], s[10:11], 0, v[16:17]
	v_or_b32_e32 v16, 0xc0, v16
	v_lshl_add_u64 v[36:37], s[8:9], 0, v[16:17]
	v_mov_b32_e32 v36, v145
	v_mul_f32_e32 v37, 0x4b800000, v20
	v_cndmask_b32_e32 v20, v20, v37, vcc
	v_rsq_f32_e32 v20, v20
	v_add_u32_e32 v79, 0x1400, v71
	v_mul_f32_e32 v52, 0x45800000, v20
	v_cndmask_b32_e32 v20, v20, v52, vcc
	v_mul_f32_e32 v4, v4, v20
	v_mul_f32_e32 v4, v4, v69
	v_mul_f32_e32 v2, v2, v20
	v_mul_f32_e32 v2, v2, v49
	v_lshlrev_b32_e32 v21, 16, v21
	v_mul_f32_e32 v37, 0xbfb8aa3b, v21
	v_exp_f32_e32 v37, v37
	v_lshlrev_b32_e32 v50, 16, v50
	v_add_f32_e32 v37, 1.0, v37
	v_div_scale_f32 v53, s[0:1], v37, v37, v21
	v_rcp_f32_e32 v73, v53
	s_nop 0
	v_fma_f32 v52, -v53, v73, 1.0
	v_fmac_f32_e32 v73, v52, v73
	v_div_scale_f32 v52, vcc, v21, v37, v21
	v_mul_f32_e32 v75, v52, v73
	v_fma_f32 v77, -v53, v75, v52
	v_fmac_f32_e32 v75, v77, v73
	v_fma_f32 v52, -v53, v75, v52
	v_mul_f32_e32 v53, 0xbfb8aa3b, v50
	v_exp_f32_e32 v53, v53
	v_div_fmas_f32 v52, v52, v73, v75
	v_div_fixup_f32 v21, v52, v37, v21
	v_mul_f32_e32 v4, v4, v21
	v_add_f32_e32 v21, 1.0, v53
	v_cvt_pk_bf16_f32 v4, v4, s0
	v_div_scale_f32 v37, s[0:1], v21, v21, v50
	v_rcp_f32_e32 v52, v37
	global_store_short v[34:35], v4, off
	v_mul_f32_e32 v4, v5, v20
	v_mul_f32_e32 v4, v4, v67
	v_fma_f32 v5, -v37, v52, 1.0
	v_fmac_f32_e32 v52, v5, v52
	v_div_scale_f32 v5, vcc, v50, v21, v50
	v_mul_f32_e32 v34, v5, v52
	v_fma_f32 v35, -v37, v34, v5
	v_fmac_f32_e32 v34, v35, v52
	v_fma_f32 v5, -v37, v34, v5
	v_div_fmas_f32 v5, v5, v52, v34
	v_div_fixup_f32 v5, v5, v21, v50
	v_lshlrev_b32_e32 v21, 16, v51
	v_mul_f32_e32 v34, 0xbfb8aa3b, v21
	v_exp_f32_e32 v34, v34
	v_mul_f32_e32 v4, v4, v5
	v_cvt_pk_bf16_f32 v35, v4, s0
	v_lshl_add_u64 v[4:5], s[10:11], 0, v[18:19]
	v_add_f32_e32 v18, 1.0, v34
	v_div_scale_f32 v19, s[0:1], v18, v18, v21
	v_rcp_f32_e32 v34, v19
	global_store_short v[4:5], v35, off
	v_fma_f32 v4, -v19, v34, 1.0
	v_fmac_f32_e32 v34, v4, v34
	v_div_scale_f32 v4, vcc, v21, v18, v21
	v_mul_f32_e32 v5, v4, v34
	v_fma_f32 v35, -v19, v5, v4
	v_fmac_f32_e32 v5, v35, v34
	v_fma_f32 v4, -v19, v5, v4
	v_div_fmas_f32 v4, v4, v34, v5
	v_div_fixup_f32 v4, v4, v18, v21
	v_lshlrev_b32_e32 v18, 16, v36
	v_mul_f32_e32 v5, 0xbfb8aa3b, v18
	v_exp_f32_e32 v19, v5
	v_mul_f32_e32 v2, v2, v4
	v_cvt_pk_bf16_f32 v2, v2, s0
	v_lshl_add_u64 v[4:5], s[10:11], 0, v[32:33]
	v_add_f32_e32 v19, 1.0, v19
	v_div_scale_f32 v21, s[0:1], v19, v19, v18
	v_rcp_f32_e32 v32, v21
	global_store_short v[4:5], v2, off
	v_mul_f32_e32 v2, v3, v20
	v_mul_f32_e32 v2, v2, v48
	v_fma_f32 v3, -v21, v32, 1.0
	v_fmac_f32_e32 v32, v3, v32
	v_div_scale_f32 v3, vcc, v18, v19, v18
	v_mul_f32_e32 v4, v3, v32
	v_fma_f32 v5, -v21, v4, v3
	v_fmac_f32_e32 v4, v5, v32
	v_fma_f32 v3, -v21, v4, v3
	v_div_fmas_f32 v3, v3, v32, v4
	v_div_fixup_f32 v3, v3, v19, v18
	v_mul_f32_e32 v2, v2, v3
	v_cvt_pk_bf16_f32 v4, v2, s0
	v_lshl_add_u64 v[2:3], s[10:11], 0, v[16:17]
	global_store_short v[2:3], v4, off
	v_or_b32_e32 v2, 10, v68
	v_ashrrev_i32_e32 v3, 31, v2
	v_lshlrev_b64 v[16:17], 10, v[2:3]
	v_or_b32_e32 v16, v16, v65
	v_lshl_add_u64 v[2:3], s[8:9], 0, v[16:17]
	v_mov_b32_e32 v73, v146
	v_or_b32_e32 v18, 64, v16
	v_mov_b32_e32 v19, v17
	v_lshl_add_u64 v[2:3], s[8:9], 0, v[18:19]
	v_mov_b32_e32 v75, v147
	v_or_b32_e32 v20, 0x80, v16
	v_mov_b32_e32 v21, v17
	v_lshl_add_u64 v[2:3], s[8:9], 0, v[20:21]
	v_mov_b32_e32 v77, v148
	ds_read2_b32 v[2:3], v79 offset1:32
	ds_read2_b32 v[32:33], v79 offset0:64 offset1:96
	v_mov_b32_e32 v4, v6
	v_mov_b32_e32 v5, v54
	v_lshl_add_u64 v[52:53], s[10:11], 0, v[16:17]
	s_waitcnt lgkmcnt(1)
	v_pk_mul_f32 v[2:3], v[164:165], v[2:3]
	v_or_b32_e32 v16, 0xc0, v16
	v_pk_fma_f32 v[34:35], v[4:5], v[84:85], v[2:3] op_sel_hi:[1,0,1] neg_lo:[0,0,1] neg_hi:[0,0,1]
	v_mov_b32_e32 v2, v38
	v_mov_b32_e32 v3, v22
	s_waitcnt lgkmcnt(0)
	v_pk_mul_f32 v[4:5], v[164:165], v[32:33]
	v_mov_b32_e32 v54, v7
	v_pk_fma_f32 v[32:33], v[2:3], v[84:85], v[4:5] op_sel_hi:[1,0,1] neg_lo:[0,0,1] neg_hi:[0,0,1]
	v_lshl_add_u64 v[4:5], s[8:9], 0, v[16:17]
	v_mov_b32_e32 v81, v149
	ds_read2_b32 v[2:3], v79 offset0:128 offset1:160
	v_mov_b32_e32 v22, v39
	v_pk_mul_f32 v[36:37], v[34:35], v[34:35]
	v_pk_mul_f32 v[50:51], v[32:33], v[32:33]
	v_lshl_add_u64 v[18:19], s[10:11], 0, v[18:19]
	s_waitcnt lgkmcnt(0)
	v_pk_mul_f32 v[2:3], v[164:165], v[2:3]
	v_lshl_add_u64 v[16:17], s[10:11], 0, v[16:17]
	v_pk_fma_f32 v[4:5], v[54:55], v[82:83], v[2:3] op_sel_hi:[1,0,1] neg_lo:[0,0,1] neg_hi:[0,0,1]
	v_lshl_add_u64 v[20:21], s[10:11], 0, v[20:21]
	v_pk_mul_f32 v[6:7], v[4:5], v[4:5]
	v_lshlrev_b32_e32 v38, 16, v73
	v_mul_f32_e32 v2, 0xbfb8aa3b, v38
	v_exp_f32_e32 v54, v2
	ds_read2_b32 v[2:3], v79 offset0:192 offset1:224
	v_lshlrev_b32_e32 v75, 16, v75
	v_add_f32_e32 v39, 1.0, v54
	v_div_scale_f32 v54, s[0:1], v39, v39, v38
	v_rcp_f32_e32 v55, v54
	s_waitcnt lgkmcnt(0)
	v_pk_mul_f32 v[2:3], v[164:165], v[2:3]
	v_fma_f32 v73, -v54, v55, 1.0
	v_pk_fma_f32 v[2:3], v[22:23], v[82:83], v[2:3] op_sel_hi:[1,0,1] neg_lo:[0,0,1] neg_hi:[0,0,1]
	v_mul_f32_e32 v82, 0xbfb8aa3b, v75
	v_fmac_f32_e32 v55, v73, v55
	v_div_scale_f32 v73, vcc, v38, v39, v38
	v_exp_f32_e32 v82, v82
	v_mul_f32_e32 v79, v73, v55
	v_fma_f32 v83, -v54, v79, v73
	v_fmac_f32_e32 v79, v83, v55
	v_fma_f32 v54, -v54, v79, v73
	v_add_f32_e32 v73, 1.0, v82
	v_div_scale_f32 v82, s[0:1], v73, v73, v75
	v_rcp_f32_e32 v83, v82
	v_div_fmas_f32 v54, v54, v55, v79
	v_lshlrev_b32_e32 v55, 16, v77
	v_mul_f32_e32 v77, 0xbfb8aa3b, v55
	v_exp_f32_e32 v77, v77
	v_div_fixup_f32 v54, v54, v39, v38
	v_fma_f32 v38, -v82, v83, 1.0
	v_fmac_f32_e32 v83, v38, v83
	v_div_scale_f32 v38, vcc, v75, v73, v75
	v_mul_f32_e32 v39, v38, v83
	v_fma_f32 v79, -v82, v39, v38
	v_add_f32_e32 v77, 1.0, v77
	v_fmac_f32_e32 v39, v79, v83
	v_div_scale_f32 v79, s[0:1], v77, v77, v55
	v_fma_f32 v38, -v82, v39, v38
	v_rcp_f32_e32 v82, v79
	v_div_fmas_f32 v38, v38, v83, v39
	v_div_fixup_f32 v73, v38, v73, v75
	v_div_scale_f32 v75, vcc, v55, v77, v55
	v_fma_f32 v38, -v79, v82, 1.0
	v_fmac_f32_e32 v82, v38, v82
	v_mul_f32_e32 v83, v75, v82
	v_fma_f32 v38, -v79, v83, v75
	v_pk_mul_f32 v[22:23], v[2:3], v[2:3]
	v_fmac_f32_e32 v83, v38, v82
	v_mov_b32_e32 v38, v6
	v_mov_b32_e32 v39, v36
	v_mov_b32_e32 v36, v7
	v_pk_add_f32 v[6:7], v[38:39], v[36:37]
	v_mov_b32_e32 v36, v22
	v_mov_b32_e32 v37, v50
	v_pk_add_f32 v[6:7], v[6:7], v[36:37]
	v_mov_b32_e32 v50, v23
	v_pk_add_f32 v[6:7], v[6:7], v[50:51]
	ds_bpermute_b32 v23, v216, v7
	ds_bpermute_b32 v22, v216, v6
	v_lshlrev_b32_e32 v37, 16, v81
	v_mul_f32_e32 v38, 0xbfb8aa3b, v37
	v_exp_f32_e32 v38, v38
	v_fma_f32 v36, -v79, v83, v75
	s_waitcnt lgkmcnt(0)
	v_pk_add_f32 v[6:7], v[6:7], v[22:23]
	ds_bpermute_b32 v23, v217, v7
	ds_bpermute_b32 v22, v217, v6
	v_add_f32_e32 v38, 1.0, v38
	v_div_scale_f32 v39, s[0:1], v38, v38, v37
	v_rcp_f32_e32 v50, v39
	s_waitcnt lgkmcnt(0)
	v_pk_add_f32 v[6:7], v[6:7], v[22:23]
	ds_bpermute_b32 v23, v218, v7
	ds_bpermute_b32 v22, v218, v6
	v_fma_f32 v51, -v39, v50, 1.0
	v_div_fmas_f32 v36, v36, v82, v83
	v_fmac_f32_e32 v50, v51, v50
	v_div_scale_f32 v51, vcc, v37, v38, v37
	s_waitcnt lgkmcnt(0)
	v_pk_add_f32 v[6:7], v[6:7], v[22:23]
	ds_bpermute_b32 v23, v219, v7
	ds_bpermute_b32 v22, v219, v6
	v_div_fixup_f32 v36, v36, v77, v55
	v_mul_f32_e32 v55, v51, v50
	v_fma_f32 v75, -v39, v55, v51
	v_fmac_f32_e32 v55, v75, v50
	s_waitcnt lgkmcnt(0)
	v_pk_add_f32 v[6:7], v[6:7], v[22:23]
	ds_bpermute_b32 v23, v220, v7
	ds_bpermute_b32 v22, v220, v6
	v_fma_f32 v39, -v39, v55, v51
	v_add_u32_e32 v51, 0x2000, v71
	s_waitcnt lgkmcnt(0)
	v_pk_add_f32 v[6:7], v[6:7], v[22:23]
	s_nop 0
	v_pk_fma_f32 v[6:7], v[6:7], s[46:47], v[0:1] op_sel_hi:[1,0,0]
	s_nop 0
	v_mul_f32_e32 v22, 0x4b800000, v7
	v_cmp_gt_f32_e64 s[0:1], s49, v7
	s_nop 1
	v_cndmask_b32_e64 v7, v7, v22, s[0:1]
	v_rsq_f32_e32 v7, v7
	v_div_fmas_f32 v22, v39, v50, v55
	v_div_fixup_f32 v22, v22, v38, v37
	v_cmp_gt_f32_e32 vcc, s49, v6
	v_mul_f32_e32 v23, 0x45800000, v7
	v_cndmask_b32_e64 v7, v7, v23, s[0:1]
	v_mul_f32_e32 v23, v34, v7
	v_mul_f32_e32 v23, v23, v69
	v_mul_f32_e32 v23, v23, v54
	v_cvt_pk_bf16_f32 v23, v23, s0
	global_store_short v[52:53], v23, off
	v_mul_f32_e32 v23, v35, v7
	v_mul_f32_e32 v23, v23, v67
	v_mul_f32_e32 v23, v23, v73
	v_cvt_pk_bf16_f32 v23, v23, s0
	global_store_short v[18:19], v23, off
	v_mul_f32_e32 v18, v32, v7
	v_mul_f32_e32 v7, v33, v7
	v_mul_f32_e32 v7, v7, v48
	v_mul_f32_e32 v7, v7, v22
	v_cvt_pk_bf16_f32 v7, v7, s0
	global_store_short v[16:17], v7, off
	v_or_b32_e32 v16, 11, v68
	v_mul_f32_e32 v18, v18, v49
	v_ashrrev_i32_e32 v17, 31, v16
	v_mul_f32_e32 v18, v18, v36
	v_lshlrev_b64 v[16:17], 10, v[16:17]
	v_cvt_pk_bf16_f32 v18, v18, s0
	v_or_b32_e32 v16, v16, v65
	global_store_short v[20:21], v18, off
	v_lshl_add_u64 v[18:19], s[8:9], 0, v[16:17]
	v_mov_b32_e32 v7, v150
	v_or_b32_e32 v18, 64, v16
	v_mov_b32_e32 v19, v17
	v_lshl_add_u64 v[20:21], s[8:9], 0, v[18:19]
	v_mov_b32_e32 v34, v151
	v_or_b32_e32 v20, 0x80, v16
	v_mov_b32_e32 v21, v17
	v_lshl_add_u64 v[22:23], s[8:9], 0, v[20:21]
	v_mov_b32_e32 v35, v152
	v_lshl_add_u64 v[22:23], s[10:11], 0, v[16:17]
	v_or_b32_e32 v16, 0xc0, v16
	v_lshl_add_u64 v[32:33], s[8:9], 0, v[16:17]
	v_mov_b32_e32 v32, v153
	v_mul_f32_e32 v33, 0x4b800000, v6
	v_cndmask_b32_e32 v6, v6, v33, vcc
	v_rsq_f32_e32 v6, v6
	v_lshlrev_b32_e32 v7, 16, v7
	v_mul_f32_e32 v33, 0xbfb8aa3b, v7
	v_exp_f32_e32 v33, v33
	v_mul_f32_e32 v36, 0x45800000, v6
	v_cndmask_b32_e32 v6, v6, v36, vcc
	v_lshlrev_b32_e32 v34, 16, v34
	v_add_f32_e32 v33, 1.0, v33
	v_div_scale_f32 v37, s[0:1], v33, v33, v7
	v_rcp_f32_e32 v38, v37
	v_mul_f32_e32 v4, v4, v6
	v_mul_f32_e32 v4, v4, v69
	v_mul_f32_e32 v2, v2, v6
	v_fma_f32 v36, -v37, v38, 1.0
	v_fmac_f32_e32 v38, v36, v38
	v_div_scale_f32 v36, vcc, v7, v33, v7
	v_mul_f32_e32 v39, v36, v38
	v_fma_f32 v50, -v37, v39, v36
	v_fmac_f32_e32 v39, v50, v38
	v_fma_f32 v36, -v37, v39, v36
	v_mul_f32_e32 v37, 0xbfb8aa3b, v34
	v_exp_f32_e32 v37, v37
	v_div_fmas_f32 v36, v36, v38, v39
	v_div_fixup_f32 v7, v36, v33, v7
	v_mul_f32_e32 v4, v4, v7
	v_add_f32_e32 v7, 1.0, v37
	v_cvt_pk_bf16_f32 v4, v4, s0
	v_div_scale_f32 v33, s[0:1], v7, v7, v34
	v_rcp_f32_e32 v36, v33
	global_store_short v[22:23], v4, off
	v_mul_f32_e32 v4, v5, v6
	v_mul_f32_e32 v4, v4, v67
	v_fma_f32 v5, -v33, v36, 1.0
	v_fmac_f32_e32 v36, v5, v36
	v_div_scale_f32 v5, vcc, v34, v7, v34
	v_mul_f32_e32 v22, v5, v36
	v_fma_f32 v23, -v33, v22, v5
	v_fmac_f32_e32 v22, v23, v36
	v_fma_f32 v5, -v33, v22, v5
	v_div_fmas_f32 v5, v5, v36, v22
	v_div_fixup_f32 v5, v5, v7, v34
	v_lshlrev_b32_e32 v7, 16, v35
	v_mul_f32_e32 v22, 0xbfb8aa3b, v7
	v_exp_f32_e32 v22, v22
	v_mul_f32_e32 v4, v4, v5
	v_cvt_pk_bf16_f32 v23, v4, s0
	v_lshl_add_u64 v[4:5], s[10:11], 0, v[18:19]
	v_add_f32_e32 v18, 1.0, v22
	v_div_scale_f32 v19, s[0:1], v18, v18, v7
	v_rcp_f32_e32 v22, v19
	global_store_short v[4:5], v23, off
	v_mul_f32_e32 v2, v2, v49
	v_fma_f32 v4, -v19, v22, 1.0
	v_fmac_f32_e32 v22, v4, v22
	v_div_scale_f32 v4, vcc, v7, v18, v7
	v_mul_f32_e32 v5, v4, v22
	v_fma_f32 v23, -v19, v5, v4
	v_fmac_f32_e32 v5, v23, v22
	v_fma_f32 v4, -v19, v5, v4
	v_div_fmas_f32 v4, v4, v22, v5
	v_div_fixup_f32 v4, v4, v18, v7
	v_lshlrev_b32_e32 v7, 16, v32
	v_mul_f32_e32 v5, 0xbfb8aa3b, v7
	v_exp_f32_e32 v18, v5
	v_mul_f32_e32 v2, v2, v4
	v_cvt_pk_bf16_f32 v2, v2, s0
	v_lshl_add_u64 v[4:5], s[10:11], 0, v[20:21]
	v_add_f32_e32 v18, 1.0, v18
	v_div_scale_f32 v19, s[0:1], v18, v18, v7
	v_rcp_f32_e32 v20, v19
	global_store_short v[4:5], v2, off
	v_mul_f32_e32 v2, v3, v6
	v_mul_f32_e32 v2, v2, v48
	v_fma_f32 v3, -v19, v20, 1.0
	v_fmac_f32_e32 v20, v3, v20
	v_div_scale_f32 v3, vcc, v7, v18, v7
	v_mul_f32_e32 v4, v3, v20
	v_fma_f32 v5, -v19, v4, v3
	v_fmac_f32_e32 v4, v5, v20
	v_fma_f32 v3, -v19, v4, v3
	v_div_fmas_f32 v3, v3, v20, v4
	v_div_fixup_f32 v3, v3, v18, v7
	v_mul_f32_e32 v2, v2, v3
	v_cvt_pk_bf16_f32 v4, v2, s0
	v_lshl_add_u64 v[2:3], s[10:11], 0, v[16:17]
	global_store_short v[2:3], v4, off
	v_or_b32_e32 v2, 16, v68
	v_ashrrev_i32_e32 v3, 31, v2
	v_lshlrev_b64 v[6:7], 10, v[2:3]
	v_or_b32_e32 v6, v6, v65
	v_lshl_add_u64 v[2:3], s[8:9], 0, v[6:7]
	v_mov_b32_e32 v38, v154
	v_or_b32_e32 v16, 64, v6
	v_mov_b32_e32 v17, v7
	v_lshl_add_u64 v[2:3], s[8:9], 0, v[16:17]
	v_mov_b32_e32 v39, v155
	v_or_b32_e32 v18, 0x80, v6
	v_mov_b32_e32 v19, v7
	v_lshl_add_u64 v[2:3], s[8:9], 0, v[18:19]
	v_mov_b32_e32 v50, v156
	ds_read2_b32 v[2:3], v51 offset1:32
	ds_read2_b32 v[20:21], v51 offset0:64 offset1:96
	v_mov_b32_e32 v4, v8
	v_mov_b32_e32 v5, v56
	v_lshl_add_u64 v[36:37], s[10:11], 0, v[6:7]
	s_waitcnt lgkmcnt(1)
	v_pk_mul_f32 v[2:3], v[164:165], v[2:3]
	v_or_b32_e32 v6, 0xc0, v6
	v_pk_fma_f32 v[22:23], v[4:5], v[80:81], v[2:3] op_sel_hi:[1,0,1] neg_lo:[0,0,1] neg_hi:[0,0,1]
	v_mov_b32_e32 v2, v40
	v_mov_b32_e32 v3, v24
	s_waitcnt lgkmcnt(0)
	v_pk_mul_f32 v[4:5], v[164:165], v[20:21]
	v_mov_b32_e32 v56, v9
	v_pk_fma_f32 v[20:21], v[2:3], v[80:81], v[4:5] op_sel_hi:[1,0,1] neg_lo:[0,0,1] neg_hi:[0,0,1]
	v_lshl_add_u64 v[4:5], s[8:9], 0, v[6:7]
	v_mov_b32_e32 v40, v157
	ds_read2_b32 v[2:3], v51 offset0:128 offset1:160
	v_mov_b32_e32 v24, v41
	v_pk_mul_f32 v[32:33], v[22:23], v[22:23]
	v_pk_mul_f32 v[34:35], v[20:21], v[20:21]
	v_lshl_add_u64 v[16:17], s[10:11], 0, v[16:17]
	s_waitcnt lgkmcnt(0)
	v_pk_mul_f32 v[2:3], v[164:165], v[2:3]
	v_lshl_add_u64 v[6:7], s[10:11], 0, v[6:7]
	v_pk_fma_f32 v[4:5], v[56:57], v[78:79], v[2:3] op_sel_hi:[1,0,1] neg_lo:[0,0,1] neg_hi:[0,0,1]
	v_lshl_add_u64 v[18:19], s[10:11], 0, v[18:19]
	v_pk_mul_f32 v[8:9], v[4:5], v[4:5]
	v_lshlrev_b32_e32 v38, 16, v38
	v_mul_f32_e32 v2, 0xbfb8aa3b, v38
	v_exp_f32_e32 v52, v2
	ds_read2_b32 v[2:3], v51 offset0:192 offset1:224
	v_lshlrev_b32_e32 v39, 16, v39
	v_mul_f32_e32 v55, 0xbfb8aa3b, v39
	v_add_f32_e32 v41, 1.0, v52
	v_div_scale_f32 v51, s[0:1], v41, v41, v38
	v_rcp_f32_e32 v52, v51
	v_exp_f32_e32 v55, v55
	v_lshlrev_b32_e32 v50, 16, v50
	s_waitcnt lgkmcnt(0)
	v_pk_mul_f32 v[2:3], v[164:165], v[2:3]
	v_fma_f32 v53, -v51, v52, 1.0
	v_fmac_f32_e32 v52, v53, v52
	v_div_scale_f32 v53, vcc, v38, v41, v38
	v_mul_f32_e32 v54, v53, v52
	v_fma_f32 v56, -v51, v54, v53
	v_fmac_f32_e32 v54, v56, v52
	v_fma_f32 v51, -v51, v54, v53
	v_add_f32_e32 v53, 1.0, v55
	v_div_scale_f32 v55, s[0:1], v53, v53, v39
	v_rcp_f32_e32 v56, v55
	v_div_fmas_f32 v51, v51, v52, v54
	v_mul_f32_e32 v52, 0xbfb8aa3b, v50
	v_exp_f32_e32 v52, v52
	v_div_fixup_f32 v41, v51, v41, v38
	v_fma_f32 v38, -v55, v56, 1.0
	v_fmac_f32_e32 v56, v38, v56
	v_div_scale_f32 v38, vcc, v39, v53, v39
	v_mul_f32_e32 v51, v38, v56
	v_fma_f32 v54, -v55, v51, v38
	v_add_f32_e32 v52, 1.0, v52
	v_fmac_f32_e32 v51, v54, v56
	v_div_scale_f32 v54, s[0:1], v52, v52, v50
	v_fma_f32 v38, -v55, v51, v38
	v_rcp_f32_e32 v55, v54
	v_div_fmas_f32 v38, v38, v56, v51
	v_div_fixup_f32 v51, v38, v53, v39
	v_div_scale_f32 v53, vcc, v50, v52, v50
	v_fma_f32 v38, -v54, v55, 1.0
	v_fmac_f32_e32 v55, v38, v55
	v_mul_f32_e32 v56, v53, v55
	v_pk_fma_f32 v[2:3], v[24:25], v[78:79], v[2:3] op_sel_hi:[1,0,1] neg_lo:[0,0,1] neg_hi:[0,0,1]
	v_fma_f32 v38, -v54, v56, v53
	v_pk_mul_f32 v[24:25], v[2:3], v[2:3]
	v_fmac_f32_e32 v56, v38, v55
	v_mov_b32_e32 v38, v8
	v_mov_b32_e32 v39, v32
	v_mov_b32_e32 v32, v9
	v_pk_add_f32 v[8:9], v[38:39], v[32:33]
	v_mov_b32_e32 v32, v24
	v_mov_b32_e32 v33, v34
	v_pk_add_f32 v[8:9], v[8:9], v[32:33]
	v_mov_b32_e32 v34, v25
	v_pk_add_f32 v[8:9], v[8:9], v[34:35]
	ds_bpermute_b32 v25, v216, v9
	ds_bpermute_b32 v24, v216, v8
	v_lshlrev_b32_e32 v33, 16, v40
	v_mul_f32_e32 v34, 0xbfb8aa3b, v33
	v_exp_f32_e32 v34, v34
	v_fma_f32 v32, -v54, v56, v53
	s_waitcnt lgkmcnt(0)
	v_pk_add_f32 v[8:9], v[8:9], v[24:25]
	ds_bpermute_b32 v25, v217, v9
	ds_bpermute_b32 v24, v217, v8
	v_add_f32_e32 v34, 1.0, v34
	v_div_scale_f32 v35, s[0:1], v34, v34, v33
	v_rcp_f32_e32 v38, v35
	s_waitcnt lgkmcnt(0)
	v_pk_add_f32 v[8:9], v[8:9], v[24:25]
	ds_bpermute_b32 v25, v218, v9
	ds_bpermute_b32 v24, v218, v8
	v_fma_f32 v39, -v35, v38, 1.0
	v_div_fmas_f32 v32, v32, v55, v56
	v_fmac_f32_e32 v38, v39, v38
	v_div_scale_f32 v39, vcc, v33, v34, v33
	s_waitcnt lgkmcnt(0)
	v_pk_add_f32 v[8:9], v[8:9], v[24:25]
	ds_bpermute_b32 v25, v219, v9
	ds_bpermute_b32 v24, v219, v8
	v_mul_f32_e32 v40, v39, v38
	v_div_fixup_f32 v32, v32, v52, v50
	v_fma_f32 v50, -v35, v40, v39
	v_fmac_f32_e32 v40, v50, v38
	s_waitcnt lgkmcnt(0)
	v_pk_add_f32 v[8:9], v[8:9], v[24:25]
	ds_bpermute_b32 v25, v220, v9
	ds_bpermute_b32 v24, v220, v8
	v_fma_f32 v35, -v35, v40, v39
	s_waitcnt lgkmcnt(0)
	v_pk_add_f32 v[8:9], v[8:9], v[24:25]
	s_nop 0
	v_pk_fma_f32 v[8:9], v[8:9], s[46:47], v[0:1] op_sel_hi:[1,0,0]
	s_nop 0
	v_mul_f32_e32 v24, 0x4b800000, v9
	v_cmp_gt_f32_e64 s[0:1], s49, v9
	s_nop 1
	v_cndmask_b32_e64 v9, v9, v24, s[0:1]
	v_rsq_f32_e32 v9, v9
	v_div_fmas_f32 v24, v35, v38, v40
	v_div_fixup_f32 v24, v24, v34, v33
	v_cmp_gt_f32_e32 vcc, s49, v8
	v_mul_f32_e32 v25, 0x45800000, v9
	v_cndmask_b32_e64 v9, v9, v25, s[0:1]
	v_mul_f32_e32 v22, v22, v9
	v_mul_f32_e32 v22, v22, v69
	v_mul_f32_e32 v22, v22, v41
	v_cvt_pk_bf16_f32 v22, v22, s0
	global_store_short v[36:37], v22, off
	v_mul_f32_e32 v22, v23, v9
	v_mul_f32_e32 v22, v22, v67
	v_mul_f32_e32 v22, v22, v51
	v_cvt_pk_bf16_f32 v22, v22, s0
	global_store_short v[16:17], v22, off
	v_mul_f32_e32 v16, v20, v9
	v_mul_f32_e32 v9, v21, v9
	v_mul_f32_e32 v9, v9, v48
	v_mul_f32_e32 v9, v9, v24
	v_cvt_pk_bf16_f32 v9, v9, s0
	global_store_short v[6:7], v9, off
	v_or_b32_e32 v6, 17, v68
	v_mul_f32_e32 v16, v16, v49
	v_ashrrev_i32_e32 v7, 31, v6
	v_mul_f32_e32 v16, v16, v32
	v_lshlrev_b64 v[6:7], 10, v[6:7]
	v_cvt_pk_bf16_f32 v16, v16, s0
	v_or_b32_e32 v6, v6, v65
	global_store_short v[18:19], v16, off
	v_lshl_add_u64 v[16:17], s[8:9], 0, v[6:7]
	v_mov_b32_e32 v9, v158
	v_or_b32_e32 v16, 64, v6
	v_mov_b32_e32 v17, v7
	v_lshl_add_u64 v[18:19], s[8:9], 0, v[16:17]
	v_mov_b32_e32 v24, v159
	v_or_b32_e32 v18, 0x80, v6
	v_mov_b32_e32 v19, v7
	v_lshl_add_u64 v[20:21], s[8:9], 0, v[18:19]
	v_mov_b32_e32 v25, v178
	v_lshl_add_u64 v[20:21], s[10:11], 0, v[6:7]
	v_or_b32_e32 v6, 0xc0, v6
	v_lshl_add_u64 v[22:23], s[8:9], 0, v[6:7]
	v_mov_b32_e32 v22, v179
	v_mul_f32_e32 v23, 0x4b800000, v8
	v_cndmask_b32_e32 v8, v8, v23, vcc
	v_rsq_f32_e32 v8, v8
	v_add_u32_e32 v37, 0x2400, v71
	v_mul_f32_e32 v32, 0x45800000, v8
	v_cndmask_b32_e32 v8, v8, v32, vcc
	v_mul_f32_e32 v4, v4, v8
	v_mul_f32_e32 v4, v4, v69
	v_mul_f32_e32 v2, v2, v8
	v_mul_f32_e32 v2, v2, v49
	v_lshlrev_b32_e32 v9, 16, v9
	v_mul_f32_e32 v23, 0xbfb8aa3b, v9
	v_exp_f32_e32 v23, v23
	v_lshlrev_b32_e32 v24, 16, v24
	v_add_f32_e32 v23, 1.0, v23
	v_div_scale_f32 v33, s[0:1], v23, v23, v9
	v_rcp_f32_e32 v34, v33
	s_nop 0
	v_fma_f32 v32, -v33, v34, 1.0
	v_fmac_f32_e32 v34, v32, v34
	v_div_scale_f32 v32, vcc, v9, v23, v9
	v_mul_f32_e32 v35, v32, v34
	v_fma_f32 v36, -v33, v35, v32
	v_fmac_f32_e32 v35, v36, v34
	v_fma_f32 v32, -v33, v35, v32
	v_mul_f32_e32 v33, 0xbfb8aa3b, v24
	v_exp_f32_e32 v33, v33
	v_div_fmas_f32 v32, v32, v34, v35
	v_div_fixup_f32 v9, v32, v23, v9
	v_mul_f32_e32 v4, v4, v9
	v_add_f32_e32 v9, 1.0, v33
	v_cvt_pk_bf16_f32 v4, v4, s0
	v_div_scale_f32 v23, s[0:1], v9, v9, v24
	v_rcp_f32_e32 v32, v23
	global_store_short v[20:21], v4, off
	v_mul_f32_e32 v4, v5, v8
	v_mul_f32_e32 v4, v4, v67
	v_fma_f32 v5, -v23, v32, 1.0
	v_fmac_f32_e32 v32, v5, v32
	v_div_scale_f32 v5, vcc, v24, v9, v24
	v_mul_f32_e32 v20, v5, v32
	v_fma_f32 v21, -v23, v20, v5
	v_fmac_f32_e32 v20, v21, v32
	v_fma_f32 v5, -v23, v20, v5
	v_div_fmas_f32 v5, v5, v32, v20
	v_div_fixup_f32 v5, v5, v9, v24
	v_lshlrev_b32_e32 v9, 16, v25
	v_mul_f32_e32 v20, 0xbfb8aa3b, v9
	v_exp_f32_e32 v20, v20
	v_mul_f32_e32 v4, v4, v5
	v_cvt_pk_bf16_f32 v21, v4, s0
	v_lshl_add_u64 v[4:5], s[10:11], 0, v[16:17]
	v_add_f32_e32 v16, 1.0, v20
	v_div_scale_f32 v17, s[0:1], v16, v16, v9
	v_rcp_f32_e32 v20, v17
	global_store_short v[4:5], v21, off
	v_fma_f32 v4, -v17, v20, 1.0
	v_fmac_f32_e32 v20, v4, v20
	v_div_scale_f32 v4, vcc, v9, v16, v9
	v_mul_f32_e32 v5, v4, v20
	v_fma_f32 v21, -v17, v5, v4
	v_fmac_f32_e32 v5, v21, v20
	v_fma_f32 v4, -v17, v5, v4
	v_div_fmas_f32 v4, v4, v20, v5
	v_div_fixup_f32 v4, v4, v16, v9
	v_lshlrev_b32_e32 v9, 16, v22
	v_mul_f32_e32 v5, 0xbfb8aa3b, v9
	v_exp_f32_e32 v16, v5
	v_mul_f32_e32 v2, v2, v4
	v_cvt_pk_bf16_f32 v2, v2, s0
	v_lshl_add_u64 v[4:5], s[10:11], 0, v[18:19]
	v_add_f32_e32 v16, 1.0, v16
	v_div_scale_f32 v17, s[0:1], v16, v16, v9
	v_rcp_f32_e32 v18, v17
	global_store_short v[4:5], v2, off
	v_mul_f32_e32 v2, v3, v8
	v_mul_f32_e32 v2, v2, v48
	v_fma_f32 v3, -v17, v18, 1.0
	v_fmac_f32_e32 v18, v3, v18
	v_div_scale_f32 v3, vcc, v9, v16, v9
	v_mul_f32_e32 v4, v3, v18
	v_fma_f32 v5, -v17, v4, v3
	v_fmac_f32_e32 v4, v5, v18
	v_fma_f32 v3, -v17, v4, v3
	v_div_fmas_f32 v3, v3, v18, v4
	v_div_fixup_f32 v3, v3, v16, v9
	v_mul_f32_e32 v2, v2, v3
	v_cvt_pk_bf16_f32 v4, v2, s0
	v_lshl_add_u64 v[2:3], s[10:11], 0, v[6:7]
	global_store_short v[2:3], v4, off
	v_or_b32_e32 v2, 18, v68
	v_ashrrev_i32_e32 v3, 31, v2
	v_lshlrev_b64 v[6:7], 10, v[2:3]
	v_or_b32_e32 v6, v6, v65
	v_lshl_add_u64 v[2:3], s[8:9], 0, v[6:7]
	v_mov_b32_e32 v34, v180
	v_or_b32_e32 v8, 64, v6
	v_mov_b32_e32 v9, v7
	v_lshl_add_u64 v[2:3], s[8:9], 0, v[8:9]
	v_mov_b32_e32 v35, v181
	v_or_b32_e32 v16, 0x80, v6
	v_mov_b32_e32 v17, v7
	v_lshl_add_u64 v[2:3], s[8:9], 0, v[16:17]
	v_mov_b32_e32 v36, v182
	ds_read2_b32 v[2:3], v37 offset1:32
	ds_read2_b32 v[18:19], v37 offset0:64 offset1:96
	v_mov_b32_e32 v4, v10
	v_mov_b32_e32 v5, v58
	v_lshl_add_u64 v[32:33], s[10:11], 0, v[6:7]
	s_waitcnt lgkmcnt(1)
	v_pk_mul_f32 v[2:3], v[164:165], v[2:3]
	v_or_b32_e32 v6, 0xc0, v6
	v_pk_fma_f32 v[20:21], v[4:5], v[76:77], v[2:3] op_sel_hi:[1,0,1] neg_lo:[0,0,1] neg_hi:[0,0,1]
	v_mov_b32_e32 v2, v42
	v_mov_b32_e32 v3, v26
	s_waitcnt lgkmcnt(0)
	v_pk_mul_f32 v[4:5], v[164:165], v[18:19]
	v_mov_b32_e32 v58, v11
	v_pk_fma_f32 v[18:19], v[2:3], v[76:77], v[4:5] op_sel_hi:[1,0,1] neg_lo:[0,0,1] neg_hi:[0,0,1]
	v_lshl_add_u64 v[4:5], s[8:9], 0, v[6:7]
	v_mov_b32_e32 v38, v183
	ds_read2_b32 v[2:3], v37 offset0:128 offset1:160
	v_mov_b32_e32 v26, v43
	v_pk_mul_f32 v[22:23], v[20:21], v[20:21]
	v_pk_mul_f32 v[24:25], v[18:19], v[18:19]
	v_lshl_add_u64 v[8:9], s[10:11], 0, v[8:9]
	s_waitcnt lgkmcnt(0)
	v_pk_mul_f32 v[2:3], v[164:165], v[2:3]
	v_lshl_add_u64 v[16:17], s[10:11], 0, v[16:17]
	v_pk_fma_f32 v[4:5], v[58:59], v[74:75], v[2:3] op_sel_hi:[1,0,1] neg_lo:[0,0,1] neg_hi:[0,0,1]
	v_lshl_add_u64 v[6:7], s[10:11], 0, v[6:7]
	v_pk_mul_f32 v[10:11], v[4:5], v[4:5]
	v_lshlrev_b32_e32 v34, 16, v34
	v_mul_f32_e32 v2, 0xbfb8aa3b, v34
	v_exp_f32_e32 v39, v2
	ds_read2_b32 v[2:3], v37 offset0:192 offset1:224
	v_lshlrev_b32_e32 v35, 16, v35
	v_mul_f32_e32 v43, 0xbfb8aa3b, v35
	v_add_f32_e32 v37, 1.0, v39
	v_div_scale_f32 v39, s[0:1], v37, v37, v34
	v_rcp_f32_e32 v40, v39
	v_exp_f32_e32 v43, v43
	v_lshlrev_b32_e32 v36, 16, v36
	s_waitcnt lgkmcnt(0)
	v_pk_mul_f32 v[2:3], v[164:165], v[2:3]
	v_fma_f32 v41, -v39, v40, 1.0
	v_fmac_f32_e32 v40, v41, v40
	v_div_scale_f32 v41, vcc, v34, v37, v34
	v_mul_f32_e32 v42, v41, v40
	v_fma_f32 v50, -v39, v42, v41
	v_fmac_f32_e32 v42, v50, v40
	v_fma_f32 v39, -v39, v42, v41
	v_add_f32_e32 v41, 1.0, v43
	v_div_scale_f32 v43, s[0:1], v41, v41, v35
	v_rcp_f32_e32 v50, v43
	v_div_fmas_f32 v39, v39, v40, v42
	v_mul_f32_e32 v40, 0xbfb8aa3b, v36
	v_exp_f32_e32 v40, v40
	v_div_fixup_f32 v37, v39, v37, v34
	v_fma_f32 v34, -v43, v50, 1.0
	v_fmac_f32_e32 v50, v34, v50
	v_div_scale_f32 v34, vcc, v35, v41, v35
	v_mul_f32_e32 v39, v34, v50
	v_fma_f32 v42, -v43, v39, v34
	v_add_f32_e32 v40, 1.0, v40
	v_fmac_f32_e32 v39, v42, v50
	v_div_scale_f32 v42, s[0:1], v40, v40, v36
	v_fma_f32 v34, -v43, v39, v34
	v_rcp_f32_e32 v43, v42
	v_div_fmas_f32 v34, v34, v50, v39
	v_div_fixup_f32 v39, v34, v41, v35
	v_div_scale_f32 v41, vcc, v36, v40, v36
	v_fma_f32 v34, -v42, v43, 1.0
	v_fmac_f32_e32 v43, v34, v43
	v_mul_f32_e32 v50, v41, v43
	v_pk_fma_f32 v[2:3], v[26:27], v[74:75], v[2:3] op_sel_hi:[1,0,1] neg_lo:[0,0,1] neg_hi:[0,0,1]
	v_fma_f32 v34, -v42, v50, v41
	v_pk_mul_f32 v[26:27], v[2:3], v[2:3]
	v_fmac_f32_e32 v50, v34, v43
	v_mov_b32_e32 v34, v10
	v_mov_b32_e32 v35, v22
	v_mov_b32_e32 v22, v11
	v_pk_add_f32 v[10:11], v[34:35], v[22:23]
	v_mov_b32_e32 v22, v26
	v_mov_b32_e32 v23, v24
	v_pk_add_f32 v[10:11], v[10:11], v[22:23]
	v_mov_b32_e32 v24, v27
	v_pk_add_f32 v[10:11], v[10:11], v[24:25]
	ds_bpermute_b32 v23, v216, v11
	ds_bpermute_b32 v22, v216, v10
	v_lshlrev_b32_e32 v25, 16, v38
	v_mul_f32_e32 v26, 0xbfb8aa3b, v25
	v_exp_f32_e32 v26, v26
	v_fma_f32 v24, -v42, v50, v41
	s_waitcnt lgkmcnt(0)
	v_pk_add_f32 v[10:11], v[10:11], v[22:23]
	ds_bpermute_b32 v23, v217, v11
	ds_bpermute_b32 v22, v217, v10
	v_add_f32_e32 v26, 1.0, v26
	v_div_scale_f32 v27, s[0:1], v26, v26, v25
	v_rcp_f32_e32 v34, v27
	s_waitcnt lgkmcnt(0)
	v_pk_add_f32 v[10:11], v[10:11], v[22:23]
	ds_bpermute_b32 v23, v218, v11
	ds_bpermute_b32 v22, v218, v10
	v_fma_f32 v35, -v27, v34, 1.0
	v_div_fmas_f32 v24, v24, v43, v50
	v_fmac_f32_e32 v34, v35, v34
	v_div_scale_f32 v35, vcc, v25, v26, v25
	s_waitcnt lgkmcnt(0)
	v_pk_add_f32 v[10:11], v[10:11], v[22:23]
	ds_bpermute_b32 v23, v219, v11
	ds_bpermute_b32 v22, v219, v10
	v_div_fixup_f32 v24, v24, v40, v36
	v_mul_f32_e32 v36, v35, v34
	v_fma_f32 v38, -v27, v36, v35
	v_fmac_f32_e32 v36, v38, v34
	s_waitcnt lgkmcnt(0)
	v_pk_add_f32 v[10:11], v[10:11], v[22:23]
	ds_bpermute_b32 v23, v220, v11
	ds_bpermute_b32 v22, v220, v10
	v_fma_f32 v27, -v27, v36, v35
	s_waitcnt lgkmcnt(0)
	v_pk_add_f32 v[10:11], v[10:11], v[22:23]
	s_nop 0
	v_pk_fma_f32 v[10:11], v[10:11], s[46:47], v[0:1] op_sel_hi:[1,0,0]
	s_nop 0
	v_mul_f32_e32 v22, 0x4b800000, v11
	v_cmp_gt_f32_e64 s[0:1], s49, v11
	s_nop 1
	v_cndmask_b32_e64 v11, v11, v22, s[0:1]
	v_rsq_f32_e32 v11, v11
	v_div_fmas_f32 v22, v27, v34, v36
	v_div_fixup_f32 v22, v22, v26, v25
	v_cmp_gt_f32_e32 vcc, s49, v10
	v_mul_f32_e32 v23, 0x45800000, v11
	v_cndmask_b32_e64 v11, v11, v23, s[0:1]
	v_mul_f32_e32 v20, v20, v11
	v_mul_f32_e32 v20, v20, v69
	v_mul_f32_e32 v20, v20, v37
	v_cvt_pk_bf16_f32 v20, v20, s0
	global_store_short v[32:33], v20, off
	v_mul_f32_e32 v20, v21, v11
	v_mul_f32_e32 v20, v20, v67
	v_mul_f32_e32 v20, v20, v39
	v_cvt_pk_bf16_f32 v20, v20, s0
	global_store_short v[8:9], v20, off
	v_mul_f32_e32 v8, v18, v11
	v_mul_f32_e32 v8, v8, v49
	v_mul_f32_e32 v8, v8, v24
	v_cvt_pk_bf16_f32 v8, v8, s0
	global_store_short v[16:17], v8, off
	v_mul_f32_e32 v8, v19, v11
	v_mul_f32_e32 v8, v8, v48
	v_mul_f32_e32 v8, v8, v22
	v_cvt_pk_bf16_f32 v8, v8, s0
	global_store_short v[6:7], v8, off
	v_or_b32_e32 v6, 19, v68
	v_ashrrev_i32_e32 v7, 31, v6
	v_lshlrev_b64 v[6:7], 10, v[6:7]
	v_or_b32_e32 v6, v6, v65
	v_lshl_add_u64 v[8:9], s[8:9], 0, v[6:7]
	v_mov_b32_e32 v11, v184
	v_or_b32_e32 v8, 64, v6
	v_mov_b32_e32 v9, v7
	v_lshl_add_u64 v[16:17], s[8:9], 0, v[8:9]
	v_mov_b32_e32 v22, v185
	v_or_b32_e32 v16, 0x80, v6
	v_mov_b32_e32 v17, v7
	v_lshl_add_u64 v[18:19], s[8:9], 0, v[16:17]
	v_mov_b32_e32 v23, v186
	v_lshl_add_u64 v[18:19], s[10:11], 0, v[6:7]
	v_or_b32_e32 v6, 0xc0, v6
	v_lshl_add_u64 v[20:21], s[8:9], 0, v[6:7]
	v_mov_b32_e32 v20, v187
	v_mul_f32_e32 v21, 0x4b800000, v10
	v_cndmask_b32_e32 v10, v10, v21, vcc
	v_rsq_f32_e32 v10, v10
	v_lshlrev_b32_e32 v11, 16, v11
	v_mul_f32_e32 v21, 0xbfb8aa3b, v11
	v_exp_f32_e32 v21, v21
	v_mul_f32_e32 v24, 0x45800000, v10
	v_cndmask_b32_e32 v10, v10, v24, vcc
	v_lshlrev_b32_e32 v22, 16, v22
	v_add_f32_e32 v21, 1.0, v21
	v_div_scale_f32 v25, s[0:1], v21, v21, v11
	v_rcp_f32_e32 v26, v25
	v_mul_f32_e32 v4, v4, v10
	v_mul_f32_e32 v4, v4, v69
	v_mul_f32_e32 v2, v2, v10
	v_fma_f32 v24, -v25, v26, 1.0
	v_fmac_f32_e32 v26, v24, v26
	v_div_scale_f32 v24, vcc, v11, v21, v11
	v_mul_f32_e32 v27, v24, v26
	v_fma_f32 v32, -v25, v27, v24
	v_fmac_f32_e32 v27, v32, v26
	v_fma_f32 v24, -v25, v27, v24
	v_mul_f32_e32 v25, 0xbfb8aa3b, v22
	v_exp_f32_e32 v25, v25
	v_div_fmas_f32 v24, v24, v26, v27
	v_div_fixup_f32 v11, v24, v21, v11
	v_mul_f32_e32 v4, v4, v11
	v_add_f32_e32 v11, 1.0, v25
	v_cvt_pk_bf16_f32 v4, v4, s0
	v_div_scale_f32 v21, s[0:1], v11, v11, v22
	v_rcp_f32_e32 v24, v21
	global_store_short v[18:19], v4, off
	v_mul_f32_e32 v4, v5, v10
	v_mul_f32_e32 v4, v4, v67
	v_fma_f32 v5, -v21, v24, 1.0
	v_fmac_f32_e32 v24, v5, v24
	v_div_scale_f32 v5, vcc, v22, v11, v22
	v_mul_f32_e32 v18, v5, v24
	v_fma_f32 v19, -v21, v18, v5
	v_fmac_f32_e32 v18, v19, v24
	v_fma_f32 v5, -v21, v18, v5
	v_div_fmas_f32 v5, v5, v24, v18
	v_div_fixup_f32 v5, v5, v11, v22
	v_lshlrev_b32_e32 v11, 16, v23
	v_mul_f32_e32 v18, 0xbfb8aa3b, v11
	v_exp_f32_e32 v18, v18
	v_mul_f32_e32 v4, v4, v5
	v_cvt_pk_bf16_f32 v19, v4, s0
	v_lshl_add_u64 v[4:5], s[10:11], 0, v[8:9]
	v_add_f32_e32 v8, 1.0, v18
	v_div_scale_f32 v9, s[0:1], v8, v8, v11
	v_rcp_f32_e32 v18, v9
	global_store_short v[4:5], v19, off
	v_mul_f32_e32 v2, v2, v49
	v_add_u32_e32 v27, 0x3000, v71
	v_fma_f32 v4, -v9, v18, 1.0
	v_fmac_f32_e32 v18, v4, v18
	v_div_scale_f32 v4, vcc, v11, v8, v11
	v_mul_f32_e32 v5, v4, v18
	v_fma_f32 v19, -v9, v5, v4
	v_fmac_f32_e32 v5, v19, v18
	v_fma_f32 v4, -v9, v5, v4
	v_div_fmas_f32 v4, v4, v18, v5
	v_div_fixup_f32 v4, v4, v8, v11
	v_lshlrev_b32_e32 v8, 16, v20
	v_mul_f32_e32 v5, 0xbfb8aa3b, v8
	v_exp_f32_e32 v9, v5
	v_mul_f32_e32 v2, v2, v4
	v_cvt_pk_bf16_f32 v2, v2, s0
	v_lshl_add_u64 v[4:5], s[10:11], 0, v[16:17]
	v_add_f32_e32 v9, 1.0, v9
	v_div_scale_f32 v11, s[0:1], v9, v9, v8
	v_rcp_f32_e32 v16, v11
	global_store_short v[4:5], v2, off
	v_mul_f32_e32 v2, v3, v10
	v_mul_f32_e32 v2, v2, v48
	v_fma_f32 v3, -v11, v16, 1.0
	v_fmac_f32_e32 v16, v3, v16
	v_div_scale_f32 v3, vcc, v8, v9, v8
	v_mul_f32_e32 v4, v3, v16
	v_fma_f32 v5, -v11, v4, v3
	v_fmac_f32_e32 v4, v5, v16
	v_fma_f32 v3, -v11, v4, v3
	v_div_fmas_f32 v3, v3, v16, v4
	v_div_fixup_f32 v3, v3, v9, v8
	v_mul_f32_e32 v2, v2, v3
	v_cvt_pk_bf16_f32 v4, v2, s0
	v_lshl_add_u64 v[2:3], s[10:11], 0, v[6:7]
	global_store_short v[2:3], v4, off
	v_or_b32_e32 v2, 24, v68
	v_ashrrev_i32_e32 v3, 31, v2
	v_lshlrev_b64 v[6:7], 10, v[2:3]
	v_or_b32_e32 v6, v6, v65
	v_lshl_add_u64 v[2:3], s[8:9], 0, v[6:7]
	v_mov_b32_e32 v26, v188
	v_or_b32_e32 v8, 64, v6
	v_mov_b32_e32 v9, v7
	v_lshl_add_u64 v[2:3], s[8:9], 0, v[8:9]
	v_mov_b32_e32 v32, v189
	v_or_b32_e32 v10, 0x80, v6
	v_mov_b32_e32 v11, v7
	v_lshl_add_u64 v[2:3], s[8:9], 0, v[10:11]
	v_mov_b32_e32 v33, v190
	ds_read2_b32 v[2:3], v27 offset1:32
	ds_read2_b32 v[16:17], v27 offset0:64 offset1:96
	v_mov_b32_e32 v4, v12
	v_mov_b32_e32 v5, v60
	v_lshl_add_u64 v[24:25], s[10:11], 0, v[6:7]
	s_waitcnt lgkmcnt(1)
	v_pk_mul_f32 v[2:3], v[164:165], v[2:3]
	v_or_b32_e32 v6, 0xc0, v6
	v_pk_fma_f32 v[18:19], v[4:5], v[72:73], v[2:3] op_sel_hi:[1,0,1] neg_lo:[0,0,1] neg_hi:[0,0,1]
	v_mov_b32_e32 v2, v44
	v_mov_b32_e32 v3, v28
	s_waitcnt lgkmcnt(0)
	v_pk_mul_f32 v[4:5], v[164:165], v[16:17]
	v_mov_b32_e32 v60, v13
	v_pk_fma_f32 v[16:17], v[2:3], v[72:73], v[4:5] op_sel_hi:[1,0,1] neg_lo:[0,0,1] neg_hi:[0,0,1]
	v_lshl_add_u64 v[4:5], s[8:9], 0, v[6:7]
	v_mov_b32_e32 v34, v191
	ds_read2_b32 v[2:3], v27 offset0:128 offset1:160
	v_mov_b32_e32 v28, v45
	v_pk_mul_f32 v[20:21], v[18:19], v[18:19]
	v_pk_mul_f32 v[22:23], v[16:17], v[16:17]
	v_lshl_add_u64 v[8:9], s[10:11], 0, v[8:9]
	s_waitcnt lgkmcnt(0)
	v_pk_mul_f32 v[2:3], v[164:165], v[2:3]
	v_lshl_add_u64 v[10:11], s[10:11], 0, v[10:11]
	v_pk_fma_f32 v[4:5], v[60:61], v[70:71], v[2:3] op_sel_hi:[1,0,1] neg_lo:[0,0,1] neg_hi:[0,0,1]
	v_lshl_add_u64 v[6:7], s[10:11], 0, v[6:7]
	v_pk_mul_f32 v[12:13], v[4:5], v[4:5]
	v_lshlrev_b32_e32 v35, 16, v26
	v_mul_f32_e32 v2, 0xbfb8aa3b, v35
	v_exp_f32_e32 v26, v2
	ds_read2_b32 v[2:3], v27 offset0:192 offset1:224
	v_lshlrev_b32_e32 v32, 16, v32
	v_mul_f32_e32 v39, 0xbfb8aa3b, v32
	v_add_f32_e32 v36, 1.0, v26
	v_div_scale_f32 v37, s[0:1], v36, v36, v35
	v_rcp_f32_e32 v38, v37
	s_waitcnt lgkmcnt(0)
	v_pk_mul_f32 v[2:3], v[164:165], v[2:3]
	v_exp_f32_e32 v39, v39
	v_pk_fma_f32 v[2:3], v[28:29], v[70:71], v[2:3] op_sel_hi:[1,0,1] neg_lo:[0,0,1] neg_hi:[0,0,1]
	v_fma_f32 v28, -v37, v38, 1.0
	v_fmac_f32_e32 v38, v28, v38
	v_div_scale_f32 v28, vcc, v35, v36, v35
	v_mul_f32_e32 v29, v28, v38
	v_fma_f32 v40, -v37, v29, v28
	v_fmac_f32_e32 v29, v40, v38
	v_fma_f32 v28, -v37, v29, v28
	v_add_f32_e32 v37, 1.0, v39
	v_div_scale_f32 v39, s[0:1], v37, v37, v32
	v_rcp_f32_e32 v40, v39
	v_div_fmas_f32 v28, v28, v38, v29
	v_lshlrev_b32_e32 v33, 16, v33
	v_div_fixup_f32 v35, v28, v36, v35
	v_mul_f32_e32 v36, 0xbfb8aa3b, v33
	v_exp_f32_e32 v36, v36
	v_fma_f32 v28, -v39, v40, 1.0
	v_fmac_f32_e32 v40, v28, v40
	v_div_scale_f32 v28, vcc, v32, v37, v32
	v_mul_f32_e32 v29, v28, v40
	v_fma_f32 v38, -v39, v29, v28
	v_add_f32_e32 v36, 1.0, v36
	v_fmac_f32_e32 v29, v38, v40
	v_div_scale_f32 v38, s[0:1], v36, v36, v33
	v_fma_f32 v28, -v39, v29, v28
	v_rcp_f32_e32 v39, v38
	v_div_fmas_f32 v28, v28, v40, v29
	v_div_fixup_f32 v32, v28, v37, v32
	v_div_scale_f32 v37, vcc, v33, v36, v33
	v_fma_f32 v28, -v38, v39, 1.0
	v_fmac_f32_e32 v39, v28, v39
	v_mul_f32_e32 v40, v37, v39
	v_fma_f32 v28, -v38, v40, v37
	v_pk_mul_f32 v[26:27], v[2:3], v[2:3]
	v_fmac_f32_e32 v40, v28, v39
	v_mov_b32_e32 v28, v12
	v_mov_b32_e32 v29, v20
	v_mov_b32_e32 v20, v13
	v_pk_add_f32 v[12:13], v[28:29], v[20:21]
	v_mov_b32_e32 v20, v26
	v_mov_b32_e32 v21, v22
	v_pk_add_f32 v[12:13], v[12:13], v[20:21]
	v_mov_b32_e32 v22, v27
	v_pk_add_f32 v[12:13], v[12:13], v[22:23]
	ds_bpermute_b32 v21, v216, v13
	ds_bpermute_b32 v20, v216, v12
	v_lshlrev_b32_e32 v23, 16, v34
	v_mul_f32_e32 v26, 0xbfb8aa3b, v23
	v_exp_f32_e32 v26, v26
	v_fma_f32 v22, -v38, v40, v37
	s_waitcnt lgkmcnt(0)
	v_pk_add_f32 v[12:13], v[12:13], v[20:21]
	ds_bpermute_b32 v21, v217, v13
	ds_bpermute_b32 v20, v217, v12
	v_add_f32_e32 v26, 1.0, v26
	v_div_scale_f32 v27, s[0:1], v26, v26, v23
	v_rcp_f32_e32 v28, v27
	s_waitcnt lgkmcnt(0)
	v_pk_add_f32 v[12:13], v[12:13], v[20:21]
	ds_bpermute_b32 v21, v218, v13
	ds_bpermute_b32 v20, v218, v12
	v_fma_f32 v29, -v27, v28, 1.0
	v_div_fmas_f32 v22, v22, v39, v40
	v_fmac_f32_e32 v28, v29, v28
	v_div_scale_f32 v29, vcc, v23, v26, v23
	s_waitcnt lgkmcnt(0)
	v_pk_add_f32 v[12:13], v[12:13], v[20:21]
	ds_bpermute_b32 v21, v219, v13
	ds_bpermute_b32 v20, v219, v12
	v_div_fixup_f32 v22, v22, v36, v33
	v_mul_f32_e32 v33, v29, v28
	v_fma_f32 v34, -v27, v33, v29
	v_fmac_f32_e32 v33, v34, v28
	s_waitcnt lgkmcnt(0)
	v_pk_add_f32 v[12:13], v[12:13], v[20:21]
	ds_bpermute_b32 v21, v220, v13
	ds_bpermute_b32 v20, v220, v12
	v_fma_f32 v27, -v27, v33, v29
	s_waitcnt lgkmcnt(0)
	v_pk_add_f32 v[12:13], v[12:13], v[20:21]
	s_nop 0
	v_pk_fma_f32 v[12:13], v[12:13], s[46:47], v[0:1] op_sel_hi:[1,0,0]
	s_nop 0
	v_mul_f32_e32 v20, 0x4b800000, v13
	v_cmp_gt_f32_e64 s[0:1], s49, v13
	s_nop 1
	v_cndmask_b32_e64 v13, v13, v20, s[0:1]
	v_rsq_f32_e32 v13, v13
	v_div_fmas_f32 v20, v27, v28, v33
	v_div_fixup_f32 v20, v20, v26, v23
	v_cmp_gt_f32_e32 vcc, s49, v12
	v_mul_f32_e32 v21, 0x45800000, v13
	v_cndmask_b32_e64 v13, v13, v21, s[0:1]
	v_mul_f32_e32 v18, v18, v13
	v_mul_f32_e32 v18, v18, v69
	v_mul_f32_e32 v18, v18, v35
	v_cvt_pk_bf16_f32 v18, v18, s0
	global_store_short v[24:25], v18, off
	v_mul_f32_e32 v18, v19, v13
	v_mul_f32_e32 v18, v18, v67
	v_mul_f32_e32 v18, v18, v32
	v_cvt_pk_bf16_f32 v18, v18, s0
	global_store_short v[8:9], v18, off
	v_mul_f32_e32 v8, v16, v13
	v_mul_f32_e32 v8, v8, v49
	v_mul_f32_e32 v8, v8, v22
	v_cvt_pk_bf16_f32 v8, v8, s0
	global_store_short v[10:11], v8, off
	v_mul_f32_e32 v8, v17, v13
	v_mul_f32_e32 v8, v8, v48
	v_mul_f32_e32 v8, v8, v20
	v_cvt_pk_bf16_f32 v8, v8, s0
	global_store_short v[6:7], v8, off
	v_or_b32_e32 v6, 25, v68
	v_ashrrev_i32_e32 v7, 31, v6
	v_lshlrev_b64 v[6:7], 10, v[6:7]
	v_or_b32_e32 v6, v6, v65
	v_lshl_add_u64 v[8:9], s[8:9], 0, v[6:7]
	v_mov_b32_e32 v13, v192
	v_or_b32_e32 v8, 64, v6
	v_mov_b32_e32 v9, v7
	v_lshl_add_u64 v[10:11], s[8:9], 0, v[8:9]
	v_mov_b32_e32 v20, v193
	v_or_b32_e32 v10, 0x80, v6
	v_mov_b32_e32 v11, v7
	v_lshl_add_u64 v[16:17], s[8:9], 0, v[10:11]
	v_mov_b32_e32 v21, v194
	v_lshl_add_u64 v[16:17], s[10:11], 0, v[6:7]
	v_or_b32_e32 v6, 0xc0, v6
	v_lshl_add_u64 v[18:19], s[8:9], 0, v[6:7]
	v_mov_b32_e32 v18, v195
	v_mul_f32_e32 v19, 0x4b800000, v12
	v_cndmask_b32_e32 v12, v12, v19, vcc
	v_rsq_f32_e32 v12, v12
	v_lshlrev_b32_e32 v13, 16, v13
	v_mul_f32_e32 v19, 0xbfb8aa3b, v13
	v_exp_f32_e32 v19, v19
	v_mul_f32_e32 v22, 0x45800000, v12
	v_cndmask_b32_e32 v12, v12, v22, vcc
	v_lshlrev_b32_e32 v20, 16, v20
	v_add_f32_e32 v19, 1.0, v19
	v_div_scale_f32 v23, s[0:1], v19, v19, v13
	v_rcp_f32_e32 v24, v23
	v_mul_f32_e32 v4, v4, v12
	v_mul_f32_e32 v4, v4, v69
	v_mul_f32_e32 v2, v2, v12
	v_fma_f32 v22, -v23, v24, 1.0
	v_fmac_f32_e32 v24, v22, v24
	v_div_scale_f32 v22, vcc, v13, v19, v13
	v_mul_f32_e32 v25, v22, v24
	v_fma_f32 v26, -v23, v25, v22
	v_fmac_f32_e32 v25, v26, v24
	v_fma_f32 v22, -v23, v25, v22
	v_mul_f32_e32 v23, 0xbfb8aa3b, v20
	v_exp_f32_e32 v23, v23
	v_div_fmas_f32 v22, v22, v24, v25
	v_div_fixup_f32 v13, v22, v19, v13
	v_mul_f32_e32 v4, v4, v13
	v_add_f32_e32 v13, 1.0, v23
	v_cvt_pk_bf16_f32 v4, v4, s0
	v_div_scale_f32 v19, s[0:1], v13, v13, v20
	v_rcp_f32_e32 v22, v19
	global_store_short v[16:17], v4, off
	v_mul_f32_e32 v4, v5, v12
	v_mul_f32_e32 v4, v4, v67
	v_fma_f32 v5, -v19, v22, 1.0
	v_fmac_f32_e32 v22, v5, v22
	v_div_scale_f32 v5, vcc, v20, v13, v20
	v_mul_f32_e32 v16, v5, v22
	v_fma_f32 v17, -v19, v16, v5
	v_fmac_f32_e32 v16, v17, v22
	v_fma_f32 v5, -v19, v16, v5
	v_div_fmas_f32 v5, v5, v22, v16
	v_div_fixup_f32 v5, v5, v13, v20
	v_lshlrev_b32_e32 v13, 16, v21
	v_mul_f32_e32 v16, 0xbfb8aa3b, v13
	v_exp_f32_e32 v16, v16
	v_mul_f32_e32 v4, v4, v5
	v_cvt_pk_bf16_f32 v17, v4, s0
	v_lshl_add_u64 v[4:5], s[10:11], 0, v[8:9]
	v_add_f32_e32 v8, 1.0, v16
	v_div_scale_f32 v9, s[0:1], v8, v8, v13
	v_rcp_f32_e32 v16, v9
	global_store_short v[4:5], v17, off
	v_mul_f32_e32 v2, v2, v49
	v_add_u32_e32 v25, 0x3400, v71
	v_fma_f32 v4, -v9, v16, 1.0
	v_fmac_f32_e32 v16, v4, v16
	v_div_scale_f32 v4, vcc, v13, v8, v13
	v_mul_f32_e32 v5, v4, v16
	v_fma_f32 v17, -v9, v5, v4
	v_fmac_f32_e32 v5, v17, v16
	v_fma_f32 v4, -v9, v5, v4
	v_div_fmas_f32 v4, v4, v16, v5
	v_div_fixup_f32 v4, v4, v8, v13
	v_lshlrev_b32_e32 v8, 16, v18
	v_mul_f32_e32 v5, 0xbfb8aa3b, v8
	v_exp_f32_e32 v9, v5
	v_mul_f32_e32 v2, v2, v4
	v_cvt_pk_bf16_f32 v2, v2, s0
	v_lshl_add_u64 v[4:5], s[10:11], 0, v[10:11]
	v_add_f32_e32 v9, 1.0, v9
	v_div_scale_f32 v10, s[0:1], v9, v9, v8
	v_rcp_f32_e32 v11, v10
	global_store_short v[4:5], v2, off
	v_mul_f32_e32 v2, v3, v12
	v_mul_f32_e32 v2, v2, v48
	v_fma_f32 v3, -v10, v11, 1.0
	v_fmac_f32_e32 v11, v3, v11
	v_div_scale_f32 v3, vcc, v8, v9, v8
	v_mul_f32_e32 v4, v3, v11
	v_fma_f32 v5, -v10, v4, v3
	v_fmac_f32_e32 v4, v5, v11
	v_fma_f32 v3, -v10, v4, v3
	v_div_fmas_f32 v3, v3, v11, v4
	v_div_fixup_f32 v3, v3, v9, v8
	v_mul_f32_e32 v2, v2, v3
	v_cvt_pk_bf16_f32 v4, v2, s0
	v_lshl_add_u64 v[2:3], s[10:11], 0, v[6:7]
	global_store_short v[2:3], v4, off
	v_or_b32_e32 v2, 26, v68
	v_ashrrev_i32_e32 v3, 31, v2
	v_lshlrev_b64 v[6:7], 10, v[2:3]
	v_or_b32_e32 v6, v6, v65
	v_lshl_add_u64 v[2:3], s[8:9], 0, v[6:7]
	v_mov_b32_e32 v24, v196
	v_or_b32_e32 v8, 64, v6
	v_mov_b32_e32 v9, v7
	v_lshl_add_u64 v[2:3], s[8:9], 0, v[8:9]
	v_mov_b32_e32 v26, v197
	v_or_b32_e32 v10, 0x80, v6
	v_mov_b32_e32 v11, v7
	v_lshl_add_u64 v[2:3], s[8:9], 0, v[10:11]
	v_mov_b32_e32 v27, v198
	ds_read2_b32 v[2:3], v25 offset1:32
	ds_read2_b32 v[12:13], v25 offset0:64 offset1:96
	v_mov_b32_e32 v4, v14
	v_mov_b32_e32 v5, v62
	v_lshl_add_u64 v[22:23], s[10:11], 0, v[6:7]
	s_waitcnt lgkmcnt(1)
	v_pk_mul_f32 v[2:3], v[164:165], v[2:3]
	v_or_b32_e32 v6, 0xc0, v6
	v_pk_fma_f32 v[16:17], v[4:5], v[66:67], v[2:3] op_sel_hi:[1,0,1] neg_lo:[0,0,1] neg_hi:[0,0,1]
	v_mov_b32_e32 v2, v46
	v_mov_b32_e32 v3, v30
	s_waitcnt lgkmcnt(0)
	v_pk_mul_f32 v[4:5], v[164:165], v[12:13]
	v_mov_b32_e32 v62, v15
	v_pk_fma_f32 v[12:13], v[2:3], v[66:67], v[4:5] op_sel_hi:[1,0,1] neg_lo:[0,0,1] neg_hi:[0,0,1]
	v_lshl_add_u64 v[4:5], s[8:9], 0, v[6:7]
	v_mov_b32_e32 v28, v199
	ds_read2_b32 v[2:3], v25 offset0:128 offset1:160
	v_mov_b32_e32 v30, v47
	v_pk_mul_f32 v[18:19], v[16:17], v[16:17]
	v_pk_mul_f32 v[20:21], v[12:13], v[12:13]
	v_lshl_add_u64 v[8:9], s[10:11], 0, v[8:9]
	s_waitcnt lgkmcnt(0)
	v_pk_mul_f32 v[2:3], v[164:165], v[2:3]
	v_lshl_add_u64 v[6:7], s[10:11], 0, v[6:7]
	v_pk_fma_f32 v[4:5], v[62:63], v[64:65], v[2:3] op_sel_hi:[1,0,1] neg_lo:[0,0,1] neg_hi:[0,0,1]
	v_lshl_add_u64 v[10:11], s[10:11], 0, v[10:11]
	v_pk_mul_f32 v[14:15], v[4:5], v[4:5]
	v_lshlrev_b32_e32 v29, 16, v24
	v_mul_f32_e32 v2, 0xbfb8aa3b, v29
	v_exp_f32_e32 v24, v2
	ds_read2_b32 v[2:3], v25 offset0:192 offset1:224
	v_lshlrev_b32_e32 v26, 16, v26
	v_mul_f32_e32 v35, 0xbfb8aa3b, v26
	v_add_f32_e32 v32, 1.0, v24
	v_div_scale_f32 v33, s[0:1], v32, v32, v29
	v_rcp_f32_e32 v34, v33
	s_waitcnt lgkmcnt(0)
	v_pk_mul_f32 v[2:3], v[164:165], v[2:3]
	v_exp_f32_e32 v35, v35
	v_pk_fma_f32 v[2:3], v[30:31], v[64:65], v[2:3] op_sel_hi:[1,0,1] neg_lo:[0,0,1] neg_hi:[0,0,1]
	v_fma_f32 v30, -v33, v34, 1.0
	v_fmac_f32_e32 v34, v30, v34
	v_div_scale_f32 v30, vcc, v29, v32, v29
	v_mul_f32_e32 v31, v30, v34
	v_fma_f32 v36, -v33, v31, v30
	v_fmac_f32_e32 v31, v36, v34
	v_fma_f32 v30, -v33, v31, v30
	v_add_f32_e32 v33, 1.0, v35
	v_div_scale_f32 v35, s[0:1], v33, v33, v26
	v_rcp_f32_e32 v36, v35
	v_div_fmas_f32 v30, v30, v34, v31
	v_div_fixup_f32 v29, v30, v32, v29
	v_lshlrev_b32_e32 v32, 16, v27
	v_mul_f32_e32 v27, 0xbfb8aa3b, v32
	v_fma_f32 v30, -v35, v36, 1.0
	v_exp_f32_e32 v27, v27
	v_fmac_f32_e32 v36, v30, v36
	v_div_scale_f32 v30, vcc, v26, v33, v26
	v_mul_f32_e32 v31, v30, v36
	v_fma_f32 v34, -v35, v31, v30
	v_fmac_f32_e32 v31, v34, v36
	v_add_f32_e32 v34, 1.0, v27
	v_fma_f32 v30, -v35, v31, v30
	v_div_scale_f32 v35, s[0:1], v34, v34, v32
	v_rcp_f32_e32 v37, v35
	v_div_fmas_f32 v27, v30, v36, v31
	v_div_fixup_f32 v30, v27, v33, v26
	v_div_scale_f32 v31, vcc, v32, v34, v32
	v_fma_f32 v26, -v35, v37, 1.0
	v_fmac_f32_e32 v37, v26, v37
	v_mul_f32_e32 v33, v31, v37
	v_fma_f32 v26, -v35, v33, v31
	v_pk_mul_f32 v[24:25], v[2:3], v[2:3]
	v_fmac_f32_e32 v33, v26, v37
	v_mov_b32_e32 v26, v14
	v_mov_b32_e32 v27, v18
	v_mov_b32_e32 v18, v15
	v_pk_add_f32 v[14:15], v[26:27], v[18:19]
	v_mov_b32_e32 v18, v24
	v_mov_b32_e32 v19, v20
	v_pk_add_f32 v[14:15], v[14:15], v[18:19]
	v_mov_b32_e32 v20, v25
	v_pk_add_f32 v[14:15], v[14:15], v[20:21]
	ds_bpermute_b32 v19, v216, v15
	ds_bpermute_b32 v18, v216, v14
	v_lshlrev_b32_e32 v21, 16, v28
	v_mul_f32_e32 v24, 0xbfb8aa3b, v21
	v_exp_f32_e32 v24, v24
	v_fma_f32 v20, -v35, v33, v31
	s_waitcnt lgkmcnt(0)
	v_pk_add_f32 v[14:15], v[14:15], v[18:19]
	ds_bpermute_b32 v19, v217, v15
	ds_bpermute_b32 v18, v217, v14
	v_add_f32_e32 v24, 1.0, v24
	v_div_scale_f32 v25, s[0:1], v24, v24, v21
	v_rcp_f32_e32 v26, v25
	s_waitcnt lgkmcnt(0)
	v_pk_add_f32 v[14:15], v[14:15], v[18:19]
	ds_bpermute_b32 v19, v218, v15
	ds_bpermute_b32 v18, v218, v14
	v_fma_f32 v27, -v25, v26, 1.0
	v_div_fmas_f32 v20, v20, v37, v33
	v_fmac_f32_e32 v26, v27, v26
	v_div_scale_f32 v27, vcc, v21, v24, v21
	s_waitcnt lgkmcnt(0)
	v_pk_add_f32 v[14:15], v[14:15], v[18:19]
	ds_bpermute_b32 v19, v219, v15
	ds_bpermute_b32 v18, v219, v14
	v_mul_f32_e32 v28, v27, v26
	v_fma_f32 v31, -v25, v28, v27
	v_fmac_f32_e32 v28, v31, v26
	v_fma_f32 v25, -v25, v28, v27
	s_waitcnt lgkmcnt(0)
	v_pk_add_f32 v[14:15], v[14:15], v[18:19]
	ds_bpermute_b32 v19, v220, v15
	ds_bpermute_b32 v18, v220, v14
	v_div_fixup_f32 v20, v20, v34, v32
	s_waitcnt lgkmcnt(0)
	v_pk_add_f32 v[14:15], v[14:15], v[18:19]
	s_nop 0
	v_pk_fma_f32 v[0:1], v[14:15], s[46:47], v[0:1] op_sel_hi:[1,0,0]
	s_nop 0
	v_mul_f32_e32 v14, 0x4b800000, v1
	v_cmp_gt_f32_e64 s[0:1], s49, v1
	s_nop 1
	v_cndmask_b32_e64 v1, v1, v14, s[0:1]
	v_rsq_f32_e32 v1, v1
	v_div_fmas_f32 v14, v25, v26, v28
	v_div_fixup_f32 v14, v14, v24, v21
	v_cmp_gt_f32_e32 vcc, s49, v0
	v_mul_f32_e32 v15, 0x45800000, v1
	v_cndmask_b32_e64 v1, v1, v15, s[0:1]
	v_mul_f32_e32 v15, v16, v1
	v_mul_f32_e32 v15, v69, v15
	v_mul_f32_e32 v15, v15, v29
	v_cvt_pk_bf16_f32 v15, v15, s0
	global_store_short v[22:23], v15, off
	v_mul_f32_e32 v15, v17, v1
	v_mul_f32_e32 v15, v67, v15
	v_mul_f32_e32 v15, v15, v30
	v_cvt_pk_bf16_f32 v15, v15, s0
	global_store_short v[8:9], v15, off
	v_mul_f32_e32 v8, v12, v1
	v_mul_f32_e32 v1, v13, v1
	v_mul_f32_e32 v1, v1, v48
	v_mul_f32_e32 v1, v1, v14
	v_cvt_pk_bf16_f32 v1, v1, s0
	global_store_short v[6:7], v1, off
	v_or_b32_e32 v6, 27, v68
	v_mul_f32_e32 v8, v49, v8
	v_ashrrev_i32_e32 v7, 31, v6
	v_mul_f32_e32 v8, v8, v20
	v_lshlrev_b64 v[6:7], 10, v[6:7]
	v_cvt_pk_bf16_f32 v8, v8, s0
	v_or_b32_e32 v6, v6, v65
	global_store_short v[10:11], v8, off
	v_lshl_add_u64 v[8:9], s[8:9], 0, v[6:7]
	v_mov_b32_e32 v1, v200
	v_or_b32_e32 v8, 64, v6
	v_mov_b32_e32 v9, v7
	v_lshl_add_u64 v[10:11], s[8:9], 0, v[8:9]
	v_mov_b32_e32 v16, v201
	v_or_b32_e32 v10, 0x80, v6
	v_mov_b32_e32 v11, v7
	v_lshl_add_u64 v[12:13], s[8:9], 0, v[10:11]
	v_mov_b32_e32 v17, v202
	v_lshl_add_u64 v[12:13], s[10:11], 0, v[6:7]
	v_or_b32_e32 v6, 0xc0, v6
	v_lshl_add_u64 v[14:15], s[8:9], 0, v[6:7]
	v_mov_b32_e32 v14, v203
	v_mul_f32_e32 v15, 0x4b800000, v0
	v_cndmask_b32_e32 v0, v0, v15, vcc
	v_rsq_f32_e32 v0, v0
	v_lshlrev_b32_e32 v1, 16, v1
	v_mul_f32_e32 v15, 0xbfb8aa3b, v1
	v_exp_f32_e32 v15, v15
	v_mul_f32_e32 v18, 0x45800000, v0
	v_cndmask_b32_e32 v18, v0, v18, vcc
	v_mul_f32_e32 v0, v4, v18
	v_add_f32_e32 v15, 1.0, v15
	v_div_scale_f32 v19, s[0:1], v15, v15, v1
	v_rcp_f32_e32 v20, v19
	v_lshlrev_b32_e32 v16, 16, v16
	v_mul_f32_e32 v0, v69, v0
	v_fma_f32 v4, -v19, v20, 1.0
	v_fmac_f32_e32 v20, v4, v20
	v_div_scale_f32 v4, vcc, v1, v15, v1
	v_mul_f32_e32 v21, v4, v20
	v_fma_f32 v22, -v19, v21, v4
	v_fmac_f32_e32 v21, v22, v20
	v_fma_f32 v4, -v19, v21, v4
	v_mul_f32_e32 v19, 0xbfb8aa3b, v16
	v_exp_f32_e32 v19, v19
	v_div_fmas_f32 v4, v4, v20, v21
	v_div_fixup_f32 v1, v4, v15, v1
	v_mul_f32_e32 v0, v0, v1
	v_add_f32_e32 v1, 1.0, v19
	v_cvt_pk_bf16_f32 v0, v0, s0
	v_div_scale_f32 v4, s[0:1], v1, v1, v16
	v_rcp_f32_e32 v15, v4
	global_store_short v[12:13], v0, off
	v_mul_f32_e32 v0, v5, v18
	v_mul_f32_e32 v0, v67, v0
	v_fma_f32 v5, -v4, v15, 1.0
	v_fmac_f32_e32 v15, v5, v15
	v_div_scale_f32 v5, vcc, v16, v1, v16
	v_mul_f32_e32 v12, v5, v15
	v_fma_f32 v13, -v4, v12, v5
	v_fmac_f32_e32 v12, v13, v15
	v_fma_f32 v4, -v4, v12, v5
	v_div_fmas_f32 v4, v4, v15, v12
	v_div_fixup_f32 v1, v4, v1, v16
	v_lshlrev_b32_e32 v4, 16, v17
	v_mul_f32_e32 v5, 0xbfb8aa3b, v4
	v_exp_f32_e32 v5, v5
	v_mul_f32_e32 v0, v0, v1
	v_cvt_pk_bf16_f32 v12, v0, s0
	v_lshl_add_u64 v[0:1], s[10:11], 0, v[8:9]
	v_add_f32_e32 v5, 1.0, v5
	v_div_scale_f32 v8, s[0:1], v5, v5, v4
	v_rcp_f32_e32 v9, v8
	global_store_short v[0:1], v12, off
	v_mul_f32_e32 v0, v2, v18
	v_mul_f32_e32 v0, v49, v0
	v_fma_f32 v1, -v8, v9, 1.0
	v_fmac_f32_e32 v9, v1, v9
	v_div_scale_f32 v1, vcc, v4, v5, v4
	v_mul_f32_e32 v2, v1, v9
	v_fma_f32 v12, -v8, v2, v1
	v_fmac_f32_e32 v2, v12, v9
	v_fma_f32 v1, -v8, v2, v1
	v_div_fmas_f32 v1, v1, v9, v2
	v_lshlrev_b32_e32 v2, 16, v14
	v_div_fixup_f32 v1, v1, v5, v4
	v_mul_f32_e32 v4, 0xbfb8aa3b, v2
	v_exp_f32_e32 v4, v4
	v_mul_f32_e32 v0, v0, v1
	v_cvt_pk_bf16_f32 v5, v0, s0
	v_lshl_add_u64 v[0:1], s[10:11], 0, v[10:11]
	v_add_f32_e32 v4, 1.0, v4
	v_div_scale_f32 v8, s[0:1], v4, v4, v2
	v_rcp_f32_e32 v9, v8
	global_store_short v[0:1], v5, off
	v_mul_f32_e32 v0, v3, v18
	v_mul_f32_e32 v0, v48, v0
	v_fma_f32 v1, -v8, v9, 1.0
	v_fmac_f32_e32 v9, v1, v9
	v_div_scale_f32 v1, vcc, v2, v4, v2
	v_mul_f32_e32 v3, v1, v9
	v_fma_f32 v5, -v8, v3, v1
	v_fmac_f32_e32 v3, v5, v9
	v_fma_f32 v1, -v8, v3, v1
	v_div_fmas_f32 v1, v1, v9, v3
	v_div_fixup_f32 v1, v1, v4, v2
	v_mul_f32_e32 v0, v0, v1
	v_cvt_pk_bf16_f32 v2, v0, s0
	v_lshl_add_u64 v[0:1], s[10:11], 0, v[6:7]
	global_store_short v[0:1], v2, off
	s_branch .LBB0_421

.LBB0_544:
	s_or_b64 exec, exec, s[4:5]
	v_lshl_or_b32 v186, v168, 2, v165
	v_or_b32_e32 v190, s6, v167
	v_lshlrev_b32_e32 v186, 10, v186
	v_lshl_or_b32 v186, v190, 1, v186
	v_add_u32_e32 v187, 0x2000, v186
	v_add_u32_e32 v188, 0x4000, v186
	v_add_u32_e32 v189, 0x6000, v186
	global_load_ushort v109, v186, s[12:13]
	global_load_ushort v110, v186, s[12:13] offset:64
	global_load_ushort v111, v186, s[12:13] offset:128
	global_load_ushort v112, v186, s[12:13] offset:192
	global_load_ushort v113, v186, s[12:13] offset:1024
	global_load_ushort v114, v186, s[12:13] offset:1088
	global_load_ushort v115, v186, s[12:13] offset:1152
	global_load_ushort v116, v186, s[12:13] offset:1216
	global_load_ushort v117, v186, s[12:13] offset:2048
	global_load_ushort v118, v186, s[12:13] offset:2112
	global_load_ushort v119, v186, s[12:13] offset:2176
	global_load_ushort v120, v186, s[12:13] offset:2240
	global_load_ushort v121, v186, s[12:13] offset:3072
	global_load_ushort v122, v186, s[12:13] offset:3136
	global_load_ushort v123, v186, s[12:13] offset:3200
	global_load_ushort v124, v186, s[12:13] offset:3264
	global_load_ushort v125, v187, s[12:13]
	global_load_ushort v126, v187, s[12:13] offset:64
	global_load_ushort v127, v187, s[12:13] offset:128
	global_load_ushort v128, v187, s[12:13] offset:192
	global_load_ushort v129, v187, s[12:13] offset:1024
	global_load_ushort v130, v187, s[12:13] offset:1088
	global_load_ushort v131, v187, s[12:13] offset:1152
	global_load_ushort v132, v187, s[12:13] offset:1216
	global_load_ushort v133, v187, s[12:13] offset:2048
	global_load_ushort v134, v187, s[12:13] offset:2112
	global_load_ushort v135, v187, s[12:13] offset:2176
	global_load_ushort v136, v187, s[12:13] offset:2240
	global_load_ushort v137, v187, s[12:13] offset:3072
	global_load_ushort v138, v187, s[12:13] offset:3136
	global_load_ushort v139, v187, s[12:13] offset:3200
	global_load_ushort v140, v187, s[12:13] offset:3264
	global_load_ushort v141, v188, s[12:13]
	global_load_ushort v142, v188, s[12:13] offset:64
	global_load_ushort v143, v188, s[12:13] offset:128
	global_load_ushort v144, v188, s[12:13] offset:192
	global_load_ushort v145, v188, s[12:13] offset:1024
	global_load_ushort v146, v188, s[12:13] offset:1088
	global_load_ushort v147, v188, s[12:13] offset:1152
	global_load_ushort v148, v188, s[12:13] offset:1216
	global_load_ushort v149, v188, s[12:13] offset:2048
	global_load_ushort v150, v188, s[12:13] offset:2112
	global_load_ushort v151, v188, s[12:13] offset:2176
	global_load_ushort v152, v188, s[12:13] offset:2240
	global_load_ushort v153, v188, s[12:13] offset:3072
	global_load_ushort v154, v188, s[12:13] offset:3136
	global_load_ushort v155, v188, s[12:13] offset:3200
	global_load_ushort v156, v188, s[12:13] offset:3264
	global_load_ushort v157, v189, s[12:13]
	global_load_ushort v158, v189, s[12:13] offset:64
	global_load_ushort v159, v189, s[12:13] offset:128
	global_load_ushort v173, v189, s[12:13] offset:192
	global_load_ushort v174, v189, s[12:13] offset:1024
	global_load_ushort v175, v189, s[12:13] offset:1088
	global_load_ushort v176, v189, s[12:13] offset:1152
	global_load_ushort v177, v189, s[12:13] offset:1216
	global_load_ushort v178, v189, s[12:13] offset:2048
	global_load_ushort v179, v189, s[12:13] offset:2112
	global_load_ushort v180, v189, s[12:13] offset:2176
	global_load_ushort v181, v189, s[12:13] offset:2240
	global_load_ushort v182, v189, s[12:13] offset:3072
	global_load_ushort v183, v189, s[12:13] offset:3136
	global_load_ushort v184, v189, s[12:13] offset:3200
	global_load_ushort v185, v189, s[12:13] offset:3264
	v_lshl_or_b32 v72, v168, 2, v165
	v_or_b32_e32 v64, s6, v167
	v_ashrrev_i32_e32 v73, 31, v72
	v_lshlrev_b64 v[76:77], 10, v[72:73]
	v_lshlrev_b32_e32 v73, 1, v64
	v_or_b32_e32 v76, v76, v73
	s_waitcnt lgkmcnt(0)
	v_lshl_add_u64 v[64:65], s[12:13], 0, v[76:77]
	s_waitcnt vmcnt(0)
	v_mov_b32_e32 v75, v109
	v_or_b32_e32 v80, 64, v76
	v_mov_b32_e32 v81, v77
	v_lshl_add_u64 v[78:79], s[14:15], 0, v[76:77]
	v_lshl_add_u64 v[64:65], s[12:13], 0, v[80:81]
	v_or_b32_e32 v82, 0x80, v76
	v_mov_b32_e32 v83, v77
	v_or_b32_e32 v76, 0xc0, v76
	v_lshl_add_u64 v[66:67], s[12:13], 0, v[82:83]
	v_lshl_add_u64 v[68:69], s[12:13], 0, v[76:77]
	v_mov_b32_e32 v84, v110
	v_mov_b32_e32 v85, v111
	v_mov_b32_e32 v86, v112
	v_add_u32_e32 v74, v172, v166
	ds_read_b128 v[68:71], v74
	ds_read_b128 v[64:67], v74 offset:32
	v_lshl_add_u64 v[80:81], s[14:15], 0, v[80:81]
	v_lshl_add_u64 v[82:83], s[14:15], 0, v[82:83]
	v_lshl_add_u64 v[76:77], s[14:15], 0, v[76:77]
	s_waitcnt lgkmcnt(1)
	v_rcp_f32_e32 v68, v68
	v_rcp_f32_e32 v70, v70
	s_add_i32 s44, s44, s92
	s_add_i32 s2, s2, s3
	v_mul_f32_e32 v0, v0, v68
	v_mul_f32_e32 v16, v16, v68
	v_mul_f32_e32 v32, v32, v68
	v_mul_f32_e32 v48, v48, v68
	v_mul_f32_e32 v2, v2, v70
	v_mul_f32_e32 v18, v18, v70
	v_mul_f32_e32 v34, v34, v70
	v_mul_f32_e32 v50, v50, v70
	s_add_i32 s45, s45, s24
	s_cmpk_lt_i32 s44, 0x100
	v_lshlrev_b32_e32 v68, 16, v75
	v_mul_f32_e32 v75, 0xbfb8aa3b, v68
	v_exp_f32_e32 v75, v75
	v_lshlrev_b32_e32 v84, 16, v84
	v_lshlrev_b32_e32 v85, 16, v85
	v_mul_f32_e32 v87, 0xbfb8aa3b, v84
	v_lshlrev_b32_e32 v86, 16, v86
	v_mul_f32_e32 v88, 0xbfb8aa3b, v85
	v_exp_f32_e32 v87, v87
	v_mul_f32_e32 v89, 0xbfb8aa3b, v86
	v_exp_f32_e32 v88, v88
	v_exp_f32_e32 v89, v89
	v_add_f32_e32 v75, 1.0, v75
	v_div_scale_f32 v90, s[0:1], v75, v75, v68
	v_add_f32_e32 v87, 1.0, v87
	v_add_f32_e32 v88, 1.0, v88
	v_rcp_f32_e32 v92, v90
	v_div_scale_f32 v93, s[0:1], v87, v87, v84
	v_add_f32_e32 v89, 1.0, v89
	v_div_scale_f32 v95, s[4:5], v88, v88, v85
	v_rcp_f32_e32 v99, v93
	v_div_scale_f32 v97, s[6:7], v89, v89, v86
	v_rcp_f32_e32 v100, v95
	v_rcp_f32_e32 v101, v97
	v_fma_f32 v102, -v90, v92, 1.0
	v_div_scale_f32 v91, vcc, v68, v75, v68
	v_fmac_f32_e32 v92, v102, v92
	v_fma_f32 v102, -v93, v99, 1.0
	v_div_scale_f32 v94, s[0:1], v84, v87, v84
	v_fma_f32 v103, -v95, v100, 1.0
	v_mul_f32_e32 v105, v91, v92
	v_fmac_f32_e32 v99, v102, v99
	v_div_scale_f32 v96, s[4:5], v85, v88, v85
	v_fma_f32 v104, -v97, v101, 1.0
	v_fmac_f32_e32 v100, v103, v100
	v_fma_f32 v102, -v90, v105, v91
	v_mul_f32_e32 v103, v94, v99
	v_fmac_f32_e32 v101, v104, v101
	v_mul_f32_e32 v104, v96, v100
	v_fmac_f32_e32 v105, v102, v92
	v_fma_f32 v102, -v93, v103, v94
	v_fma_f32 v107, -v95, v104, v96
	v_fma_f32 v90, -v90, v105, v91
	v_fmac_f32_e32 v103, v102, v99
	v_fmac_f32_e32 v104, v107, v100
	v_div_fmas_f32 v90, v90, v92, v105
	v_fma_f32 v91, -v93, v103, v94
	s_mov_b64 vcc, s[0:1]
	v_div_scale_f32 v98, s[6:7], v86, v89, v86
	v_fma_f32 v92, -v95, v104, v96
	v_div_fixup_f32 v68, v90, v75, v68
	v_div_fmas_f32 v75, v91, v99, v103
	s_mov_b64 vcc, s[4:5]
	v_mul_f32_e32 v106, v98, v101
	v_mul_f32_e32 v0, v0, v68
	v_div_fixup_f32 v68, v75, v87, v84
	v_div_fmas_f32 v75, v92, v100, v104
	v_fma_f32 v108, -v97, v106, v98
	v_cvt_pk_bf16_f32 v0, v0, s0
	v_mul_f32_e32 v16, v16, v68
	v_div_fixup_f32 v68, v75, v88, v85
	v_fmac_f32_e32 v106, v108, v101
	global_store_short v[78:79], v0, off
	v_cvt_pk_bf16_f32 v0, v16, s0
	v_mul_f32_e32 v16, v32, v68
	v_fma_f32 v93, -v97, v106, v98
	global_store_short v[80:81], v0, off
	v_cvt_pk_bf16_f32 v0, v16, s0
	s_mov_b64 vcc, s[6:7]
	global_store_short v[82:83], v0, off
	v_div_fmas_f32 v0, v93, v101, v106
	v_div_fixup_f32 v0, v0, v89, v86
	v_mul_f32_e32 v0, v48, v0
	v_cvt_pk_bf16_f32 v0, v0, s0
	global_store_short v[76:77], v0, off
	v_or_b32_e32 v76, 1, v72
	v_ashrrev_i32_e32 v77, 31, v76
	v_lshlrev_b64 v[76:77], 10, v[76:77]
	v_or_b32_e32 v76, v76, v73
	v_lshl_add_u64 v[78:79], s[12:13], 0, v[76:77]
	v_lshl_add_u64 v[80:81], s[14:15], 0, v[76:77]
	v_or_b32_e32 v82, 64, v76
	v_mov_b32_e32 v83, v77
	v_or_b32_e32 v86, 0x80, v76
	v_mov_b32_e32 v87, v77
	v_or_b32_e32 v76, 0xc0, v76
	v_lshl_add_u64 v[84:85], s[12:13], 0, v[82:83]
	v_lshl_add_u64 v[88:89], s[12:13], 0, v[86:87]
	v_lshl_add_u64 v[90:91], s[12:13], 0, v[76:77]
	v_mov_b32_e32 v0, v113
	v_mov_b32_e32 v16, v114
	v_mov_b32_e32 v32, v115
	v_mov_b32_e32 v48, v116
	v_rcp_f32_e32 v75, v69
	v_lshl_add_u64 v[68:69], s[14:15], 0, v[82:83]
	v_lshl_add_u64 v[78:79], s[14:15], 0, v[86:87]
	v_mul_f32_e32 v1, v1, v75
	v_mul_f32_e32 v17, v17, v75
	v_mul_f32_e32 v33, v33, v75
	v_mul_f32_e32 v49, v49, v75
	v_lshlrev_b32_e32 v0, 16, v0
	v_lshlrev_b32_e32 v16, 16, v16
	v_mul_f32_e32 v75, 0xbfb8aa3b, v0
	v_lshlrev_b32_e32 v32, 16, v32
	v_mul_f32_e32 v82, 0xbfb8aa3b, v16
	v_exp_f32_e32 v75, v75
	v_mul_f32_e32 v83, 0xbfb8aa3b, v32
	v_exp_f32_e32 v82, v82
	v_exp_f32_e32 v83, v83
	v_add_f32_e32 v75, 1.0, v75
	v_div_scale_f32 v85, s[0:1], v75, v75, v0
	v_add_f32_e32 v82, 1.0, v82
	v_add_f32_e32 v83, 1.0, v83
	v_div_scale_f32 v87, s[0:1], v82, v82, v16
	v_rcp_f32_e32 v93, v85
	v_lshlrev_b32_e32 v48, 16, v48
	v_div_scale_f32 v89, s[4:5], v83, v83, v32
	v_rcp_f32_e32 v94, v87
	v_mul_f32_e32 v84, 0xbfb8aa3b, v48
	v_rcp_f32_e32 v95, v89
	v_exp_f32_e32 v84, v84
	v_fma_f32 v97, -v85, v93, 1.0
	v_div_scale_f32 v86, vcc, v0, v75, v0
	v_fma_f32 v98, -v87, v94, 1.0
	v_fmac_f32_e32 v93, v97, v93
	v_div_scale_f32 v88, s[0:1], v16, v82, v16
	v_fma_f32 v99, -v89, v95, 1.0
	v_fmac_f32_e32 v94, v98, v94
	v_mul_f32_e32 v97, v86, v93
	v_add_f32_e32 v84, 1.0, v84
	v_div_scale_f32 v90, s[4:5], v32, v83, v32
	v_fmac_f32_e32 v95, v99, v95
	v_mul_f32_e32 v98, v88, v94
	v_fma_f32 v101, -v85, v97, v86
	v_div_scale_f32 v91, s[6:7], v84, v84, v48
	v_mul_f32_e32 v99, v90, v95
	v_fma_f32 v102, -v87, v98, v88
	v_fmac_f32_e32 v97, v101, v93
	v_rcp_f32_e32 v96, v91
	v_fma_f32 v103, -v89, v99, v90
	v_fmac_f32_e32 v98, v102, v94
	v_fma_f32 v85, -v85, v97, v86
	v_fmac_f32_e32 v99, v103, v95
	v_fma_f32 v86, -v87, v98, v88
	v_div_fmas_f32 v85, v85, v93, v97
	s_mov_b64 vcc, s[0:1]
	v_fma_f32 v87, -v89, v99, v90
	v_div_fixup_f32 v0, v85, v75, v0
	v_div_fmas_f32 v75, v86, v94, v98
	s_mov_b64 vcc, s[4:5]
	v_mul_f32_e32 v0, v1, v0
	v_div_fixup_f32 v1, v75, v82, v16
	v_div_fmas_f32 v16, v87, v95, v99
	v_fma_f32 v100, -v91, v96, 1.0
	v_cvt_pk_bf16_f32 v0, v0, s0
	v_mul_f32_e32 v1, v17, v1
	v_div_fixup_f32 v16, v16, v83, v32
	v_div_scale_f32 v92, s[6:7], v48, v84, v48
	v_fmac_f32_e32 v96, v100, v96
	global_store_short v[80:81], v0, off
	v_cvt_pk_bf16_f32 v0, v1, s0
	v_mul_f32_e32 v1, v33, v16
	v_mul_f32_e32 v100, v92, v96
	global_store_short v[68:69], v0, off
	v_cvt_pk_bf16_f32 v0, v1, s0
	global_store_short v[78:79], v0, off
	v_fma_f32 v0, -v91, v100, v92
	v_fmac_f32_e32 v100, v0, v96
	v_fma_f32 v0, -v91, v100, v92
	s_mov_b64 vcc, s[6:7]
	v_div_fmas_f32 v0, v0, v96, v100
	v_div_fixup_f32 v0, v0, v84, v48
	v_mul_f32_e32 v0, v49, v0
	v_cvt_pk_bf16_f32 v16, v0, s0
	v_lshl_add_u64 v[0:1], s[14:15], 0, v[76:77]
	global_store_short v[0:1], v16, off
	v_or_b32_e32 v0, 2, v72
	v_ashrrev_i32_e32 v1, 31, v0
	v_lshlrev_b64 v[0:1], 10, v[0:1]
	v_or_b32_e32 v0, v0, v73
	v_or_b32_e32 v48, 64, v0
	v_mov_b32_e32 v49, v1
	v_or_b32_e32 v76, 0x80, v0
	v_mov_b32_e32 v77, v1
	v_lshl_add_u64 v[16:17], s[12:13], 0, v[0:1]
	v_lshl_add_u64 v[32:33], s[14:15], 0, v[0:1]
	v_lshl_add_u64 v[68:69], s[12:13], 0, v[48:49]
	v_lshl_add_u64 v[78:79], s[12:13], 0, v[76:77]
	v_or_b32_e32 v0, 0xc0, v0
	v_lshl_add_u64 v[80:81], s[12:13], 0, v[0:1]
	v_mov_b32_e32 v75, v117
	s_nop 0
	v_mov_b32_e32 v68, v118
	s_nop 0
	v_mov_b32_e32 v69, v119
	s_nop 0
	v_mov_b32_e32 v78, v120
	v_lshl_add_u64 v[16:17], s[14:15], 0, v[48:49]
	v_lshl_add_u64 v[48:49], s[14:15], 0, v[76:77]
	v_lshl_add_u64 v[0:1], s[14:15], 0, v[0:1]
	v_lshlrev_b32_e32 v70, 16, v75
	v_lshlrev_b32_e32 v68, 16, v68
	v_mul_f32_e32 v76, 0xbfb8aa3b, v70
	v_lshlrev_b32_e32 v69, 16, v69
	v_mul_f32_e32 v77, 0xbfb8aa3b, v68
	v_exp_f32_e32 v76, v76
	v_lshlrev_b32_e32 v75, 16, v78
	v_mul_f32_e32 v78, 0xbfb8aa3b, v69
	v_exp_f32_e32 v77, v77
	v_exp_f32_e32 v78, v78
	v_add_f32_e32 v76, 1.0, v76
	v_div_scale_f32 v80, s[0:1], v76, v76, v70
	v_add_f32_e32 v77, 1.0, v77
	v_add_f32_e32 v78, 1.0, v78
	v_div_scale_f32 v82, s[0:1], v77, v77, v68
	v_rcp_f32_e32 v87, v80
	v_div_scale_f32 v84, s[4:5], v78, v78, v69
	v_rcp_f32_e32 v88, v82
	v_rcp_f32_e32 v89, v84
	v_mul_f32_e32 v79, 0xbfb8aa3b, v75
	v_fma_f32 v91, -v80, v87, 1.0
	v_exp_f32_e32 v79, v79
	v_div_scale_f32 v81, vcc, v70, v76, v70
	v_fma_f32 v92, -v82, v88, 1.0
	v_fmac_f32_e32 v87, v91, v87
	v_div_scale_f32 v83, s[0:1], v68, v77, v68
	v_fma_f32 v93, -v84, v89, 1.0
	v_fmac_f32_e32 v88, v92, v88
	v_mul_f32_e32 v91, v81, v87
	v_div_scale_f32 v85, s[4:5], v69, v78, v69
	v_fmac_f32_e32 v89, v93, v89
	v_mul_f32_e32 v92, v83, v88
	v_fma_f32 v95, -v80, v91, v81
	v_mul_f32_e32 v93, v85, v89
	v_fma_f32 v96, -v82, v92, v83
	v_fmac_f32_e32 v91, v95, v87
	v_add_f32_e32 v79, 1.0, v79
	v_fma_f32 v97, -v84, v93, v85
	v_fmac_f32_e32 v92, v96, v88
	v_fma_f32 v80, -v80, v91, v81
	v_div_scale_f32 v86, s[6:7], v79, v79, v75
	v_fmac_f32_e32 v93, v97, v89
	v_fma_f32 v81, -v82, v92, v83
	v_div_fmas_f32 v80, v80, v87, v91
	s_mov_b64 vcc, s[0:1]
	v_rcp_f32_e32 v90, v86
	v_fma_f32 v82, -v84, v93, v85
	v_div_fixup_f32 v70, v80, v76, v70
	v_div_fmas_f32 v76, v81, v88, v92
	s_mov_b64 vcc, s[4:5]
	v_mul_f32_e32 v2, v2, v70
	v_div_fixup_f32 v68, v76, v77, v68
	v_div_fmas_f32 v70, v82, v89, v93
	v_cvt_pk_bf16_f32 v2, v2, s0
	v_mul_f32_e32 v18, v18, v68
	v_div_fixup_f32 v68, v70, v78, v69
	global_store_short v[32:33], v2, off
	v_cvt_pk_bf16_f32 v2, v18, s0
	v_mul_f32_e32 v18, v34, v68
	v_fma_f32 v94, -v86, v90, 1.0
	global_store_short v[16:17], v2, off
	v_cvt_pk_bf16_f32 v2, v18, s0
	global_store_short v[48:49], v2, off
	v_fmac_f32_e32 v90, v94, v90
	v_div_scale_f32 v2, vcc, v75, v79, v75
	v_mul_f32_e32 v16, v2, v90
	v_fma_f32 v17, -v86, v16, v2
	v_fmac_f32_e32 v16, v17, v90
	v_fma_f32 v2, -v86, v16, v2
	v_div_fmas_f32 v2, v2, v90, v16
	v_div_fixup_f32 v2, v2, v79, v75
	v_mul_f32_e32 v2, v50, v2
	v_cvt_pk_bf16_f32 v2, v2, s0
	global_store_short v[0:1], v2, off
	v_or_b32_e32 v0, 3, v72
	v_ashrrev_i32_e32 v1, 31, v0
	v_lshlrev_b64 v[0:1], 10, v[0:1]
	v_or_b32_e32 v0, v0, v73
	v_lshl_add_u64 v[16:17], s[12:13], 0, v[0:1]
	v_lshl_add_u64 v[32:33], s[14:15], 0, v[0:1]
	v_or_b32_e32 v48, 64, v0
	v_mov_b32_e32 v49, v1
	v_or_b32_e32 v76, 0x80, v0
	v_mov_b32_e32 v77, v1
	v_or_b32_e32 v0, 0xc0, v0
	v_lshl_add_u64 v[68:69], s[12:13], 0, v[48:49]
	v_lshl_add_u64 v[78:79], s[12:13], 0, v[76:77]
	v_lshl_add_u64 v[80:81], s[12:13], 0, v[0:1]
	v_mov_b32_e32 v2, v121
	v_mov_b32_e32 v18, v122
	v_mov_b32_e32 v34, v123
	v_mov_b32_e32 v50, v124
	v_lshl_add_u64 v[16:17], s[14:15], 0, v[48:49]
	v_rcp_f32_e32 v68, v71
	v_lshl_add_u64 v[0:1], s[14:15], 0, v[0:1]
	v_mul_f32_e32 v3, v3, v68
	v_mul_f32_e32 v19, v19, v68
	v_mul_f32_e32 v35, v35, v68
	v_lshlrev_b32_e32 v2, 16, v2
	v_lshlrev_b32_e32 v18, 16, v18
	v_mul_f32_e32 v49, 0xbfb8aa3b, v2
	v_lshlrev_b32_e32 v48, 16, v50
	v_mul_f32_e32 v50, 0xbfb8aa3b, v18
	v_exp_f32_e32 v49, v49
	v_exp_f32_e32 v50, v50
	v_lshlrev_b32_e32 v34, 16, v34
	v_mul_f32_e32 v69, 0xbfb8aa3b, v34
	v_add_f32_e32 v49, 1.0, v49
	v_exp_f32_e32 v69, v69
	v_add_f32_e32 v50, 1.0, v50
	v_div_scale_f32 v71, s[0:1], v49, v49, v2
	v_div_scale_f32 v78, s[0:1], v50, v50, v18
	v_rcp_f32_e32 v82, v71
	v_rcp_f32_e32 v83, v78
	v_add_f32_e32 v69, 1.0, v69
	v_div_scale_f32 v80, s[4:5], v69, v69, v34
	v_fma_f32 v86, -v71, v82, 1.0
	v_div_scale_f32 v75, vcc, v2, v49, v2
	v_rcp_f32_e32 v84, v80
	v_fma_f32 v87, -v78, v83, 1.0
	v_fmac_f32_e32 v82, v86, v82
	v_div_scale_f32 v79, s[0:1], v18, v50, v18
	v_fmac_f32_e32 v83, v87, v83
	v_mul_f32_e32 v86, v75, v82
	v_mul_f32_e32 v87, v79, v83
	v_fma_f32 v89, -v71, v86, v75
	v_mul_f32_e32 v70, 0xbfb8aa3b, v48
	v_fma_f32 v90, -v78, v87, v79
	v_fmac_f32_e32 v86, v89, v82
	v_exp_f32_e32 v70, v70
	v_fma_f32 v88, -v80, v84, 1.0
	v_fmac_f32_e32 v87, v90, v83
	v_fma_f32 v71, -v71, v86, v75
	v_div_scale_f32 v81, s[4:5], v34, v69, v34
	v_fmac_f32_e32 v84, v88, v84
	v_fma_f32 v75, -v78, v87, v79
	v_div_fmas_f32 v71, v71, v82, v86
	s_mov_b64 vcc, s[0:1]
	v_mul_f32_e32 v88, v81, v84
	v_div_fixup_f32 v2, v71, v49, v2
	v_div_fmas_f32 v49, v75, v83, v87
	v_fma_f32 v91, -v80, v88, v81
	v_mul_f32_e32 v2, v3, v2
	v_div_fixup_f32 v3, v49, v50, v18
	v_add_f32_e32 v70, 1.0, v70
	v_fmac_f32_e32 v88, v91, v84
	v_cvt_pk_bf16_f32 v2, v2, s0
	v_mul_f32_e32 v3, v19, v3
	v_div_scale_f32 v85, s[6:7], v70, v70, v48
	v_fma_f32 v78, -v80, v88, v81
	s_mov_b64 vcc, s[4:5]
	global_store_short v[32:33], v2, off
	v_cvt_pk_bf16_f32 v2, v3, s0
	v_div_fmas_f32 v18, v78, v84, v88
	global_store_short v[16:17], v2, off
	v_rcp_f32_e32 v17, v85
	v_div_fixup_f32 v18, v18, v69, v34
	v_mul_f32_e32 v3, v35, v18
	v_cvt_pk_bf16_f32 v16, v3, s0
	v_lshl_add_u64 v[2:3], s[14:15], 0, v[76:77]
	global_store_short v[2:3], v16, off
	v_fma_f32 v3, -v85, v17, 1.0
	v_fmac_f32_e32 v17, v3, v17
	v_div_scale_f32 v3, vcc, v48, v70, v48
	v_mul_f32_e32 v16, v3, v17
	v_fma_f32 v18, -v85, v16, v3
	v_fmac_f32_e32 v16, v18, v17
	v_fma_f32 v3, -v85, v16, v3
	v_div_fmas_f32 v3, v3, v17, v16
	v_mul_f32_e32 v2, v51, v68
	v_div_fixup_f32 v3, v3, v70, v48
	v_mul_f32_e32 v2, v2, v3
	v_cvt_pk_bf16_f32 v2, v2, s0
	global_store_short v[0:1], v2, off
	v_or_b32_e32 v0, 8, v72
	v_ashrrev_i32_e32 v1, 31, v0
	v_lshlrev_b64 v[0:1], 10, v[0:1]
	v_or_b32_e32 v0, v0, v73
	v_or_b32_e32 v18, 64, v0
	v_mov_b32_e32 v19, v1
	v_or_b32_e32 v34, 0x80, v0
	v_mov_b32_e32 v35, v1
	v_lshl_add_u64 v[2:3], s[12:13], 0, v[0:1]
	v_lshl_add_u64 v[16:17], s[14:15], 0, v[0:1]
	v_lshl_add_u64 v[32:33], s[12:13], 0, v[18:19]
	v_lshl_add_u64 v[48:49], s[12:13], 0, v[34:35]
	v_or_b32_e32 v0, 0xc0, v0
	v_lshl_add_u64 v[50:51], s[12:13], 0, v[0:1]
	v_mov_b32_e32 v68, v125
	s_nop 0
	v_mov_b32_e32 v32, v126
	s_nop 0
	v_mov_b32_e32 v33, v127
	s_nop 0
	v_mov_b32_e32 v48, v128
	s_waitcnt lgkmcnt(0)
	v_rcp_f32_e32 v49, v64
	v_lshl_add_u64 v[2:3], s[14:15], 0, v[18:19]
	v_lshl_add_u64 v[0:1], s[14:15], 0, v[0:1]
	v_mul_f32_e32 v18, v20, v49
	v_mul_f32_e32 v19, v36, v49
	v_mul_f32_e32 v4, v4, v49
	v_lshlrev_b32_e32 v20, 16, v68
	v_lshlrev_b32_e32 v32, 16, v32
	v_lshlrev_b32_e32 v33, 16, v33
	v_lshlrev_b32_e32 v36, 16, v48
	v_mul_f32_e32 v48, 0xbfb8aa3b, v20
	v_mul_f32_e32 v50, 0xbfb8aa3b, v32
	v_exp_f32_e32 v48, v48
	v_mul_f32_e32 v51, 0xbfb8aa3b, v33
	v_exp_f32_e32 v50, v50
	v_exp_f32_e32 v51, v51
	v_add_f32_e32 v48, 1.0, v48
	v_div_scale_f32 v68, s[0:1], v48, v48, v20
	v_add_f32_e32 v50, 1.0, v50
	v_add_f32_e32 v51, 1.0, v51
	v_div_scale_f32 v70, s[0:1], v50, v50, v32
	v_rcp_f32_e32 v76, v68
	v_div_scale_f32 v75, s[4:5], v51, v51, v33
	v_rcp_f32_e32 v77, v70
	v_rcp_f32_e32 v78, v75
	v_fma_f32 v80, -v68, v76, 1.0
	v_div_scale_f32 v69, vcc, v20, v48, v20
	v_fma_f32 v81, -v70, v77, 1.0
	v_fmac_f32_e32 v76, v80, v76
	v_div_scale_f32 v71, s[0:1], v32, v50, v32
	v_fma_f32 v82, -v75, v78, 1.0
	v_fmac_f32_e32 v77, v81, v77
	v_mul_f32_e32 v80, v69, v76
	v_div_scale_f32 v79, s[4:5], v33, v51, v33
	v_fmac_f32_e32 v78, v82, v78
	v_mul_f32_e32 v81, v71, v77
	v_fma_f32 v83, -v68, v80, v69
	v_mul_f32_e32 v82, v79, v78
	v_fma_f32 v84, -v70, v81, v71
	v_fmac_f32_e32 v80, v83, v76
	v_fma_f32 v85, -v75, v82, v79
	v_fmac_f32_e32 v81, v84, v77
	v_fma_f32 v68, -v68, v80, v69
	v_mul_f32_e32 v64, 0xbfb8aa3b, v36
	v_fmac_f32_e32 v82, v85, v78
	v_fma_f32 v69, -v70, v81, v71
	v_div_fmas_f32 v68, v68, v76, v80
	s_mov_b64 vcc, s[0:1]
	v_exp_f32_e32 v64, v64
	v_fma_f32 v70, -v75, v82, v79
	v_div_fixup_f32 v20, v68, v48, v20
	v_div_fmas_f32 v48, v69, v77, v81
	s_mov_b64 vcc, s[4:5]
	v_mul_f32_e32 v4, v4, v20
	v_div_fixup_f32 v20, v48, v50, v32
	v_div_fmas_f32 v32, v70, v78, v82
	v_cvt_pk_bf16_f32 v4, v4, s0
	v_mul_f32_e32 v18, v18, v20
	v_div_fixup_f32 v20, v32, v51, v33
	global_store_short v[16:17], v4, off
	v_cvt_pk_bf16_f32 v4, v18, s0
	v_mul_f32_e32 v16, v19, v20
	global_store_short v[2:3], v4, off
	v_cvt_pk_bf16_f32 v4, v16, s0
	v_add_f32_e32 v16, 1.0, v64
	v_div_scale_f32 v17, s[0:1], v16, v16, v36
	v_rcp_f32_e32 v18, v17
	v_lshl_add_u64 v[2:3], s[14:15], 0, v[34:35]
	global_store_short v[2:3], v4, off
	v_mul_f32_e32 v2, v52, v49
	v_fma_f32 v3, -v17, v18, 1.0
	v_fmac_f32_e32 v18, v3, v18
	v_div_scale_f32 v3, vcc, v36, v16, v36
	v_mul_f32_e32 v4, v3, v18
	v_fma_f32 v19, -v17, v4, v3
	v_fmac_f32_e32 v4, v19, v18
	v_fma_f32 v3, -v17, v4, v3
	v_div_fmas_f32 v3, v3, v18, v4
	v_div_fixup_f32 v3, v3, v16, v36
	v_mul_f32_e32 v2, v2, v3
	v_cvt_pk_bf16_f32 v2, v2, s0
	global_store_short v[0:1], v2, off
	v_or_b32_e32 v0, 9, v72
	v_ashrrev_i32_e32 v1, 31, v0
	v_lshlrev_b64 v[0:1], 10, v[0:1]
	v_or_b32_e32 v0, v0, v73
	v_or_b32_e32 v32, 0x80, v0
	v_mov_b32_e32 v33, v1
	v_lshl_add_u64 v[2:3], s[12:13], 0, v[0:1]
	v_or_b32_e32 v16, 64, v0
	v_mov_b32_e32 v17, v1
	v_lshl_add_u64 v[34:35], s[12:13], 0, v[32:33]
	v_lshl_add_u64 v[18:19], s[12:13], 0, v[16:17]
	v_mov_b32_e32 v4, v129
	v_mov_b32_e32 v20, v130
	s_nop 0
	v_mov_b32_e32 v34, v131
	v_lshl_add_u64 v[2:3], s[14:15], 0, v[0:1]
	v_or_b32_e32 v0, 0xc0, v0
	v_lshl_add_u64 v[18:19], s[12:13], 0, v[0:1]
	v_mov_b32_e32 v18, v132
	v_rcp_f32_e32 v19, v65
	v_lshl_add_u64 v[16:17], s[14:15], 0, v[16:17]
	v_lshl_add_u64 v[0:1], s[14:15], 0, v[0:1]
	v_mul_f32_e32 v35, v37, v19
	v_mul_f32_e32 v5, v5, v19
	v_mul_f32_e32 v21, v21, v19
	v_lshlrev_b32_e32 v4, 16, v4
	v_lshlrev_b32_e32 v20, 16, v20
	v_mul_f32_e32 v36, 0xbfb8aa3b, v4
	v_mul_f32_e32 v37, 0xbfb8aa3b, v20
	v_exp_f32_e32 v36, v36
	v_exp_f32_e32 v37, v37
	v_lshlrev_b32_e32 v34, 16, v34
	v_mul_f32_e32 v48, 0xbfb8aa3b, v34
	v_add_f32_e32 v36, 1.0, v36
	v_add_f32_e32 v37, 1.0, v37
	v_div_scale_f32 v49, s[0:1], v36, v36, v4
	v_div_scale_f32 v51, s[0:1], v37, v37, v20
	v_rcp_f32_e32 v65, v49
	v_rcp_f32_e32 v68, v51
	v_exp_f32_e32 v48, v48
	v_div_scale_f32 v50, vcc, v4, v36, v4
	v_fma_f32 v71, -v49, v65, 1.0
	v_fma_f32 v75, -v51, v68, 1.0
	v_fmac_f32_e32 v65, v71, v65
	v_add_f32_e32 v48, 1.0, v48
	v_div_scale_f32 v52, s[0:1], v20, v37, v20
	v_fmac_f32_e32 v68, v75, v68
	v_mul_f32_e32 v71, v50, v65
	v_div_scale_f32 v64, s[4:5], v48, v48, v34
	v_mul_f32_e32 v75, v52, v68
	v_fma_f32 v77, -v49, v71, v50
	v_rcp_f32_e32 v69, v64
	v_fma_f32 v78, -v51, v75, v52
	v_fmac_f32_e32 v71, v77, v65
	v_fmac_f32_e32 v75, v78, v68
	v_fma_f32 v49, -v49, v71, v50
	v_fma_f32 v50, -v51, v75, v52
	v_div_fmas_f32 v49, v49, v65, v71
	s_mov_b64 vcc, s[0:1]
	v_div_fixup_f32 v4, v49, v36, v4
	v_div_fmas_f32 v36, v50, v68, v75
	v_fma_f32 v76, -v64, v69, 1.0
	v_mul_f32_e32 v4, v5, v4
	v_div_fixup_f32 v5, v36, v37, v20
	v_div_scale_f32 v70, s[4:5], v34, v48, v34
	v_fmac_f32_e32 v69, v76, v69
	v_cvt_pk_bf16_f32 v4, v4, s0
	v_mul_f32_e32 v5, v21, v5
	v_lshlrev_b32_e32 v18, 16, v18
	v_mul_f32_e32 v76, v70, v69
	global_store_short v[2:3], v4, off
	v_cvt_pk_bf16_f32 v2, v5, s0
	v_fma_f32 v79, -v64, v76, v70
	global_store_short v[16:17], v2, off
	v_mul_f32_e32 v2, 0xbfb8aa3b, v18
	v_fmac_f32_e32 v76, v79, v69
	v_exp_f32_e32 v2, v2
	v_fma_f32 v51, -v64, v76, v70
	s_mov_b64 vcc, s[4:5]
	v_div_fmas_f32 v20, v51, v69, v76
	v_div_fixup_f32 v3, v20, v48, v34
	v_mul_f32_e32 v3, v35, v3
	v_add_f32_e32 v5, 1.0, v2
	v_cvt_pk_bf16_f32 v4, v3, s0
	v_div_scale_f32 v16, s[0:1], v5, v5, v18
	v_rcp_f32_e32 v17, v16
	v_lshl_add_u64 v[2:3], s[14:15], 0, v[32:33]
	global_store_short v[2:3], v4, off
	v_mul_f32_e32 v2, v53, v19
	v_fma_f32 v3, -v16, v17, 1.0
	v_fmac_f32_e32 v17, v3, v17
	v_div_scale_f32 v3, vcc, v18, v5, v18
	v_mul_f32_e32 v4, v3, v17
	v_fma_f32 v19, -v16, v4, v3
	v_fmac_f32_e32 v4, v19, v17
	v_fma_f32 v3, -v16, v4, v3
	v_div_fmas_f32 v3, v3, v17, v4
	v_div_fixup_f32 v3, v3, v5, v18
	v_mul_f32_e32 v2, v2, v3
	v_cvt_pk_bf16_f32 v2, v2, s0
	global_store_short v[0:1], v2, off
	v_or_b32_e32 v0, 10, v72
	v_ashrrev_i32_e32 v1, 31, v0
	v_lshlrev_b64 v[0:1], 10, v[0:1]
	v_or_b32_e32 v0, v0, v73
	v_or_b32_e32 v18, 0x80, v0
	v_mov_b32_e32 v19, v1
	v_lshl_add_u64 v[2:3], s[12:13], 0, v[0:1]
	v_or_b32_e32 v4, 64, v0
	v_mov_b32_e32 v5, v1
	v_lshl_add_u64 v[20:21], s[12:13], 0, v[18:19]
	v_lshl_add_u64 v[16:17], s[12:13], 0, v[4:5]
	v_mov_b32_e32 v32, v133
	v_mov_b32_e32 v33, v134
	s_nop 0
	v_mov_b32_e32 v20, v135
	v_lshl_add_u64 v[2:3], s[14:15], 0, v[0:1]
	v_or_b32_e32 v0, 0xc0, v0
	v_lshl_add_u64 v[16:17], s[12:13], 0, v[0:1]
	v_mov_b32_e32 v16, v136
	v_rcp_f32_e32 v17, v66
	v_lshl_add_u64 v[4:5], s[14:15], 0, v[4:5]
	v_lshl_add_u64 v[0:1], s[14:15], 0, v[0:1]
	v_mul_f32_e32 v21, v22, v17
	v_mul_f32_e32 v36, v38, v17
	v_mul_f32_e32 v6, v6, v17
	v_lshlrev_b32_e32 v22, 16, v32
	v_lshlrev_b32_e32 v32, 16, v33
	v_mul_f32_e32 v33, 0xbfb8aa3b, v22
	v_mul_f32_e32 v34, 0xbfb8aa3b, v32
	v_exp_f32_e32 v33, v33
	v_exp_f32_e32 v34, v34
	v_lshlrev_b32_e32 v20, 16, v20
	v_mul_f32_e32 v35, 0xbfb8aa3b, v20
	v_add_f32_e32 v33, 1.0, v33
	v_add_f32_e32 v34, 1.0, v34
	v_div_scale_f32 v37, s[0:1], v33, v33, v22
	v_div_scale_f32 v48, s[0:1], v34, v34, v32
	v_rcp_f32_e32 v51, v37
	v_rcp_f32_e32 v52, v48
	v_exp_f32_e32 v35, v35
	v_div_scale_f32 v38, vcc, v22, v33, v22
	v_fma_f32 v65, -v37, v51, 1.0
	v_fma_f32 v66, -v48, v52, 1.0
	v_fmac_f32_e32 v51, v65, v51
	v_div_scale_f32 v49, s[0:1], v32, v34, v32
	v_fmac_f32_e32 v52, v66, v52
	v_mul_f32_e32 v65, v38, v51
	v_add_f32_e32 v35, 1.0, v35
	v_mul_f32_e32 v66, v49, v52
	v_fma_f32 v69, -v37, v65, v38
	v_div_scale_f32 v50, s[4:5], v35, v35, v20
	v_fma_f32 v70, -v48, v66, v49
	v_fmac_f32_e32 v65, v69, v51
	v_rcp_f32_e32 v53, v50
	v_fmac_f32_e32 v66, v70, v52
	v_fma_f32 v37, -v37, v65, v38
	v_fma_f32 v38, -v48, v66, v49
	v_div_fmas_f32 v37, v37, v51, v65
	s_mov_b64 vcc, s[0:1]
	v_div_fixup_f32 v22, v37, v33, v22
	v_div_fmas_f32 v33, v38, v52, v66
	v_mul_f32_e32 v6, v6, v22
	v_div_fixup_f32 v22, v33, v34, v32
	v_fma_f32 v68, -v50, v53, 1.0
	v_cvt_pk_bf16_f32 v6, v6, s0
	v_mul_f32_e32 v21, v21, v22
	v_div_scale_f32 v64, s[4:5], v20, v35, v20
	v_fmac_f32_e32 v53, v68, v53
	global_store_short v[2:3], v6, off
	v_cvt_pk_bf16_f32 v2, v21, s0
	v_mul_f32_e32 v68, v64, v53
	global_store_short v[4:5], v2, off
	v_lshlrev_b32_e32 v4, 16, v16
	v_fma_f32 v71, -v50, v68, v64
	v_mul_f32_e32 v3, 0xbfb8aa3b, v4
	v_fmac_f32_e32 v68, v71, v53
	v_exp_f32_e32 v3, v3
	v_fma_f32 v2, -v50, v68, v64
	s_mov_b64 vcc, s[4:5]
	v_div_fmas_f32 v2, v2, v53, v68
	v_div_fixup_f32 v2, v2, v35, v20
	v_mul_f32_e32 v2, v36, v2
	v_add_f32_e32 v6, 1.0, v3
	v_cvt_pk_bf16_f32 v5, v2, s0
	v_div_scale_f32 v16, s[0:1], v6, v6, v4
	v_rcp_f32_e32 v20, v16
	v_lshl_add_u64 v[2:3], s[14:15], 0, v[18:19]
	global_store_short v[2:3], v5, off
	v_mul_f32_e32 v2, v54, v17
	v_fma_f32 v3, -v16, v20, 1.0
	v_fmac_f32_e32 v20, v3, v20
	v_div_scale_f32 v3, vcc, v4, v6, v4
	v_mul_f32_e32 v5, v3, v20
	v_fma_f32 v17, -v16, v5, v3
	v_fmac_f32_e32 v5, v17, v20
	v_fma_f32 v3, -v16, v5, v3
	v_div_fmas_f32 v3, v3, v20, v5
	v_div_fixup_f32 v3, v3, v6, v4
	v_mul_f32_e32 v2, v2, v3
	v_cvt_pk_bf16_f32 v2, v2, s0
	global_store_short v[0:1], v2, off
	v_or_b32_e32 v0, 11, v72
	v_ashrrev_i32_e32 v1, 31, v0
	v_lshlrev_b64 v[0:1], 10, v[0:1]
	v_or_b32_e32 v0, v0, v73
	v_or_b32_e32 v18, 0x80, v0
	v_mov_b32_e32 v19, v1
	v_lshl_add_u64 v[2:3], s[12:13], 0, v[0:1]
	v_or_b32_e32 v4, 64, v0
	v_mov_b32_e32 v5, v1
	v_lshl_add_u64 v[20:21], s[12:13], 0, v[18:19]
	v_lshl_add_u64 v[16:17], s[12:13], 0, v[4:5]
	v_mov_b32_e32 v6, v137
	v_mov_b32_e32 v22, v138
	s_nop 0
	v_mov_b32_e32 v20, v139
	v_lshl_add_u64 v[2:3], s[14:15], 0, v[0:1]
	v_or_b32_e32 v0, 0xc0, v0
	v_lshl_add_u64 v[16:17], s[12:13], 0, v[0:1]
	v_mov_b32_e32 v16, v140
	v_rcp_f32_e32 v17, v67
	v_lshl_add_u64 v[4:5], s[14:15], 0, v[4:5]
	v_lshl_add_u64 v[0:1], s[14:15], 0, v[0:1]
	v_mul_f32_e32 v21, v23, v17
	v_mul_f32_e32 v34, v39, v17
	v_mul_f32_e32 v7, v7, v17
	v_lshlrev_b32_e32 v6, 16, v6
	v_lshlrev_b32_e32 v22, 16, v22
	v_mul_f32_e32 v23, 0xbfb8aa3b, v6
	v_lshlrev_b32_e32 v20, 16, v20
	v_mul_f32_e32 v32, 0xbfb8aa3b, v22
	v_exp_f32_e32 v23, v23
	v_mul_f32_e32 v33, 0xbfb8aa3b, v20
	v_exp_f32_e32 v32, v32
	v_exp_f32_e32 v33, v33
	v_add_f32_e32 v23, 1.0, v23
	v_div_scale_f32 v35, s[0:1], v23, v23, v6
	v_add_f32_e32 v32, 1.0, v32
	v_add_f32_e32 v33, 1.0, v33
	v_div_scale_f32 v37, s[0:1], v32, v32, v22
	v_rcp_f32_e32 v39, v35
	v_div_scale_f32 v38, s[0:1], v33, v33, v20
	v_rcp_f32_e32 v48, v37
	v_rcp_f32_e32 v49, v38
	v_fma_f32 v51, -v35, v39, 1.0
	v_div_scale_f32 v36, vcc, v6, v23, v6
	v_fma_f32 v52, -v37, v48, 1.0
	v_fmac_f32_e32 v39, v51, v39
	v_div_scale_f32 v50, s[0:1], v22, v32, v22
	v_fma_f32 v53, -v38, v49, 1.0
	v_fmac_f32_e32 v48, v52, v48
	v_mul_f32_e32 v51, v36, v39
	v_fmac_f32_e32 v49, v53, v49
	v_mul_f32_e32 v52, v50, v48
	v_fma_f32 v53, -v35, v51, v36
	v_fma_f32 v54, -v37, v52, v50
	v_fmac_f32_e32 v51, v53, v39
	v_fmac_f32_e32 v52, v54, v48
	v_fma_f32 v35, -v35, v51, v36
	v_fma_f32 v36, -v37, v52, v50
	v_div_fmas_f32 v35, v35, v39, v51
	s_mov_b64 vcc, s[0:1]
	v_div_fixup_f32 v6, v35, v23, v6
	v_div_fmas_f32 v23, v36, v48, v52
	v_mul_f32_e32 v6, v7, v6
	v_div_fixup_f32 v7, v23, v32, v22
	v_cvt_pk_bf16_f32 v6, v6, s0
	v_mul_f32_e32 v7, v21, v7
	global_store_short v[2:3], v6, off
	v_cvt_pk_bf16_f32 v2, v7, s0
	global_store_short v[4:5], v2, off
	v_div_scale_f32 v2, vcc, v20, v33, v20
	v_mul_f32_e32 v3, v2, v49
	v_fma_f32 v4, -v38, v3, v2
	v_fmac_f32_e32 v3, v4, v49
	v_fma_f32 v2, -v38, v3, v2
	v_lshlrev_b32_e32 v4, 16, v16
	v_div_fmas_f32 v2, v2, v49, v3
	v_mul_f32_e32 v3, 0xbfb8aa3b, v4
	v_exp_f32_e32 v3, v3
	v_div_fixup_f32 v2, v2, v33, v20
	v_mul_f32_e32 v2, v34, v2
	v_cvt_pk_bf16_f32 v5, v2, s0
	v_add_f32_e32 v6, 1.0, v3
	v_div_scale_f32 v7, s[0:1], v6, v6, v4
	v_rcp_f32_e32 v16, v7
	v_lshl_add_u64 v[2:3], s[14:15], 0, v[18:19]
	global_store_short v[2:3], v5, off
	v_mul_f32_e32 v2, v55, v17
	v_fma_f32 v3, -v7, v16, 1.0
	v_fmac_f32_e32 v16, v3, v16
	v_div_scale_f32 v3, vcc, v4, v6, v4
	v_mul_f32_e32 v5, v3, v16
	v_fma_f32 v17, -v7, v5, v3
	v_fmac_f32_e32 v5, v17, v16
	v_fma_f32 v3, -v7, v5, v3
	v_div_fmas_f32 v3, v3, v16, v5
	v_div_fixup_f32 v3, v3, v6, v4
	v_mul_f32_e32 v2, v2, v3
	v_cvt_pk_bf16_f32 v2, v2, s0
	global_store_short v[0:1], v2, off
	v_or_b32_e32 v0, 16, v72
	v_ashrrev_i32_e32 v1, 31, v0
	v_lshlrev_b64 v[16:17], 10, v[0:1]
	v_or_b32_e32 v16, v16, v73
	v_lshl_add_u64 v[0:1], s[12:13], 0, v[16:17]
	v_or_b32_e32 v18, 64, v16
	v_mov_b32_e32 v19, v17
	v_or_b32_e32 v20, 0x80, v16
	v_mov_b32_e32 v21, v17
	v_lshl_add_u64 v[2:3], s[12:13], 0, v[18:19]
	v_lshl_add_u64 v[4:5], s[12:13], 0, v[20:21]
	v_mov_b32_e32 v32, v141
	v_mov_b32_e32 v33, v142
	v_mov_b32_e32 v34, v143
	v_lshl_add_u64 v[22:23], s[14:15], 0, v[16:17]
	v_or_b32_e32 v16, 0xc0, v16
	v_lshl_add_u64 v[0:1], s[12:13], 0, v[16:17]
	v_mov_b32_e32 v35, v144
	ds_read_b128 v[4:7], v74 offset:64
	ds_read_b128 v[0:3], v74 offset:96
	v_lshl_add_u64 v[18:19], s[14:15], 0, v[18:19]
	v_lshl_add_u64 v[16:17], s[14:15], 0, v[16:17]
	s_waitcnt lgkmcnt(1)
	v_rcp_f32_e32 v4, v4
	v_rcp_f32_e32 v6, v6
	s_waitcnt lgkmcnt(0)
	v_rcp_f32_e32 v0, v0
	v_rcp_f32_e32 v2, v2
	v_mul_f32_e32 v8, v8, v4
	v_mul_f32_e32 v24, v24, v4
	v_mul_f32_e32 v10, v10, v6
	v_mul_f32_e32 v26, v26, v6
	v_mul_f32_e32 v12, v12, v0
	v_mul_f32_e32 v14, v14, v2
	v_lshlrev_b32_e32 v32, 16, v32
	v_mul_f32_e32 v36, 0xbfb8aa3b, v32
	v_exp_f32_e32 v36, v36
	v_lshlrev_b32_e32 v33, 16, v33
	v_mul_f32_e32 v37, 0xbfb8aa3b, v33
	v_exp_f32_e32 v37, v37
	v_add_f32_e32 v36, 1.0, v36
	v_div_scale_f32 v39, s[0:1], v36, v36, v32
	v_rcp_f32_e32 v51, v39
	v_add_f32_e32 v37, 1.0, v37
	v_div_scale_f32 v49, s[0:1], v37, v37, v33
	v_rcp_f32_e32 v52, v49
	v_fma_f32 v54, -v39, v51, 1.0
	v_div_scale_f32 v48, vcc, v32, v36, v32
	v_fmac_f32_e32 v51, v54, v51
	v_lshlrev_b32_e32 v34, 16, v34
	v_mul_f32_e32 v54, v48, v51
	v_mul_f32_e32 v38, 0xbfb8aa3b, v34
	v_fma_f32 v64, -v39, v54, v48
	v_exp_f32_e32 v38, v38
	v_fma_f32 v55, -v49, v52, 1.0
	v_fmac_f32_e32 v54, v64, v51
	v_div_scale_f32 v50, s[0:1], v33, v37, v33
	v_fmac_f32_e32 v52, v55, v52
	v_fma_f32 v39, -v39, v54, v48
	v_mul_f32_e32 v55, v50, v52
	v_div_fmas_f32 v39, v39, v51, v54
	v_fma_f32 v65, -v49, v55, v50
	v_div_fixup_f32 v32, v39, v36, v32
	v_add_f32_e32 v38, 1.0, v38
	v_fmac_f32_e32 v55, v65, v52
	v_mul_f32_e32 v8, v8, v32
	v_div_scale_f32 v53, s[4:5], v38, v38, v34
	v_fma_f32 v48, -v49, v55, v50
	s_mov_b64 vcc, s[0:1]
	v_cvt_pk_bf16_f32 v8, v8, s0
	v_div_fmas_f32 v36, v48, v52, v55
	global_store_short v[22:23], v8, off
	v_rcp_f32_e32 v22, v53
	v_div_fixup_f32 v32, v36, v37, v33
	v_mul_f32_e32 v24, v24, v32
	v_cvt_pk_bf16_f32 v8, v24, s0
	global_store_short v[18:19], v8, off
	v_fma_f32 v18, -v53, v22, 1.0
	v_fmac_f32_e32 v22, v18, v22
	v_div_scale_f32 v18, vcc, v34, v38, v34
	v_mul_f32_e32 v19, v18, v22
	v_fma_f32 v23, -v53, v19, v18
	v_fmac_f32_e32 v19, v23, v22
	v_fma_f32 v18, -v53, v19, v18
	v_div_fmas_f32 v18, v18, v22, v19
	v_lshlrev_b32_e32 v22, 16, v35
	v_mul_f32_e32 v19, 0xbfb8aa3b, v22
	v_exp_f32_e32 v19, v19
	v_mul_f32_e32 v8, v40, v4
	v_div_fixup_f32 v18, v18, v38, v34
	v_mul_f32_e32 v8, v8, v18
	v_add_f32_e32 v23, 1.0, v19
	v_cvt_pk_bf16_f32 v8, v8, s0
	v_div_scale_f32 v24, s[0:1], v23, v23, v22
	v_rcp_f32_e32 v32, v24
	v_lshl_add_u64 v[18:19], s[14:15], 0, v[20:21]
	global_store_short v[18:19], v8, off
	v_mul_f32_e32 v4, v56, v4
	v_fma_f32 v8, -v24, v32, 1.0
	v_fmac_f32_e32 v32, v8, v32
	v_div_scale_f32 v8, vcc, v22, v23, v22
	v_mul_f32_e32 v18, v8, v32
	v_fma_f32 v19, -v24, v18, v8
	v_fmac_f32_e32 v18, v19, v32
	v_fma_f32 v8, -v24, v18, v8
	v_div_fmas_f32 v8, v8, v32, v18
	v_div_fixup_f32 v8, v8, v23, v22
	v_mul_f32_e32 v4, v4, v8
	v_cvt_pk_bf16_f32 v4, v4, s0
	global_store_short v[16:17], v4, off
	v_or_b32_e32 v16, 17, v72
	v_ashrrev_i32_e32 v17, 31, v16
	v_lshlrev_b64 v[16:17], 10, v[16:17]
	v_or_b32_e32 v16, v16, v73
	v_lshl_add_u64 v[18:19], s[12:13], 0, v[16:17]
	v_or_b32_e32 v20, 64, v16
	v_mov_b32_e32 v21, v17
	v_or_b32_e32 v32, 0x80, v16
	v_mov_b32_e32 v33, v17
	v_lshl_add_u64 v[22:23], s[12:13], 0, v[20:21]
	v_lshl_add_u64 v[34:35], s[12:13], 0, v[32:33]
	v_mov_b32_e32 v4, v145
	v_mov_b32_e32 v8, v146
	v_mov_b32_e32 v24, v147
	v_lshl_add_u64 v[18:19], s[14:15], 0, v[16:17]
	v_or_b32_e32 v16, 0xc0, v16
	v_lshl_add_u64 v[22:23], s[12:13], 0, v[16:17]
	v_mov_b32_e32 v22, v148
	v_rcp_f32_e32 v23, v5
	v_lshlrev_b32_e32 v4, 16, v4
	v_mul_f32_e32 v5, v9, v23
	v_mul_f32_e32 v9, v25, v23
	v_lshlrev_b32_e32 v8, 16, v8
	v_mul_f32_e32 v25, 0xbfb8aa3b, v4
	v_mul_f32_e32 v34, 0xbfb8aa3b, v8
	v_exp_f32_e32 v25, v25
	v_exp_f32_e32 v34, v34
	v_lshlrev_b32_e32 v24, 16, v24
	v_mul_f32_e32 v35, 0xbfb8aa3b, v24
	v_add_f32_e32 v25, 1.0, v25
	v_add_f32_e32 v34, 1.0, v34
	v_div_scale_f32 v36, s[0:1], v25, v25, v4
	v_div_scale_f32 v38, s[0:1], v34, v34, v8
	v_rcp_f32_e32 v39, v36
	v_rcp_f32_e32 v40, v38
	v_div_scale_f32 v37, vcc, v4, v25, v4
	v_fma_f32 v49, -v36, v39, 1.0
	v_fma_f32 v50, -v38, v40, 1.0
	v_fmac_f32_e32 v39, v49, v39
	v_div_scale_f32 v48, s[0:1], v8, v34, v8
	v_fmac_f32_e32 v40, v50, v40
	v_mul_f32_e32 v49, v37, v39
	v_mul_f32_e32 v50, v48, v40
	v_fma_f32 v51, -v36, v49, v37
	v_fma_f32 v52, -v38, v50, v48
	v_fmac_f32_e32 v49, v51, v39
	v_exp_f32_e32 v35, v35
	v_fmac_f32_e32 v50, v52, v40
	v_fma_f32 v36, -v36, v49, v37
	v_fma_f32 v37, -v38, v50, v48
	v_div_fmas_f32 v36, v36, v39, v49
	s_mov_b64 vcc, s[0:1]
	v_div_fixup_f32 v4, v36, v25, v4
	v_div_fmas_f32 v25, v37, v40, v50
	v_mul_f32_e32 v4, v5, v4
	v_div_fixup_f32 v5, v25, v34, v8
	v_cvt_pk_bf16_f32 v4, v4, s0
	v_mul_f32_e32 v5, v9, v5
	v_add_f32_e32 v9, 1.0, v35
	global_store_short v[18:19], v4, off
	v_cvt_pk_bf16_f32 v8, v5, s0
	v_div_scale_f32 v18, s[0:1], v9, v9, v24
	v_rcp_f32_e32 v19, v18
	v_lshl_add_u64 v[4:5], s[14:15], 0, v[20:21]
	global_store_short v[4:5], v8, off
	v_mul_f32_e32 v4, v41, v23
	v_fma_f32 v5, -v18, v19, 1.0
	v_fmac_f32_e32 v19, v5, v19
	v_div_scale_f32 v5, vcc, v24, v9, v24
	v_mul_f32_e32 v8, v5, v19
	v_fma_f32 v20, -v18, v8, v5
	v_fmac_f32_e32 v8, v20, v19
	v_fma_f32 v5, -v18, v8, v5
	v_div_fmas_f32 v5, v5, v19, v8
	v_lshlrev_b32_e32 v8, 16, v22
	v_mul_f32_e32 v18, 0xbfb8aa3b, v8
	v_exp_f32_e32 v18, v18
	v_div_fixup_f32 v5, v5, v9, v24
	v_mul_f32_e32 v4, v4, v5
	v_cvt_pk_bf16_f32 v9, v4, s0
	v_add_f32_e32 v18, 1.0, v18
	v_div_scale_f32 v19, s[0:1], v18, v18, v8
	v_rcp_f32_e32 v20, v19
	v_lshl_add_u64 v[4:5], s[14:15], 0, v[32:33]
	global_store_short v[4:5], v9, off
	v_mul_f32_e32 v4, v57, v23
	v_fma_f32 v5, -v19, v20, 1.0
	v_fmac_f32_e32 v20, v5, v20
	v_div_scale_f32 v5, vcc, v8, v18, v8
	v_mul_f32_e32 v9, v5, v20
	v_fma_f32 v21, -v19, v9, v5
	v_fmac_f32_e32 v9, v21, v20
	v_fma_f32 v5, -v19, v9, v5
	v_div_fmas_f32 v5, v5, v20, v9
	v_div_fixup_f32 v5, v5, v18, v8
	v_mul_f32_e32 v4, v4, v5
	v_cvt_pk_bf16_f32 v8, v4, s0
	v_lshl_add_u64 v[4:5], s[14:15], 0, v[16:17]
	global_store_short v[4:5], v8, off
	v_or_b32_e32 v4, 18, v72
	v_ashrrev_i32_e32 v5, 31, v4
	v_lshlrev_b64 v[4:5], 10, v[4:5]
	v_or_b32_e32 v4, v4, v73
	v_lshl_add_u64 v[8:9], s[12:13], 0, v[4:5]
	v_or_b32_e32 v16, 64, v4
	v_mov_b32_e32 v17, v5
	v_lshl_add_u64 v[18:19], s[12:13], 0, v[16:17]
	v_mov_b32_e32 v22, v149
	v_mov_b32_e32 v23, v150
	v_or_b32_e32 v8, 0x80, v4
	v_mov_b32_e32 v9, v5
	v_lshl_add_u64 v[18:19], s[12:13], 0, v[8:9]
	v_mov_b32_e32 v24, v151
	v_lshl_add_u64 v[18:19], s[14:15], 0, v[4:5]
	v_or_b32_e32 v4, 0xc0, v4
	v_lshl_add_u64 v[20:21], s[12:13], 0, v[4:5]
	v_mov_b32_e32 v20, v152
	v_lshl_add_u64 v[16:17], s[14:15], 0, v[16:17]
	v_lshl_add_u64 v[8:9], s[14:15], 0, v[8:9]
	v_lshl_add_u64 v[4:5], s[14:15], 0, v[4:5]
	v_lshlrev_b32_e32 v21, 16, v22
	v_lshlrev_b32_e32 v22, 16, v23
	v_mul_f32_e32 v23, 0xbfb8aa3b, v21
	v_exp_f32_e32 v23, v23
	v_mul_f32_e32 v25, 0xbfb8aa3b, v22
	v_exp_f32_e32 v25, v25
	v_lshlrev_b32_e32 v24, 16, v24
	v_add_f32_e32 v23, 1.0, v23
	v_div_scale_f32 v32, s[0:1], v23, v23, v21
	v_rcp_f32_e32 v35, v32
	v_add_f32_e32 v25, 1.0, v25
	v_div_scale_f32 v33, vcc, v21, v23, v21
	v_fma_f32 v38, -v32, v35, 1.0
	v_fmac_f32_e32 v35, v38, v35
	v_div_scale_f32 v34, s[0:1], v25, v25, v22
	v_mul_f32_e32 v38, v33, v35
	v_rcp_f32_e32 v36, v34
	v_fma_f32 v40, -v32, v38, v33
	v_fmac_f32_e32 v38, v40, v35
	v_fma_f32 v32, -v32, v38, v33
	v_div_fmas_f32 v32, v32, v35, v38
	v_fma_f32 v39, -v34, v36, 1.0
	v_div_fixup_f32 v21, v32, v23, v21
	v_div_scale_f32 v37, s[0:1], v22, v25, v22
	v_fmac_f32_e32 v36, v39, v36
	v_mul_f32_e32 v10, v10, v21
	v_mul_f32_e32 v39, v37, v36
	v_cvt_pk_bf16_f32 v10, v10, s0
	v_fma_f32 v41, -v34, v39, v37
	global_store_short v[18:19], v10, off
	v_mul_f32_e32 v10, 0xbfb8aa3b, v24
	v_fmac_f32_e32 v39, v41, v36
	v_exp_f32_e32 v10, v10
	v_fma_f32 v33, -v34, v39, v37
	s_mov_b64 vcc, s[0:1]
	v_div_fmas_f32 v23, v33, v36, v39
	v_div_fixup_f32 v18, v23, v25, v22
	v_mul_f32_e32 v18, v26, v18
	v_add_f32_e32 v10, 1.0, v10
	v_cvt_pk_bf16_f32 v18, v18, s0
	v_div_scale_f32 v19, s[0:1], v10, v10, v24
	v_rcp_f32_e32 v21, v19
	global_store_short v[16:17], v18, off
	v_mul_f32_e32 v16, v42, v6
	v_mul_f32_e32 v6, v58, v6
	v_fma_f32 v17, -v19, v21, 1.0
	v_fmac_f32_e32 v21, v17, v21
	v_div_scale_f32 v17, vcc, v24, v10, v24
	v_mul_f32_e32 v18, v17, v21
	v_fma_f32 v22, -v19, v18, v17
	v_fmac_f32_e32 v18, v22, v21
	v_fma_f32 v17, -v19, v18, v17
	v_div_fmas_f32 v17, v17, v21, v18
	v_lshlrev_b32_e32 v18, 16, v20
	v_mul_f32_e32 v19, 0xbfb8aa3b, v18
	v_exp_f32_e32 v19, v19
	v_div_fixup_f32 v10, v17, v10, v24
	v_mul_f32_e32 v10, v16, v10
	v_cvt_pk_bf16_f32 v10, v10, s0
	v_add_f32_e32 v16, 1.0, v19
	v_div_scale_f32 v17, s[0:1], v16, v16, v18
	v_rcp_f32_e32 v19, v17
	global_store_short v[8:9], v10, off
	v_fma_f32 v8, -v17, v19, 1.0
	v_fmac_f32_e32 v19, v8, v19
	v_div_scale_f32 v8, vcc, v18, v16, v18
	v_mul_f32_e32 v9, v8, v19
	v_fma_f32 v10, -v17, v9, v8
	v_fmac_f32_e32 v9, v10, v19
	v_fma_f32 v8, -v17, v9, v8
	v_div_fmas_f32 v8, v8, v19, v9
	v_div_fixup_f32 v8, v8, v16, v18
	v_mul_f32_e32 v6, v6, v8
	v_cvt_pk_bf16_f32 v6, v6, s0
	global_store_short v[4:5], v6, off
	v_or_b32_e32 v4, 19, v72
	v_ashrrev_i32_e32 v5, 31, v4
	v_lshlrev_b64 v[4:5], 10, v[4:5]
	v_or_b32_e32 v4, v4, v73
	v_lshl_add_u64 v[8:9], s[12:13], 0, v[4:5]
	v_or_b32_e32 v16, 64, v4
	v_mov_b32_e32 v17, v5
	v_lshl_add_u64 v[18:19], s[12:13], 0, v[16:17]
	v_mov_b32_e32 v6, v153
	v_mov_b32_e32 v10, v154
	v_or_b32_e32 v8, 0x80, v4
	v_mov_b32_e32 v9, v5
	v_lshl_add_u64 v[18:19], s[12:13], 0, v[8:9]
	v_mov_b32_e32 v22, v155
	v_lshl_add_u64 v[18:19], s[14:15], 0, v[4:5]
	v_or_b32_e32 v4, 0xc0, v4
	v_lshl_add_u64 v[20:21], s[12:13], 0, v[4:5]
	v_mov_b32_e32 v20, v156
	v_rcp_f32_e32 v21, v7
	v_lshl_add_u64 v[4:5], s[14:15], 0, v[4:5]
	v_mul_f32_e32 v24, v27, v21
	v_mul_f32_e32 v11, v11, v21
	v_lshlrev_b32_e32 v6, 16, v6
	v_lshlrev_b32_e32 v7, 16, v10
	v_mul_f32_e32 v10, 0xbfb8aa3b, v6
	v_exp_f32_e32 v10, v10
	v_mul_f32_e32 v23, 0xbfb8aa3b, v7
	v_exp_f32_e32 v23, v23
	v_add_f32_e32 v10, 1.0, v10
	v_div_scale_f32 v25, s[0:1], v10, v10, v6
	v_rcp_f32_e32 v32, v25
	v_add_f32_e32 v23, 1.0, v23
	v_div_scale_f32 v27, s[0:1], v23, v23, v7
	v_fma_f32 v35, -v25, v32, 1.0
	v_div_scale_f32 v26, vcc, v6, v10, v6
	v_rcp_f32_e32 v33, v27
	v_fmac_f32_e32 v32, v35, v32
	v_mul_f32_e32 v35, v26, v32
	v_fma_f32 v37, -v25, v35, v26
	v_fmac_f32_e32 v35, v37, v32
	v_fma_f32 v36, -v27, v33, 1.0
	v_fma_f32 v25, -v25, v35, v26
	v_div_scale_f32 v34, s[0:1], v7, v23, v7
	v_fmac_f32_e32 v33, v36, v33
	v_div_fmas_f32 v25, v25, v32, v35
	v_mul_f32_e32 v36, v34, v33
	v_div_fixup_f32 v6, v25, v10, v6
	v_lshlrev_b32_e32 v10, 16, v22
	v_fma_f32 v38, -v27, v36, v34
	v_mul_f32_e32 v6, v11, v6
	v_mul_f32_e32 v11, 0xbfb8aa3b, v10
	v_fmac_f32_e32 v36, v38, v33
	v_cvt_pk_bf16_f32 v6, v6, s0
	v_exp_f32_e32 v11, v11
	global_store_short v[18:19], v6, off
	v_fma_f32 v6, -v27, v36, v34
	s_mov_b64 vcc, s[0:1]
	v_div_fmas_f32 v6, v6, v33, v36
	v_div_fixup_f32 v6, v6, v23, v7
	v_mul_f32_e32 v6, v24, v6
	v_add_f32_e32 v11, 1.0, v11
	v_cvt_pk_bf16_f32 v18, v6, s0
	v_div_scale_f32 v19, s[0:1], v11, v11, v10
	v_rcp_f32_e32 v22, v19
	v_lshl_add_u64 v[6:7], s[14:15], 0, v[16:17]
	global_store_short v[6:7], v18, off
	v_mul_f32_e32 v6, v43, v21
	v_fma_f32 v7, -v19, v22, 1.0
	v_fmac_f32_e32 v22, v7, v22
	v_div_scale_f32 v7, vcc, v10, v11, v10
	v_mul_f32_e32 v16, v7, v22
	v_fma_f32 v17, -v19, v16, v7
	v_fmac_f32_e32 v16, v17, v22
	v_fma_f32 v7, -v19, v16, v7
	v_div_fmas_f32 v7, v7, v22, v16
	v_lshlrev_b32_e32 v16, 16, v20
	v_mul_f32_e32 v17, 0xbfb8aa3b, v16
	v_exp_f32_e32 v17, v17
	v_div_fixup_f32 v7, v7, v11, v10
	v_mul_f32_e32 v6, v6, v7
	v_cvt_pk_bf16_f32 v10, v6, s0
	v_add_f32_e32 v11, 1.0, v17
	v_div_scale_f32 v17, s[0:1], v11, v11, v16
	v_rcp_f32_e32 v18, v17
	v_lshl_add_u64 v[6:7], s[14:15], 0, v[8:9]
	global_store_short v[6:7], v10, off
	v_mul_f32_e32 v6, v59, v21
	v_fma_f32 v7, -v17, v18, 1.0
	v_fmac_f32_e32 v18, v7, v18
	v_div_scale_f32 v7, vcc, v16, v11, v16
	v_mul_f32_e32 v8, v7, v18
	v_fma_f32 v9, -v17, v8, v7
	v_fmac_f32_e32 v8, v9, v18
	v_fma_f32 v7, -v17, v8, v7
	v_div_fmas_f32 v7, v7, v18, v8
	v_div_fixup_f32 v7, v7, v11, v16
	v_mul_f32_e32 v6, v6, v7
	v_cvt_pk_bf16_f32 v6, v6, s0
	global_store_short v[4:5], v6, off
	v_or_b32_e32 v4, 24, v72
	v_ashrrev_i32_e32 v5, 31, v4
	v_lshlrev_b64 v[4:5], 10, v[4:5]
	v_or_b32_e32 v4, v4, v73
	v_lshl_add_u64 v[6:7], s[12:13], 0, v[4:5]
	v_or_b32_e32 v8, 64, v4
	v_mov_b32_e32 v9, v5
	v_lshl_add_u64 v[10:11], s[12:13], 0, v[8:9]
	v_mov_b32_e32 v18, v157
	v_mov_b32_e32 v19, v158
	v_or_b32_e32 v6, 0x80, v4
	v_mov_b32_e32 v7, v5
	v_lshl_add_u64 v[10:11], s[12:13], 0, v[6:7]
	v_mov_b32_e32 v20, v159
	v_lshl_add_u64 v[10:11], s[14:15], 0, v[4:5]
	v_or_b32_e32 v4, 0xc0, v4
	v_lshl_add_u64 v[16:17], s[12:13], 0, v[4:5]
	v_mov_b32_e32 v16, v173
	v_mul_f32_e32 v22, v28, v0
	v_lshl_add_u64 v[8:9], s[14:15], 0, v[8:9]
	v_lshl_add_u64 v[6:7], s[14:15], 0, v[6:7]
	v_lshl_add_u64 v[4:5], s[14:15], 0, v[4:5]
	v_lshlrev_b32_e32 v17, 16, v18
	v_lshlrev_b32_e32 v18, 16, v19
	v_mul_f32_e32 v19, 0xbfb8aa3b, v17
	v_exp_f32_e32 v19, v19
	v_mul_f32_e32 v21, 0xbfb8aa3b, v18
	v_exp_f32_e32 v21, v21
	v_add_f32_e32 v19, 1.0, v19
	v_div_scale_f32 v23, s[0:1], v19, v19, v17
	v_add_f32_e32 v21, 1.0, v21
	v_rcp_f32_e32 v25, v23
	v_div_scale_f32 v24, s[0:1], v21, v21, v18
	v_rcp_f32_e32 v26, v24
	v_fma_f32 v28, -v23, v25, 1.0
	v_div_scale_f32 v27, vcc, v17, v19, v17
	v_fmac_f32_e32 v25, v28, v25
	v_fma_f32 v32, -v24, v26, 1.0
	v_mul_f32_e32 v28, v27, v25
	v_fmac_f32_e32 v26, v32, v26
	v_fma_f32 v32, -v23, v28, v27
	v_fmac_f32_e32 v28, v32, v25
	v_fma_f32 v23, -v23, v28, v27
	v_div_fmas_f32 v23, v23, v25, v28
	v_div_fixup_f32 v17, v23, v19, v17
	v_mul_f32_e32 v12, v12, v17
	v_cvt_pk_bf16_f32 v12, v12, s0
	global_store_short v[10:11], v12, off
	v_div_scale_f32 v10, vcc, v18, v21, v18
	v_mul_f32_e32 v11, v10, v26
	v_fma_f32 v12, -v24, v11, v10
	v_fmac_f32_e32 v11, v12, v26
	v_fma_f32 v10, -v24, v11, v10
	v_div_fmas_f32 v10, v10, v26, v11
	v_lshlrev_b32_e32 v11, 16, v20
	v_mul_f32_e32 v12, 0xbfb8aa3b, v11
	v_exp_f32_e32 v12, v12
	v_div_fixup_f32 v10, v10, v21, v18
	v_mul_f32_e32 v10, v22, v10
	v_cvt_pk_bf16_f32 v10, v10, s0
	v_add_f32_e32 v12, 1.0, v12
	v_div_scale_f32 v17, s[0:1], v12, v12, v11
	v_rcp_f32_e32 v18, v17
	global_store_short v[8:9], v10, off
	v_mul_f32_e32 v8, v44, v0
	v_mul_f32_e32 v0, v60, v0
	v_fma_f32 v9, -v17, v18, 1.0
	v_fmac_f32_e32 v18, v9, v18
	v_div_scale_f32 v9, vcc, v11, v12, v11
	v_mul_f32_e32 v10, v9, v18
	v_fma_f32 v19, -v17, v10, v9
	v_fmac_f32_e32 v10, v19, v18
	v_fma_f32 v9, -v17, v10, v9
	v_div_fmas_f32 v9, v9, v18, v10
	v_lshlrev_b32_e32 v10, 16, v16
	v_mul_f32_e32 v16, 0xbfb8aa3b, v10
	v_exp_f32_e32 v16, v16
	v_div_fixup_f32 v9, v9, v12, v11
	v_mul_f32_e32 v8, v8, v9
	v_cvt_pk_bf16_f32 v8, v8, s0
	v_add_f32_e32 v9, 1.0, v16
	v_div_scale_f32 v11, s[0:1], v9, v9, v10
	v_rcp_f32_e32 v12, v11
	global_store_short v[6:7], v8, off
	v_fma_f32 v6, -v11, v12, 1.0
	v_fmac_f32_e32 v12, v6, v12
	v_div_scale_f32 v6, vcc, v10, v9, v10
	v_mul_f32_e32 v7, v6, v12
	v_fma_f32 v8, -v11, v7, v6
	v_fmac_f32_e32 v7, v8, v12
	v_fma_f32 v6, -v11, v7, v6
	v_div_fmas_f32 v6, v6, v12, v7
	v_div_fixup_f32 v6, v6, v9, v10
	v_mul_f32_e32 v0, v0, v6
	v_cvt_pk_bf16_f32 v0, v0, s0
	global_store_short v[4:5], v0, off
	v_or_b32_e32 v4, 25, v72
	v_ashrrev_i32_e32 v5, 31, v4
	v_lshlrev_b64 v[4:5], 10, v[4:5]
	v_or_b32_e32 v4, v4, v73
	v_lshl_add_u64 v[6:7], s[12:13], 0, v[4:5]
	v_or_b32_e32 v8, 64, v4
	v_mov_b32_e32 v9, v5
	v_lshl_add_u64 v[10:11], s[12:13], 0, v[8:9]
	v_mov_b32_e32 v0, v174
	v_mov_b32_e32 v12, v175
	v_or_b32_e32 v6, 0x80, v4
	v_mov_b32_e32 v7, v5
	v_lshl_add_u64 v[10:11], s[12:13], 0, v[6:7]
	v_mov_b32_e32 v18, v176
	v_lshl_add_u64 v[10:11], s[14:15], 0, v[4:5]
	v_or_b32_e32 v4, 0xc0, v4
	v_lshl_add_u64 v[16:17], s[12:13], 0, v[4:5]
	v_mov_b32_e32 v16, v177
	v_rcp_f32_e32 v17, v1
	v_lshlrev_b32_e32 v0, 16, v0
	v_lshlrev_b32_e32 v1, 16, v12
	v_mul_f32_e32 v12, 0xbfb8aa3b, v0
	v_exp_f32_e32 v12, v12
	v_mul_f32_e32 v19, 0xbfb8aa3b, v1
	v_exp_f32_e32 v19, v19
	v_mul_f32_e32 v13, v13, v17
	v_add_f32_e32 v12, 1.0, v12
	v_div_scale_f32 v20, s[0:1], v12, v12, v0
	v_rcp_f32_e32 v22, v20
	v_div_scale_f32 v21, vcc, v0, v12, v0
	v_add_f32_e32 v19, 1.0, v19
	v_fma_f32 v25, -v20, v22, 1.0
	v_fmac_f32_e32 v22, v25, v22
	v_mul_f32_e32 v25, v21, v22
	v_fma_f32 v26, -v20, v25, v21
	v_fmac_f32_e32 v25, v26, v22
	v_div_scale_f32 v23, s[0:1], v19, v19, v1
	v_fma_f32 v20, -v20, v25, v21
	v_rcp_f32_e32 v24, v23
	v_div_fmas_f32 v20, v20, v22, v25
	v_div_fixup_f32 v0, v20, v12, v0
	v_mul_f32_e32 v0, v13, v0
	v_cvt_pk_bf16_f32 v0, v0, s0
	global_store_short v[10:11], v0, off
	v_fma_f32 v10, -v23, v24, 1.0
	v_fmac_f32_e32 v24, v10, v24
	v_div_scale_f32 v10, vcc, v1, v19, v1
	v_mul_f32_e32 v11, v10, v24
	v_fma_f32 v12, -v23, v11, v10
	v_fmac_f32_e32 v11, v12, v24
	v_fma_f32 v10, -v23, v11, v10
	v_div_fmas_f32 v10, v10, v24, v11
	v_lshlrev_b32_e32 v11, 16, v18
	v_mul_f32_e32 v12, 0xbfb8aa3b, v11
	v_exp_f32_e32 v12, v12
	v_mul_f32_e32 v0, v29, v17
	v_div_fixup_f32 v1, v10, v19, v1
	v_mul_f32_e32 v0, v0, v1
	v_add_f32_e32 v12, 1.0, v12
	v_cvt_pk_bf16_f32 v10, v0, s0
	v_div_scale_f32 v13, s[0:1], v12, v12, v11
	v_rcp_f32_e32 v18, v13
	v_lshl_add_u64 v[0:1], s[14:15], 0, v[8:9]
	global_store_short v[0:1], v10, off
	v_mul_f32_e32 v0, v45, v17
	v_fma_f32 v1, -v13, v18, 1.0
	v_fmac_f32_e32 v18, v1, v18
	v_div_scale_f32 v1, vcc, v11, v12, v11
	v_mul_f32_e32 v8, v1, v18
	v_fma_f32 v9, -v13, v8, v1
	v_fmac_f32_e32 v8, v9, v18
	v_fma_f32 v1, -v13, v8, v1
	v_div_fmas_f32 v1, v1, v18, v8
	v_lshlrev_b32_e32 v8, 16, v16
	v_mul_f32_e32 v9, 0xbfb8aa3b, v8
	v_exp_f32_e32 v9, v9
	v_div_fixup_f32 v1, v1, v12, v11
	v_mul_f32_e32 v0, v0, v1
	v_cvt_pk_bf16_f32 v10, v0, s0
	v_add_f32_e32 v9, 1.0, v9
	v_div_scale_f32 v11, s[0:1], v9, v9, v8
	v_rcp_f32_e32 v12, v11
	v_lshl_add_u64 v[0:1], s[14:15], 0, v[6:7]
	global_store_short v[0:1], v10, off
	v_mul_f32_e32 v0, v61, v17
	v_fma_f32 v1, -v11, v12, 1.0
	v_fmac_f32_e32 v12, v1, v12
	v_div_scale_f32 v1, vcc, v8, v9, v8
	v_mul_f32_e32 v6, v1, v12
	v_fma_f32 v7, -v11, v6, v1
	v_fmac_f32_e32 v6, v7, v12
	v_fma_f32 v1, -v11, v6, v1
	v_div_fmas_f32 v1, v1, v12, v6
	v_div_fixup_f32 v1, v1, v9, v8
	v_mul_f32_e32 v0, v0, v1
	v_cvt_pk_bf16_f32 v6, v0, s0
	v_lshl_add_u64 v[0:1], s[14:15], 0, v[4:5]
	global_store_short v[0:1], v6, off
	v_or_b32_e32 v0, 26, v72
	v_ashrrev_i32_e32 v1, 31, v0
	v_lshlrev_b64 v[0:1], 10, v[0:1]
	v_or_b32_e32 v0, v0, v73
	v_lshl_add_u64 v[4:5], s[12:13], 0, v[0:1]
	v_mov_b32_e32 v12, v178
	v_or_b32_e32 v4, 64, v0
	v_mov_b32_e32 v5, v1
	v_lshl_add_u64 v[6:7], s[12:13], 0, v[4:5]
	v_mov_b32_e32 v13, v179
	v_or_b32_e32 v6, 0x80, v0
	v_mov_b32_e32 v7, v1
	v_lshl_add_u64 v[8:9], s[12:13], 0, v[6:7]
	v_mov_b32_e32 v16, v180
	v_lshl_add_u64 v[8:9], s[14:15], 0, v[0:1]
	v_or_b32_e32 v0, 0xc0, v0
	v_lshl_add_u64 v[10:11], s[12:13], 0, v[0:1]
	v_mov_b32_e32 v10, v181
	v_lshl_add_u64 v[4:5], s[14:15], 0, v[4:5]
	v_lshl_add_u64 v[0:1], s[14:15], 0, v[0:1]
	v_lshlrev_b32_e32 v11, 16, v12
	v_mul_f32_e32 v12, 0xbfb8aa3b, v11
	v_exp_f32_e32 v12, v12
	v_lshlrev_b32_e32 v13, 16, v13
	v_mul_f32_e32 v17, 0xbfb8aa3b, v13
	v_add_f32_e32 v12, 1.0, v12
	v_div_scale_f32 v18, s[0:1], v12, v12, v11
	v_rcp_f32_e32 v19, v18
	v_div_scale_f32 v20, vcc, v11, v12, v11
	v_exp_f32_e32 v17, v17
	v_fma_f32 v21, -v18, v19, 1.0
	v_fmac_f32_e32 v19, v21, v19
	v_mul_f32_e32 v21, v20, v19
	v_fma_f32 v22, -v18, v21, v20
	v_fmac_f32_e32 v21, v22, v19
	v_fma_f32 v18, -v18, v21, v20
	v_div_fmas_f32 v18, v18, v19, v21
	v_div_fixup_f32 v11, v18, v12, v11
	v_add_f32_e32 v12, 1.0, v17
	v_mul_f32_e32 v11, v14, v11
	v_div_scale_f32 v14, s[0:1], v12, v12, v13
	v_rcp_f32_e32 v17, v14
	s_nop 0
	v_cvt_pk_bf16_f32 v11, v11, s0
	global_store_short v[8:9], v11, off
	v_mul_f32_e32 v8, v30, v2
	v_fma_f32 v9, -v14, v17, 1.0
	v_fmac_f32_e32 v17, v9, v17
	v_div_scale_f32 v9, vcc, v13, v12, v13
	v_mul_f32_e32 v11, v9, v17
	v_fma_f32 v18, -v14, v11, v9
	v_fmac_f32_e32 v11, v18, v17
	v_fma_f32 v9, -v14, v11, v9
	v_div_fmas_f32 v9, v9, v17, v11
	v_lshlrev_b32_e32 v11, 16, v16
	v_mul_f32_e32 v14, 0xbfb8aa3b, v11
	v_exp_f32_e32 v14, v14
	v_div_fixup_f32 v9, v9, v12, v13
	v_mul_f32_e32 v8, v8, v9
	v_cvt_pk_bf16_f32 v8, v8, s0
	v_add_f32_e32 v9, 1.0, v14
	v_div_scale_f32 v12, s[0:1], v9, v9, v11
	v_rcp_f32_e32 v13, v12
	global_store_short v[4:5], v8, off
	v_mul_f32_e32 v4, v46, v2
	v_mul_f32_e32 v2, v62, v2
	v_fma_f32 v5, -v12, v13, 1.0
	v_fmac_f32_e32 v13, v5, v13
	v_div_scale_f32 v5, vcc, v11, v9, v11
	v_mul_f32_e32 v8, v5, v13
	v_fma_f32 v14, -v12, v8, v5
	v_fmac_f32_e32 v8, v14, v13
	v_fma_f32 v5, -v12, v8, v5
	v_div_fmas_f32 v5, v5, v13, v8
	v_lshlrev_b32_e32 v8, 16, v10
	v_mul_f32_e32 v10, 0xbfb8aa3b, v8
	v_exp_f32_e32 v10, v10
	v_div_fixup_f32 v5, v5, v9, v11
	v_mul_f32_e32 v4, v4, v5
	v_cvt_pk_bf16_f32 v9, v4, s0
	v_add_f32_e32 v10, 1.0, v10
	v_div_scale_f32 v11, s[0:1], v10, v10, v8
	v_rcp_f32_e32 v12, v11
	v_lshl_add_u64 v[4:5], s[14:15], 0, v[6:7]
	global_store_short v[4:5], v9, off
	v_rcp_f32_e32 v14, v3
	v_fma_f32 v4, -v11, v12, 1.0
	v_fmac_f32_e32 v12, v4, v12
	v_div_scale_f32 v4, vcc, v8, v10, v8
	v_mul_f32_e32 v5, v4, v12
	v_fma_f32 v6, -v11, v5, v4
	v_fmac_f32_e32 v5, v6, v12
	v_fma_f32 v4, -v11, v5, v4
	v_div_fmas_f32 v4, v4, v12, v5
	v_div_fixup_f32 v4, v4, v10, v8
	v_mul_f32_e32 v2, v2, v4
	v_cvt_pk_bf16_f32 v2, v2, s0
	global_store_short v[0:1], v2, off
	v_or_b32_e32 v0, 27, v72
	v_ashrrev_i32_e32 v1, 31, v0
	v_lshlrev_b64 v[0:1], 10, v[0:1]
	v_or_b32_e32 v0, v0, v73
	v_lshl_add_u64 v[4:5], s[12:13], 0, v[0:1]
	v_mov_b32_e32 v2, v182
	v_or_b32_e32 v4, 64, v0
	v_mov_b32_e32 v5, v1
	v_lshl_add_u64 v[6:7], s[12:13], 0, v[4:5]
	v_mov_b32_e32 v12, v183
	v_or_b32_e32 v6, 0x80, v0
	v_mov_b32_e32 v7, v1
	v_lshl_add_u64 v[8:9], s[12:13], 0, v[6:7]
	v_mov_b32_e32 v13, v184
	v_lshl_add_u64 v[8:9], s[14:15], 0, v[0:1]
	v_or_b32_e32 v0, 0xc0, v0
	v_lshl_add_u64 v[10:11], s[12:13], 0, v[0:1]
	v_mov_b32_e32 v10, v185
	v_mul_f32_e32 v15, v15, v14
	v_lshl_add_u64 v[0:1], s[14:15], 0, v[0:1]
	v_lshlrev_b32_e32 v2, 16, v2
	v_mul_f32_e32 v11, 0xbfb8aa3b, v2
	v_exp_f32_e32 v11, v11
	v_lshlrev_b32_e32 v12, 16, v12
	v_add_f32_e32 v3, 1.0, v11
	v_div_scale_f32 v11, s[0:1], v3, v3, v2
	v_rcp_f32_e32 v16, v11
	v_div_scale_f32 v17, vcc, v2, v3, v2
	v_fma_f32 v18, -v11, v16, 1.0
	v_fmac_f32_e32 v16, v18, v16
	v_mul_f32_e32 v18, v17, v16
	v_fma_f32 v19, -v11, v18, v17
	v_fmac_f32_e32 v18, v19, v16
	v_fma_f32 v11, -v11, v18, v17
	v_mul_f32_e32 v17, 0xbfb8aa3b, v12
	v_exp_f32_e32 v17, v17
	v_div_fmas_f32 v11, v11, v16, v18
	v_div_fixup_f32 v2, v11, v3, v2
	v_mul_f32_e32 v2, v15, v2
	v_add_f32_e32 v3, 1.0, v17
	v_div_scale_f32 v11, s[0:1], v3, v3, v12
	v_rcp_f32_e32 v15, v11
	s_nop 0
	v_cvt_pk_bf16_f32 v2, v2, s0
	global_store_short v[8:9], v2, off
	v_mul_f32_e32 v2, v31, v14
	v_fma_f32 v8, -v11, v15, 1.0
	v_fmac_f32_e32 v15, v8, v15
	v_div_scale_f32 v8, vcc, v12, v3, v12
	v_mul_f32_e32 v9, v8, v15
	v_fma_f32 v16, -v11, v9, v8
	v_fmac_f32_e32 v9, v16, v15
	v_fma_f32 v8, -v11, v9, v8
	v_div_fmas_f32 v8, v8, v15, v9
	v_lshlrev_b32_e32 v9, 16, v13
	v_mul_f32_e32 v11, 0xbfb8aa3b, v9
	v_exp_f32_e32 v11, v11
	v_div_fixup_f32 v3, v8, v3, v12
	v_mul_f32_e32 v2, v2, v3
	v_cvt_pk_bf16_f32 v8, v2, s0
	v_add_f32_e32 v11, 1.0, v11
	v_div_scale_f32 v12, s[0:1], v11, v11, v9
	v_rcp_f32_e32 v13, v12
	v_lshl_add_u64 v[2:3], s[14:15], 0, v[4:5]
	global_store_short v[2:3], v8, off
	v_mul_f32_e32 v2, v47, v14
	v_fma_f32 v3, -v12, v13, 1.0
	v_fmac_f32_e32 v13, v3, v13
	v_div_scale_f32 v3, vcc, v9, v11, v9
	v_mul_f32_e32 v4, v3, v13
	v_fma_f32 v5, -v12, v4, v3
	v_fmac_f32_e32 v4, v5, v13
	v_fma_f32 v3, -v12, v4, v3
	v_div_fmas_f32 v3, v3, v13, v4
	v_lshlrev_b32_e32 v4, 16, v10
	v_mul_f32_e32 v5, 0xbfb8aa3b, v4
	v_exp_f32_e32 v5, v5
	v_div_fixup_f32 v3, v3, v11, v9
	v_mul_f32_e32 v2, v2, v3
	v_cvt_pk_bf16_f32 v8, v2, s0
	v_add_f32_e32 v5, 1.0, v5
	v_div_scale_f32 v9, s[0:1], v5, v5, v4
	v_rcp_f32_e32 v10, v9
	v_lshl_add_u64 v[2:3], s[14:15], 0, v[6:7]
	global_store_short v[2:3], v8, off
	v_mul_f32_e32 v2, v63, v14
	v_fma_f32 v3, -v9, v10, 1.0
	v_fmac_f32_e32 v10, v3, v10
	v_div_scale_f32 v3, vcc, v4, v5, v4
	v_mul_f32_e32 v6, v3, v10
	v_fma_f32 v7, -v9, v6, v3
	v_fmac_f32_e32 v6, v7, v10
	v_fma_f32 v3, -v9, v6, v3
	v_div_fmas_f32 v3, v3, v10, v6
	v_div_fixup_f32 v3, v3, v5, v4
	v_mul_f32_e32 v2, v2, v3
	v_cvt_pk_bf16_f32 v2, v2, s0
	global_store_short v[0:1], v2, off
	s_barrier
	s_cbranch_scc0 .LBB0_565

.LBB0_832:
	s_or_b64 exec, exec, s[0:1]
	v_cmp_gt_u32_e32 vcc, s51, v174
	s_waitcnt lgkmcnt(0)
	s_barrier
	s_and_saveexec_b64 s[16:17], vcc
	s_cbranch_execz .LBB0_804
	v_lshl_or_b32 v204, v172, 2, v171
	v_or_b32_e32 v208, s64, v173
	v_lshlrev_b32_e32 v204, 10, v204
	v_lshl_or_b32 v204, v208, 1, v204
	v_add_u32_e32 v205, 0x2000, v204
	v_add_u32_e32 v206, 0x4000, v204
	v_add_u32_e32 v207, 0x6000, v204
	global_load_ushort v122, v204, s[8:9]
	global_load_ushort v123, v204, s[8:9] offset:64
	global_load_ushort v124, v204, s[8:9] offset:128
	global_load_ushort v125, v204, s[8:9] offset:192
	global_load_ushort v126, v204, s[8:9] offset:1024
	global_load_ushort v127, v204, s[8:9] offset:1088
	global_load_ushort v128, v204, s[8:9] offset:1152
	global_load_ushort v129, v204, s[8:9] offset:1216
	global_load_ushort v130, v204, s[8:9] offset:2048
	global_load_ushort v131, v204, s[8:9] offset:2112
	global_load_ushort v132, v204, s[8:9] offset:2176
	global_load_ushort v133, v204, s[8:9] offset:2240
	global_load_ushort v134, v204, s[8:9] offset:3072
	global_load_ushort v135, v204, s[8:9] offset:3136
	global_load_ushort v136, v204, s[8:9] offset:3200
	global_load_ushort v137, v204, s[8:9] offset:3264
	global_load_ushort v138, v205, s[8:9]
	global_load_ushort v139, v205, s[8:9] offset:64
	global_load_ushort v140, v205, s[8:9] offset:128
	global_load_ushort v141, v205, s[8:9] offset:192
	global_load_ushort v142, v205, s[8:9] offset:1024
	global_load_ushort v143, v205, s[8:9] offset:1088
	global_load_ushort v144, v205, s[8:9] offset:1152
	global_load_ushort v145, v205, s[8:9] offset:1216
	global_load_ushort v146, v205, s[8:9] offset:2048
	global_load_ushort v147, v205, s[8:9] offset:2112
	global_load_ushort v148, v205, s[8:9] offset:2176
	global_load_ushort v149, v205, s[8:9] offset:2240
	global_load_ushort v150, v205, s[8:9] offset:3072
	global_load_ushort v151, v205, s[8:9] offset:3136
	global_load_ushort v152, v205, s[8:9] offset:3200
	global_load_ushort v153, v205, s[8:9] offset:3264
	global_load_ushort v154, v206, s[8:9]
	global_load_ushort v155, v206, s[8:9] offset:64
	global_load_ushort v156, v206, s[8:9] offset:128
	global_load_ushort v157, v206, s[8:9] offset:192
	global_load_ushort v158, v206, s[8:9] offset:1024
	global_load_ushort v159, v206, s[8:9] offset:1088
	global_load_ushort v178, v206, s[8:9] offset:1152
	global_load_ushort v179, v206, s[8:9] offset:1216
	global_load_ushort v180, v206, s[8:9] offset:2048
	global_load_ushort v181, v206, s[8:9] offset:2112
	global_load_ushort v182, v206, s[8:9] offset:2176
	global_load_ushort v183, v206, s[8:9] offset:2240
	global_load_ushort v184, v206, s[8:9] offset:3072
	global_load_ushort v185, v206, s[8:9] offset:3136
	global_load_ushort v186, v206, s[8:9] offset:3200
	global_load_ushort v187, v206, s[8:9] offset:3264
	global_load_ushort v188, v207, s[8:9]
	global_load_ushort v189, v207, s[8:9] offset:64
	global_load_ushort v190, v207, s[8:9] offset:128
	global_load_ushort v191, v207, s[8:9] offset:192
	global_load_ushort v192, v207, s[8:9] offset:1024
	global_load_ushort v193, v207, s[8:9] offset:1088
	global_load_ushort v194, v207, s[8:9] offset:1152
	global_load_ushort v195, v207, s[8:9] offset:1216
	global_load_ushort v196, v207, s[8:9] offset:2048
	global_load_ushort v197, v207, s[8:9] offset:2112
	global_load_ushort v198, v207, s[8:9] offset:2176
	global_load_ushort v199, v207, s[8:9] offset:2240
	global_load_ushort v200, v207, s[8:9] offset:3072
	global_load_ushort v201, v207, s[8:9] offset:3136
	global_load_ushort v202, v207, s[8:9] offset:3200
	global_load_ushort v203, v207, s[8:9] offset:3264
	v_lshl_or_b32 v68, v172, 2, v171
	v_or_b32_e32 v65, s64, v173
	v_ashrrev_i32_e32 v69, 31, v68
	v_lshlrev_b64 v[98:99], 10, v[68:69]
	v_lshlrev_b32_e32 v65, 1, v65
	v_or_b32_e32 v98, v98, v65
	v_lshlrev_b32_e32 v73, 2, v173
	v_lshl_add_u64 v[100:101], s[8:9], 0, v[98:99]
	global_load_dword v75, v73, s[52:53] offset:512
	global_load_dword v77, v73, s[52:53] offset:640
	global_load_dword v79, v73, s[52:53] offset:768
	global_load_dword v81, v73, s[52:53] offset:896
	s_waitcnt vmcnt(0)
	v_mov_b32_e32 v83, v122
	v_or_b32_e32 v100, 64, v98
	v_mov_b32_e32 v101, v99
	v_lshl_add_u64 v[102:103], s[8:9], 0, v[100:101]
	v_or_b32_e32 v104, 0x80, v98
	v_mov_b32_e32 v105, v99
	v_lshl_add_u64 v[106:107], s[8:9], 0, v[104:105]
	v_mov_b32_e32 v85, v123
	v_mov_b32_e32 v87, v124
	v_lshl_add_u32 v67, v67, 14, 16
	v_lshl_add_u64 v[112:113], s[10:11], 0, v[98:99]
	v_or_b32_e32 v98, 0xc0, v98
	v_add3_u32 v71, v67, v71, v73
	v_lshl_add_u64 v[114:115], s[8:9], 0, v[98:99]
	v_mov_b32_e32 v102, v0
	v_mov_b32_e32 v103, v48
	v_mov_b32_e32 v106, v32
	v_mov_b32_e32 v107, v16
	v_mov_b32_e32 v48, v1
	v_mov_b32_e32 v16, v33
	ds_read2_b32 v[0:1], v71 offset1:32
	ds_read2_b32 v[32:33], v71 offset0:64 offset1:96
	ds_read2_b32 v[108:109], v71 offset0:128 offset1:160
	ds_read2_b32 v[110:111], v71 offset0:192 offset1:224
	v_mov_b32_e32 v73, v125
	s_waitcnt lgkmcnt(3)
	v_pk_mul_f32 v[0:1], v[164:165], v[0:1]
	s_waitcnt lgkmcnt(2)
	v_pk_mul_f32 v[32:33], v[164:165], v[32:33]
	v_pk_fma_f32 v[102:103], v[102:103], v[96:97], v[0:1] op_sel_hi:[1,0,1] neg_lo:[0,0,1] neg_hi:[0,0,1]
	s_waitcnt lgkmcnt(0)
	v_pk_mul_f32 v[110:111], v[164:165], v[110:111]
	v_pk_mul_f32 v[0:1], v[102:103], v[102:103]
	v_pk_fma_f32 v[16:17], v[16:17], v[94:95], v[110:111] op_sel_hi:[1,0,1] neg_lo:[0,0,1] neg_hi:[0,0,1]
	v_mov_b32_e32 v111, v0
	v_pk_mul_f32 v[108:109], v[164:165], v[108:109]
	v_pk_fma_f32 v[96:97], v[106:107], v[96:97], v[32:33] op_sel_hi:[1,0,1] neg_lo:[0,0,1] neg_hi:[0,0,1]
	v_pk_fma_f32 v[32:33], v[48:49], v[94:95], v[108:109] op_sel_hi:[1,0,1] neg_lo:[0,0,1] neg_hi:[0,0,1]
	v_pk_mul_f32 v[94:95], v[96:97], v[96:97]
	v_pk_mul_f32 v[106:107], v[32:33], v[32:33]
	v_pk_mul_f32 v[108:109], v[16:17], v[16:17]
	v_mov_b32_e32 v110, v106
	v_lshl_add_u64 v[100:101], s[10:11], 0, v[100:101]
	v_lshl_add_u64 v[104:105], s[10:11], 0, v[104:105]
	v_lshl_add_u64 v[98:99], s[10:11], 0, v[98:99]
	v_mul_f32_e32 v69, 0x3f24fd5c, v75
	v_mul_f32_e32 v67, 0x3f24fd5c, v77
	v_mul_f32_e32 v49, 0x3f24fd5c, v79
	v_mul_f32_e32 v48, 0x3f24fd5c, v81
	v_lshlrev_b32_e32 v0, 16, v83
	v_mul_f32_e32 v75, 0xbfb8aa3b, v0
	v_exp_f32_e32 v75, v75
	v_lshlrev_b32_e32 v77, 16, v85
	v_lshlrev_b32_e32 v79, 16, v87
	v_mul_f32_e32 v81, 0xbfb8aa3b, v77
	v_mul_f32_e32 v83, 0xbfb8aa3b, v79
	v_exp_f32_e32 v81, v81
	v_exp_f32_e32 v83, v83
	v_add_f32_e32 v75, 1.0, v75
	v_div_scale_f32 v85, s[0:1], v75, v75, v0
	v_add_f32_e32 v81, 1.0, v81
	v_add_f32_e32 v83, 1.0, v83
	v_rcp_f32_e32 v89, v85
	v_div_scale_f32 v91, s[0:1], v81, v81, v77
	v_div_scale_f32 v114, s[4:5], v83, v83, v79
	v_rcp_f32_e32 v106, v91
	v_rcp_f32_e32 v116, v114
	v_fma_f32 v117, -v85, v89, 1.0
	v_div_scale_f32 v87, vcc, v0, v75, v0
	v_fmac_f32_e32 v89, v117, v89
	v_fma_f32 v117, -v91, v106, 1.0
	v_div_scale_f32 v93, s[0:1], v77, v81, v77
	v_fma_f32 v118, -v114, v116, 1.0
	v_mul_f32_e32 v119, v87, v89
	v_fmac_f32_e32 v106, v117, v106
	v_fmac_f32_e32 v116, v118, v116
	v_fma_f32 v117, -v85, v119, v87
	v_mul_f32_e32 v118, v93, v106
	v_fmac_f32_e32 v119, v117, v89
	v_fma_f32 v117, -v91, v118, v93
	v_fma_f32 v85, -v85, v119, v87
	v_fmac_f32_e32 v118, v117, v106
	v_div_fmas_f32 v85, v85, v89, v119
	v_fma_f32 v87, -v91, v118, v93
	s_mov_b64 vcc, s[0:1]
	v_div_fixup_f32 v75, v85, v75, v0
	v_div_fmas_f32 v0, v87, v106, v118
	v_div_fixup_f32 v77, v0, v81, v77
	v_mov_b32_e32 v0, v107
	v_pk_add_f32 v[0:1], v[110:111], v[0:1]
	v_mov_b32_e32 v106, v108
	v_mov_b32_e32 v107, v94
	v_pk_add_f32 v[0:1], v[0:1], v[106:107]
	v_mov_b32_e32 v94, v109
	v_pk_add_f32 v[0:1], v[0:1], v[94:95]
	ds_bpermute_b32 v95, v216, v1
	ds_bpermute_b32 v94, v216, v0
	v_div_scale_f32 v115, s[4:5], v79, v83, v79
	v_mul_f32_e32 v120, v115, v116
	v_fma_f32 v121, -v114, v120, v115
	s_waitcnt lgkmcnt(0)
	v_pk_add_f32 v[0:1], v[0:1], v[94:95]
	ds_bpermute_b32 v95, v217, v1
	ds_bpermute_b32 v94, v217, v0
	v_fmac_f32_e32 v120, v121, v116
	v_fma_f32 v81, -v114, v120, v115
	s_mov_b64 vcc, s[4:5]
	v_div_fmas_f32 v81, v81, v116, v120
	s_waitcnt lgkmcnt(0)
	v_pk_add_f32 v[0:1], v[0:1], v[94:95]
	ds_bpermute_b32 v95, v218, v1
	ds_bpermute_b32 v94, v218, v0
	v_lshlrev_b32_e32 v73, 16, v73
	v_div_fixup_f32 v79, v81, v83, v79
	v_mul_f32_e32 v81, 0xbfb8aa3b, v73
	v_exp_f32_e32 v81, v81
	s_waitcnt lgkmcnt(0)
	v_pk_add_f32 v[0:1], v[0:1], v[94:95]
	ds_bpermute_b32 v95, v219, v1
	ds_bpermute_b32 v94, v219, v0
	v_add_f32_e32 v81, 1.0, v81
	v_div_scale_f32 v83, s[0:1], v81, v81, v73
	v_rcp_f32_e32 v85, v83
	s_waitcnt lgkmcnt(0)
	v_pk_add_f32 v[0:1], v[0:1], v[94:95]
	ds_bpermute_b32 v95, v220, v1
	ds_bpermute_b32 v94, v220, v0
	v_fma_f32 v87, -v83, v85, 1.0
	v_fmac_f32_e32 v85, v87, v85
	v_div_scale_f32 v87, vcc, v73, v81, v73
	v_mul_f32_e32 v89, v87, v85
	v_fma_f32 v91, -v83, v89, v87
	s_waitcnt lgkmcnt(0)
	v_pk_add_f32 v[94:95], v[0:1], v[94:95]
	v_mov_b64_e32 v[0:1], s[48:49]
	v_fmac_f32_e32 v89, v91, v85
	v_pk_fma_f32 v[94:95], v[94:95], s[46:47], v[0:1] op_sel_hi:[1,0,0]
	v_fma_f32 v83, -v83, v89, v87
	v_mul_f32_e32 v87, 0x4b800000, v95
	v_cmp_gt_f32_e64 s[0:1], s49, v95
	v_div_fmas_f32 v83, v83, v85, v89
	v_div_fixup_f32 v73, v83, v81, v73
	v_cndmask_b32_e64 v87, v95, v87, s[0:1]
	v_rsq_f32_e32 v87, v87
	v_cmp_gt_f32_e32 vcc, s49, v94
	v_mul_f32_e32 v81, 0x45800000, v87
	v_cndmask_b32_e64 v81, v87, v81, s[0:1]
	v_mul_f32_e32 v83, v102, v81
	v_mul_f32_e32 v83, v83, v69
	v_mul_f32_e32 v75, v83, v75
	v_cvt_pk_bf16_f32 v75, v75, s0
	global_store_short v[112:113], v75, off
	v_mul_f32_e32 v75, v103, v81
	v_mul_f32_e32 v75, v75, v67
	v_mul_f32_e32 v75, v75, v77
	v_cvt_pk_bf16_f32 v75, v75, s0
	global_store_short v[100:101], v75, off
	v_mul_f32_e32 v75, v96, v81
	v_mul_f32_e32 v75, v75, v49
	v_mul_f32_e32 v75, v75, v79
	v_cvt_pk_bf16_f32 v75, v75, s0
	global_store_short v[104:105], v75, off
	v_mul_f32_e32 v75, v97, v81
	v_or_b32_e32 v96, 1, v68
	v_mul_f32_e32 v75, v75, v48
	v_ashrrev_i32_e32 v97, 31, v96
	v_mul_f32_e32 v73, v75, v73
	v_lshlrev_b64 v[96:97], 10, v[96:97]
	v_cvt_pk_bf16_f32 v73, v73, s0
	v_or_b32_e32 v96, v96, v65
	global_store_short v[98:99], v73, off
	v_lshl_add_u64 v[98:99], s[8:9], 0, v[96:97]
	v_mov_b32_e32 v73, v126
	v_or_b32_e32 v98, 64, v96
	v_mov_b32_e32 v99, v97
	v_lshl_add_u64 v[100:101], s[8:9], 0, v[98:99]
	v_mov_b32_e32 v75, v127
	v_or_b32_e32 v100, 0x80, v96
	v_mov_b32_e32 v101, v97
	v_lshl_add_u64 v[102:103], s[8:9], 0, v[100:101]
	v_mov_b32_e32 v77, v128
	v_lshl_add_u64 v[102:103], s[10:11], 0, v[96:97]
	v_or_b32_e32 v96, 0xc0, v96
	v_lshl_add_u64 v[104:105], s[8:9], 0, v[96:97]
	v_mov_b32_e32 v79, v129
	v_mul_f32_e32 v81, 0x4b800000, v94
	v_cndmask_b32_e32 v81, v94, v81, vcc
	v_rsq_f32_e32 v81, v81
	v_lshlrev_b32_e32 v73, 16, v73
	v_mul_f32_e32 v83, 0xbfb8aa3b, v73
	v_exp_f32_e32 v83, v83
	v_mul_f32_e32 v85, 0x45800000, v81
	v_cndmask_b32_e32 v81, v81, v85, vcc
	v_lshlrev_b32_e32 v75, 16, v75
	v_add_f32_e32 v83, 1.0, v83
	v_div_scale_f32 v87, s[0:1], v83, v83, v73
	v_rcp_f32_e32 v89, v87
	v_mul_f32_e32 v32, v32, v81
	v_mul_f32_e32 v32, v32, v69
	v_mul_f32_e32 v16, v16, v81
	v_fma_f32 v85, -v87, v89, 1.0
	v_fmac_f32_e32 v89, v85, v89
	v_div_scale_f32 v85, vcc, v73, v83, v73
	v_mul_f32_e32 v91, v85, v89
	v_fma_f32 v93, -v87, v91, v85
	v_fmac_f32_e32 v91, v93, v89
	v_fma_f32 v85, -v87, v91, v85
	v_mul_f32_e32 v87, 0xbfb8aa3b, v75
	v_exp_f32_e32 v87, v87
	v_div_fmas_f32 v85, v85, v89, v91
	v_div_fixup_f32 v73, v85, v83, v73
	v_mul_f32_e32 v32, v32, v73
	v_add_f32_e32 v73, 1.0, v87
	v_cvt_pk_bf16_f32 v32, v32, s0
	v_div_scale_f32 v83, s[0:1], v73, v73, v75
	v_rcp_f32_e32 v85, v83
	global_store_short v[102:103], v32, off
	v_mul_f32_e32 v32, v33, v81
	v_mul_f32_e32 v32, v32, v67
	v_fma_f32 v33, -v83, v85, 1.0
	v_fmac_f32_e32 v85, v33, v85
	v_div_scale_f32 v33, vcc, v75, v73, v75
	v_mul_f32_e32 v87, v33, v85
	v_fma_f32 v89, -v83, v87, v33
	v_fmac_f32_e32 v87, v89, v85
	v_fma_f32 v33, -v83, v87, v33
	v_div_fmas_f32 v33, v33, v85, v87
	v_div_fixup_f32 v33, v33, v73, v75
	v_lshlrev_b32_e32 v73, 16, v77
	v_mul_f32_e32 v75, 0xbfb8aa3b, v73
	v_exp_f32_e32 v75, v75
	v_mul_f32_e32 v32, v32, v33
	v_cvt_pk_bf16_f32 v77, v32, s0
	v_lshl_add_u64 v[32:33], s[10:11], 0, v[98:99]
	v_add_f32_e32 v75, 1.0, v75
	v_div_scale_f32 v83, s[0:1], v75, v75, v73
	v_rcp_f32_e32 v85, v83
	global_store_short v[32:33], v77, off
	v_mul_f32_e32 v16, v16, v49
	v_mov_b32_e32 v98, v2
	v_fma_f32 v32, -v83, v85, 1.0
	v_fmac_f32_e32 v85, v32, v85
	v_div_scale_f32 v32, vcc, v73, v75, v73
	v_mul_f32_e32 v33, v32, v85
	v_fma_f32 v77, -v83, v33, v32
	v_fmac_f32_e32 v33, v77, v85
	v_fma_f32 v32, -v83, v33, v32
	v_div_fmas_f32 v32, v32, v85, v33
	v_div_fixup_f32 v32, v32, v75, v73
	v_lshlrev_b32_e32 v73, 16, v79
	v_mul_f32_e32 v33, 0xbfb8aa3b, v73
	v_exp_f32_e32 v75, v33
	v_mul_f32_e32 v16, v16, v32
	v_cvt_pk_bf16_f32 v16, v16, s0
	v_lshl_add_u64 v[32:33], s[10:11], 0, v[100:101]
	v_add_f32_e32 v75, 1.0, v75
	v_div_scale_f32 v77, s[0:1], v75, v75, v73
	v_rcp_f32_e32 v79, v77
	global_store_short v[32:33], v16, off
	v_mul_f32_e32 v16, v17, v81
	v_mul_f32_e32 v16, v16, v48
	v_fma_f32 v17, -v77, v79, 1.0
	v_fmac_f32_e32 v79, v17, v79
	v_div_scale_f32 v17, vcc, v73, v75, v73
	v_mul_f32_e32 v32, v17, v79
	v_fma_f32 v33, -v77, v32, v17
	v_fmac_f32_e32 v32, v33, v79
	v_fma_f32 v17, -v77, v32, v17
	v_div_fmas_f32 v17, v17, v79, v32
	v_div_fixup_f32 v17, v17, v75, v73
	v_mul_f32_e32 v16, v16, v17
	v_cvt_pk_bf16_f32 v32, v16, s0
	v_lshl_add_u64 v[16:17], s[10:11], 0, v[96:97]
	global_store_short v[16:17], v32, off
	v_or_b32_e32 v16, 2, v68
	v_ashrrev_i32_e32 v17, 31, v16
	v_lshlrev_b64 v[32:33], 10, v[16:17]
	v_or_b32_e32 v32, v32, v65
	v_lshl_add_u64 v[16:17], s[8:9], 0, v[32:33]
	v_mov_b32_e32 v73, v130
	v_or_b32_e32 v94, 64, v32
	v_or_b32_e32 v96, 0x80, v32
	v_lshl_add_u64 v[104:105], s[10:11], 0, v[32:33]
	v_or_b32_e32 v32, 0xc0, v32
	v_mov_b32_e32 v95, v33
	v_lshl_add_u64 v[106:107], s[8:9], 0, v[32:33]
	v_mov_b32_e32 v81, v133
	v_lshl_add_u64 v[16:17], s[8:9], 0, v[94:95]
	v_mov_b32_e32 v75, v131
	v_mov_b32_e32 v97, v33
	v_lshl_add_u64 v[16:17], s[8:9], 0, v[96:97]
	v_mov_b32_e32 v77, v132
	v_add_u32_e32 v79, 0x400, v71
	ds_read2_b32 v[16:17], v79 offset1:32
	ds_read2_b32 v[100:101], v79 offset0:64 offset1:96
	v_mov_b32_e32 v99, v50
	v_mov_b32_e32 v50, v3
	v_lshl_add_u64 v[32:33], s[10:11], 0, v[32:33]
	s_waitcnt lgkmcnt(1)
	v_pk_mul_f32 v[16:17], v[164:165], v[16:17]
	s_waitcnt lgkmcnt(0)
	v_pk_mul_f32 v[100:101], v[164:165], v[100:101]
	v_pk_fma_f32 v[98:99], v[98:99], v[92:93], v[16:17] op_sel_hi:[1,0,1] neg_lo:[0,0,1] neg_hi:[0,0,1]
	v_mov_b32_e32 v16, v34
	v_mov_b32_e32 v17, v18
	v_pk_fma_f32 v[92:93], v[16:17], v[92:93], v[100:101] op_sel_hi:[1,0,1] neg_lo:[0,0,1] neg_hi:[0,0,1]
	ds_read2_b32 v[16:17], v79 offset0:128 offset1:160
	v_mov_b32_e32 v18, v35
	v_pk_mul_f32 v[102:103], v[98:99], v[98:99]
	v_pk_mul_f32 v[100:101], v[92:93], v[92:93]
	s_waitcnt lgkmcnt(0)
	v_pk_mul_f32 v[2:3], v[164:165], v[16:17]
	s_nop 0
	v_pk_fma_f32 v[16:17], v[50:51], v[90:91], v[2:3] op_sel_hi:[1,0,1] neg_lo:[0,0,1] neg_hi:[0,0,1]
	v_lshlrev_b32_e32 v34, 16, v73
	v_mul_f32_e32 v2, 0xbfb8aa3b, v34
	v_exp_f32_e32 v73, v2
	ds_read2_b32 v[2:3], v79 offset0:192 offset1:224
	v_pk_mul_f32 v[50:51], v[16:17], v[16:17]
	v_add_f32_e32 v35, 1.0, v73
	v_div_scale_f32 v73, s[0:1], v35, v35, v34
	v_rcp_f32_e32 v79, v73
	v_lshlrev_b32_e32 v75, 16, v75
	v_mul_f32_e32 v87, 0xbfb8aa3b, v75
	v_exp_f32_e32 v87, v87
	v_fma_f32 v83, -v73, v79, 1.0
	v_fmac_f32_e32 v79, v83, v79
	v_div_scale_f32 v83, vcc, v34, v35, v34
	v_mul_f32_e32 v85, v83, v79
	v_fma_f32 v89, -v73, v85, v83
	v_fmac_f32_e32 v85, v89, v79
	v_fma_f32 v73, -v73, v85, v83
	v_add_f32_e32 v83, 1.0, v87
	v_div_scale_f32 v87, s[0:1], v83, v83, v75
	v_rcp_f32_e32 v89, v87
	v_lshlrev_b32_e32 v77, 16, v77
	v_div_fmas_f32 v73, v73, v79, v85
	v_mul_f32_e32 v79, 0xbfb8aa3b, v77
	v_exp_f32_e32 v79, v79
	v_div_fixup_f32 v73, v73, v35, v34
	v_fma_f32 v34, -v87, v89, 1.0
	v_fmac_f32_e32 v89, v34, v89
	v_div_scale_f32 v34, vcc, v75, v83, v75
	v_mul_f32_e32 v35, v34, v89
	v_fma_f32 v85, -v87, v35, v34
	v_add_f32_e32 v79, 1.0, v79
	v_fmac_f32_e32 v35, v85, v89
	v_div_scale_f32 v85, s[0:1], v79, v79, v77
	v_fma_f32 v34, -v87, v35, v34
	v_rcp_f32_e32 v87, v85
	v_div_fmas_f32 v34, v34, v89, v35
	v_div_fixup_f32 v75, v34, v83, v75
	s_waitcnt lgkmcnt(0)
	v_pk_mul_f32 v[2:3], v[164:165], v[2:3]
	v_fma_f32 v83, -v85, v87, 1.0
	v_fmac_f32_e32 v87, v83, v87
	v_div_scale_f32 v83, vcc, v77, v79, v77
	v_mul_f32_e32 v89, v83, v87
	v_pk_fma_f32 v[2:3], v[18:19], v[90:91], v[2:3] op_sel_hi:[1,0,1] neg_lo:[0,0,1] neg_hi:[0,0,1]
	v_fma_f32 v90, -v85, v89, v83
	v_pk_mul_f32 v[18:19], v[2:3], v[2:3]
	v_fmac_f32_e32 v89, v90, v87
	v_mov_b32_e32 v90, v50
	v_mov_b32_e32 v91, v102
	v_mov_b32_e32 v102, v51
	v_pk_add_f32 v[50:51], v[90:91], v[102:103]
	v_mov_b32_e32 v90, v18
	v_mov_b32_e32 v91, v100
	v_pk_add_f32 v[50:51], v[50:51], v[90:91]
	v_mov_b32_e32 v100, v19
	v_pk_add_f32 v[18:19], v[50:51], v[100:101]
	ds_bpermute_b32 v51, v216, v19
	ds_bpermute_b32 v50, v216, v18
	v_fma_f32 v83, -v85, v89, v83
	v_div_fmas_f32 v83, v83, v87, v89
	v_div_fixup_f32 v77, v83, v79, v77
	v_lshlrev_b32_e32 v79, 16, v81
	s_waitcnt lgkmcnt(0)
	v_pk_add_f32 v[18:19], v[18:19], v[50:51]
	ds_bpermute_b32 v51, v217, v19
	ds_bpermute_b32 v50, v217, v18
	v_mul_f32_e32 v81, 0xbfb8aa3b, v79
	v_exp_f32_e32 v81, v81
	v_lshl_add_u64 v[34:35], s[10:11], 0, v[94:95]
	v_lshl_add_u64 v[90:91], s[10:11], 0, v[96:97]
	s_waitcnt lgkmcnt(0)
	v_pk_add_f32 v[18:19], v[18:19], v[50:51]
	ds_bpermute_b32 v51, v218, v19
	ds_bpermute_b32 v50, v218, v18
	v_add_f32_e32 v81, 1.0, v81
	v_div_scale_f32 v83, s[0:1], v81, v81, v79
	v_rcp_f32_e32 v85, v83
	s_waitcnt lgkmcnt(0)
	v_pk_add_f32 v[18:19], v[18:19], v[50:51]
	ds_bpermute_b32 v51, v219, v19
	ds_bpermute_b32 v50, v219, v18
	v_fma_f32 v87, -v83, v85, 1.0
	v_fmac_f32_e32 v85, v87, v85
	v_div_scale_f32 v87, vcc, v79, v81, v79
	s_waitcnt lgkmcnt(0)
	v_pk_add_f32 v[18:19], v[18:19], v[50:51]
	ds_bpermute_b32 v51, v220, v19
	ds_bpermute_b32 v50, v220, v18
	v_mul_f32_e32 v89, v87, v85
	v_fma_f32 v94, -v83, v89, v87
	v_fmac_f32_e32 v89, v94, v85
	v_fma_f32 v83, -v83, v89, v87
	s_waitcnt lgkmcnt(0)
	v_pk_add_f32 v[18:19], v[18:19], v[50:51]
	s_nop 0
	v_pk_fma_f32 v[18:19], v[18:19], s[46:47], v[0:1] op_sel_hi:[1,0,0]
	s_nop 0
	v_mul_f32_e32 v50, 0x4b800000, v19
	v_cmp_gt_f32_e64 s[0:1], s49, v19
	s_nop 1
	v_cndmask_b32_e64 v19, v19, v50, s[0:1]
	v_rsq_f32_e32 v19, v19
	v_div_fmas_f32 v50, v83, v85, v89
	v_div_fixup_f32 v50, v50, v81, v79
	v_mul_f32_e32 v79, 0x4b800000, v18
	v_mul_f32_e32 v51, 0x45800000, v19
	v_cndmask_b32_e64 v19, v19, v51, s[0:1]
	v_mul_f32_e32 v51, v98, v19
	v_mul_f32_e32 v51, v51, v69
	v_mul_f32_e32 v51, v51, v73
	v_cvt_pk_bf16_f32 v51, v51, s0
	global_store_short v[104:105], v51, off
	v_mul_f32_e32 v51, v99, v19
	v_mul_f32_e32 v51, v51, v67
	v_mul_f32_e32 v51, v51, v75
	v_cvt_pk_bf16_f32 v51, v51, s0
	global_store_short v[34:35], v51, off
	v_mul_f32_e32 v34, v92, v19
	v_mul_f32_e32 v19, v93, v19
	v_mul_f32_e32 v19, v19, v48
	v_mul_f32_e32 v19, v19, v50
	v_cvt_pk_bf16_f32 v19, v19, s0
	global_store_short v[32:33], v19, off
	v_or_b32_e32 v32, 3, v68
	v_mul_f32_e32 v34, v34, v49
	v_ashrrev_i32_e32 v33, 31, v32
	v_mul_f32_e32 v34, v34, v77
	v_lshlrev_b64 v[32:33], 10, v[32:33]
	v_cvt_pk_bf16_f32 v34, v34, s0
	v_or_b32_e32 v32, v32, v65
	global_store_short v[90:91], v34, off
	v_lshl_add_u64 v[34:35], s[8:9], 0, v[32:33]
	v_mov_b32_e32 v19, v134
	v_or_b32_e32 v34, 64, v32
	v_mov_b32_e32 v35, v33
	v_lshl_add_u64 v[50:51], s[8:9], 0, v[34:35]
	v_mov_b32_e32 v73, v135
	v_or_b32_e32 v50, 0x80, v32
	v_mov_b32_e32 v51, v33
	v_lshl_add_u64 v[90:91], s[8:9], 0, v[50:51]
	v_mov_b32_e32 v75, v136
	v_lshl_add_u64 v[90:91], s[10:11], 0, v[32:33]
	v_or_b32_e32 v32, 0xc0, v32
	v_lshl_add_u64 v[92:93], s[8:9], 0, v[32:33]
	v_mov_b32_e32 v77, v137
	v_cmp_gt_f32_e32 vcc, s49, v18
	v_lshlrev_b32_e32 v19, 16, v19
	v_cndmask_b32_e32 v18, v18, v79, vcc
	v_mul_f32_e32 v79, 0xbfb8aa3b, v19
	v_exp_f32_e32 v79, v79
	v_rsq_f32_e32 v18, v18
	v_lshlrev_b32_e32 v73, 16, v73
	v_add_f32_e32 v79, 1.0, v79
	v_div_scale_f32 v83, s[0:1], v79, v79, v19
	v_rcp_f32_e32 v85, v83
	v_mul_f32_e32 v81, 0x45800000, v18
	v_cndmask_b32_e32 v18, v18, v81, vcc
	v_mul_f32_e32 v16, v16, v18
	v_fma_f32 v81, -v83, v85, 1.0
	v_fmac_f32_e32 v85, v81, v85
	v_div_scale_f32 v81, vcc, v19, v79, v19
	v_mul_f32_e32 v87, v81, v85
	v_fma_f32 v89, -v83, v87, v81
	v_fmac_f32_e32 v87, v89, v85
	v_fma_f32 v81, -v83, v87, v81
	v_mul_f32_e32 v83, 0xbfb8aa3b, v73
	v_exp_f32_e32 v83, v83
	v_div_fmas_f32 v81, v81, v85, v87
	v_mul_f32_e32 v16, v16, v69
	v_div_fixup_f32 v19, v81, v79, v19
	v_mul_f32_e32 v16, v16, v19
	v_add_f32_e32 v19, 1.0, v83
	v_cvt_pk_bf16_f32 v16, v16, s0
	v_div_scale_f32 v79, s[0:1], v19, v19, v73
	v_rcp_f32_e32 v81, v79
	global_store_short v[90:91], v16, off
	v_mul_f32_e32 v16, v17, v18
	v_mul_f32_e32 v16, v16, v67
	v_fma_f32 v17, -v79, v81, 1.0
	v_fmac_f32_e32 v81, v17, v81
	v_div_scale_f32 v17, vcc, v73, v19, v73
	v_mul_f32_e32 v83, v17, v81
	v_fma_f32 v85, -v79, v83, v17
	v_fmac_f32_e32 v83, v85, v81
	v_fma_f32 v17, -v79, v83, v17
	v_div_fmas_f32 v17, v17, v81, v83
	v_div_fixup_f32 v17, v17, v19, v73
	v_lshlrev_b32_e32 v19, 16, v75
	v_mul_f32_e32 v73, 0xbfb8aa3b, v19
	v_exp_f32_e32 v73, v73
	v_mul_f32_e32 v16, v16, v17
	v_cvt_pk_bf16_f32 v75, v16, s0
	v_lshl_add_u64 v[16:17], s[10:11], 0, v[34:35]
	v_add_f32_e32 v34, 1.0, v73
	v_div_scale_f32 v35, s[0:1], v34, v34, v19
	v_rcp_f32_e32 v73, v35
	global_store_short v[16:17], v75, off
	v_mul_f32_e32 v2, v2, v18
	v_mul_f32_e32 v2, v2, v49
	v_fma_f32 v16, -v35, v73, 1.0
	v_fmac_f32_e32 v73, v16, v73
	v_div_scale_f32 v16, vcc, v19, v34, v19
	v_mul_f32_e32 v17, v16, v73
	v_fma_f32 v75, -v35, v17, v16
	v_fmac_f32_e32 v17, v75, v73
	v_fma_f32 v16, -v35, v17, v16
	v_div_fmas_f32 v16, v16, v73, v17
	v_div_fixup_f32 v16, v16, v34, v19
	v_lshlrev_b32_e32 v19, 16, v77
	v_mul_f32_e32 v17, 0xbfb8aa3b, v19
	v_exp_f32_e32 v34, v17
	v_mul_f32_e32 v2, v2, v16
	v_cvt_pk_bf16_f32 v2, v2, s0
	v_lshl_add_u64 v[16:17], s[10:11], 0, v[50:51]
	v_add_f32_e32 v34, 1.0, v34
	v_div_scale_f32 v35, s[0:1], v34, v34, v19
	v_rcp_f32_e32 v50, v35
	global_store_short v[16:17], v2, off
	v_mul_f32_e32 v2, v3, v18
	v_mul_f32_e32 v2, v2, v48
	v_fma_f32 v3, -v35, v50, 1.0
	v_fmac_f32_e32 v50, v3, v50
	v_div_scale_f32 v3, vcc, v19, v34, v19
	v_mul_f32_e32 v16, v3, v50
	v_fma_f32 v17, -v35, v16, v3
	v_fmac_f32_e32 v16, v17, v50
	v_fma_f32 v3, -v35, v16, v3
	v_div_fmas_f32 v3, v3, v50, v16
	v_div_fixup_f32 v3, v3, v34, v19
	v_mul_f32_e32 v2, v2, v3
	v_cvt_pk_bf16_f32 v16, v2, s0
	v_lshl_add_u64 v[2:3], s[10:11], 0, v[32:33]
	global_store_short v[2:3], v16, off
	v_or_b32_e32 v2, 8, v68
	v_ashrrev_i32_e32 v3, 31, v2
	v_lshlrev_b64 v[16:17], 10, v[2:3]
	v_or_b32_e32 v16, v16, v65
	v_lshl_add_u64 v[2:3], s[8:9], 0, v[16:17]
	v_mov_b32_e32 v73, v138
	v_or_b32_e32 v18, 64, v16
	v_or_b32_e32 v32, 0x80, v16
	v_lshl_add_u64 v[92:93], s[10:11], 0, v[16:17]
	v_or_b32_e32 v16, 0xc0, v16
	v_mov_b32_e32 v19, v17
	v_lshl_add_u64 v[94:95], s[8:9], 0, v[16:17]
	v_mov_b32_e32 v81, v141
	v_lshl_add_u64 v[2:3], s[8:9], 0, v[18:19]
	v_mov_b32_e32 v75, v139
	v_mov_b32_e32 v33, v17
	v_lshl_add_u64 v[2:3], s[8:9], 0, v[32:33]
	v_mov_b32_e32 v77, v140
	v_add_u32_e32 v79, 0x1000, v71
	ds_read2_b32 v[2:3], v79 offset1:32
	ds_read2_b32 v[50:51], v79 offset0:64 offset1:96
	v_mov_b32_e32 v34, v4
	v_mov_b32_e32 v35, v52
	v_mov_b32_e32 v52, v5
	s_waitcnt lgkmcnt(1)
	v_pk_mul_f32 v[2:3], v[164:165], v[2:3]
	s_waitcnt lgkmcnt(0)
	v_pk_mul_f32 v[50:51], v[164:165], v[50:51]
	v_pk_fma_f32 v[34:35], v[34:35], v[88:89], v[2:3] op_sel_hi:[1,0,1] neg_lo:[0,0,1] neg_hi:[0,0,1]
	v_mov_b32_e32 v2, v36
	v_mov_b32_e32 v3, v20
	v_pk_fma_f32 v[50:51], v[2:3], v[88:89], v[50:51] op_sel_hi:[1,0,1] neg_lo:[0,0,1] neg_hi:[0,0,1]
	ds_read2_b32 v[2:3], v79 offset0:128 offset1:160
	v_mov_b32_e32 v20, v37
	v_pk_mul_f32 v[90:91], v[34:35], v[34:35]
	v_pk_mul_f32 v[88:89], v[50:51], v[50:51]
	v_lshl_add_u64 v[18:19], s[10:11], 0, v[18:19]
	s_waitcnt lgkmcnt(0)
	v_pk_mul_f32 v[2:3], v[164:165], v[2:3]
	v_lshl_add_u64 v[32:33], s[10:11], 0, v[32:33]
	v_pk_fma_f32 v[4:5], v[52:53], v[86:87], v[2:3] op_sel_hi:[1,0,1] neg_lo:[0,0,1] neg_hi:[0,0,1]
	v_lshl_add_u64 v[16:17], s[10:11], 0, v[16:17]
	v_pk_mul_f32 v[52:53], v[4:5], v[4:5]
	v_lshlrev_b32_e32 v36, 16, v73
	v_mul_f32_e32 v2, 0xbfb8aa3b, v36
	v_exp_f32_e32 v73, v2
	ds_read2_b32 v[2:3], v79 offset0:192 offset1:224
	v_add_f32_e32 v37, 1.0, v73
	v_div_scale_f32 v73, s[0:1], v37, v37, v36
	v_rcp_f32_e32 v79, v73
	s_waitcnt lgkmcnt(0)
	v_pk_mul_f32 v[2:3], v[164:165], v[2:3]
	v_lshlrev_b32_e32 v75, 16, v75
	v_pk_fma_f32 v[2:3], v[20:21], v[86:87], v[2:3] op_sel_hi:[1,0,1] neg_lo:[0,0,1] neg_hi:[0,0,1]
	v_fma_f32 v83, -v73, v79, 1.0
	v_mul_f32_e32 v86, 0xbfb8aa3b, v75
	v_fmac_f32_e32 v79, v83, v79
	v_div_scale_f32 v83, vcc, v36, v37, v36
	v_exp_f32_e32 v86, v86
	v_mul_f32_e32 v85, v83, v79
	v_fma_f32 v87, -v73, v85, v83
	v_fmac_f32_e32 v85, v87, v79
	v_fma_f32 v73, -v73, v85, v83
	v_add_f32_e32 v83, 1.0, v86
	v_div_scale_f32 v86, s[0:1], v83, v83, v75
	v_rcp_f32_e32 v87, v86
	v_lshlrev_b32_e32 v77, 16, v77
	v_div_fmas_f32 v73, v73, v79, v85
	v_mul_f32_e32 v79, 0xbfb8aa3b, v77
	v_exp_f32_e32 v79, v79
	v_div_fixup_f32 v73, v73, v37, v36
	v_fma_f32 v36, -v86, v87, 1.0
	v_fmac_f32_e32 v87, v36, v87
	v_div_scale_f32 v36, vcc, v75, v83, v75
	v_mul_f32_e32 v37, v36, v87
	v_fma_f32 v85, -v86, v37, v36
	v_add_f32_e32 v79, 1.0, v79
	v_fmac_f32_e32 v37, v85, v87
	v_div_scale_f32 v85, s[0:1], v79, v79, v77
	v_fma_f32 v36, -v86, v37, v36
	v_rcp_f32_e32 v86, v85
	v_div_fmas_f32 v36, v36, v87, v37
	v_div_fixup_f32 v75, v36, v83, v75
	v_div_scale_f32 v83, vcc, v77, v79, v77
	v_fma_f32 v36, -v85, v86, 1.0
	v_fmac_f32_e32 v86, v36, v86
	v_mul_f32_e32 v87, v83, v86
	v_fma_f32 v36, -v85, v87, v83
	v_pk_mul_f32 v[20:21], v[2:3], v[2:3]
	v_fmac_f32_e32 v87, v36, v86
	v_mov_b32_e32 v36, v52
	v_mov_b32_e32 v37, v90
	v_mov_b32_e32 v90, v53
	v_pk_add_f32 v[36:37], v[36:37], v[90:91]
	v_mov_b32_e32 v52, v20
	v_mov_b32_e32 v53, v88
	v_pk_add_f32 v[36:37], v[36:37], v[52:53]
	v_mov_b32_e32 v88, v21
	v_pk_add_f32 v[20:21], v[36:37], v[88:89]
	ds_bpermute_b32 v37, v216, v21
	ds_bpermute_b32 v36, v216, v20
	v_fma_f32 v52, -v85, v87, v83
	v_div_fmas_f32 v52, v52, v86, v87
	v_lshlrev_b32_e32 v53, 16, v81
	v_div_fixup_f32 v52, v52, v79, v77
	s_waitcnt lgkmcnt(0)
	v_pk_add_f32 v[20:21], v[20:21], v[36:37]
	ds_bpermute_b32 v37, v217, v21
	ds_bpermute_b32 v36, v217, v20
	v_mul_f32_e32 v77, 0xbfb8aa3b, v53
	v_exp_f32_e32 v77, v77
	s_waitcnt lgkmcnt(0)
	v_pk_add_f32 v[20:21], v[20:21], v[36:37]
	ds_bpermute_b32 v37, v218, v21
	ds_bpermute_b32 v36, v218, v20
	v_add_f32_e32 v77, 1.0, v77
	v_div_scale_f32 v79, s[0:1], v77, v77, v53
	v_rcp_f32_e32 v81, v79
	s_waitcnt lgkmcnt(0)
	v_pk_add_f32 v[20:21], v[20:21], v[36:37]
	ds_bpermute_b32 v37, v219, v21
	ds_bpermute_b32 v36, v219, v20
	v_fma_f32 v83, -v79, v81, 1.0
	v_fmac_f32_e32 v81, v83, v81
	v_div_scale_f32 v83, vcc, v53, v77, v53
	s_waitcnt lgkmcnt(0)
	v_pk_add_f32 v[20:21], v[20:21], v[36:37]
	ds_bpermute_b32 v37, v220, v21
	ds_bpermute_b32 v36, v220, v20
	v_mul_f32_e32 v85, v83, v81
	v_fma_f32 v86, -v79, v85, v83
	v_fmac_f32_e32 v85, v86, v81
	v_fma_f32 v79, -v79, v85, v83
	s_waitcnt lgkmcnt(0)
	v_pk_add_f32 v[20:21], v[20:21], v[36:37]
	s_nop 0
	v_pk_fma_f32 v[20:21], v[20:21], s[46:47], v[0:1] op_sel_hi:[1,0,0]
	s_nop 0
	v_mul_f32_e32 v36, 0x4b800000, v21
	v_cmp_gt_f32_e64 s[0:1], s49, v21
	s_nop 1
	v_cndmask_b32_e64 v21, v21, v36, s[0:1]
	v_rsq_f32_e32 v21, v21
	v_div_fmas_f32 v36, v79, v81, v85
	v_div_fixup_f32 v36, v36, v77, v53
	v_cmp_gt_f32_e32 vcc, s49, v20
	v_mul_f32_e32 v37, 0x45800000, v21
	v_cndmask_b32_e64 v21, v21, v37, s[0:1]
	v_mul_f32_e32 v34, v34, v21
	v_mul_f32_e32 v34, v34, v69
	v_mul_f32_e32 v34, v34, v73
	v_cvt_pk_bf16_f32 v34, v34, s0
	global_store_short v[92:93], v34, off
	v_mul_f32_e32 v34, v35, v21
	v_mul_f32_e32 v34, v34, v67
	v_mul_f32_e32 v34, v34, v75
	v_cvt_pk_bf16_f32 v34, v34, s0
	global_store_short v[18:19], v34, off
	v_mul_f32_e32 v18, v50, v21
	v_mul_f32_e32 v18, v18, v49
	v_mul_f32_e32 v18, v18, v52
	v_cvt_pk_bf16_f32 v18, v18, s0
	global_store_short v[32:33], v18, off
	v_mul_f32_e32 v18, v51, v21
	v_mul_f32_e32 v18, v18, v48
	v_mul_f32_e32 v18, v18, v36
	v_cvt_pk_bf16_f32 v18, v18, s0
	global_store_short v[16:17], v18, off
	v_or_b32_e32 v16, 9, v68
	v_ashrrev_i32_e32 v17, 31, v16
	v_lshlrev_b64 v[16:17], 10, v[16:17]
	v_or_b32_e32 v16, v16, v65
	v_lshl_add_u64 v[18:19], s[8:9], 0, v[16:17]
	v_mov_b32_e32 v21, v142
	v_or_b32_e32 v18, 64, v16
	v_mov_b32_e32 v19, v17
	v_lshl_add_u64 v[32:33], s[8:9], 0, v[18:19]
	v_mov_b32_e32 v50, v143
	v_or_b32_e32 v32, 0x80, v16
	v_mov_b32_e32 v33, v17
	v_lshl_add_u64 v[34:35], s[8:9], 0, v[32:33]
	v_mov_b32_e32 v51, v144
	v_lshl_add_u64 v[34:35], s[10:11], 0, v[16:17]
	v_or_b32_e32 v16, 0xc0, v16
	v_lshl_add_u64 v[36:37], s[8:9], 0, v[16:17]
	v_mov_b32_e32 v36, v145
	v_mul_f32_e32 v37, 0x4b800000, v20
	v_cndmask_b32_e32 v20, v20, v37, vcc
	v_rsq_f32_e32 v20, v20
	v_add_u32_e32 v79, 0x1400, v71
	v_mul_f32_e32 v52, 0x45800000, v20
	v_cndmask_b32_e32 v20, v20, v52, vcc
	v_mul_f32_e32 v4, v4, v20
	v_mul_f32_e32 v4, v4, v69
	v_mul_f32_e32 v2, v2, v20
	v_mul_f32_e32 v2, v2, v49
	v_lshlrev_b32_e32 v21, 16, v21
	v_mul_f32_e32 v37, 0xbfb8aa3b, v21
	v_exp_f32_e32 v37, v37
	v_lshlrev_b32_e32 v50, 16, v50
	v_add_f32_e32 v37, 1.0, v37
	v_div_scale_f32 v53, s[0:1], v37, v37, v21
	v_rcp_f32_e32 v73, v53
	s_nop 0
	v_fma_f32 v52, -v53, v73, 1.0
	v_fmac_f32_e32 v73, v52, v73
	v_div_scale_f32 v52, vcc, v21, v37, v21
	v_mul_f32_e32 v75, v52, v73
	v_fma_f32 v77, -v53, v75, v52
	v_fmac_f32_e32 v75, v77, v73
	v_fma_f32 v52, -v53, v75, v52
	v_mul_f32_e32 v53, 0xbfb8aa3b, v50
	v_exp_f32_e32 v53, v53
	v_div_fmas_f32 v52, v52, v73, v75
	v_div_fixup_f32 v21, v52, v37, v21
	v_mul_f32_e32 v4, v4, v21
	v_add_f32_e32 v21, 1.0, v53
	v_cvt_pk_bf16_f32 v4, v4, s0
	v_div_scale_f32 v37, s[0:1], v21, v21, v50
	v_rcp_f32_e32 v52, v37
	global_store_short v[34:35], v4, off
	v_mul_f32_e32 v4, v5, v20
	v_mul_f32_e32 v4, v4, v67
	v_fma_f32 v5, -v37, v52, 1.0
	v_fmac_f32_e32 v52, v5, v52
	v_div_scale_f32 v5, vcc, v50, v21, v50
	v_mul_f32_e32 v34, v5, v52
	v_fma_f32 v35, -v37, v34, v5
	v_fmac_f32_e32 v34, v35, v52
	v_fma_f32 v5, -v37, v34, v5
	v_div_fmas_f32 v5, v5, v52, v34
	v_div_fixup_f32 v5, v5, v21, v50
	v_lshlrev_b32_e32 v21, 16, v51
	v_mul_f32_e32 v34, 0xbfb8aa3b, v21
	v_exp_f32_e32 v34, v34
	v_mul_f32_e32 v4, v4, v5
	v_cvt_pk_bf16_f32 v35, v4, s0
	v_lshl_add_u64 v[4:5], s[10:11], 0, v[18:19]
	v_add_f32_e32 v18, 1.0, v34
	v_div_scale_f32 v19, s[0:1], v18, v18, v21
	v_rcp_f32_e32 v34, v19
	global_store_short v[4:5], v35, off
	v_fma_f32 v4, -v19, v34, 1.0
	v_fmac_f32_e32 v34, v4, v34
	v_div_scale_f32 v4, vcc, v21, v18, v21
	v_mul_f32_e32 v5, v4, v34
	v_fma_f32 v35, -v19, v5, v4
	v_fmac_f32_e32 v5, v35, v34
	v_fma_f32 v4, -v19, v5, v4
	v_div_fmas_f32 v4, v4, v34, v5
	v_div_fixup_f32 v4, v4, v18, v21
	v_lshlrev_b32_e32 v18, 16, v36
	v_mul_f32_e32 v5, 0xbfb8aa3b, v18
	v_exp_f32_e32 v19, v5
	v_mul_f32_e32 v2, v2, v4
	v_cvt_pk_bf16_f32 v2, v2, s0
	v_lshl_add_u64 v[4:5], s[10:11], 0, v[32:33]
	v_add_f32_e32 v19, 1.0, v19
	v_div_scale_f32 v21, s[0:1], v19, v19, v18
	v_rcp_f32_e32 v32, v21
	global_store_short v[4:5], v2, off
	v_mul_f32_e32 v2, v3, v20
	v_mul_f32_e32 v2, v2, v48
	v_fma_f32 v3, -v21, v32, 1.0
	v_fmac_f32_e32 v32, v3, v32
	v_div_scale_f32 v3, vcc, v18, v19, v18
	v_mul_f32_e32 v4, v3, v32
	v_fma_f32 v5, -v21, v4, v3
	v_fmac_f32_e32 v4, v5, v32
	v_fma_f32 v3, -v21, v4, v3
	v_div_fmas_f32 v3, v3, v32, v4
	v_div_fixup_f32 v3, v3, v19, v18
	v_mul_f32_e32 v2, v2, v3
	v_cvt_pk_bf16_f32 v4, v2, s0
	v_lshl_add_u64 v[2:3], s[10:11], 0, v[16:17]
	global_store_short v[2:3], v4, off
	v_or_b32_e32 v2, 10, v68
	v_ashrrev_i32_e32 v3, 31, v2
	v_lshlrev_b64 v[16:17], 10, v[2:3]
	v_or_b32_e32 v16, v16, v65
	v_lshl_add_u64 v[2:3], s[8:9], 0, v[16:17]
	v_mov_b32_e32 v73, v146
	v_or_b32_e32 v18, 64, v16
	v_mov_b32_e32 v19, v17
	v_lshl_add_u64 v[2:3], s[8:9], 0, v[18:19]
	v_mov_b32_e32 v75, v147
	v_or_b32_e32 v20, 0x80, v16
	v_mov_b32_e32 v21, v17
	v_lshl_add_u64 v[2:3], s[8:9], 0, v[20:21]
	v_mov_b32_e32 v77, v148
	ds_read2_b32 v[2:3], v79 offset1:32
	ds_read2_b32 v[32:33], v79 offset0:64 offset1:96
	v_mov_b32_e32 v4, v6
	v_mov_b32_e32 v5, v54
	v_lshl_add_u64 v[52:53], s[10:11], 0, v[16:17]
	s_waitcnt lgkmcnt(1)
	v_pk_mul_f32 v[2:3], v[164:165], v[2:3]
	v_or_b32_e32 v16, 0xc0, v16
	v_pk_fma_f32 v[34:35], v[4:5], v[84:85], v[2:3] op_sel_hi:[1,0,1] neg_lo:[0,0,1] neg_hi:[0,0,1]
	v_mov_b32_e32 v2, v38
	v_mov_b32_e32 v3, v22
	s_waitcnt lgkmcnt(0)
	v_pk_mul_f32 v[4:5], v[164:165], v[32:33]
	v_mov_b32_e32 v54, v7
	v_pk_fma_f32 v[32:33], v[2:3], v[84:85], v[4:5] op_sel_hi:[1,0,1] neg_lo:[0,0,1] neg_hi:[0,0,1]
	v_lshl_add_u64 v[4:5], s[8:9], 0, v[16:17]
	v_mov_b32_e32 v81, v149
	ds_read2_b32 v[2:3], v79 offset0:128 offset1:160
	v_mov_b32_e32 v22, v39
	v_pk_mul_f32 v[36:37], v[34:35], v[34:35]
	v_pk_mul_f32 v[50:51], v[32:33], v[32:33]
	v_lshl_add_u64 v[18:19], s[10:11], 0, v[18:19]
	s_waitcnt lgkmcnt(0)
	v_pk_mul_f32 v[2:3], v[164:165], v[2:3]
	v_lshl_add_u64 v[16:17], s[10:11], 0, v[16:17]
	v_pk_fma_f32 v[4:5], v[54:55], v[82:83], v[2:3] op_sel_hi:[1,0,1] neg_lo:[0,0,1] neg_hi:[0,0,1]
	v_lshl_add_u64 v[20:21], s[10:11], 0, v[20:21]
	v_pk_mul_f32 v[6:7], v[4:5], v[4:5]
	v_lshlrev_b32_e32 v38, 16, v73
	v_mul_f32_e32 v2, 0xbfb8aa3b, v38
	v_exp_f32_e32 v54, v2
	ds_read2_b32 v[2:3], v79 offset0:192 offset1:224
	v_lshlrev_b32_e32 v75, 16, v75
	v_add_f32_e32 v39, 1.0, v54
	v_div_scale_f32 v54, s[0:1], v39, v39, v38
	v_rcp_f32_e32 v55, v54
	s_waitcnt lgkmcnt(0)
	v_pk_mul_f32 v[2:3], v[164:165], v[2:3]
	v_fma_f32 v73, -v54, v55, 1.0
	v_pk_fma_f32 v[2:3], v[22:23], v[82:83], v[2:3] op_sel_hi:[1,0,1] neg_lo:[0,0,1] neg_hi:[0,0,1]
	v_mul_f32_e32 v82, 0xbfb8aa3b, v75
	v_fmac_f32_e32 v55, v73, v55
	v_div_scale_f32 v73, vcc, v38, v39, v38
	v_exp_f32_e32 v82, v82
	v_mul_f32_e32 v79, v73, v55
	v_fma_f32 v83, -v54, v79, v73
	v_fmac_f32_e32 v79, v83, v55
	v_fma_f32 v54, -v54, v79, v73
	v_add_f32_e32 v73, 1.0, v82
	v_div_scale_f32 v82, s[0:1], v73, v73, v75
	v_rcp_f32_e32 v83, v82
	v_div_fmas_f32 v54, v54, v55, v79
	v_lshlrev_b32_e32 v55, 16, v77
	v_mul_f32_e32 v77, 0xbfb8aa3b, v55
	v_exp_f32_e32 v77, v77
	v_div_fixup_f32 v54, v54, v39, v38
	v_fma_f32 v38, -v82, v83, 1.0
	v_fmac_f32_e32 v83, v38, v83
	v_div_scale_f32 v38, vcc, v75, v73, v75
	v_mul_f32_e32 v39, v38, v83
	v_fma_f32 v79, -v82, v39, v38
	v_add_f32_e32 v77, 1.0, v77
	v_fmac_f32_e32 v39, v79, v83
	v_div_scale_f32 v79, s[0:1], v77, v77, v55
	v_fma_f32 v38, -v82, v39, v38
	v_rcp_f32_e32 v82, v79
	v_div_fmas_f32 v38, v38, v83, v39
	v_div_fixup_f32 v73, v38, v73, v75
	v_div_scale_f32 v75, vcc, v55, v77, v55
	v_fma_f32 v38, -v79, v82, 1.0
	v_fmac_f32_e32 v82, v38, v82
	v_mul_f32_e32 v83, v75, v82
	v_fma_f32 v38, -v79, v83, v75
	v_pk_mul_f32 v[22:23], v[2:3], v[2:3]
	v_fmac_f32_e32 v83, v38, v82
	v_mov_b32_e32 v38, v6
	v_mov_b32_e32 v39, v36
	v_mov_b32_e32 v36, v7
	v_pk_add_f32 v[6:7], v[38:39], v[36:37]
	v_mov_b32_e32 v36, v22
	v_mov_b32_e32 v37, v50
	v_pk_add_f32 v[6:7], v[6:7], v[36:37]
	v_mov_b32_e32 v50, v23
	v_pk_add_f32 v[6:7], v[6:7], v[50:51]
	ds_bpermute_b32 v23, v216, v7
	ds_bpermute_b32 v22, v216, v6
	v_lshlrev_b32_e32 v37, 16, v81
	v_mul_f32_e32 v38, 0xbfb8aa3b, v37
	v_exp_f32_e32 v38, v38
	v_fma_f32 v36, -v79, v83, v75
	s_waitcnt lgkmcnt(0)
	v_pk_add_f32 v[6:7], v[6:7], v[22:23]
	ds_bpermute_b32 v23, v217, v7
	ds_bpermute_b32 v22, v217, v6
	v_add_f32_e32 v38, 1.0, v38
	v_div_scale_f32 v39, s[0:1], v38, v38, v37
	v_rcp_f32_e32 v50, v39
	s_waitcnt lgkmcnt(0)
	v_pk_add_f32 v[6:7], v[6:7], v[22:23]
	ds_bpermute_b32 v23, v218, v7
	ds_bpermute_b32 v22, v218, v6
	v_fma_f32 v51, -v39, v50, 1.0
	v_div_fmas_f32 v36, v36, v82, v83
	v_fmac_f32_e32 v50, v51, v50
	v_div_scale_f32 v51, vcc, v37, v38, v37
	s_waitcnt lgkmcnt(0)
	v_pk_add_f32 v[6:7], v[6:7], v[22:23]
	ds_bpermute_b32 v23, v219, v7
	ds_bpermute_b32 v22, v219, v6
	v_div_fixup_f32 v36, v36, v77, v55
	v_mul_f32_e32 v55, v51, v50
	v_fma_f32 v75, -v39, v55, v51
	v_fmac_f32_e32 v55, v75, v50
	s_waitcnt lgkmcnt(0)
	v_pk_add_f32 v[6:7], v[6:7], v[22:23]
	ds_bpermute_b32 v23, v220, v7
	ds_bpermute_b32 v22, v220, v6
	v_fma_f32 v39, -v39, v55, v51
	v_add_u32_e32 v51, 0x2000, v71
	s_waitcnt lgkmcnt(0)
	v_pk_add_f32 v[6:7], v[6:7], v[22:23]
	s_nop 0
	v_pk_fma_f32 v[6:7], v[6:7], s[46:47], v[0:1] op_sel_hi:[1,0,0]
	s_nop 0
	v_mul_f32_e32 v22, 0x4b800000, v7
	v_cmp_gt_f32_e64 s[0:1], s49, v7
	s_nop 1
	v_cndmask_b32_e64 v7, v7, v22, s[0:1]
	v_rsq_f32_e32 v7, v7
	v_div_fmas_f32 v22, v39, v50, v55
	v_div_fixup_f32 v22, v22, v38, v37
	v_cmp_gt_f32_e32 vcc, s49, v6
	v_mul_f32_e32 v23, 0x45800000, v7
	v_cndmask_b32_e64 v7, v7, v23, s[0:1]
	v_mul_f32_e32 v23, v34, v7
	v_mul_f32_e32 v23, v23, v69
	v_mul_f32_e32 v23, v23, v54
	v_cvt_pk_bf16_f32 v23, v23, s0
	global_store_short v[52:53], v23, off
	v_mul_f32_e32 v23, v35, v7
	v_mul_f32_e32 v23, v23, v67
	v_mul_f32_e32 v23, v23, v73
	v_cvt_pk_bf16_f32 v23, v23, s0
	global_store_short v[18:19], v23, off
	v_mul_f32_e32 v18, v32, v7
	v_mul_f32_e32 v7, v33, v7
	v_mul_f32_e32 v7, v7, v48
	v_mul_f32_e32 v7, v7, v22
	v_cvt_pk_bf16_f32 v7, v7, s0
	global_store_short v[16:17], v7, off
	v_or_b32_e32 v16, 11, v68
	v_mul_f32_e32 v18, v18, v49
	v_ashrrev_i32_e32 v17, 31, v16
	v_mul_f32_e32 v18, v18, v36
	v_lshlrev_b64 v[16:17], 10, v[16:17]
	v_cvt_pk_bf16_f32 v18, v18, s0
	v_or_b32_e32 v16, v16, v65
	global_store_short v[20:21], v18, off
	v_lshl_add_u64 v[18:19], s[8:9], 0, v[16:17]
	v_mov_b32_e32 v7, v150
	v_or_b32_e32 v18, 64, v16
	v_mov_b32_e32 v19, v17
	v_lshl_add_u64 v[20:21], s[8:9], 0, v[18:19]
	v_mov_b32_e32 v34, v151
	v_or_b32_e32 v20, 0x80, v16
	v_mov_b32_e32 v21, v17
	v_lshl_add_u64 v[22:23], s[8:9], 0, v[20:21]
	v_mov_b32_e32 v35, v152
	v_lshl_add_u64 v[22:23], s[10:11], 0, v[16:17]
	v_or_b32_e32 v16, 0xc0, v16
	v_lshl_add_u64 v[32:33], s[8:9], 0, v[16:17]
	v_mov_b32_e32 v32, v153
	v_mul_f32_e32 v33, 0x4b800000, v6
	v_cndmask_b32_e32 v6, v6, v33, vcc
	v_rsq_f32_e32 v6, v6
	v_lshlrev_b32_e32 v7, 16, v7
	v_mul_f32_e32 v33, 0xbfb8aa3b, v7
	v_exp_f32_e32 v33, v33
	v_mul_f32_e32 v36, 0x45800000, v6
	v_cndmask_b32_e32 v6, v6, v36, vcc
	v_lshlrev_b32_e32 v34, 16, v34
	v_add_f32_e32 v33, 1.0, v33
	v_div_scale_f32 v37, s[0:1], v33, v33, v7
	v_rcp_f32_e32 v38, v37
	v_mul_f32_e32 v4, v4, v6
	v_mul_f32_e32 v4, v4, v69
	v_mul_f32_e32 v2, v2, v6
	v_fma_f32 v36, -v37, v38, 1.0
	v_fmac_f32_e32 v38, v36, v38
	v_div_scale_f32 v36, vcc, v7, v33, v7
	v_mul_f32_e32 v39, v36, v38
	v_fma_f32 v50, -v37, v39, v36
	v_fmac_f32_e32 v39, v50, v38
	v_fma_f32 v36, -v37, v39, v36
	v_mul_f32_e32 v37, 0xbfb8aa3b, v34
	v_exp_f32_e32 v37, v37
	v_div_fmas_f32 v36, v36, v38, v39
	v_div_fixup_f32 v7, v36, v33, v7
	v_mul_f32_e32 v4, v4, v7
	v_add_f32_e32 v7, 1.0, v37
	v_cvt_pk_bf16_f32 v4, v4, s0
	v_div_scale_f32 v33, s[0:1], v7, v7, v34
	v_rcp_f32_e32 v36, v33
	global_store_short v[22:23], v4, off
	v_mul_f32_e32 v4, v5, v6
	v_mul_f32_e32 v4, v4, v67
	v_fma_f32 v5, -v33, v36, 1.0
	v_fmac_f32_e32 v36, v5, v36
	v_div_scale_f32 v5, vcc, v34, v7, v34
	v_mul_f32_e32 v22, v5, v36
	v_fma_f32 v23, -v33, v22, v5
	v_fmac_f32_e32 v22, v23, v36
	v_fma_f32 v5, -v33, v22, v5
	v_div_fmas_f32 v5, v5, v36, v22
	v_div_fixup_f32 v5, v5, v7, v34
	v_lshlrev_b32_e32 v7, 16, v35
	v_mul_f32_e32 v22, 0xbfb8aa3b, v7
	v_exp_f32_e32 v22, v22
	v_mul_f32_e32 v4, v4, v5
	v_cvt_pk_bf16_f32 v23, v4, s0
	v_lshl_add_u64 v[4:5], s[10:11], 0, v[18:19]
	v_add_f32_e32 v18, 1.0, v22
	v_div_scale_f32 v19, s[0:1], v18, v18, v7
	v_rcp_f32_e32 v22, v19
	global_store_short v[4:5], v23, off
	v_mul_f32_e32 v2, v2, v49
	v_fma_f32 v4, -v19, v22, 1.0
	v_fmac_f32_e32 v22, v4, v22
	v_div_scale_f32 v4, vcc, v7, v18, v7
	v_mul_f32_e32 v5, v4, v22
	v_fma_f32 v23, -v19, v5, v4
	v_fmac_f32_e32 v5, v23, v22
	v_fma_f32 v4, -v19, v5, v4
	v_div_fmas_f32 v4, v4, v22, v5
	v_div_fixup_f32 v4, v4, v18, v7
	v_lshlrev_b32_e32 v7, 16, v32
	v_mul_f32_e32 v5, 0xbfb8aa3b, v7
	v_exp_f32_e32 v18, v5
	v_mul_f32_e32 v2, v2, v4
	v_cvt_pk_bf16_f32 v2, v2, s0
	v_lshl_add_u64 v[4:5], s[10:11], 0, v[20:21]
	v_add_f32_e32 v18, 1.0, v18
	v_div_scale_f32 v19, s[0:1], v18, v18, v7
	v_rcp_f32_e32 v20, v19
	global_store_short v[4:5], v2, off
	v_mul_f32_e32 v2, v3, v6
	v_mul_f32_e32 v2, v2, v48
	v_fma_f32 v3, -v19, v20, 1.0
	v_fmac_f32_e32 v20, v3, v20
	v_div_scale_f32 v3, vcc, v7, v18, v7
	v_mul_f32_e32 v4, v3, v20
	v_fma_f32 v5, -v19, v4, v3
	v_fmac_f32_e32 v4, v5, v20
	v_fma_f32 v3, -v19, v4, v3
	v_div_fmas_f32 v3, v3, v20, v4
	v_div_fixup_f32 v3, v3, v18, v7
	v_mul_f32_e32 v2, v2, v3
	v_cvt_pk_bf16_f32 v4, v2, s0
	v_lshl_add_u64 v[2:3], s[10:11], 0, v[16:17]
	global_store_short v[2:3], v4, off
	v_or_b32_e32 v2, 16, v68
	v_ashrrev_i32_e32 v3, 31, v2
	v_lshlrev_b64 v[6:7], 10, v[2:3]
	v_or_b32_e32 v6, v6, v65
	v_lshl_add_u64 v[2:3], s[8:9], 0, v[6:7]
	v_mov_b32_e32 v38, v154
	v_or_b32_e32 v16, 64, v6
	v_mov_b32_e32 v17, v7
	v_lshl_add_u64 v[2:3], s[8:9], 0, v[16:17]
	v_mov_b32_e32 v39, v155
	v_or_b32_e32 v18, 0x80, v6
	v_mov_b32_e32 v19, v7
	v_lshl_add_u64 v[2:3], s[8:9], 0, v[18:19]
	v_mov_b32_e32 v50, v156
	ds_read2_b32 v[2:3], v51 offset1:32
	ds_read2_b32 v[20:21], v51 offset0:64 offset1:96
	v_mov_b32_e32 v4, v8
	v_mov_b32_e32 v5, v56
	v_lshl_add_u64 v[36:37], s[10:11], 0, v[6:7]
	s_waitcnt lgkmcnt(1)
	v_pk_mul_f32 v[2:3], v[164:165], v[2:3]
	v_or_b32_e32 v6, 0xc0, v6
	v_pk_fma_f32 v[22:23], v[4:5], v[80:81], v[2:3] op_sel_hi:[1,0,1] neg_lo:[0,0,1] neg_hi:[0,0,1]
	v_mov_b32_e32 v2, v40
	v_mov_b32_e32 v3, v24
	s_waitcnt lgkmcnt(0)
	v_pk_mul_f32 v[4:5], v[164:165], v[20:21]
	v_mov_b32_e32 v56, v9
	v_pk_fma_f32 v[20:21], v[2:3], v[80:81], v[4:5] op_sel_hi:[1,0,1] neg_lo:[0,0,1] neg_hi:[0,0,1]
	v_lshl_add_u64 v[4:5], s[8:9], 0, v[6:7]
	v_mov_b32_e32 v40, v157
	ds_read2_b32 v[2:3], v51 offset0:128 offset1:160
	v_mov_b32_e32 v24, v41
	v_pk_mul_f32 v[32:33], v[22:23], v[22:23]
	v_pk_mul_f32 v[34:35], v[20:21], v[20:21]
	v_lshl_add_u64 v[16:17], s[10:11], 0, v[16:17]
	s_waitcnt lgkmcnt(0)
	v_pk_mul_f32 v[2:3], v[164:165], v[2:3]
	v_lshl_add_u64 v[6:7], s[10:11], 0, v[6:7]
	v_pk_fma_f32 v[4:5], v[56:57], v[78:79], v[2:3] op_sel_hi:[1,0,1] neg_lo:[0,0,1] neg_hi:[0,0,1]
	v_lshl_add_u64 v[18:19], s[10:11], 0, v[18:19]
	v_pk_mul_f32 v[8:9], v[4:5], v[4:5]
	v_lshlrev_b32_e32 v38, 16, v38
	v_mul_f32_e32 v2, 0xbfb8aa3b, v38
	v_exp_f32_e32 v52, v2
	ds_read2_b32 v[2:3], v51 offset0:192 offset1:224
	v_lshlrev_b32_e32 v39, 16, v39
	v_mul_f32_e32 v55, 0xbfb8aa3b, v39
	v_add_f32_e32 v41, 1.0, v52
	v_div_scale_f32 v51, s[0:1], v41, v41, v38
	v_rcp_f32_e32 v52, v51
	v_exp_f32_e32 v55, v55
	v_lshlrev_b32_e32 v50, 16, v50
	s_waitcnt lgkmcnt(0)
	v_pk_mul_f32 v[2:3], v[164:165], v[2:3]
	v_fma_f32 v53, -v51, v52, 1.0
	v_fmac_f32_e32 v52, v53, v52
	v_div_scale_f32 v53, vcc, v38, v41, v38
	v_mul_f32_e32 v54, v53, v52
	v_fma_f32 v56, -v51, v54, v53
	v_fmac_f32_e32 v54, v56, v52
	v_fma_f32 v51, -v51, v54, v53
	v_add_f32_e32 v53, 1.0, v55
	v_div_scale_f32 v55, s[0:1], v53, v53, v39
	v_rcp_f32_e32 v56, v55
	v_div_fmas_f32 v51, v51, v52, v54
	v_mul_f32_e32 v52, 0xbfb8aa3b, v50
	v_exp_f32_e32 v52, v52
	v_div_fixup_f32 v41, v51, v41, v38
	v_fma_f32 v38, -v55, v56, 1.0
	v_fmac_f32_e32 v56, v38, v56
	v_div_scale_f32 v38, vcc, v39, v53, v39
	v_mul_f32_e32 v51, v38, v56
	v_fma_f32 v54, -v55, v51, v38
	v_add_f32_e32 v52, 1.0, v52
	v_fmac_f32_e32 v51, v54, v56
	v_div_scale_f32 v54, s[0:1], v52, v52, v50
	v_fma_f32 v38, -v55, v51, v38
	v_rcp_f32_e32 v55, v54
	v_div_fmas_f32 v38, v38, v56, v51
	v_div_fixup_f32 v51, v38, v53, v39
	v_div_scale_f32 v53, vcc, v50, v52, v50
	v_fma_f32 v38, -v54, v55, 1.0
	v_fmac_f32_e32 v55, v38, v55
	v_mul_f32_e32 v56, v53, v55
	v_pk_fma_f32 v[2:3], v[24:25], v[78:79], v[2:3] op_sel_hi:[1,0,1] neg_lo:[0,0,1] neg_hi:[0,0,1]
	v_fma_f32 v38, -v54, v56, v53
	v_pk_mul_f32 v[24:25], v[2:3], v[2:3]
	v_fmac_f32_e32 v56, v38, v55
	v_mov_b32_e32 v38, v8
	v_mov_b32_e32 v39, v32
	v_mov_b32_e32 v32, v9
	v_pk_add_f32 v[8:9], v[38:39], v[32:33]
	v_mov_b32_e32 v32, v24
	v_mov_b32_e32 v33, v34
	v_pk_add_f32 v[8:9], v[8:9], v[32:33]
	v_mov_b32_e32 v34, v25
	v_pk_add_f32 v[8:9], v[8:9], v[34:35]
	ds_bpermute_b32 v25, v216, v9
	ds_bpermute_b32 v24, v216, v8
	v_lshlrev_b32_e32 v33, 16, v40
	v_mul_f32_e32 v34, 0xbfb8aa3b, v33
	v_exp_f32_e32 v34, v34
	v_fma_f32 v32, -v54, v56, v53
	s_waitcnt lgkmcnt(0)
	v_pk_add_f32 v[8:9], v[8:9], v[24:25]
	ds_bpermute_b32 v25, v217, v9
	ds_bpermute_b32 v24, v217, v8
	v_add_f32_e32 v34, 1.0, v34
	v_div_scale_f32 v35, s[0:1], v34, v34, v33
	v_rcp_f32_e32 v38, v35
	s_waitcnt lgkmcnt(0)
	v_pk_add_f32 v[8:9], v[8:9], v[24:25]
	ds_bpermute_b32 v25, v218, v9
	ds_bpermute_b32 v24, v218, v8
	v_fma_f32 v39, -v35, v38, 1.0
	v_div_fmas_f32 v32, v32, v55, v56
	v_fmac_f32_e32 v38, v39, v38
	v_div_scale_f32 v39, vcc, v33, v34, v33
	s_waitcnt lgkmcnt(0)
	v_pk_add_f32 v[8:9], v[8:9], v[24:25]
	ds_bpermute_b32 v25, v219, v9
	ds_bpermute_b32 v24, v219, v8
	v_mul_f32_e32 v40, v39, v38
	v_div_fixup_f32 v32, v32, v52, v50
	v_fma_f32 v50, -v35, v40, v39
	v_fmac_f32_e32 v40, v50, v38
	s_waitcnt lgkmcnt(0)
	v_pk_add_f32 v[8:9], v[8:9], v[24:25]
	ds_bpermute_b32 v25, v220, v9
	ds_bpermute_b32 v24, v220, v8
	v_fma_f32 v35, -v35, v40, v39
	s_waitcnt lgkmcnt(0)
	v_pk_add_f32 v[8:9], v[8:9], v[24:25]
	s_nop 0
	v_pk_fma_f32 v[8:9], v[8:9], s[46:47], v[0:1] op_sel_hi:[1,0,0]
	s_nop 0
	v_mul_f32_e32 v24, 0x4b800000, v9
	v_cmp_gt_f32_e64 s[0:1], s49, v9
	s_nop 1
	v_cndmask_b32_e64 v9, v9, v24, s[0:1]
	v_rsq_f32_e32 v9, v9
	v_div_fmas_f32 v24, v35, v38, v40
	v_div_fixup_f32 v24, v24, v34, v33
	v_cmp_gt_f32_e32 vcc, s49, v8
	v_mul_f32_e32 v25, 0x45800000, v9
	v_cndmask_b32_e64 v9, v9, v25, s[0:1]
	v_mul_f32_e32 v22, v22, v9
	v_mul_f32_e32 v22, v22, v69
	v_mul_f32_e32 v22, v22, v41
	v_cvt_pk_bf16_f32 v22, v22, s0
	global_store_short v[36:37], v22, off
	v_mul_f32_e32 v22, v23, v9
	v_mul_f32_e32 v22, v22, v67
	v_mul_f32_e32 v22, v22, v51
	v_cvt_pk_bf16_f32 v22, v22, s0
	global_store_short v[16:17], v22, off
	v_mul_f32_e32 v16, v20, v9
	v_mul_f32_e32 v9, v21, v9
	v_mul_f32_e32 v9, v9, v48
	v_mul_f32_e32 v9, v9, v24
	v_cvt_pk_bf16_f32 v9, v9, s0
	global_store_short v[6:7], v9, off
	v_or_b32_e32 v6, 17, v68
	v_mul_f32_e32 v16, v16, v49
	v_ashrrev_i32_e32 v7, 31, v6
	v_mul_f32_e32 v16, v16, v32
	v_lshlrev_b64 v[6:7], 10, v[6:7]
	v_cvt_pk_bf16_f32 v16, v16, s0
	v_or_b32_e32 v6, v6, v65
	global_store_short v[18:19], v16, off
	v_lshl_add_u64 v[16:17], s[8:9], 0, v[6:7]
	v_mov_b32_e32 v9, v158
	v_or_b32_e32 v16, 64, v6
	v_mov_b32_e32 v17, v7
	v_lshl_add_u64 v[18:19], s[8:9], 0, v[16:17]
	v_mov_b32_e32 v24, v159
	v_or_b32_e32 v18, 0x80, v6
	v_mov_b32_e32 v19, v7
	v_lshl_add_u64 v[20:21], s[8:9], 0, v[18:19]
	v_mov_b32_e32 v25, v178
	v_lshl_add_u64 v[20:21], s[10:11], 0, v[6:7]
	v_or_b32_e32 v6, 0xc0, v6
	v_lshl_add_u64 v[22:23], s[8:9], 0, v[6:7]
	v_mov_b32_e32 v22, v179
	v_mul_f32_e32 v23, 0x4b800000, v8
	v_cndmask_b32_e32 v8, v8, v23, vcc
	v_rsq_f32_e32 v8, v8
	v_add_u32_e32 v37, 0x2400, v71
	v_mul_f32_e32 v32, 0x45800000, v8
	v_cndmask_b32_e32 v8, v8, v32, vcc
	v_mul_f32_e32 v4, v4, v8
	v_mul_f32_e32 v4, v4, v69
	v_mul_f32_e32 v2, v2, v8
	v_mul_f32_e32 v2, v2, v49
	v_lshlrev_b32_e32 v9, 16, v9
	v_mul_f32_e32 v23, 0xbfb8aa3b, v9
	v_exp_f32_e32 v23, v23
	v_lshlrev_b32_e32 v24, 16, v24
	v_add_f32_e32 v23, 1.0, v23
	v_div_scale_f32 v33, s[0:1], v23, v23, v9
	v_rcp_f32_e32 v34, v33
	s_nop 0
	v_fma_f32 v32, -v33, v34, 1.0
	v_fmac_f32_e32 v34, v32, v34
	v_div_scale_f32 v32, vcc, v9, v23, v9
	v_mul_f32_e32 v35, v32, v34
	v_fma_f32 v36, -v33, v35, v32
	v_fmac_f32_e32 v35, v36, v34
	v_fma_f32 v32, -v33, v35, v32
	v_mul_f32_e32 v33, 0xbfb8aa3b, v24
	v_exp_f32_e32 v33, v33
	v_div_fmas_f32 v32, v32, v34, v35
	v_div_fixup_f32 v9, v32, v23, v9
	v_mul_f32_e32 v4, v4, v9
	v_add_f32_e32 v9, 1.0, v33
	v_cvt_pk_bf16_f32 v4, v4, s0
	v_div_scale_f32 v23, s[0:1], v9, v9, v24
	v_rcp_f32_e32 v32, v23
	global_store_short v[20:21], v4, off
	v_mul_f32_e32 v4, v5, v8
	v_mul_f32_e32 v4, v4, v67
	v_fma_f32 v5, -v23, v32, 1.0
	v_fmac_f32_e32 v32, v5, v32
	v_div_scale_f32 v5, vcc, v24, v9, v24
	v_mul_f32_e32 v20, v5, v32
	v_fma_f32 v21, -v23, v20, v5
	v_fmac_f32_e32 v20, v21, v32
	v_fma_f32 v5, -v23, v20, v5
	v_div_fmas_f32 v5, v5, v32, v20
	v_div_fixup_f32 v5, v5, v9, v24
	v_lshlrev_b32_e32 v9, 16, v25
	v_mul_f32_e32 v20, 0xbfb8aa3b, v9
	v_exp_f32_e32 v20, v20
	v_mul_f32_e32 v4, v4, v5
	v_cvt_pk_bf16_f32 v21, v4, s0
	v_lshl_add_u64 v[4:5], s[10:11], 0, v[16:17]
	v_add_f32_e32 v16, 1.0, v20
	v_div_scale_f32 v17, s[0:1], v16, v16, v9
	v_rcp_f32_e32 v20, v17
	global_store_short v[4:5], v21, off
	v_fma_f32 v4, -v17, v20, 1.0
	v_fmac_f32_e32 v20, v4, v20
	v_div_scale_f32 v4, vcc, v9, v16, v9
	v_mul_f32_e32 v5, v4, v20
	v_fma_f32 v21, -v17, v5, v4
	v_fmac_f32_e32 v5, v21, v20
	v_fma_f32 v4, -v17, v5, v4
	v_div_fmas_f32 v4, v4, v20, v5
	v_div_fixup_f32 v4, v4, v16, v9
	v_lshlrev_b32_e32 v9, 16, v22
	v_mul_f32_e32 v5, 0xbfb8aa3b, v9
	v_exp_f32_e32 v16, v5
	v_mul_f32_e32 v2, v2, v4
	v_cvt_pk_bf16_f32 v2, v2, s0
	v_lshl_add_u64 v[4:5], s[10:11], 0, v[18:19]
	v_add_f32_e32 v16, 1.0, v16
	v_div_scale_f32 v17, s[0:1], v16, v16, v9
	v_rcp_f32_e32 v18, v17
	global_store_short v[4:5], v2, off
	v_mul_f32_e32 v2, v3, v8
	v_mul_f32_e32 v2, v2, v48
	v_fma_f32 v3, -v17, v18, 1.0
	v_fmac_f32_e32 v18, v3, v18
	v_div_scale_f32 v3, vcc, v9, v16, v9
	v_mul_f32_e32 v4, v3, v18
	v_fma_f32 v5, -v17, v4, v3
	v_fmac_f32_e32 v4, v5, v18
	v_fma_f32 v3, -v17, v4, v3
	v_div_fmas_f32 v3, v3, v18, v4
	v_div_fixup_f32 v3, v3, v16, v9
	v_mul_f32_e32 v2, v2, v3
	v_cvt_pk_bf16_f32 v4, v2, s0
	v_lshl_add_u64 v[2:3], s[10:11], 0, v[6:7]
	global_store_short v[2:3], v4, off
	v_or_b32_e32 v2, 18, v68
	v_ashrrev_i32_e32 v3, 31, v2
	v_lshlrev_b64 v[6:7], 10, v[2:3]
	v_or_b32_e32 v6, v6, v65
	v_lshl_add_u64 v[2:3], s[8:9], 0, v[6:7]
	v_mov_b32_e32 v34, v180
	v_or_b32_e32 v8, 64, v6
	v_mov_b32_e32 v9, v7
	v_lshl_add_u64 v[2:3], s[8:9], 0, v[8:9]
	v_mov_b32_e32 v35, v181
	v_or_b32_e32 v16, 0x80, v6
	v_mov_b32_e32 v17, v7
	v_lshl_add_u64 v[2:3], s[8:9], 0, v[16:17]
	v_mov_b32_e32 v36, v182
	ds_read2_b32 v[2:3], v37 offset1:32
	ds_read2_b32 v[18:19], v37 offset0:64 offset1:96
	v_mov_b32_e32 v4, v10
	v_mov_b32_e32 v5, v58
	v_lshl_add_u64 v[32:33], s[10:11], 0, v[6:7]
	s_waitcnt lgkmcnt(1)
	v_pk_mul_f32 v[2:3], v[164:165], v[2:3]
	v_or_b32_e32 v6, 0xc0, v6
	v_pk_fma_f32 v[20:21], v[4:5], v[76:77], v[2:3] op_sel_hi:[1,0,1] neg_lo:[0,0,1] neg_hi:[0,0,1]
	v_mov_b32_e32 v2, v42
	v_mov_b32_e32 v3, v26
	s_waitcnt lgkmcnt(0)
	v_pk_mul_f32 v[4:5], v[164:165], v[18:19]
	v_mov_b32_e32 v58, v11
	v_pk_fma_f32 v[18:19], v[2:3], v[76:77], v[4:5] op_sel_hi:[1,0,1] neg_lo:[0,0,1] neg_hi:[0,0,1]
	v_lshl_add_u64 v[4:5], s[8:9], 0, v[6:7]
	v_mov_b32_e32 v38, v183
	ds_read2_b32 v[2:3], v37 offset0:128 offset1:160
	v_mov_b32_e32 v26, v43
	v_pk_mul_f32 v[22:23], v[20:21], v[20:21]
	v_pk_mul_f32 v[24:25], v[18:19], v[18:19]
	v_lshl_add_u64 v[8:9], s[10:11], 0, v[8:9]
	s_waitcnt lgkmcnt(0)
	v_pk_mul_f32 v[2:3], v[164:165], v[2:3]
	v_lshl_add_u64 v[16:17], s[10:11], 0, v[16:17]
	v_pk_fma_f32 v[4:5], v[58:59], v[74:75], v[2:3] op_sel_hi:[1,0,1] neg_lo:[0,0,1] neg_hi:[0,0,1]
	v_lshl_add_u64 v[6:7], s[10:11], 0, v[6:7]
	v_pk_mul_f32 v[10:11], v[4:5], v[4:5]
	v_lshlrev_b32_e32 v34, 16, v34
	v_mul_f32_e32 v2, 0xbfb8aa3b, v34
	v_exp_f32_e32 v39, v2
	ds_read2_b32 v[2:3], v37 offset0:192 offset1:224
	v_lshlrev_b32_e32 v35, 16, v35
	v_mul_f32_e32 v43, 0xbfb8aa3b, v35
	v_add_f32_e32 v37, 1.0, v39
	v_div_scale_f32 v39, s[0:1], v37, v37, v34
	v_rcp_f32_e32 v40, v39
	v_exp_f32_e32 v43, v43
	v_lshlrev_b32_e32 v36, 16, v36
	s_waitcnt lgkmcnt(0)
	v_pk_mul_f32 v[2:3], v[164:165], v[2:3]
	v_fma_f32 v41, -v39, v40, 1.0
	v_fmac_f32_e32 v40, v41, v40
	v_div_scale_f32 v41, vcc, v34, v37, v34
	v_mul_f32_e32 v42, v41, v40
	v_fma_f32 v50, -v39, v42, v41
	v_fmac_f32_e32 v42, v50, v40
	v_fma_f32 v39, -v39, v42, v41
	v_add_f32_e32 v41, 1.0, v43
	v_div_scale_f32 v43, s[0:1], v41, v41, v35
	v_rcp_f32_e32 v50, v43
	v_div_fmas_f32 v39, v39, v40, v42
	v_mul_f32_e32 v40, 0xbfb8aa3b, v36
	v_exp_f32_e32 v40, v40
	v_div_fixup_f32 v37, v39, v37, v34
	v_fma_f32 v34, -v43, v50, 1.0
	v_fmac_f32_e32 v50, v34, v50
	v_div_scale_f32 v34, vcc, v35, v41, v35
	v_mul_f32_e32 v39, v34, v50
	v_fma_f32 v42, -v43, v39, v34
	v_add_f32_e32 v40, 1.0, v40
	v_fmac_f32_e32 v39, v42, v50
	v_div_scale_f32 v42, s[0:1], v40, v40, v36
	v_fma_f32 v34, -v43, v39, v34
	v_rcp_f32_e32 v43, v42
	v_div_fmas_f32 v34, v34, v50, v39
	v_div_fixup_f32 v39, v34, v41, v35
	v_div_scale_f32 v41, vcc, v36, v40, v36
	v_fma_f32 v34, -v42, v43, 1.0
	v_fmac_f32_e32 v43, v34, v43
	v_mul_f32_e32 v50, v41, v43
	v_pk_fma_f32 v[2:3], v[26:27], v[74:75], v[2:3] op_sel_hi:[1,0,1] neg_lo:[0,0,1] neg_hi:[0,0,1]
	v_fma_f32 v34, -v42, v50, v41
	v_pk_mul_f32 v[26:27], v[2:3], v[2:3]
	v_fmac_f32_e32 v50, v34, v43
	v_mov_b32_e32 v34, v10
	v_mov_b32_e32 v35, v22
	v_mov_b32_e32 v22, v11
	v_pk_add_f32 v[10:11], v[34:35], v[22:23]
	v_mov_b32_e32 v22, v26
	v_mov_b32_e32 v23, v24
	v_pk_add_f32 v[10:11], v[10:11], v[22:23]
	v_mov_b32_e32 v24, v27
	v_pk_add_f32 v[10:11], v[10:11], v[24:25]
	ds_bpermute_b32 v23, v216, v11
	ds_bpermute_b32 v22, v216, v10
	v_lshlrev_b32_e32 v25, 16, v38
	v_mul_f32_e32 v26, 0xbfb8aa3b, v25
	v_exp_f32_e32 v26, v26
	v_fma_f32 v24, -v42, v50, v41
	s_waitcnt lgkmcnt(0)
	v_pk_add_f32 v[10:11], v[10:11], v[22:23]
	ds_bpermute_b32 v23, v217, v11
	ds_bpermute_b32 v22, v217, v10
	v_add_f32_e32 v26, 1.0, v26
	v_div_scale_f32 v27, s[0:1], v26, v26, v25
	v_rcp_f32_e32 v34, v27
	s_waitcnt lgkmcnt(0)
	v_pk_add_f32 v[10:11], v[10:11], v[22:23]
	ds_bpermute_b32 v23, v218, v11
	ds_bpermute_b32 v22, v218, v10
	v_fma_f32 v35, -v27, v34, 1.0
	v_div_fmas_f32 v24, v24, v43, v50
	v_fmac_f32_e32 v34, v35, v34
	v_div_scale_f32 v35, vcc, v25, v26, v25
	s_waitcnt lgkmcnt(0)
	v_pk_add_f32 v[10:11], v[10:11], v[22:23]
	ds_bpermute_b32 v23, v219, v11
	ds_bpermute_b32 v22, v219, v10
	v_div_fixup_f32 v24, v24, v40, v36
	v_mul_f32_e32 v36, v35, v34
	v_fma_f32 v38, -v27, v36, v35
	v_fmac_f32_e32 v36, v38, v34
	s_waitcnt lgkmcnt(0)
	v_pk_add_f32 v[10:11], v[10:11], v[22:23]
	ds_bpermute_b32 v23, v220, v11
	ds_bpermute_b32 v22, v220, v10
	v_fma_f32 v27, -v27, v36, v35
	s_waitcnt lgkmcnt(0)
	v_pk_add_f32 v[10:11], v[10:11], v[22:23]
	s_nop 0
	v_pk_fma_f32 v[10:11], v[10:11], s[46:47], v[0:1] op_sel_hi:[1,0,0]
	s_nop 0
	v_mul_f32_e32 v22, 0x4b800000, v11
	v_cmp_gt_f32_e64 s[0:1], s49, v11
	s_nop 1
	v_cndmask_b32_e64 v11, v11, v22, s[0:1]
	v_rsq_f32_e32 v11, v11
	v_div_fmas_f32 v22, v27, v34, v36
	v_div_fixup_f32 v22, v22, v26, v25
	v_cmp_gt_f32_e32 vcc, s49, v10
	v_mul_f32_e32 v23, 0x45800000, v11
	v_cndmask_b32_e64 v11, v11, v23, s[0:1]
	v_mul_f32_e32 v20, v20, v11
	v_mul_f32_e32 v20, v20, v69
	v_mul_f32_e32 v20, v20, v37
	v_cvt_pk_bf16_f32 v20, v20, s0
	global_store_short v[32:33], v20, off
	v_mul_f32_e32 v20, v21, v11
	v_mul_f32_e32 v20, v20, v67
	v_mul_f32_e32 v20, v20, v39
	v_cvt_pk_bf16_f32 v20, v20, s0
	global_store_short v[8:9], v20, off
	v_mul_f32_e32 v8, v18, v11
	v_mul_f32_e32 v8, v8, v49
	v_mul_f32_e32 v8, v8, v24
	v_cvt_pk_bf16_f32 v8, v8, s0
	global_store_short v[16:17], v8, off
	v_mul_f32_e32 v8, v19, v11
	v_mul_f32_e32 v8, v8, v48
	v_mul_f32_e32 v8, v8, v22
	v_cvt_pk_bf16_f32 v8, v8, s0
	global_store_short v[6:7], v8, off
	v_or_b32_e32 v6, 19, v68
	v_ashrrev_i32_e32 v7, 31, v6
	v_lshlrev_b64 v[6:7], 10, v[6:7]
	v_or_b32_e32 v6, v6, v65
	v_lshl_add_u64 v[8:9], s[8:9], 0, v[6:7]
	v_mov_b32_e32 v11, v184
	v_or_b32_e32 v8, 64, v6
	v_mov_b32_e32 v9, v7
	v_lshl_add_u64 v[16:17], s[8:9], 0, v[8:9]
	v_mov_b32_e32 v22, v185
	v_or_b32_e32 v16, 0x80, v6
	v_mov_b32_e32 v17, v7
	v_lshl_add_u64 v[18:19], s[8:9], 0, v[16:17]
	v_mov_b32_e32 v23, v186
	v_lshl_add_u64 v[18:19], s[10:11], 0, v[6:7]
	v_or_b32_e32 v6, 0xc0, v6
	v_lshl_add_u64 v[20:21], s[8:9], 0, v[6:7]
	v_mov_b32_e32 v20, v187
	v_mul_f32_e32 v21, 0x4b800000, v10
	v_cndmask_b32_e32 v10, v10, v21, vcc
	v_rsq_f32_e32 v10, v10
	v_lshlrev_b32_e32 v11, 16, v11
	v_mul_f32_e32 v21, 0xbfb8aa3b, v11
	v_exp_f32_e32 v21, v21
	v_mul_f32_e32 v24, 0x45800000, v10
	v_cndmask_b32_e32 v10, v10, v24, vcc
	v_lshlrev_b32_e32 v22, 16, v22
	v_add_f32_e32 v21, 1.0, v21
	v_div_scale_f32 v25, s[0:1], v21, v21, v11
	v_rcp_f32_e32 v26, v25
	v_mul_f32_e32 v4, v4, v10
	v_mul_f32_e32 v4, v4, v69
	v_mul_f32_e32 v2, v2, v10
	v_fma_f32 v24, -v25, v26, 1.0
	v_fmac_f32_e32 v26, v24, v26
	v_div_scale_f32 v24, vcc, v11, v21, v11
	v_mul_f32_e32 v27, v24, v26
	v_fma_f32 v32, -v25, v27, v24
	v_fmac_f32_e32 v27, v32, v26
	v_fma_f32 v24, -v25, v27, v24
	v_mul_f32_e32 v25, 0xbfb8aa3b, v22
	v_exp_f32_e32 v25, v25
	v_div_fmas_f32 v24, v24, v26, v27
	v_div_fixup_f32 v11, v24, v21, v11
	v_mul_f32_e32 v4, v4, v11
	v_add_f32_e32 v11, 1.0, v25
	v_cvt_pk_bf16_f32 v4, v4, s0
	v_div_scale_f32 v21, s[0:1], v11, v11, v22
	v_rcp_f32_e32 v24, v21
	global_store_short v[18:19], v4, off
	v_mul_f32_e32 v4, v5, v10
	v_mul_f32_e32 v4, v4, v67
	v_fma_f32 v5, -v21, v24, 1.0
	v_fmac_f32_e32 v24, v5, v24
	v_div_scale_f32 v5, vcc, v22, v11, v22
	v_mul_f32_e32 v18, v5, v24
	v_fma_f32 v19, -v21, v18, v5
	v_fmac_f32_e32 v18, v19, v24
	v_fma_f32 v5, -v21, v18, v5
	v_div_fmas_f32 v5, v5, v24, v18
	v_div_fixup_f32 v5, v5, v11, v22
	v_lshlrev_b32_e32 v11, 16, v23
	v_mul_f32_e32 v18, 0xbfb8aa3b, v11
	v_exp_f32_e32 v18, v18
	v_mul_f32_e32 v4, v4, v5
	v_cvt_pk_bf16_f32 v19, v4, s0
	v_lshl_add_u64 v[4:5], s[10:11], 0, v[8:9]
	v_add_f32_e32 v8, 1.0, v18
	v_div_scale_f32 v9, s[0:1], v8, v8, v11
	v_rcp_f32_e32 v18, v9
	global_store_short v[4:5], v19, off
	v_mul_f32_e32 v2, v2, v49
	v_add_u32_e32 v27, 0x3000, v71
	v_fma_f32 v4, -v9, v18, 1.0
	v_fmac_f32_e32 v18, v4, v18
	v_div_scale_f32 v4, vcc, v11, v8, v11
	v_mul_f32_e32 v5, v4, v18
	v_fma_f32 v19, -v9, v5, v4
	v_fmac_f32_e32 v5, v19, v18
	v_fma_f32 v4, -v9, v5, v4
	v_div_fmas_f32 v4, v4, v18, v5
	v_div_fixup_f32 v4, v4, v8, v11
	v_lshlrev_b32_e32 v8, 16, v20
	v_mul_f32_e32 v5, 0xbfb8aa3b, v8
	v_exp_f32_e32 v9, v5
	v_mul_f32_e32 v2, v2, v4
	v_cvt_pk_bf16_f32 v2, v2, s0
	v_lshl_add_u64 v[4:5], s[10:11], 0, v[16:17]
	v_add_f32_e32 v9, 1.0, v9
	v_div_scale_f32 v11, s[0:1], v9, v9, v8
	v_rcp_f32_e32 v16, v11
	global_store_short v[4:5], v2, off
	v_mul_f32_e32 v2, v3, v10
	v_mul_f32_e32 v2, v2, v48
	v_fma_f32 v3, -v11, v16, 1.0
	v_fmac_f32_e32 v16, v3, v16
	v_div_scale_f32 v3, vcc, v8, v9, v8
	v_mul_f32_e32 v4, v3, v16
	v_fma_f32 v5, -v11, v4, v3
	v_fmac_f32_e32 v4, v5, v16
	v_fma_f32 v3, -v11, v4, v3
	v_div_fmas_f32 v3, v3, v16, v4
	v_div_fixup_f32 v3, v3, v9, v8
	v_mul_f32_e32 v2, v2, v3
	v_cvt_pk_bf16_f32 v4, v2, s0
	v_lshl_add_u64 v[2:3], s[10:11], 0, v[6:7]
	global_store_short v[2:3], v4, off
	v_or_b32_e32 v2, 24, v68
	v_ashrrev_i32_e32 v3, 31, v2
	v_lshlrev_b64 v[6:7], 10, v[2:3]
	v_or_b32_e32 v6, v6, v65
	v_lshl_add_u64 v[2:3], s[8:9], 0, v[6:7]
	v_mov_b32_e32 v26, v188
	v_or_b32_e32 v8, 64, v6
	v_mov_b32_e32 v9, v7
	v_lshl_add_u64 v[2:3], s[8:9], 0, v[8:9]
	v_mov_b32_e32 v32, v189
	v_or_b32_e32 v10, 0x80, v6
	v_mov_b32_e32 v11, v7
	v_lshl_add_u64 v[2:3], s[8:9], 0, v[10:11]
	v_mov_b32_e32 v33, v190
	ds_read2_b32 v[2:3], v27 offset1:32
	ds_read2_b32 v[16:17], v27 offset0:64 offset1:96
	v_mov_b32_e32 v4, v12
	v_mov_b32_e32 v5, v60
	v_lshl_add_u64 v[24:25], s[10:11], 0, v[6:7]
	s_waitcnt lgkmcnt(1)
	v_pk_mul_f32 v[2:3], v[164:165], v[2:3]
	v_or_b32_e32 v6, 0xc0, v6
	v_pk_fma_f32 v[18:19], v[4:5], v[72:73], v[2:3] op_sel_hi:[1,0,1] neg_lo:[0,0,1] neg_hi:[0,0,1]
	v_mov_b32_e32 v2, v44
	v_mov_b32_e32 v3, v28
	s_waitcnt lgkmcnt(0)
	v_pk_mul_f32 v[4:5], v[164:165], v[16:17]
	v_mov_b32_e32 v60, v13
	v_pk_fma_f32 v[16:17], v[2:3], v[72:73], v[4:5] op_sel_hi:[1,0,1] neg_lo:[0,0,1] neg_hi:[0,0,1]
	v_lshl_add_u64 v[4:5], s[8:9], 0, v[6:7]
	v_mov_b32_e32 v34, v191
	ds_read2_b32 v[2:3], v27 offset0:128 offset1:160
	v_mov_b32_e32 v28, v45
	v_pk_mul_f32 v[20:21], v[18:19], v[18:19]
	v_pk_mul_f32 v[22:23], v[16:17], v[16:17]
	v_lshl_add_u64 v[8:9], s[10:11], 0, v[8:9]
	s_waitcnt lgkmcnt(0)
	v_pk_mul_f32 v[2:3], v[164:165], v[2:3]
	v_lshl_add_u64 v[10:11], s[10:11], 0, v[10:11]
	v_pk_fma_f32 v[4:5], v[60:61], v[70:71], v[2:3] op_sel_hi:[1,0,1] neg_lo:[0,0,1] neg_hi:[0,0,1]
	v_lshl_add_u64 v[6:7], s[10:11], 0, v[6:7]
	v_pk_mul_f32 v[12:13], v[4:5], v[4:5]
	v_lshlrev_b32_e32 v35, 16, v26
	v_mul_f32_e32 v2, 0xbfb8aa3b, v35
	v_exp_f32_e32 v26, v2
	ds_read2_b32 v[2:3], v27 offset0:192 offset1:224
	v_lshlrev_b32_e32 v32, 16, v32
	v_mul_f32_e32 v39, 0xbfb8aa3b, v32
	v_add_f32_e32 v36, 1.0, v26
	v_div_scale_f32 v37, s[0:1], v36, v36, v35
	v_rcp_f32_e32 v38, v37
	s_waitcnt lgkmcnt(0)
	v_pk_mul_f32 v[2:3], v[164:165], v[2:3]
	v_exp_f32_e32 v39, v39
	v_pk_fma_f32 v[2:3], v[28:29], v[70:71], v[2:3] op_sel_hi:[1,0,1] neg_lo:[0,0,1] neg_hi:[0,0,1]
	v_fma_f32 v28, -v37, v38, 1.0
	v_fmac_f32_e32 v38, v28, v38
	v_div_scale_f32 v28, vcc, v35, v36, v35
	v_mul_f32_e32 v29, v28, v38
	v_fma_f32 v40, -v37, v29, v28
	v_fmac_f32_e32 v29, v40, v38
	v_fma_f32 v28, -v37, v29, v28
	v_add_f32_e32 v37, 1.0, v39
	v_div_scale_f32 v39, s[0:1], v37, v37, v32
	v_rcp_f32_e32 v40, v39
	v_div_fmas_f32 v28, v28, v38, v29
	v_lshlrev_b32_e32 v33, 16, v33
	v_div_fixup_f32 v35, v28, v36, v35
	v_mul_f32_e32 v36, 0xbfb8aa3b, v33
	v_exp_f32_e32 v36, v36
	v_fma_f32 v28, -v39, v40, 1.0
	v_fmac_f32_e32 v40, v28, v40
	v_div_scale_f32 v28, vcc, v32, v37, v32
	v_mul_f32_e32 v29, v28, v40
	v_fma_f32 v38, -v39, v29, v28
	v_add_f32_e32 v36, 1.0, v36
	v_fmac_f32_e32 v29, v38, v40
	v_div_scale_f32 v38, s[0:1], v36, v36, v33
	v_fma_f32 v28, -v39, v29, v28
	v_rcp_f32_e32 v39, v38
	v_div_fmas_f32 v28, v28, v40, v29
	v_div_fixup_f32 v32, v28, v37, v32
	v_div_scale_f32 v37, vcc, v33, v36, v33
	v_fma_f32 v28, -v38, v39, 1.0
	v_fmac_f32_e32 v39, v28, v39
	v_mul_f32_e32 v40, v37, v39
	v_fma_f32 v28, -v38, v40, v37
	v_pk_mul_f32 v[26:27], v[2:3], v[2:3]
	v_fmac_f32_e32 v40, v28, v39
	v_mov_b32_e32 v28, v12
	v_mov_b32_e32 v29, v20
	v_mov_b32_e32 v20, v13
	v_pk_add_f32 v[12:13], v[28:29], v[20:21]
	v_mov_b32_e32 v20, v26
	v_mov_b32_e32 v21, v22
	v_pk_add_f32 v[12:13], v[12:13], v[20:21]
	v_mov_b32_e32 v22, v27
	v_pk_add_f32 v[12:13], v[12:13], v[22:23]
	ds_bpermute_b32 v21, v216, v13
	ds_bpermute_b32 v20, v216, v12
	v_lshlrev_b32_e32 v23, 16, v34
	v_mul_f32_e32 v26, 0xbfb8aa3b, v23
	v_exp_f32_e32 v26, v26
	v_fma_f32 v22, -v38, v40, v37
	s_waitcnt lgkmcnt(0)
	v_pk_add_f32 v[12:13], v[12:13], v[20:21]
	ds_bpermute_b32 v21, v217, v13
	ds_bpermute_b32 v20, v217, v12
	v_add_f32_e32 v26, 1.0, v26
	v_div_scale_f32 v27, s[0:1], v26, v26, v23
	v_rcp_f32_e32 v28, v27
	s_waitcnt lgkmcnt(0)
	v_pk_add_f32 v[12:13], v[12:13], v[20:21]
	ds_bpermute_b32 v21, v218, v13
	ds_bpermute_b32 v20, v218, v12
	v_fma_f32 v29, -v27, v28, 1.0
	v_div_fmas_f32 v22, v22, v39, v40
	v_fmac_f32_e32 v28, v29, v28
	v_div_scale_f32 v29, vcc, v23, v26, v23
	s_waitcnt lgkmcnt(0)
	v_pk_add_f32 v[12:13], v[12:13], v[20:21]
	ds_bpermute_b32 v21, v219, v13
	ds_bpermute_b32 v20, v219, v12
	v_div_fixup_f32 v22, v22, v36, v33
	v_mul_f32_e32 v33, v29, v28
	v_fma_f32 v34, -v27, v33, v29
	v_fmac_f32_e32 v33, v34, v28
	s_waitcnt lgkmcnt(0)
	v_pk_add_f32 v[12:13], v[12:13], v[20:21]
	ds_bpermute_b32 v21, v220, v13
	ds_bpermute_b32 v20, v220, v12
	v_fma_f32 v27, -v27, v33, v29
	s_waitcnt lgkmcnt(0)
	v_pk_add_f32 v[12:13], v[12:13], v[20:21]
	s_nop 0
	v_pk_fma_f32 v[12:13], v[12:13], s[46:47], v[0:1] op_sel_hi:[1,0,0]
	s_nop 0
	v_mul_f32_e32 v20, 0x4b800000, v13
	v_cmp_gt_f32_e64 s[0:1], s49, v13
	s_nop 1
	v_cndmask_b32_e64 v13, v13, v20, s[0:1]
	v_rsq_f32_e32 v13, v13
	v_div_fmas_f32 v20, v27, v28, v33
	v_div_fixup_f32 v20, v20, v26, v23
	v_cmp_gt_f32_e32 vcc, s49, v12
	v_mul_f32_e32 v21, 0x45800000, v13
	v_cndmask_b32_e64 v13, v13, v21, s[0:1]
	v_mul_f32_e32 v18, v18, v13
	v_mul_f32_e32 v18, v18, v69
	v_mul_f32_e32 v18, v18, v35
	v_cvt_pk_bf16_f32 v18, v18, s0
	global_store_short v[24:25], v18, off
	v_mul_f32_e32 v18, v19, v13
	v_mul_f32_e32 v18, v18, v67
	v_mul_f32_e32 v18, v18, v32
	v_cvt_pk_bf16_f32 v18, v18, s0
	global_store_short v[8:9], v18, off
	v_mul_f32_e32 v8, v16, v13
	v_mul_f32_e32 v8, v8, v49
	v_mul_f32_e32 v8, v8, v22
	v_cvt_pk_bf16_f32 v8, v8, s0
	global_store_short v[10:11], v8, off
	v_mul_f32_e32 v8, v17, v13
	v_mul_f32_e32 v8, v8, v48
	v_mul_f32_e32 v8, v8, v20
	v_cvt_pk_bf16_f32 v8, v8, s0
	global_store_short v[6:7], v8, off
	v_or_b32_e32 v6, 25, v68
	v_ashrrev_i32_e32 v7, 31, v6
	v_lshlrev_b64 v[6:7], 10, v[6:7]
	v_or_b32_e32 v6, v6, v65
	v_lshl_add_u64 v[8:9], s[8:9], 0, v[6:7]
	v_mov_b32_e32 v13, v192
	v_or_b32_e32 v8, 64, v6
	v_mov_b32_e32 v9, v7
	v_lshl_add_u64 v[10:11], s[8:9], 0, v[8:9]
	v_mov_b32_e32 v20, v193
	v_or_b32_e32 v10, 0x80, v6
	v_mov_b32_e32 v11, v7
	v_lshl_add_u64 v[16:17], s[8:9], 0, v[10:11]
	v_mov_b32_e32 v21, v194
	v_lshl_add_u64 v[16:17], s[10:11], 0, v[6:7]
	v_or_b32_e32 v6, 0xc0, v6
	v_lshl_add_u64 v[18:19], s[8:9], 0, v[6:7]
	v_mov_b32_e32 v18, v195
	v_mul_f32_e32 v19, 0x4b800000, v12
	v_cndmask_b32_e32 v12, v12, v19, vcc
	v_rsq_f32_e32 v12, v12
	v_lshlrev_b32_e32 v13, 16, v13
	v_mul_f32_e32 v19, 0xbfb8aa3b, v13
	v_exp_f32_e32 v19, v19
	v_mul_f32_e32 v22, 0x45800000, v12
	v_cndmask_b32_e32 v12, v12, v22, vcc
	v_lshlrev_b32_e32 v20, 16, v20
	v_add_f32_e32 v19, 1.0, v19
	v_div_scale_f32 v23, s[0:1], v19, v19, v13
	v_rcp_f32_e32 v24, v23
	v_mul_f32_e32 v4, v4, v12
	v_mul_f32_e32 v4, v4, v69
	v_mul_f32_e32 v2, v2, v12
	v_fma_f32 v22, -v23, v24, 1.0
	v_fmac_f32_e32 v24, v22, v24
	v_div_scale_f32 v22, vcc, v13, v19, v13
	v_mul_f32_e32 v25, v22, v24
	v_fma_f32 v26, -v23, v25, v22
	v_fmac_f32_e32 v25, v26, v24
	v_fma_f32 v22, -v23, v25, v22
	v_mul_f32_e32 v23, 0xbfb8aa3b, v20
	v_exp_f32_e32 v23, v23
	v_div_fmas_f32 v22, v22, v24, v25
	v_div_fixup_f32 v13, v22, v19, v13
	v_mul_f32_e32 v4, v4, v13
	v_add_f32_e32 v13, 1.0, v23
	v_cvt_pk_bf16_f32 v4, v4, s0
	v_div_scale_f32 v19, s[0:1], v13, v13, v20
	v_rcp_f32_e32 v22, v19
	global_store_short v[16:17], v4, off
	v_mul_f32_e32 v4, v5, v12
	v_mul_f32_e32 v4, v4, v67
	v_fma_f32 v5, -v19, v22, 1.0
	v_fmac_f32_e32 v22, v5, v22
	v_div_scale_f32 v5, vcc, v20, v13, v20
	v_mul_f32_e32 v16, v5, v22
	v_fma_f32 v17, -v19, v16, v5
	v_fmac_f32_e32 v16, v17, v22
	v_fma_f32 v5, -v19, v16, v5
	v_div_fmas_f32 v5, v5, v22, v16
	v_div_fixup_f32 v5, v5, v13, v20
	v_lshlrev_b32_e32 v13, 16, v21
	v_mul_f32_e32 v16, 0xbfb8aa3b, v13
	v_exp_f32_e32 v16, v16
	v_mul_f32_e32 v4, v4, v5
	v_cvt_pk_bf16_f32 v17, v4, s0
	v_lshl_add_u64 v[4:5], s[10:11], 0, v[8:9]
	v_add_f32_e32 v8, 1.0, v16
	v_div_scale_f32 v9, s[0:1], v8, v8, v13
	v_rcp_f32_e32 v16, v9
	global_store_short v[4:5], v17, off
	v_mul_f32_e32 v2, v2, v49
	v_add_u32_e32 v25, 0x3400, v71
	v_fma_f32 v4, -v9, v16, 1.0
	v_fmac_f32_e32 v16, v4, v16
	v_div_scale_f32 v4, vcc, v13, v8, v13
	v_mul_f32_e32 v5, v4, v16
	v_fma_f32 v17, -v9, v5, v4
	v_fmac_f32_e32 v5, v17, v16
	v_fma_f32 v4, -v9, v5, v4
	v_div_fmas_f32 v4, v4, v16, v5
	v_div_fixup_f32 v4, v4, v8, v13
	v_lshlrev_b32_e32 v8, 16, v18
	v_mul_f32_e32 v5, 0xbfb8aa3b, v8
	v_exp_f32_e32 v9, v5
	v_mul_f32_e32 v2, v2, v4
	v_cvt_pk_bf16_f32 v2, v2, s0
	v_lshl_add_u64 v[4:5], s[10:11], 0, v[10:11]
	v_add_f32_e32 v9, 1.0, v9
	v_div_scale_f32 v10, s[0:1], v9, v9, v8
	v_rcp_f32_e32 v11, v10
	global_store_short v[4:5], v2, off
	v_mul_f32_e32 v2, v3, v12
	v_mul_f32_e32 v2, v2, v48
	v_fma_f32 v3, -v10, v11, 1.0
	v_fmac_f32_e32 v11, v3, v11
	v_div_scale_f32 v3, vcc, v8, v9, v8
	v_mul_f32_e32 v4, v3, v11
	v_fma_f32 v5, -v10, v4, v3
	v_fmac_f32_e32 v4, v5, v11
	v_fma_f32 v3, -v10, v4, v3
	v_div_fmas_f32 v3, v3, v11, v4
	v_div_fixup_f32 v3, v3, v9, v8
	v_mul_f32_e32 v2, v2, v3
	v_cvt_pk_bf16_f32 v4, v2, s0
	v_lshl_add_u64 v[2:3], s[10:11], 0, v[6:7]
	global_store_short v[2:3], v4, off
	v_or_b32_e32 v2, 26, v68
	v_ashrrev_i32_e32 v3, 31, v2
	v_lshlrev_b64 v[6:7], 10, v[2:3]
	v_or_b32_e32 v6, v6, v65
	v_lshl_add_u64 v[2:3], s[8:9], 0, v[6:7]
	v_mov_b32_e32 v24, v196
	v_or_b32_e32 v8, 64, v6
	v_mov_b32_e32 v9, v7
	v_lshl_add_u64 v[2:3], s[8:9], 0, v[8:9]
	v_mov_b32_e32 v26, v197
	v_or_b32_e32 v10, 0x80, v6
	v_mov_b32_e32 v11, v7
	v_lshl_add_u64 v[2:3], s[8:9], 0, v[10:11]
	v_mov_b32_e32 v27, v198
	ds_read2_b32 v[2:3], v25 offset1:32
	ds_read2_b32 v[12:13], v25 offset0:64 offset1:96
	v_mov_b32_e32 v4, v14
	v_mov_b32_e32 v5, v62
	v_lshl_add_u64 v[22:23], s[10:11], 0, v[6:7]
	s_waitcnt lgkmcnt(1)
	v_pk_mul_f32 v[2:3], v[164:165], v[2:3]
	v_or_b32_e32 v6, 0xc0, v6
	v_pk_fma_f32 v[16:17], v[4:5], v[66:67], v[2:3] op_sel_hi:[1,0,1] neg_lo:[0,0,1] neg_hi:[0,0,1]
	v_mov_b32_e32 v2, v46
	v_mov_b32_e32 v3, v30
	s_waitcnt lgkmcnt(0)
	v_pk_mul_f32 v[4:5], v[164:165], v[12:13]
	v_mov_b32_e32 v62, v15
	v_pk_fma_f32 v[12:13], v[2:3], v[66:67], v[4:5] op_sel_hi:[1,0,1] neg_lo:[0,0,1] neg_hi:[0,0,1]
	v_lshl_add_u64 v[4:5], s[8:9], 0, v[6:7]
	v_mov_b32_e32 v28, v199
	ds_read2_b32 v[2:3], v25 offset0:128 offset1:160
	v_mov_b32_e32 v30, v47
	v_pk_mul_f32 v[18:19], v[16:17], v[16:17]
	v_pk_mul_f32 v[20:21], v[12:13], v[12:13]
	v_lshl_add_u64 v[8:9], s[10:11], 0, v[8:9]
	s_waitcnt lgkmcnt(0)
	v_pk_mul_f32 v[2:3], v[164:165], v[2:3]
	v_lshl_add_u64 v[6:7], s[10:11], 0, v[6:7]
	v_pk_fma_f32 v[4:5], v[62:63], v[64:65], v[2:3] op_sel_hi:[1,0,1] neg_lo:[0,0,1] neg_hi:[0,0,1]
	v_lshl_add_u64 v[10:11], s[10:11], 0, v[10:11]
	v_pk_mul_f32 v[14:15], v[4:5], v[4:5]
	v_lshlrev_b32_e32 v29, 16, v24
	v_mul_f32_e32 v2, 0xbfb8aa3b, v29
	v_exp_f32_e32 v24, v2
	ds_read2_b32 v[2:3], v25 offset0:192 offset1:224
	v_lshlrev_b32_e32 v26, 16, v26
	v_mul_f32_e32 v35, 0xbfb8aa3b, v26
	v_add_f32_e32 v32, 1.0, v24
	v_div_scale_f32 v33, s[0:1], v32, v32, v29
	v_rcp_f32_e32 v34, v33
	s_waitcnt lgkmcnt(0)
	v_pk_mul_f32 v[2:3], v[164:165], v[2:3]
	v_exp_f32_e32 v35, v35
	v_pk_fma_f32 v[2:3], v[30:31], v[64:65], v[2:3] op_sel_hi:[1,0,1] neg_lo:[0,0,1] neg_hi:[0,0,1]
	v_fma_f32 v30, -v33, v34, 1.0
	v_fmac_f32_e32 v34, v30, v34
	v_div_scale_f32 v30, vcc, v29, v32, v29
	v_mul_f32_e32 v31, v30, v34
	v_fma_f32 v36, -v33, v31, v30
	v_fmac_f32_e32 v31, v36, v34
	v_fma_f32 v30, -v33, v31, v30
	v_add_f32_e32 v33, 1.0, v35
	v_div_scale_f32 v35, s[0:1], v33, v33, v26
	v_rcp_f32_e32 v36, v35
	v_div_fmas_f32 v30, v30, v34, v31
	v_div_fixup_f32 v29, v30, v32, v29
	v_lshlrev_b32_e32 v32, 16, v27
	v_mul_f32_e32 v27, 0xbfb8aa3b, v32
	v_fma_f32 v30, -v35, v36, 1.0
	v_exp_f32_e32 v27, v27
	v_fmac_f32_e32 v36, v30, v36
	v_div_scale_f32 v30, vcc, v26, v33, v26
	v_mul_f32_e32 v31, v30, v36
	v_fma_f32 v34, -v35, v31, v30
	v_fmac_f32_e32 v31, v34, v36
	v_add_f32_e32 v34, 1.0, v27
	v_fma_f32 v30, -v35, v31, v30
	v_div_scale_f32 v35, s[0:1], v34, v34, v32
	v_rcp_f32_e32 v37, v35
	v_div_fmas_f32 v27, v30, v36, v31
	v_div_fixup_f32 v30, v27, v33, v26
	v_div_scale_f32 v31, vcc, v32, v34, v32
	v_fma_f32 v26, -v35, v37, 1.0
	v_fmac_f32_e32 v37, v26, v37
	v_mul_f32_e32 v33, v31, v37
	v_fma_f32 v26, -v35, v33, v31
	v_pk_mul_f32 v[24:25], v[2:3], v[2:3]
	v_fmac_f32_e32 v33, v26, v37
	v_mov_b32_e32 v26, v14
	v_mov_b32_e32 v27, v18
	v_mov_b32_e32 v18, v15
	v_pk_add_f32 v[14:15], v[26:27], v[18:19]
	v_mov_b32_e32 v18, v24
	v_mov_b32_e32 v19, v20
	v_pk_add_f32 v[14:15], v[14:15], v[18:19]
	v_mov_b32_e32 v20, v25
	v_pk_add_f32 v[14:15], v[14:15], v[20:21]
	ds_bpermute_b32 v19, v216, v15
	ds_bpermute_b32 v18, v216, v14
	v_lshlrev_b32_e32 v21, 16, v28
	v_mul_f32_e32 v24, 0xbfb8aa3b, v21
	v_exp_f32_e32 v24, v24
	v_fma_f32 v20, -v35, v33, v31
	s_waitcnt lgkmcnt(0)
	v_pk_add_f32 v[14:15], v[14:15], v[18:19]
	ds_bpermute_b32 v19, v217, v15
	ds_bpermute_b32 v18, v217, v14
	v_add_f32_e32 v24, 1.0, v24
	v_div_scale_f32 v25, s[0:1], v24, v24, v21
	v_rcp_f32_e32 v26, v25
	s_waitcnt lgkmcnt(0)
	v_pk_add_f32 v[14:15], v[14:15], v[18:19]
	ds_bpermute_b32 v19, v218, v15
	ds_bpermute_b32 v18, v218, v14
	v_fma_f32 v27, -v25, v26, 1.0
	v_div_fmas_f32 v20, v20, v37, v33
	v_fmac_f32_e32 v26, v27, v26
	v_div_scale_f32 v27, vcc, v21, v24, v21
	s_waitcnt lgkmcnt(0)
	v_pk_add_f32 v[14:15], v[14:15], v[18:19]
	ds_bpermute_b32 v19, v219, v15
	ds_bpermute_b32 v18, v219, v14
	v_mul_f32_e32 v28, v27, v26
	v_fma_f32 v31, -v25, v28, v27
	v_fmac_f32_e32 v28, v31, v26
	v_fma_f32 v25, -v25, v28, v27
	s_waitcnt lgkmcnt(0)
	v_pk_add_f32 v[14:15], v[14:15], v[18:19]
	ds_bpermute_b32 v19, v220, v15
	ds_bpermute_b32 v18, v220, v14
	v_div_fixup_f32 v20, v20, v34, v32
	s_waitcnt lgkmcnt(0)
	v_pk_add_f32 v[14:15], v[14:15], v[18:19]
	s_nop 0
	v_pk_fma_f32 v[0:1], v[14:15], s[46:47], v[0:1] op_sel_hi:[1,0,0]
	s_nop 0
	v_mul_f32_e32 v14, 0x4b800000, v1
	v_cmp_gt_f32_e64 s[0:1], s49, v1
	s_nop 1
	v_cndmask_b32_e64 v1, v1, v14, s[0:1]
	v_rsq_f32_e32 v1, v1
	v_div_fmas_f32 v14, v25, v26, v28
	v_div_fixup_f32 v14, v14, v24, v21
	v_cmp_gt_f32_e32 vcc, s49, v0
	v_mul_f32_e32 v15, 0x45800000, v1
	v_cndmask_b32_e64 v1, v1, v15, s[0:1]
	v_mul_f32_e32 v15, v16, v1
	v_mul_f32_e32 v15, v69, v15
	v_mul_f32_e32 v15, v15, v29
	v_cvt_pk_bf16_f32 v15, v15, s0
	global_store_short v[22:23], v15, off
	v_mul_f32_e32 v15, v17, v1
	v_mul_f32_e32 v15, v67, v15
	v_mul_f32_e32 v15, v15, v30
	v_cvt_pk_bf16_f32 v15, v15, s0
	global_store_short v[8:9], v15, off
	v_mul_f32_e32 v8, v12, v1
	v_mul_f32_e32 v1, v13, v1
	v_mul_f32_e32 v1, v1, v48
	v_mul_f32_e32 v1, v1, v14
	v_cvt_pk_bf16_f32 v1, v1, s0
	global_store_short v[6:7], v1, off
	v_or_b32_e32 v6, 27, v68
	v_mul_f32_e32 v8, v49, v8
	v_ashrrev_i32_e32 v7, 31, v6
	v_mul_f32_e32 v8, v8, v20
	v_lshlrev_b64 v[6:7], 10, v[6:7]
	v_cvt_pk_bf16_f32 v8, v8, s0
	v_or_b32_e32 v6, v6, v65
	global_store_short v[10:11], v8, off
	v_lshl_add_u64 v[8:9], s[8:9], 0, v[6:7]
	v_mov_b32_e32 v1, v200
	v_or_b32_e32 v8, 64, v6
	v_mov_b32_e32 v9, v7
	v_lshl_add_u64 v[10:11], s[8:9], 0, v[8:9]
	v_mov_b32_e32 v16, v201
	v_or_b32_e32 v10, 0x80, v6
	v_mov_b32_e32 v11, v7
	v_lshl_add_u64 v[12:13], s[8:9], 0, v[10:11]
	v_mov_b32_e32 v17, v202
	v_lshl_add_u64 v[12:13], s[10:11], 0, v[6:7]
	v_or_b32_e32 v6, 0xc0, v6
	v_lshl_add_u64 v[14:15], s[8:9], 0, v[6:7]
	v_mov_b32_e32 v14, v203
	v_mul_f32_e32 v15, 0x4b800000, v0
	v_cndmask_b32_e32 v0, v0, v15, vcc
	v_rsq_f32_e32 v0, v0
	v_lshlrev_b32_e32 v1, 16, v1
	v_mul_f32_e32 v15, 0xbfb8aa3b, v1
	v_exp_f32_e32 v15, v15
	v_mul_f32_e32 v18, 0x45800000, v0
	v_cndmask_b32_e32 v18, v0, v18, vcc
	v_mul_f32_e32 v0, v4, v18
	v_add_f32_e32 v15, 1.0, v15
	v_div_scale_f32 v19, s[0:1], v15, v15, v1
	v_rcp_f32_e32 v20, v19
	v_lshlrev_b32_e32 v16, 16, v16
	v_mul_f32_e32 v0, v69, v0
	v_fma_f32 v4, -v19, v20, 1.0
	v_fmac_f32_e32 v20, v4, v20
	v_div_scale_f32 v4, vcc, v1, v15, v1
	v_mul_f32_e32 v21, v4, v20
	v_fma_f32 v22, -v19, v21, v4
	v_fmac_f32_e32 v21, v22, v20
	v_fma_f32 v4, -v19, v21, v4
	v_mul_f32_e32 v19, 0xbfb8aa3b, v16
	v_exp_f32_e32 v19, v19
	v_div_fmas_f32 v4, v4, v20, v21
	v_div_fixup_f32 v1, v4, v15, v1
	v_mul_f32_e32 v0, v0, v1
	v_add_f32_e32 v1, 1.0, v19
	v_cvt_pk_bf16_f32 v0, v0, s0
	v_div_scale_f32 v4, s[0:1], v1, v1, v16
	v_rcp_f32_e32 v15, v4
	global_store_short v[12:13], v0, off
	v_mul_f32_e32 v0, v5, v18
	v_mul_f32_e32 v0, v67, v0
	v_fma_f32 v5, -v4, v15, 1.0
	v_fmac_f32_e32 v15, v5, v15
	v_div_scale_f32 v5, vcc, v16, v1, v16
	v_mul_f32_e32 v12, v5, v15
	v_fma_f32 v13, -v4, v12, v5
	v_fmac_f32_e32 v12, v13, v15
	v_fma_f32 v4, -v4, v12, v5
	v_div_fmas_f32 v4, v4, v15, v12
	v_div_fixup_f32 v1, v4, v1, v16
	v_lshlrev_b32_e32 v4, 16, v17
	v_mul_f32_e32 v5, 0xbfb8aa3b, v4
	v_exp_f32_e32 v5, v5
	v_mul_f32_e32 v0, v0, v1
	v_cvt_pk_bf16_f32 v12, v0, s0
	v_lshl_add_u64 v[0:1], s[10:11], 0, v[8:9]
	v_add_f32_e32 v5, 1.0, v5
	v_div_scale_f32 v8, s[0:1], v5, v5, v4
	v_rcp_f32_e32 v9, v8
	global_store_short v[0:1], v12, off
	v_mul_f32_e32 v0, v2, v18
	v_mul_f32_e32 v0, v49, v0
	v_fma_f32 v1, -v8, v9, 1.0
	v_fmac_f32_e32 v9, v1, v9
	v_div_scale_f32 v1, vcc, v4, v5, v4
	v_mul_f32_e32 v2, v1, v9
	v_fma_f32 v12, -v8, v2, v1
	v_fmac_f32_e32 v2, v12, v9
	v_fma_f32 v1, -v8, v2, v1
	v_div_fmas_f32 v1, v1, v9, v2
	v_lshlrev_b32_e32 v2, 16, v14
	v_div_fixup_f32 v1, v1, v5, v4
	v_mul_f32_e32 v4, 0xbfb8aa3b, v2
	v_exp_f32_e32 v4, v4
	v_mul_f32_e32 v0, v0, v1
	v_cvt_pk_bf16_f32 v5, v0, s0
	v_lshl_add_u64 v[0:1], s[10:11], 0, v[10:11]
	v_add_f32_e32 v4, 1.0, v4
	v_div_scale_f32 v8, s[0:1], v4, v4, v2
	v_rcp_f32_e32 v9, v8
	global_store_short v[0:1], v5, off
	v_mul_f32_e32 v0, v3, v18
	v_mul_f32_e32 v0, v48, v0
	v_fma_f32 v1, -v8, v9, 1.0
	v_fmac_f32_e32 v9, v1, v9
	v_div_scale_f32 v1, vcc, v2, v4, v2
	v_mul_f32_e32 v3, v1, v9
	v_fma_f32 v5, -v8, v3, v1
	v_fmac_f32_e32 v3, v5, v9
	v_fma_f32 v1, -v8, v3, v1
	v_div_fmas_f32 v1, v1, v9, v3
	v_div_fixup_f32 v1, v1, v4, v2
	v_mul_f32_e32 v0, v0, v1
	v_cvt_pk_bf16_f32 v2, v0, s0
	v_lshl_add_u64 v[0:1], s[10:11], 0, v[6:7]
	global_store_short v[0:1], v2, off
	s_branch .LBB0_804

.LBB0_916:
	s_or_b64 exec, exec, s[4:5]
	v_lshl_or_b32 v186, v168, 2, v165
	v_or_b32_e32 v190, s6, v167
	v_lshlrev_b32_e32 v186, 10, v186
	v_lshl_or_b32 v186, v190, 1, v186
	v_add_u32_e32 v187, 0x2000, v186
	v_add_u32_e32 v188, 0x4000, v186
	v_add_u32_e32 v189, 0x6000, v186
	global_load_ushort v109, v186, s[12:13]
	global_load_ushort v110, v186, s[12:13] offset:64
	global_load_ushort v111, v186, s[12:13] offset:128
	global_load_ushort v112, v186, s[12:13] offset:192
	global_load_ushort v113, v186, s[12:13] offset:1024
	global_load_ushort v114, v186, s[12:13] offset:1088
	global_load_ushort v115, v186, s[12:13] offset:1152
	global_load_ushort v116, v186, s[12:13] offset:1216
	global_load_ushort v117, v186, s[12:13] offset:2048
	global_load_ushort v118, v186, s[12:13] offset:2112
	global_load_ushort v119, v186, s[12:13] offset:2176
	global_load_ushort v120, v186, s[12:13] offset:2240
	global_load_ushort v121, v186, s[12:13] offset:3072
	global_load_ushort v122, v186, s[12:13] offset:3136
	global_load_ushort v123, v186, s[12:13] offset:3200
	global_load_ushort v124, v186, s[12:13] offset:3264
	global_load_ushort v125, v187, s[12:13]
	global_load_ushort v126, v187, s[12:13] offset:64
	global_load_ushort v127, v187, s[12:13] offset:128
	global_load_ushort v128, v187, s[12:13] offset:192
	global_load_ushort v129, v187, s[12:13] offset:1024
	global_load_ushort v130, v187, s[12:13] offset:1088
	global_load_ushort v131, v187, s[12:13] offset:1152
	global_load_ushort v132, v187, s[12:13] offset:1216
	global_load_ushort v133, v187, s[12:13] offset:2048
	global_load_ushort v134, v187, s[12:13] offset:2112
	global_load_ushort v135, v187, s[12:13] offset:2176
	global_load_ushort v136, v187, s[12:13] offset:2240
	global_load_ushort v137, v187, s[12:13] offset:3072
	global_load_ushort v138, v187, s[12:13] offset:3136
	global_load_ushort v139, v187, s[12:13] offset:3200
	global_load_ushort v140, v187, s[12:13] offset:3264
	global_load_ushort v141, v188, s[12:13]
	global_load_ushort v142, v188, s[12:13] offset:64
	global_load_ushort v143, v188, s[12:13] offset:128
	global_load_ushort v144, v188, s[12:13] offset:192
	global_load_ushort v145, v188, s[12:13] offset:1024
	global_load_ushort v146, v188, s[12:13] offset:1088
	global_load_ushort v147, v188, s[12:13] offset:1152
	global_load_ushort v148, v188, s[12:13] offset:1216
	global_load_ushort v149, v188, s[12:13] offset:2048
	global_load_ushort v150, v188, s[12:13] offset:2112
	global_load_ushort v151, v188, s[12:13] offset:2176
	global_load_ushort v152, v188, s[12:13] offset:2240
	global_load_ushort v153, v188, s[12:13] offset:3072
	global_load_ushort v154, v188, s[12:13] offset:3136
	global_load_ushort v155, v188, s[12:13] offset:3200
	global_load_ushort v156, v188, s[12:13] offset:3264
	global_load_ushort v157, v189, s[12:13]
	global_load_ushort v158, v189, s[12:13] offset:64
	global_load_ushort v159, v189, s[12:13] offset:128
	global_load_ushort v173, v189, s[12:13] offset:192
	global_load_ushort v174, v189, s[12:13] offset:1024
	global_load_ushort v175, v189, s[12:13] offset:1088
	global_load_ushort v176, v189, s[12:13] offset:1152
	global_load_ushort v177, v189, s[12:13] offset:1216
	global_load_ushort v178, v189, s[12:13] offset:2048
	global_load_ushort v179, v189, s[12:13] offset:2112
	global_load_ushort v180, v189, s[12:13] offset:2176
	global_load_ushort v181, v189, s[12:13] offset:2240
	global_load_ushort v182, v189, s[12:13] offset:3072
	global_load_ushort v183, v189, s[12:13] offset:3136
	global_load_ushort v184, v189, s[12:13] offset:3200
	global_load_ushort v185, v189, s[12:13] offset:3264
	v_lshl_or_b32 v72, v168, 2, v165
	v_or_b32_e32 v64, s6, v167
	v_ashrrev_i32_e32 v73, 31, v72
	v_lshlrev_b64 v[76:77], 10, v[72:73]
	v_lshlrev_b32_e32 v73, 1, v64
	v_or_b32_e32 v76, v76, v73
	s_waitcnt lgkmcnt(0)
	v_lshl_add_u64 v[64:65], s[12:13], 0, v[76:77]
	s_waitcnt vmcnt(0)
	v_mov_b32_e32 v75, v109
	v_or_b32_e32 v80, 64, v76
	v_mov_b32_e32 v81, v77
	v_lshl_add_u64 v[78:79], s[14:15], 0, v[76:77]
	v_lshl_add_u64 v[64:65], s[12:13], 0, v[80:81]
	v_or_b32_e32 v82, 0x80, v76
	v_mov_b32_e32 v83, v77
	v_or_b32_e32 v76, 0xc0, v76
	v_lshl_add_u64 v[66:67], s[12:13], 0, v[82:83]
	v_lshl_add_u64 v[68:69], s[12:13], 0, v[76:77]
	v_mov_b32_e32 v84, v110
	v_mov_b32_e32 v85, v111
	v_mov_b32_e32 v86, v112
	v_add_u32_e32 v74, v172, v166
	ds_read_b128 v[68:71], v74
	ds_read_b128 v[64:67], v74 offset:32
	v_lshl_add_u64 v[80:81], s[14:15], 0, v[80:81]
	v_lshl_add_u64 v[82:83], s[14:15], 0, v[82:83]
	v_lshl_add_u64 v[76:77], s[14:15], 0, v[76:77]
	s_waitcnt lgkmcnt(1)
	v_rcp_f32_e32 v68, v68
	v_rcp_f32_e32 v70, v70
	s_add_i32 s46, s46, s50
	s_add_i32 s2, s2, s3
	v_mul_f32_e32 v0, v0, v68
	v_mul_f32_e32 v16, v16, v68
	v_mul_f32_e32 v32, v32, v68
	v_mul_f32_e32 v48, v48, v68
	v_mul_f32_e32 v2, v2, v70
	v_mul_f32_e32 v18, v18, v70
	v_mul_f32_e32 v34, v34, v70
	v_mul_f32_e32 v50, v50, v70
	s_add_i32 s47, s47, s24
	s_cmpk_lt_i32 s46, 0x100
	v_lshlrev_b32_e32 v68, 16, v75
	v_mul_f32_e32 v75, 0xbfb8aa3b, v68
	v_exp_f32_e32 v75, v75
	v_lshlrev_b32_e32 v84, 16, v84
	v_lshlrev_b32_e32 v85, 16, v85
	v_mul_f32_e32 v87, 0xbfb8aa3b, v84
	v_lshlrev_b32_e32 v86, 16, v86
	v_mul_f32_e32 v88, 0xbfb8aa3b, v85
	v_exp_f32_e32 v87, v87
	v_mul_f32_e32 v89, 0xbfb8aa3b, v86
	v_exp_f32_e32 v88, v88
	v_exp_f32_e32 v89, v89
	v_add_f32_e32 v75, 1.0, v75
	v_div_scale_f32 v90, s[0:1], v75, v75, v68
	v_add_f32_e32 v87, 1.0, v87
	v_add_f32_e32 v88, 1.0, v88
	v_rcp_f32_e32 v92, v90
	v_div_scale_f32 v93, s[0:1], v87, v87, v84
	v_add_f32_e32 v89, 1.0, v89
	v_div_scale_f32 v95, s[4:5], v88, v88, v85
	v_rcp_f32_e32 v99, v93
	v_div_scale_f32 v97, s[6:7], v89, v89, v86
	v_rcp_f32_e32 v100, v95
	v_rcp_f32_e32 v101, v97
	v_fma_f32 v102, -v90, v92, 1.0
	v_div_scale_f32 v91, vcc, v68, v75, v68
	v_fmac_f32_e32 v92, v102, v92
	v_fma_f32 v102, -v93, v99, 1.0
	v_div_scale_f32 v94, s[0:1], v84, v87, v84
	v_fma_f32 v103, -v95, v100, 1.0
	v_mul_f32_e32 v105, v91, v92
	v_fmac_f32_e32 v99, v102, v99
	v_div_scale_f32 v96, s[4:5], v85, v88, v85
	v_fma_f32 v104, -v97, v101, 1.0
	v_fmac_f32_e32 v100, v103, v100
	v_fma_f32 v102, -v90, v105, v91
	v_mul_f32_e32 v103, v94, v99
	v_fmac_f32_e32 v101, v104, v101
	v_mul_f32_e32 v104, v96, v100
	v_fmac_f32_e32 v105, v102, v92
	v_fma_f32 v102, -v93, v103, v94
	v_fma_f32 v107, -v95, v104, v96
	v_fma_f32 v90, -v90, v105, v91
	v_fmac_f32_e32 v103, v102, v99
	v_fmac_f32_e32 v104, v107, v100
	v_div_fmas_f32 v90, v90, v92, v105
	v_fma_f32 v91, -v93, v103, v94
	s_mov_b64 vcc, s[0:1]
	v_div_scale_f32 v98, s[6:7], v86, v89, v86
	v_fma_f32 v92, -v95, v104, v96
	v_div_fixup_f32 v68, v90, v75, v68
	v_div_fmas_f32 v75, v91, v99, v103
	s_mov_b64 vcc, s[4:5]
	v_mul_f32_e32 v106, v98, v101
	v_mul_f32_e32 v0, v0, v68
	v_div_fixup_f32 v68, v75, v87, v84
	v_div_fmas_f32 v75, v92, v100, v104
	v_fma_f32 v108, -v97, v106, v98
	v_cvt_pk_bf16_f32 v0, v0, s0
	v_mul_f32_e32 v16, v16, v68
	v_div_fixup_f32 v68, v75, v88, v85
	v_fmac_f32_e32 v106, v108, v101
	global_store_short v[78:79], v0, off
	v_cvt_pk_bf16_f32 v0, v16, s0
	v_mul_f32_e32 v16, v32, v68
	v_fma_f32 v93, -v97, v106, v98
	global_store_short v[80:81], v0, off
	v_cvt_pk_bf16_f32 v0, v16, s0
	s_mov_b64 vcc, s[6:7]
	global_store_short v[82:83], v0, off
	v_div_fmas_f32 v0, v93, v101, v106
	v_div_fixup_f32 v0, v0, v89, v86
	v_mul_f32_e32 v0, v48, v0
	v_cvt_pk_bf16_f32 v0, v0, s0
	global_store_short v[76:77], v0, off
	v_or_b32_e32 v76, 1, v72
	v_ashrrev_i32_e32 v77, 31, v76
	v_lshlrev_b64 v[76:77], 10, v[76:77]
	v_or_b32_e32 v76, v76, v73
	v_lshl_add_u64 v[78:79], s[12:13], 0, v[76:77]
	v_lshl_add_u64 v[80:81], s[14:15], 0, v[76:77]
	v_or_b32_e32 v82, 64, v76
	v_mov_b32_e32 v83, v77
	v_or_b32_e32 v86, 0x80, v76
	v_mov_b32_e32 v87, v77
	v_or_b32_e32 v76, 0xc0, v76
	v_lshl_add_u64 v[84:85], s[12:13], 0, v[82:83]
	v_lshl_add_u64 v[88:89], s[12:13], 0, v[86:87]
	v_lshl_add_u64 v[90:91], s[12:13], 0, v[76:77]
	v_mov_b32_e32 v0, v113
	v_mov_b32_e32 v16, v114
	v_mov_b32_e32 v32, v115
	v_mov_b32_e32 v48, v116
	v_rcp_f32_e32 v75, v69
	v_lshl_add_u64 v[68:69], s[14:15], 0, v[82:83]
	v_lshl_add_u64 v[78:79], s[14:15], 0, v[86:87]
	v_mul_f32_e32 v1, v1, v75
	v_mul_f32_e32 v17, v17, v75
	v_mul_f32_e32 v33, v33, v75
	v_mul_f32_e32 v49, v49, v75
	v_lshlrev_b32_e32 v0, 16, v0
	v_lshlrev_b32_e32 v16, 16, v16
	v_mul_f32_e32 v75, 0xbfb8aa3b, v0
	v_lshlrev_b32_e32 v32, 16, v32
	v_mul_f32_e32 v82, 0xbfb8aa3b, v16
	v_exp_f32_e32 v75, v75
	v_mul_f32_e32 v83, 0xbfb8aa3b, v32
	v_exp_f32_e32 v82, v82
	v_exp_f32_e32 v83, v83
	v_add_f32_e32 v75, 1.0, v75
	v_div_scale_f32 v85, s[0:1], v75, v75, v0
	v_add_f32_e32 v82, 1.0, v82
	v_add_f32_e32 v83, 1.0, v83
	v_div_scale_f32 v87, s[0:1], v82, v82, v16
	v_rcp_f32_e32 v93, v85
	v_lshlrev_b32_e32 v48, 16, v48
	v_div_scale_f32 v89, s[4:5], v83, v83, v32
	v_rcp_f32_e32 v94, v87
	v_mul_f32_e32 v84, 0xbfb8aa3b, v48
	v_rcp_f32_e32 v95, v89
	v_exp_f32_e32 v84, v84
	v_fma_f32 v97, -v85, v93, 1.0
	v_div_scale_f32 v86, vcc, v0, v75, v0
	v_fma_f32 v98, -v87, v94, 1.0
	v_fmac_f32_e32 v93, v97, v93
	v_div_scale_f32 v88, s[0:1], v16, v82, v16
	v_fma_f32 v99, -v89, v95, 1.0
	v_fmac_f32_e32 v94, v98, v94
	v_mul_f32_e32 v97, v86, v93
	v_add_f32_e32 v84, 1.0, v84
	v_div_scale_f32 v90, s[4:5], v32, v83, v32
	v_fmac_f32_e32 v95, v99, v95
	v_mul_f32_e32 v98, v88, v94
	v_fma_f32 v101, -v85, v97, v86
	v_div_scale_f32 v91, s[6:7], v84, v84, v48
	v_mul_f32_e32 v99, v90, v95
	v_fma_f32 v102, -v87, v98, v88
	v_fmac_f32_e32 v97, v101, v93
	v_rcp_f32_e32 v96, v91
	v_fma_f32 v103, -v89, v99, v90
	v_fmac_f32_e32 v98, v102, v94
	v_fma_f32 v85, -v85, v97, v86
	v_fmac_f32_e32 v99, v103, v95
	v_fma_f32 v86, -v87, v98, v88
	v_div_fmas_f32 v85, v85, v93, v97
	s_mov_b64 vcc, s[0:1]
	v_fma_f32 v87, -v89, v99, v90
	v_div_fixup_f32 v0, v85, v75, v0
	v_div_fmas_f32 v75, v86, v94, v98
	s_mov_b64 vcc, s[4:5]
	v_mul_f32_e32 v0, v1, v0
	v_div_fixup_f32 v1, v75, v82, v16
	v_div_fmas_f32 v16, v87, v95, v99
	v_fma_f32 v100, -v91, v96, 1.0
	v_cvt_pk_bf16_f32 v0, v0, s0
	v_mul_f32_e32 v1, v17, v1
	v_div_fixup_f32 v16, v16, v83, v32
	v_div_scale_f32 v92, s[6:7], v48, v84, v48
	v_fmac_f32_e32 v96, v100, v96
	global_store_short v[80:81], v0, off
	v_cvt_pk_bf16_f32 v0, v1, s0
	v_mul_f32_e32 v1, v33, v16
	v_mul_f32_e32 v100, v92, v96
	global_store_short v[68:69], v0, off
	v_cvt_pk_bf16_f32 v0, v1, s0
	global_store_short v[78:79], v0, off
	v_fma_f32 v0, -v91, v100, v92
	v_fmac_f32_e32 v100, v0, v96
	v_fma_f32 v0, -v91, v100, v92
	s_mov_b64 vcc, s[6:7]
	v_div_fmas_f32 v0, v0, v96, v100
	v_div_fixup_f32 v0, v0, v84, v48
	v_mul_f32_e32 v0, v49, v0
	v_cvt_pk_bf16_f32 v16, v0, s0
	v_lshl_add_u64 v[0:1], s[14:15], 0, v[76:77]
	global_store_short v[0:1], v16, off
	v_or_b32_e32 v0, 2, v72
	v_ashrrev_i32_e32 v1, 31, v0
	v_lshlrev_b64 v[0:1], 10, v[0:1]
	v_or_b32_e32 v0, v0, v73
	v_or_b32_e32 v48, 64, v0
	v_mov_b32_e32 v49, v1
	v_or_b32_e32 v76, 0x80, v0
	v_mov_b32_e32 v77, v1
	v_lshl_add_u64 v[16:17], s[12:13], 0, v[0:1]
	v_lshl_add_u64 v[32:33], s[14:15], 0, v[0:1]
	v_lshl_add_u64 v[68:69], s[12:13], 0, v[48:49]
	v_lshl_add_u64 v[78:79], s[12:13], 0, v[76:77]
	v_or_b32_e32 v0, 0xc0, v0
	v_lshl_add_u64 v[80:81], s[12:13], 0, v[0:1]
	v_mov_b32_e32 v75, v117
	s_nop 0
	v_mov_b32_e32 v68, v118
	s_nop 0
	v_mov_b32_e32 v69, v119
	s_nop 0
	v_mov_b32_e32 v78, v120
	v_lshl_add_u64 v[16:17], s[14:15], 0, v[48:49]
	v_lshl_add_u64 v[48:49], s[14:15], 0, v[76:77]
	v_lshl_add_u64 v[0:1], s[14:15], 0, v[0:1]
	v_lshlrev_b32_e32 v70, 16, v75
	v_lshlrev_b32_e32 v68, 16, v68
	v_mul_f32_e32 v76, 0xbfb8aa3b, v70
	v_lshlrev_b32_e32 v69, 16, v69
	v_mul_f32_e32 v77, 0xbfb8aa3b, v68
	v_exp_f32_e32 v76, v76
	v_lshlrev_b32_e32 v75, 16, v78
	v_mul_f32_e32 v78, 0xbfb8aa3b, v69
	v_exp_f32_e32 v77, v77
	v_exp_f32_e32 v78, v78
	v_add_f32_e32 v76, 1.0, v76
	v_div_scale_f32 v80, s[0:1], v76, v76, v70
	v_add_f32_e32 v77, 1.0, v77
	v_add_f32_e32 v78, 1.0, v78
	v_div_scale_f32 v82, s[0:1], v77, v77, v68
	v_rcp_f32_e32 v87, v80
	v_div_scale_f32 v84, s[4:5], v78, v78, v69
	v_rcp_f32_e32 v88, v82
	v_rcp_f32_e32 v89, v84
	v_mul_f32_e32 v79, 0xbfb8aa3b, v75
	v_fma_f32 v91, -v80, v87, 1.0
	v_exp_f32_e32 v79, v79
	v_div_scale_f32 v81, vcc, v70, v76, v70
	v_fma_f32 v92, -v82, v88, 1.0
	v_fmac_f32_e32 v87, v91, v87
	v_div_scale_f32 v83, s[0:1], v68, v77, v68
	v_fma_f32 v93, -v84, v89, 1.0
	v_fmac_f32_e32 v88, v92, v88
	v_mul_f32_e32 v91, v81, v87
	v_div_scale_f32 v85, s[4:5], v69, v78, v69
	v_fmac_f32_e32 v89, v93, v89
	v_mul_f32_e32 v92, v83, v88
	v_fma_f32 v95, -v80, v91, v81
	v_mul_f32_e32 v93, v85, v89
	v_fma_f32 v96, -v82, v92, v83
	v_fmac_f32_e32 v91, v95, v87
	v_add_f32_e32 v79, 1.0, v79
	v_fma_f32 v97, -v84, v93, v85
	v_fmac_f32_e32 v92, v96, v88
	v_fma_f32 v80, -v80, v91, v81
	v_div_scale_f32 v86, s[6:7], v79, v79, v75
	v_fmac_f32_e32 v93, v97, v89
	v_fma_f32 v81, -v82, v92, v83
	v_div_fmas_f32 v80, v80, v87, v91
	s_mov_b64 vcc, s[0:1]
	v_rcp_f32_e32 v90, v86
	v_fma_f32 v82, -v84, v93, v85
	v_div_fixup_f32 v70, v80, v76, v70
	v_div_fmas_f32 v76, v81, v88, v92
	s_mov_b64 vcc, s[4:5]
	v_mul_f32_e32 v2, v2, v70
	v_div_fixup_f32 v68, v76, v77, v68
	v_div_fmas_f32 v70, v82, v89, v93
	v_cvt_pk_bf16_f32 v2, v2, s0
	v_mul_f32_e32 v18, v18, v68
	v_div_fixup_f32 v68, v70, v78, v69
	global_store_short v[32:33], v2, off
	v_cvt_pk_bf16_f32 v2, v18, s0
	v_mul_f32_e32 v18, v34, v68
	v_fma_f32 v94, -v86, v90, 1.0
	global_store_short v[16:17], v2, off
	v_cvt_pk_bf16_f32 v2, v18, s0
	global_store_short v[48:49], v2, off
	v_fmac_f32_e32 v90, v94, v90
	v_div_scale_f32 v2, vcc, v75, v79, v75
	v_mul_f32_e32 v16, v2, v90
	v_fma_f32 v17, -v86, v16, v2
	v_fmac_f32_e32 v16, v17, v90
	v_fma_f32 v2, -v86, v16, v2
	v_div_fmas_f32 v2, v2, v90, v16
	v_div_fixup_f32 v2, v2, v79, v75
	v_mul_f32_e32 v2, v50, v2
	v_cvt_pk_bf16_f32 v2, v2, s0
	global_store_short v[0:1], v2, off
	v_or_b32_e32 v0, 3, v72
	v_ashrrev_i32_e32 v1, 31, v0
	v_lshlrev_b64 v[0:1], 10, v[0:1]
	v_or_b32_e32 v0, v0, v73
	v_lshl_add_u64 v[16:17], s[12:13], 0, v[0:1]
	v_lshl_add_u64 v[32:33], s[14:15], 0, v[0:1]
	v_or_b32_e32 v48, 64, v0
	v_mov_b32_e32 v49, v1
	v_or_b32_e32 v76, 0x80, v0
	v_mov_b32_e32 v77, v1
	v_or_b32_e32 v0, 0xc0, v0
	v_lshl_add_u64 v[68:69], s[12:13], 0, v[48:49]
	v_lshl_add_u64 v[78:79], s[12:13], 0, v[76:77]
	v_lshl_add_u64 v[80:81], s[12:13], 0, v[0:1]
	v_mov_b32_e32 v2, v121
	v_mov_b32_e32 v18, v122
	v_mov_b32_e32 v34, v123
	v_mov_b32_e32 v50, v124
	v_lshl_add_u64 v[16:17], s[14:15], 0, v[48:49]
	v_rcp_f32_e32 v68, v71
	v_lshl_add_u64 v[0:1], s[14:15], 0, v[0:1]
	v_mul_f32_e32 v3, v3, v68
	v_mul_f32_e32 v19, v19, v68
	v_mul_f32_e32 v35, v35, v68
	v_lshlrev_b32_e32 v2, 16, v2
	v_lshlrev_b32_e32 v18, 16, v18
	v_mul_f32_e32 v49, 0xbfb8aa3b, v2
	v_lshlrev_b32_e32 v48, 16, v50
	v_mul_f32_e32 v50, 0xbfb8aa3b, v18
	v_exp_f32_e32 v49, v49
	v_exp_f32_e32 v50, v50
	v_lshlrev_b32_e32 v34, 16, v34
	v_mul_f32_e32 v69, 0xbfb8aa3b, v34
	v_add_f32_e32 v49, 1.0, v49
	v_exp_f32_e32 v69, v69
	v_add_f32_e32 v50, 1.0, v50
	v_div_scale_f32 v71, s[0:1], v49, v49, v2
	v_div_scale_f32 v78, s[0:1], v50, v50, v18
	v_rcp_f32_e32 v82, v71
	v_rcp_f32_e32 v83, v78
	v_add_f32_e32 v69, 1.0, v69
	v_div_scale_f32 v80, s[4:5], v69, v69, v34
	v_fma_f32 v86, -v71, v82, 1.0
	v_div_scale_f32 v75, vcc, v2, v49, v2
	v_rcp_f32_e32 v84, v80
	v_fma_f32 v87, -v78, v83, 1.0
	v_fmac_f32_e32 v82, v86, v82
	v_div_scale_f32 v79, s[0:1], v18, v50, v18
	v_fmac_f32_e32 v83, v87, v83
	v_mul_f32_e32 v86, v75, v82
	v_mul_f32_e32 v87, v79, v83
	v_fma_f32 v89, -v71, v86, v75
	v_mul_f32_e32 v70, 0xbfb8aa3b, v48
	v_fma_f32 v90, -v78, v87, v79
	v_fmac_f32_e32 v86, v89, v82
	v_exp_f32_e32 v70, v70
	v_fma_f32 v88, -v80, v84, 1.0
	v_fmac_f32_e32 v87, v90, v83
	v_fma_f32 v71, -v71, v86, v75
	v_div_scale_f32 v81, s[4:5], v34, v69, v34
	v_fmac_f32_e32 v84, v88, v84
	v_fma_f32 v75, -v78, v87, v79
	v_div_fmas_f32 v71, v71, v82, v86
	s_mov_b64 vcc, s[0:1]
	v_mul_f32_e32 v88, v81, v84
	v_div_fixup_f32 v2, v71, v49, v2
	v_div_fmas_f32 v49, v75, v83, v87
	v_fma_f32 v91, -v80, v88, v81
	v_mul_f32_e32 v2, v3, v2
	v_div_fixup_f32 v3, v49, v50, v18
	v_add_f32_e32 v70, 1.0, v70
	v_fmac_f32_e32 v88, v91, v84
	v_cvt_pk_bf16_f32 v2, v2, s0
	v_mul_f32_e32 v3, v19, v3
	v_div_scale_f32 v85, s[6:7], v70, v70, v48
	v_fma_f32 v78, -v80, v88, v81
	s_mov_b64 vcc, s[4:5]
	global_store_short v[32:33], v2, off
	v_cvt_pk_bf16_f32 v2, v3, s0
	v_div_fmas_f32 v18, v78, v84, v88
	global_store_short v[16:17], v2, off
	v_rcp_f32_e32 v17, v85
	v_div_fixup_f32 v18, v18, v69, v34
	v_mul_f32_e32 v3, v35, v18
	v_cvt_pk_bf16_f32 v16, v3, s0
	v_lshl_add_u64 v[2:3], s[14:15], 0, v[76:77]
	global_store_short v[2:3], v16, off
	v_fma_f32 v3, -v85, v17, 1.0
	v_fmac_f32_e32 v17, v3, v17
	v_div_scale_f32 v3, vcc, v48, v70, v48
	v_mul_f32_e32 v16, v3, v17
	v_fma_f32 v18, -v85, v16, v3
	v_fmac_f32_e32 v16, v18, v17
	v_fma_f32 v3, -v85, v16, v3
	v_div_fmas_f32 v3, v3, v17, v16
	v_mul_f32_e32 v2, v51, v68
	v_div_fixup_f32 v3, v3, v70, v48
	v_mul_f32_e32 v2, v2, v3
	v_cvt_pk_bf16_f32 v2, v2, s0
	global_store_short v[0:1], v2, off
	v_or_b32_e32 v0, 8, v72
	v_ashrrev_i32_e32 v1, 31, v0
	v_lshlrev_b64 v[0:1], 10, v[0:1]
	v_or_b32_e32 v0, v0, v73
	v_or_b32_e32 v18, 64, v0
	v_mov_b32_e32 v19, v1
	v_or_b32_e32 v34, 0x80, v0
	v_mov_b32_e32 v35, v1
	v_lshl_add_u64 v[2:3], s[12:13], 0, v[0:1]
	v_lshl_add_u64 v[16:17], s[14:15], 0, v[0:1]
	v_lshl_add_u64 v[32:33], s[12:13], 0, v[18:19]
	v_lshl_add_u64 v[48:49], s[12:13], 0, v[34:35]
	v_or_b32_e32 v0, 0xc0, v0
	v_lshl_add_u64 v[50:51], s[12:13], 0, v[0:1]
	v_mov_b32_e32 v68, v125
	s_nop 0
	v_mov_b32_e32 v32, v126
	s_nop 0
	v_mov_b32_e32 v33, v127
	s_nop 0
	v_mov_b32_e32 v48, v128
	s_waitcnt lgkmcnt(0)
	v_rcp_f32_e32 v49, v64
	v_lshl_add_u64 v[2:3], s[14:15], 0, v[18:19]
	v_lshl_add_u64 v[0:1], s[14:15], 0, v[0:1]
	v_mul_f32_e32 v18, v20, v49
	v_mul_f32_e32 v19, v36, v49
	v_mul_f32_e32 v4, v4, v49
	v_lshlrev_b32_e32 v20, 16, v68
	v_lshlrev_b32_e32 v32, 16, v32
	v_lshlrev_b32_e32 v33, 16, v33
	v_lshlrev_b32_e32 v36, 16, v48
	v_mul_f32_e32 v48, 0xbfb8aa3b, v20
	v_mul_f32_e32 v50, 0xbfb8aa3b, v32
	v_exp_f32_e32 v48, v48
	v_mul_f32_e32 v51, 0xbfb8aa3b, v33
	v_exp_f32_e32 v50, v50
	v_exp_f32_e32 v51, v51
	v_add_f32_e32 v48, 1.0, v48
	v_div_scale_f32 v68, s[0:1], v48, v48, v20
	v_add_f32_e32 v50, 1.0, v50
	v_add_f32_e32 v51, 1.0, v51
	v_div_scale_f32 v70, s[0:1], v50, v50, v32
	v_rcp_f32_e32 v76, v68
	v_div_scale_f32 v75, s[4:5], v51, v51, v33
	v_rcp_f32_e32 v77, v70
	v_rcp_f32_e32 v78, v75
	v_fma_f32 v80, -v68, v76, 1.0
	v_div_scale_f32 v69, vcc, v20, v48, v20
	v_fma_f32 v81, -v70, v77, 1.0
	v_fmac_f32_e32 v76, v80, v76
	v_div_scale_f32 v71, s[0:1], v32, v50, v32
	v_fma_f32 v82, -v75, v78, 1.0
	v_fmac_f32_e32 v77, v81, v77
	v_mul_f32_e32 v80, v69, v76
	v_div_scale_f32 v79, s[4:5], v33, v51, v33
	v_fmac_f32_e32 v78, v82, v78
	v_mul_f32_e32 v81, v71, v77
	v_fma_f32 v83, -v68, v80, v69
	v_mul_f32_e32 v82, v79, v78
	v_fma_f32 v84, -v70, v81, v71
	v_fmac_f32_e32 v80, v83, v76
	v_fma_f32 v85, -v75, v82, v79
	v_fmac_f32_e32 v81, v84, v77
	v_fma_f32 v68, -v68, v80, v69
	v_mul_f32_e32 v64, 0xbfb8aa3b, v36
	v_fmac_f32_e32 v82, v85, v78
	v_fma_f32 v69, -v70, v81, v71
	v_div_fmas_f32 v68, v68, v76, v80
	s_mov_b64 vcc, s[0:1]
	v_exp_f32_e32 v64, v64
	v_fma_f32 v70, -v75, v82, v79
	v_div_fixup_f32 v20, v68, v48, v20
	v_div_fmas_f32 v48, v69, v77, v81
	s_mov_b64 vcc, s[4:5]
	v_mul_f32_e32 v4, v4, v20
	v_div_fixup_f32 v20, v48, v50, v32
	v_div_fmas_f32 v32, v70, v78, v82
	v_cvt_pk_bf16_f32 v4, v4, s0
	v_mul_f32_e32 v18, v18, v20
	v_div_fixup_f32 v20, v32, v51, v33
	global_store_short v[16:17], v4, off
	v_cvt_pk_bf16_f32 v4, v18, s0
	v_mul_f32_e32 v16, v19, v20
	global_store_short v[2:3], v4, off
	v_cvt_pk_bf16_f32 v4, v16, s0
	v_add_f32_e32 v16, 1.0, v64
	v_div_scale_f32 v17, s[0:1], v16, v16, v36
	v_rcp_f32_e32 v18, v17
	v_lshl_add_u64 v[2:3], s[14:15], 0, v[34:35]
	global_store_short v[2:3], v4, off
	v_mul_f32_e32 v2, v52, v49
	v_fma_f32 v3, -v17, v18, 1.0
	v_fmac_f32_e32 v18, v3, v18
	v_div_scale_f32 v3, vcc, v36, v16, v36
	v_mul_f32_e32 v4, v3, v18
	v_fma_f32 v19, -v17, v4, v3
	v_fmac_f32_e32 v4, v19, v18
	v_fma_f32 v3, -v17, v4, v3
	v_div_fmas_f32 v3, v3, v18, v4
	v_div_fixup_f32 v3, v3, v16, v36
	v_mul_f32_e32 v2, v2, v3
	v_cvt_pk_bf16_f32 v2, v2, s0
	global_store_short v[0:1], v2, off
	v_or_b32_e32 v0, 9, v72
	v_ashrrev_i32_e32 v1, 31, v0
	v_lshlrev_b64 v[0:1], 10, v[0:1]
	v_or_b32_e32 v0, v0, v73
	v_or_b32_e32 v32, 0x80, v0
	v_mov_b32_e32 v33, v1
	v_lshl_add_u64 v[2:3], s[12:13], 0, v[0:1]
	v_or_b32_e32 v16, 64, v0
	v_mov_b32_e32 v17, v1
	v_lshl_add_u64 v[34:35], s[12:13], 0, v[32:33]
	v_lshl_add_u64 v[18:19], s[12:13], 0, v[16:17]
	v_mov_b32_e32 v4, v129
	v_mov_b32_e32 v20, v130
	s_nop 0
	v_mov_b32_e32 v34, v131
	v_lshl_add_u64 v[2:3], s[14:15], 0, v[0:1]
	v_or_b32_e32 v0, 0xc0, v0
	v_lshl_add_u64 v[18:19], s[12:13], 0, v[0:1]
	v_mov_b32_e32 v18, v132
	v_rcp_f32_e32 v19, v65
	v_lshl_add_u64 v[16:17], s[14:15], 0, v[16:17]
	v_lshl_add_u64 v[0:1], s[14:15], 0, v[0:1]
	v_mul_f32_e32 v35, v37, v19
	v_mul_f32_e32 v5, v5, v19
	v_mul_f32_e32 v21, v21, v19
	v_lshlrev_b32_e32 v4, 16, v4
	v_lshlrev_b32_e32 v20, 16, v20
	v_mul_f32_e32 v36, 0xbfb8aa3b, v4
	v_mul_f32_e32 v37, 0xbfb8aa3b, v20
	v_exp_f32_e32 v36, v36
	v_exp_f32_e32 v37, v37
	v_lshlrev_b32_e32 v34, 16, v34
	v_mul_f32_e32 v48, 0xbfb8aa3b, v34
	v_add_f32_e32 v36, 1.0, v36
	v_add_f32_e32 v37, 1.0, v37
	v_div_scale_f32 v49, s[0:1], v36, v36, v4
	v_div_scale_f32 v51, s[0:1], v37, v37, v20
	v_rcp_f32_e32 v65, v49
	v_rcp_f32_e32 v68, v51
	v_exp_f32_e32 v48, v48
	v_div_scale_f32 v50, vcc, v4, v36, v4
	v_fma_f32 v71, -v49, v65, 1.0
	v_fma_f32 v75, -v51, v68, 1.0
	v_fmac_f32_e32 v65, v71, v65
	v_add_f32_e32 v48, 1.0, v48
	v_div_scale_f32 v52, s[0:1], v20, v37, v20
	v_fmac_f32_e32 v68, v75, v68
	v_mul_f32_e32 v71, v50, v65
	v_div_scale_f32 v64, s[4:5], v48, v48, v34
	v_mul_f32_e32 v75, v52, v68
	v_fma_f32 v77, -v49, v71, v50
	v_rcp_f32_e32 v69, v64
	v_fma_f32 v78, -v51, v75, v52
	v_fmac_f32_e32 v71, v77, v65
	v_fmac_f32_e32 v75, v78, v68
	v_fma_f32 v49, -v49, v71, v50
	v_fma_f32 v50, -v51, v75, v52
	v_div_fmas_f32 v49, v49, v65, v71
	s_mov_b64 vcc, s[0:1]
	v_div_fixup_f32 v4, v49, v36, v4
	v_div_fmas_f32 v36, v50, v68, v75
	v_fma_f32 v76, -v64, v69, 1.0
	v_mul_f32_e32 v4, v5, v4
	v_div_fixup_f32 v5, v36, v37, v20
	v_div_scale_f32 v70, s[4:5], v34, v48, v34
	v_fmac_f32_e32 v69, v76, v69
	v_cvt_pk_bf16_f32 v4, v4, s0
	v_mul_f32_e32 v5, v21, v5
	v_lshlrev_b32_e32 v18, 16, v18
	v_mul_f32_e32 v76, v70, v69
	global_store_short v[2:3], v4, off
	v_cvt_pk_bf16_f32 v2, v5, s0
	v_fma_f32 v79, -v64, v76, v70
	global_store_short v[16:17], v2, off
	v_mul_f32_e32 v2, 0xbfb8aa3b, v18
	v_fmac_f32_e32 v76, v79, v69
	v_exp_f32_e32 v2, v2
	v_fma_f32 v51, -v64, v76, v70
	s_mov_b64 vcc, s[4:5]
	v_div_fmas_f32 v20, v51, v69, v76
	v_div_fixup_f32 v3, v20, v48, v34
	v_mul_f32_e32 v3, v35, v3
	v_add_f32_e32 v5, 1.0, v2
	v_cvt_pk_bf16_f32 v4, v3, s0
	v_div_scale_f32 v16, s[0:1], v5, v5, v18
	v_rcp_f32_e32 v17, v16
	v_lshl_add_u64 v[2:3], s[14:15], 0, v[32:33]
	global_store_short v[2:3], v4, off
	v_mul_f32_e32 v2, v53, v19
	v_fma_f32 v3, -v16, v17, 1.0
	v_fmac_f32_e32 v17, v3, v17
	v_div_scale_f32 v3, vcc, v18, v5, v18
	v_mul_f32_e32 v4, v3, v17
	v_fma_f32 v19, -v16, v4, v3
	v_fmac_f32_e32 v4, v19, v17
	v_fma_f32 v3, -v16, v4, v3
	v_div_fmas_f32 v3, v3, v17, v4
	v_div_fixup_f32 v3, v3, v5, v18
	v_mul_f32_e32 v2, v2, v3
	v_cvt_pk_bf16_f32 v2, v2, s0
	global_store_short v[0:1], v2, off
	v_or_b32_e32 v0, 10, v72
	v_ashrrev_i32_e32 v1, 31, v0
	v_lshlrev_b64 v[0:1], 10, v[0:1]
	v_or_b32_e32 v0, v0, v73
	v_or_b32_e32 v18, 0x80, v0
	v_mov_b32_e32 v19, v1
	v_lshl_add_u64 v[2:3], s[12:13], 0, v[0:1]
	v_or_b32_e32 v4, 64, v0
	v_mov_b32_e32 v5, v1
	v_lshl_add_u64 v[20:21], s[12:13], 0, v[18:19]
	v_lshl_add_u64 v[16:17], s[12:13], 0, v[4:5]
	v_mov_b32_e32 v32, v133
	v_mov_b32_e32 v33, v134
	s_nop 0
	v_mov_b32_e32 v20, v135
	v_lshl_add_u64 v[2:3], s[14:15], 0, v[0:1]
	v_or_b32_e32 v0, 0xc0, v0
	v_lshl_add_u64 v[16:17], s[12:13], 0, v[0:1]
	v_mov_b32_e32 v16, v136
	v_rcp_f32_e32 v17, v66
	v_lshl_add_u64 v[4:5], s[14:15], 0, v[4:5]
	v_lshl_add_u64 v[0:1], s[14:15], 0, v[0:1]
	v_mul_f32_e32 v21, v22, v17
	v_mul_f32_e32 v36, v38, v17
	v_mul_f32_e32 v6, v6, v17
	v_lshlrev_b32_e32 v22, 16, v32
	v_lshlrev_b32_e32 v32, 16, v33
	v_mul_f32_e32 v33, 0xbfb8aa3b, v22
	v_mul_f32_e32 v34, 0xbfb8aa3b, v32
	v_exp_f32_e32 v33, v33
	v_exp_f32_e32 v34, v34
	v_lshlrev_b32_e32 v20, 16, v20
	v_mul_f32_e32 v35, 0xbfb8aa3b, v20
	v_add_f32_e32 v33, 1.0, v33
	v_add_f32_e32 v34, 1.0, v34
	v_div_scale_f32 v37, s[0:1], v33, v33, v22
	v_div_scale_f32 v48, s[0:1], v34, v34, v32
	v_rcp_f32_e32 v51, v37
	v_rcp_f32_e32 v52, v48
	v_exp_f32_e32 v35, v35
	v_div_scale_f32 v38, vcc, v22, v33, v22
	v_fma_f32 v65, -v37, v51, 1.0
	v_fma_f32 v66, -v48, v52, 1.0
	v_fmac_f32_e32 v51, v65, v51
	v_div_scale_f32 v49, s[0:1], v32, v34, v32
	v_fmac_f32_e32 v52, v66, v52
	v_mul_f32_e32 v65, v38, v51
	v_add_f32_e32 v35, 1.0, v35
	v_mul_f32_e32 v66, v49, v52
	v_fma_f32 v69, -v37, v65, v38
	v_div_scale_f32 v50, s[4:5], v35, v35, v20
	v_fma_f32 v70, -v48, v66, v49
	v_fmac_f32_e32 v65, v69, v51
	v_rcp_f32_e32 v53, v50
	v_fmac_f32_e32 v66, v70, v52
	v_fma_f32 v37, -v37, v65, v38
	v_fma_f32 v38, -v48, v66, v49
	v_div_fmas_f32 v37, v37, v51, v65
	s_mov_b64 vcc, s[0:1]
	v_div_fixup_f32 v22, v37, v33, v22
	v_div_fmas_f32 v33, v38, v52, v66
	v_mul_f32_e32 v6, v6, v22
	v_div_fixup_f32 v22, v33, v34, v32
	v_fma_f32 v68, -v50, v53, 1.0
	v_cvt_pk_bf16_f32 v6, v6, s0
	v_mul_f32_e32 v21, v21, v22
	v_div_scale_f32 v64, s[4:5], v20, v35, v20
	v_fmac_f32_e32 v53, v68, v53
	global_store_short v[2:3], v6, off
	v_cvt_pk_bf16_f32 v2, v21, s0
	v_mul_f32_e32 v68, v64, v53
	global_store_short v[4:5], v2, off
	v_lshlrev_b32_e32 v4, 16, v16
	v_fma_f32 v71, -v50, v68, v64
	v_mul_f32_e32 v3, 0xbfb8aa3b, v4
	v_fmac_f32_e32 v68, v71, v53
	v_exp_f32_e32 v3, v3
	v_fma_f32 v2, -v50, v68, v64
	s_mov_b64 vcc, s[4:5]
	v_div_fmas_f32 v2, v2, v53, v68
	v_div_fixup_f32 v2, v2, v35, v20
	v_mul_f32_e32 v2, v36, v2
	v_add_f32_e32 v6, 1.0, v3
	v_cvt_pk_bf16_f32 v5, v2, s0
	v_div_scale_f32 v16, s[0:1], v6, v6, v4
	v_rcp_f32_e32 v20, v16
	v_lshl_add_u64 v[2:3], s[14:15], 0, v[18:19]
	global_store_short v[2:3], v5, off
	v_mul_f32_e32 v2, v54, v17
	v_fma_f32 v3, -v16, v20, 1.0
	v_fmac_f32_e32 v20, v3, v20
	v_div_scale_f32 v3, vcc, v4, v6, v4
	v_mul_f32_e32 v5, v3, v20
	v_fma_f32 v17, -v16, v5, v3
	v_fmac_f32_e32 v5, v17, v20
	v_fma_f32 v3, -v16, v5, v3
	v_div_fmas_f32 v3, v3, v20, v5
	v_div_fixup_f32 v3, v3, v6, v4
	v_mul_f32_e32 v2, v2, v3
	v_cvt_pk_bf16_f32 v2, v2, s0
	global_store_short v[0:1], v2, off
	v_or_b32_e32 v0, 11, v72
	v_ashrrev_i32_e32 v1, 31, v0
	v_lshlrev_b64 v[0:1], 10, v[0:1]
	v_or_b32_e32 v0, v0, v73
	v_or_b32_e32 v18, 0x80, v0
	v_mov_b32_e32 v19, v1
	v_lshl_add_u64 v[2:3], s[12:13], 0, v[0:1]
	v_or_b32_e32 v4, 64, v0
	v_mov_b32_e32 v5, v1
	v_lshl_add_u64 v[20:21], s[12:13], 0, v[18:19]
	v_lshl_add_u64 v[16:17], s[12:13], 0, v[4:5]
	v_mov_b32_e32 v6, v137
	v_mov_b32_e32 v22, v138
	s_nop 0
	v_mov_b32_e32 v20, v139
	v_lshl_add_u64 v[2:3], s[14:15], 0, v[0:1]
	v_or_b32_e32 v0, 0xc0, v0
	v_lshl_add_u64 v[16:17], s[12:13], 0, v[0:1]
	v_mov_b32_e32 v16, v140
	v_rcp_f32_e32 v17, v67
	v_lshl_add_u64 v[4:5], s[14:15], 0, v[4:5]
	v_lshl_add_u64 v[0:1], s[14:15], 0, v[0:1]
	v_mul_f32_e32 v21, v23, v17
	v_mul_f32_e32 v34, v39, v17
	v_mul_f32_e32 v7, v7, v17
	v_lshlrev_b32_e32 v6, 16, v6
	v_lshlrev_b32_e32 v22, 16, v22
	v_mul_f32_e32 v23, 0xbfb8aa3b, v6
	v_lshlrev_b32_e32 v20, 16, v20
	v_mul_f32_e32 v32, 0xbfb8aa3b, v22
	v_exp_f32_e32 v23, v23
	v_mul_f32_e32 v33, 0xbfb8aa3b, v20
	v_exp_f32_e32 v32, v32
	v_exp_f32_e32 v33, v33
	v_add_f32_e32 v23, 1.0, v23
	v_div_scale_f32 v35, s[0:1], v23, v23, v6
	v_add_f32_e32 v32, 1.0, v32
	v_add_f32_e32 v33, 1.0, v33
	v_div_scale_f32 v37, s[0:1], v32, v32, v22
	v_rcp_f32_e32 v39, v35
	v_div_scale_f32 v38, s[0:1], v33, v33, v20
	v_rcp_f32_e32 v48, v37
	v_rcp_f32_e32 v49, v38
	v_fma_f32 v51, -v35, v39, 1.0
	v_div_scale_f32 v36, vcc, v6, v23, v6
	v_fma_f32 v52, -v37, v48, 1.0
	v_fmac_f32_e32 v39, v51, v39
	v_div_scale_f32 v50, s[0:1], v22, v32, v22
	v_fma_f32 v53, -v38, v49, 1.0
	v_fmac_f32_e32 v48, v52, v48
	v_mul_f32_e32 v51, v36, v39
	v_fmac_f32_e32 v49, v53, v49
	v_mul_f32_e32 v52, v50, v48
	v_fma_f32 v53, -v35, v51, v36
	v_fma_f32 v54, -v37, v52, v50
	v_fmac_f32_e32 v51, v53, v39
	v_fmac_f32_e32 v52, v54, v48
	v_fma_f32 v35, -v35, v51, v36
	v_fma_f32 v36, -v37, v52, v50
	v_div_fmas_f32 v35, v35, v39, v51
	s_mov_b64 vcc, s[0:1]
	v_div_fixup_f32 v6, v35, v23, v6
	v_div_fmas_f32 v23, v36, v48, v52
	v_mul_f32_e32 v6, v7, v6
	v_div_fixup_f32 v7, v23, v32, v22
	v_cvt_pk_bf16_f32 v6, v6, s0
	v_mul_f32_e32 v7, v21, v7
	global_store_short v[2:3], v6, off
	v_cvt_pk_bf16_f32 v2, v7, s0
	global_store_short v[4:5], v2, off
	v_div_scale_f32 v2, vcc, v20, v33, v20
	v_mul_f32_e32 v3, v2, v49
	v_fma_f32 v4, -v38, v3, v2
	v_fmac_f32_e32 v3, v4, v49
	v_fma_f32 v2, -v38, v3, v2
	v_lshlrev_b32_e32 v4, 16, v16
	v_div_fmas_f32 v2, v2, v49, v3
	v_mul_f32_e32 v3, 0xbfb8aa3b, v4
	v_exp_f32_e32 v3, v3
	v_div_fixup_f32 v2, v2, v33, v20
	v_mul_f32_e32 v2, v34, v2
	v_cvt_pk_bf16_f32 v5, v2, s0
	v_add_f32_e32 v6, 1.0, v3
	v_div_scale_f32 v7, s[0:1], v6, v6, v4
	v_rcp_f32_e32 v16, v7
	v_lshl_add_u64 v[2:3], s[14:15], 0, v[18:19]
	global_store_short v[2:3], v5, off
	v_mul_f32_e32 v2, v55, v17
	v_fma_f32 v3, -v7, v16, 1.0
	v_fmac_f32_e32 v16, v3, v16
	v_div_scale_f32 v3, vcc, v4, v6, v4
	v_mul_f32_e32 v5, v3, v16
	v_fma_f32 v17, -v7, v5, v3
	v_fmac_f32_e32 v5, v17, v16
	v_fma_f32 v3, -v7, v5, v3
	v_div_fmas_f32 v3, v3, v16, v5
	v_div_fixup_f32 v3, v3, v6, v4
	v_mul_f32_e32 v2, v2, v3
	v_cvt_pk_bf16_f32 v2, v2, s0
	global_store_short v[0:1], v2, off
	v_or_b32_e32 v0, 16, v72
	v_ashrrev_i32_e32 v1, 31, v0
	v_lshlrev_b64 v[16:17], 10, v[0:1]
	v_or_b32_e32 v16, v16, v73
	v_lshl_add_u64 v[0:1], s[12:13], 0, v[16:17]
	v_or_b32_e32 v18, 64, v16
	v_mov_b32_e32 v19, v17
	v_or_b32_e32 v20, 0x80, v16
	v_mov_b32_e32 v21, v17
	v_lshl_add_u64 v[2:3], s[12:13], 0, v[18:19]
	v_lshl_add_u64 v[4:5], s[12:13], 0, v[20:21]
	v_mov_b32_e32 v32, v141
	v_mov_b32_e32 v33, v142
	v_mov_b32_e32 v34, v143
	v_lshl_add_u64 v[22:23], s[14:15], 0, v[16:17]
	v_or_b32_e32 v16, 0xc0, v16
	v_lshl_add_u64 v[0:1], s[12:13], 0, v[16:17]
	v_mov_b32_e32 v35, v144
	ds_read_b128 v[4:7], v74 offset:64
	ds_read_b128 v[0:3], v74 offset:96
	v_lshl_add_u64 v[18:19], s[14:15], 0, v[18:19]
	v_lshl_add_u64 v[16:17], s[14:15], 0, v[16:17]
	s_waitcnt lgkmcnt(1)
	v_rcp_f32_e32 v4, v4
	v_rcp_f32_e32 v6, v6
	s_waitcnt lgkmcnt(0)
	v_rcp_f32_e32 v0, v0
	v_rcp_f32_e32 v2, v2
	v_mul_f32_e32 v8, v8, v4
	v_mul_f32_e32 v24, v24, v4
	v_mul_f32_e32 v10, v10, v6
	v_mul_f32_e32 v26, v26, v6
	v_mul_f32_e32 v12, v12, v0
	v_mul_f32_e32 v14, v14, v2
	v_lshlrev_b32_e32 v32, 16, v32
	v_mul_f32_e32 v36, 0xbfb8aa3b, v32
	v_exp_f32_e32 v36, v36
	v_lshlrev_b32_e32 v33, 16, v33
	v_mul_f32_e32 v37, 0xbfb8aa3b, v33
	v_exp_f32_e32 v37, v37
	v_add_f32_e32 v36, 1.0, v36
	v_div_scale_f32 v39, s[0:1], v36, v36, v32
	v_rcp_f32_e32 v51, v39
	v_add_f32_e32 v37, 1.0, v37
	v_div_scale_f32 v49, s[0:1], v37, v37, v33
	v_rcp_f32_e32 v52, v49
	v_fma_f32 v54, -v39, v51, 1.0
	v_div_scale_f32 v48, vcc, v32, v36, v32
	v_fmac_f32_e32 v51, v54, v51
	v_lshlrev_b32_e32 v34, 16, v34
	v_mul_f32_e32 v54, v48, v51
	v_mul_f32_e32 v38, 0xbfb8aa3b, v34
	v_fma_f32 v64, -v39, v54, v48
	v_exp_f32_e32 v38, v38
	v_fma_f32 v55, -v49, v52, 1.0
	v_fmac_f32_e32 v54, v64, v51
	v_div_scale_f32 v50, s[0:1], v33, v37, v33
	v_fmac_f32_e32 v52, v55, v52
	v_fma_f32 v39, -v39, v54, v48
	v_mul_f32_e32 v55, v50, v52
	v_div_fmas_f32 v39, v39, v51, v54
	v_fma_f32 v65, -v49, v55, v50
	v_div_fixup_f32 v32, v39, v36, v32
	v_add_f32_e32 v38, 1.0, v38
	v_fmac_f32_e32 v55, v65, v52
	v_mul_f32_e32 v8, v8, v32
	v_div_scale_f32 v53, s[4:5], v38, v38, v34
	v_fma_f32 v48, -v49, v55, v50
	s_mov_b64 vcc, s[0:1]
	v_cvt_pk_bf16_f32 v8, v8, s0
	v_div_fmas_f32 v36, v48, v52, v55
	global_store_short v[22:23], v8, off
	v_rcp_f32_e32 v22, v53
	v_div_fixup_f32 v32, v36, v37, v33
	v_mul_f32_e32 v24, v24, v32
	v_cvt_pk_bf16_f32 v8, v24, s0
	global_store_short v[18:19], v8, off
	v_fma_f32 v18, -v53, v22, 1.0
	v_fmac_f32_e32 v22, v18, v22
	v_div_scale_f32 v18, vcc, v34, v38, v34
	v_mul_f32_e32 v19, v18, v22
	v_fma_f32 v23, -v53, v19, v18
	v_fmac_f32_e32 v19, v23, v22
	v_fma_f32 v18, -v53, v19, v18
	v_div_fmas_f32 v18, v18, v22, v19
	v_lshlrev_b32_e32 v22, 16, v35
	v_mul_f32_e32 v19, 0xbfb8aa3b, v22
	v_exp_f32_e32 v19, v19
	v_mul_f32_e32 v8, v40, v4
	v_div_fixup_f32 v18, v18, v38, v34
	v_mul_f32_e32 v8, v8, v18
	v_add_f32_e32 v23, 1.0, v19
	v_cvt_pk_bf16_f32 v8, v8, s0
	v_div_scale_f32 v24, s[0:1], v23, v23, v22
	v_rcp_f32_e32 v32, v24
	v_lshl_add_u64 v[18:19], s[14:15], 0, v[20:21]
	global_store_short v[18:19], v8, off
	v_mul_f32_e32 v4, v56, v4
	v_fma_f32 v8, -v24, v32, 1.0
	v_fmac_f32_e32 v32, v8, v32
	v_div_scale_f32 v8, vcc, v22, v23, v22
	v_mul_f32_e32 v18, v8, v32
	v_fma_f32 v19, -v24, v18, v8
	v_fmac_f32_e32 v18, v19, v32
	v_fma_f32 v8, -v24, v18, v8
	v_div_fmas_f32 v8, v8, v32, v18
	v_div_fixup_f32 v8, v8, v23, v22
	v_mul_f32_e32 v4, v4, v8
	v_cvt_pk_bf16_f32 v4, v4, s0
	global_store_short v[16:17], v4, off
	v_or_b32_e32 v16, 17, v72
	v_ashrrev_i32_e32 v17, 31, v16
	v_lshlrev_b64 v[16:17], 10, v[16:17]
	v_or_b32_e32 v16, v16, v73
	v_lshl_add_u64 v[18:19], s[12:13], 0, v[16:17]
	v_or_b32_e32 v20, 64, v16
	v_mov_b32_e32 v21, v17
	v_or_b32_e32 v32, 0x80, v16
	v_mov_b32_e32 v33, v17
	v_lshl_add_u64 v[22:23], s[12:13], 0, v[20:21]
	v_lshl_add_u64 v[34:35], s[12:13], 0, v[32:33]
	v_mov_b32_e32 v4, v145
	v_mov_b32_e32 v8, v146
	v_mov_b32_e32 v24, v147
	v_lshl_add_u64 v[18:19], s[14:15], 0, v[16:17]
	v_or_b32_e32 v16, 0xc0, v16
	v_lshl_add_u64 v[22:23], s[12:13], 0, v[16:17]
	v_mov_b32_e32 v22, v148
	v_rcp_f32_e32 v23, v5
	v_lshlrev_b32_e32 v4, 16, v4
	v_mul_f32_e32 v5, v9, v23
	v_mul_f32_e32 v9, v25, v23
	v_lshlrev_b32_e32 v8, 16, v8
	v_mul_f32_e32 v25, 0xbfb8aa3b, v4
	v_mul_f32_e32 v34, 0xbfb8aa3b, v8
	v_exp_f32_e32 v25, v25
	v_exp_f32_e32 v34, v34
	v_lshlrev_b32_e32 v24, 16, v24
	v_mul_f32_e32 v35, 0xbfb8aa3b, v24
	v_add_f32_e32 v25, 1.0, v25
	v_add_f32_e32 v34, 1.0, v34
	v_div_scale_f32 v36, s[0:1], v25, v25, v4
	v_div_scale_f32 v38, s[0:1], v34, v34, v8
	v_rcp_f32_e32 v39, v36
	v_rcp_f32_e32 v40, v38
	v_div_scale_f32 v37, vcc, v4, v25, v4
	v_fma_f32 v49, -v36, v39, 1.0
	v_fma_f32 v50, -v38, v40, 1.0
	v_fmac_f32_e32 v39, v49, v39
	v_div_scale_f32 v48, s[0:1], v8, v34, v8
	v_fmac_f32_e32 v40, v50, v40
	v_mul_f32_e32 v49, v37, v39
	v_mul_f32_e32 v50, v48, v40
	v_fma_f32 v51, -v36, v49, v37
	v_fma_f32 v52, -v38, v50, v48
	v_fmac_f32_e32 v49, v51, v39
	v_exp_f32_e32 v35, v35
	v_fmac_f32_e32 v50, v52, v40
	v_fma_f32 v36, -v36, v49, v37
	v_fma_f32 v37, -v38, v50, v48
	v_div_fmas_f32 v36, v36, v39, v49
	s_mov_b64 vcc, s[0:1]
	v_div_fixup_f32 v4, v36, v25, v4
	v_div_fmas_f32 v25, v37, v40, v50
	v_mul_f32_e32 v4, v5, v4
	v_div_fixup_f32 v5, v25, v34, v8
	v_cvt_pk_bf16_f32 v4, v4, s0
	v_mul_f32_e32 v5, v9, v5
	v_add_f32_e32 v9, 1.0, v35
	global_store_short v[18:19], v4, off
	v_cvt_pk_bf16_f32 v8, v5, s0
	v_div_scale_f32 v18, s[0:1], v9, v9, v24
	v_rcp_f32_e32 v19, v18
	v_lshl_add_u64 v[4:5], s[14:15], 0, v[20:21]
	global_store_short v[4:5], v8, off
	v_mul_f32_e32 v4, v41, v23
	v_fma_f32 v5, -v18, v19, 1.0
	v_fmac_f32_e32 v19, v5, v19
	v_div_scale_f32 v5, vcc, v24, v9, v24
	v_mul_f32_e32 v8, v5, v19
	v_fma_f32 v20, -v18, v8, v5
	v_fmac_f32_e32 v8, v20, v19
	v_fma_f32 v5, -v18, v8, v5
	v_div_fmas_f32 v5, v5, v19, v8
	v_lshlrev_b32_e32 v8, 16, v22
	v_mul_f32_e32 v18, 0xbfb8aa3b, v8
	v_exp_f32_e32 v18, v18
	v_div_fixup_f32 v5, v5, v9, v24
	v_mul_f32_e32 v4, v4, v5
	v_cvt_pk_bf16_f32 v9, v4, s0
	v_add_f32_e32 v18, 1.0, v18
	v_div_scale_f32 v19, s[0:1], v18, v18, v8
	v_rcp_f32_e32 v20, v19
	v_lshl_add_u64 v[4:5], s[14:15], 0, v[32:33]
	global_store_short v[4:5], v9, off
	v_mul_f32_e32 v4, v57, v23
	v_fma_f32 v5, -v19, v20, 1.0
	v_fmac_f32_e32 v20, v5, v20
	v_div_scale_f32 v5, vcc, v8, v18, v8
	v_mul_f32_e32 v9, v5, v20
	v_fma_f32 v21, -v19, v9, v5
	v_fmac_f32_e32 v9, v21, v20
	v_fma_f32 v5, -v19, v9, v5
	v_div_fmas_f32 v5, v5, v20, v9
	v_div_fixup_f32 v5, v5, v18, v8
	v_mul_f32_e32 v4, v4, v5
	v_cvt_pk_bf16_f32 v8, v4, s0
	v_lshl_add_u64 v[4:5], s[14:15], 0, v[16:17]
	global_store_short v[4:5], v8, off
	v_or_b32_e32 v4, 18, v72
	v_ashrrev_i32_e32 v5, 31, v4
	v_lshlrev_b64 v[4:5], 10, v[4:5]
	v_or_b32_e32 v4, v4, v73
	v_lshl_add_u64 v[8:9], s[12:13], 0, v[4:5]
	v_or_b32_e32 v16, 64, v4
	v_mov_b32_e32 v17, v5
	v_lshl_add_u64 v[18:19], s[12:13], 0, v[16:17]
	v_mov_b32_e32 v22, v149
	v_mov_b32_e32 v23, v150
	v_or_b32_e32 v8, 0x80, v4
	v_mov_b32_e32 v9, v5
	v_lshl_add_u64 v[18:19], s[12:13], 0, v[8:9]
	v_mov_b32_e32 v24, v151
	v_lshl_add_u64 v[18:19], s[14:15], 0, v[4:5]
	v_or_b32_e32 v4, 0xc0, v4
	v_lshl_add_u64 v[20:21], s[12:13], 0, v[4:5]
	v_mov_b32_e32 v20, v152
	v_lshl_add_u64 v[16:17], s[14:15], 0, v[16:17]
	v_lshl_add_u64 v[8:9], s[14:15], 0, v[8:9]
	v_lshl_add_u64 v[4:5], s[14:15], 0, v[4:5]
	v_lshlrev_b32_e32 v21, 16, v22
	v_lshlrev_b32_e32 v22, 16, v23
	v_mul_f32_e32 v23, 0xbfb8aa3b, v21
	v_exp_f32_e32 v23, v23
	v_mul_f32_e32 v25, 0xbfb8aa3b, v22
	v_exp_f32_e32 v25, v25
	v_lshlrev_b32_e32 v24, 16, v24
	v_add_f32_e32 v23, 1.0, v23
	v_div_scale_f32 v32, s[0:1], v23, v23, v21
	v_rcp_f32_e32 v35, v32
	v_add_f32_e32 v25, 1.0, v25
	v_div_scale_f32 v33, vcc, v21, v23, v21
	v_fma_f32 v38, -v32, v35, 1.0
	v_fmac_f32_e32 v35, v38, v35
	v_div_scale_f32 v34, s[0:1], v25, v25, v22
	v_mul_f32_e32 v38, v33, v35
	v_rcp_f32_e32 v36, v34
	v_fma_f32 v40, -v32, v38, v33
	v_fmac_f32_e32 v38, v40, v35
	v_fma_f32 v32, -v32, v38, v33
	v_div_fmas_f32 v32, v32, v35, v38
	v_fma_f32 v39, -v34, v36, 1.0
	v_div_fixup_f32 v21, v32, v23, v21
	v_div_scale_f32 v37, s[0:1], v22, v25, v22
	v_fmac_f32_e32 v36, v39, v36
	v_mul_f32_e32 v10, v10, v21
	v_mul_f32_e32 v39, v37, v36
	v_cvt_pk_bf16_f32 v10, v10, s0
	v_fma_f32 v41, -v34, v39, v37
	global_store_short v[18:19], v10, off
	v_mul_f32_e32 v10, 0xbfb8aa3b, v24
	v_fmac_f32_e32 v39, v41, v36
	v_exp_f32_e32 v10, v10
	v_fma_f32 v33, -v34, v39, v37
	s_mov_b64 vcc, s[0:1]
	v_div_fmas_f32 v23, v33, v36, v39
	v_div_fixup_f32 v18, v23, v25, v22
	v_mul_f32_e32 v18, v26, v18
	v_add_f32_e32 v10, 1.0, v10
	v_cvt_pk_bf16_f32 v18, v18, s0
	v_div_scale_f32 v19, s[0:1], v10, v10, v24
	v_rcp_f32_e32 v21, v19
	global_store_short v[16:17], v18, off
	v_mul_f32_e32 v16, v42, v6
	v_mul_f32_e32 v6, v58, v6
	v_fma_f32 v17, -v19, v21, 1.0
	v_fmac_f32_e32 v21, v17, v21
	v_div_scale_f32 v17, vcc, v24, v10, v24
	v_mul_f32_e32 v18, v17, v21
	v_fma_f32 v22, -v19, v18, v17
	v_fmac_f32_e32 v18, v22, v21
	v_fma_f32 v17, -v19, v18, v17
	v_div_fmas_f32 v17, v17, v21, v18
	v_lshlrev_b32_e32 v18, 16, v20
	v_mul_f32_e32 v19, 0xbfb8aa3b, v18
	v_exp_f32_e32 v19, v19
	v_div_fixup_f32 v10, v17, v10, v24
	v_mul_f32_e32 v10, v16, v10
	v_cvt_pk_bf16_f32 v10, v10, s0
	v_add_f32_e32 v16, 1.0, v19
	v_div_scale_f32 v17, s[0:1], v16, v16, v18
	v_rcp_f32_e32 v19, v17
	global_store_short v[8:9], v10, off
	v_fma_f32 v8, -v17, v19, 1.0
	v_fmac_f32_e32 v19, v8, v19
	v_div_scale_f32 v8, vcc, v18, v16, v18
	v_mul_f32_e32 v9, v8, v19
	v_fma_f32 v10, -v17, v9, v8
	v_fmac_f32_e32 v9, v10, v19
	v_fma_f32 v8, -v17, v9, v8
	v_div_fmas_f32 v8, v8, v19, v9
	v_div_fixup_f32 v8, v8, v16, v18
	v_mul_f32_e32 v6, v6, v8
	v_cvt_pk_bf16_f32 v6, v6, s0
	global_store_short v[4:5], v6, off
	v_or_b32_e32 v4, 19, v72
	v_ashrrev_i32_e32 v5, 31, v4
	v_lshlrev_b64 v[4:5], 10, v[4:5]
	v_or_b32_e32 v4, v4, v73
	v_lshl_add_u64 v[8:9], s[12:13], 0, v[4:5]
	v_or_b32_e32 v16, 64, v4
	v_mov_b32_e32 v17, v5
	v_lshl_add_u64 v[18:19], s[12:13], 0, v[16:17]
	v_mov_b32_e32 v6, v153
	v_mov_b32_e32 v10, v154
	v_or_b32_e32 v8, 0x80, v4
	v_mov_b32_e32 v9, v5
	v_lshl_add_u64 v[18:19], s[12:13], 0, v[8:9]
	v_mov_b32_e32 v22, v155
	v_lshl_add_u64 v[18:19], s[14:15], 0, v[4:5]
	v_or_b32_e32 v4, 0xc0, v4
	v_lshl_add_u64 v[20:21], s[12:13], 0, v[4:5]
	v_mov_b32_e32 v20, v156
	v_rcp_f32_e32 v21, v7
	v_lshl_add_u64 v[4:5], s[14:15], 0, v[4:5]
	v_mul_f32_e32 v24, v27, v21
	v_mul_f32_e32 v11, v11, v21
	v_lshlrev_b32_e32 v6, 16, v6
	v_lshlrev_b32_e32 v7, 16, v10
	v_mul_f32_e32 v10, 0xbfb8aa3b, v6
	v_exp_f32_e32 v10, v10
	v_mul_f32_e32 v23, 0xbfb8aa3b, v7
	v_exp_f32_e32 v23, v23
	v_add_f32_e32 v10, 1.0, v10
	v_div_scale_f32 v25, s[0:1], v10, v10, v6
	v_rcp_f32_e32 v32, v25
	v_add_f32_e32 v23, 1.0, v23
	v_div_scale_f32 v27, s[0:1], v23, v23, v7
	v_fma_f32 v35, -v25, v32, 1.0
	v_div_scale_f32 v26, vcc, v6, v10, v6
	v_rcp_f32_e32 v33, v27
	v_fmac_f32_e32 v32, v35, v32
	v_mul_f32_e32 v35, v26, v32
	v_fma_f32 v37, -v25, v35, v26
	v_fmac_f32_e32 v35, v37, v32
	v_fma_f32 v36, -v27, v33, 1.0
	v_fma_f32 v25, -v25, v35, v26
	v_div_scale_f32 v34, s[0:1], v7, v23, v7
	v_fmac_f32_e32 v33, v36, v33
	v_div_fmas_f32 v25, v25, v32, v35
	v_mul_f32_e32 v36, v34, v33
	v_div_fixup_f32 v6, v25, v10, v6
	v_lshlrev_b32_e32 v10, 16, v22
	v_fma_f32 v38, -v27, v36, v34
	v_mul_f32_e32 v6, v11, v6
	v_mul_f32_e32 v11, 0xbfb8aa3b, v10
	v_fmac_f32_e32 v36, v38, v33
	v_cvt_pk_bf16_f32 v6, v6, s0
	v_exp_f32_e32 v11, v11
	global_store_short v[18:19], v6, off
	v_fma_f32 v6, -v27, v36, v34
	s_mov_b64 vcc, s[0:1]
	v_div_fmas_f32 v6, v6, v33, v36
	v_div_fixup_f32 v6, v6, v23, v7
	v_mul_f32_e32 v6, v24, v6
	v_add_f32_e32 v11, 1.0, v11
	v_cvt_pk_bf16_f32 v18, v6, s0
	v_div_scale_f32 v19, s[0:1], v11, v11, v10
	v_rcp_f32_e32 v22, v19
	v_lshl_add_u64 v[6:7], s[14:15], 0, v[16:17]
	global_store_short v[6:7], v18, off
	v_mul_f32_e32 v6, v43, v21
	v_fma_f32 v7, -v19, v22, 1.0
	v_fmac_f32_e32 v22, v7, v22
	v_div_scale_f32 v7, vcc, v10, v11, v10
	v_mul_f32_e32 v16, v7, v22
	v_fma_f32 v17, -v19, v16, v7
	v_fmac_f32_e32 v16, v17, v22
	v_fma_f32 v7, -v19, v16, v7
	v_div_fmas_f32 v7, v7, v22, v16
	v_lshlrev_b32_e32 v16, 16, v20
	v_mul_f32_e32 v17, 0xbfb8aa3b, v16
	v_exp_f32_e32 v17, v17
	v_div_fixup_f32 v7, v7, v11, v10
	v_mul_f32_e32 v6, v6, v7
	v_cvt_pk_bf16_f32 v10, v6, s0
	v_add_f32_e32 v11, 1.0, v17
	v_div_scale_f32 v17, s[0:1], v11, v11, v16
	v_rcp_f32_e32 v18, v17
	v_lshl_add_u64 v[6:7], s[14:15], 0, v[8:9]
	global_store_short v[6:7], v10, off
	v_mul_f32_e32 v6, v59, v21
	v_fma_f32 v7, -v17, v18, 1.0
	v_fmac_f32_e32 v18, v7, v18
	v_div_scale_f32 v7, vcc, v16, v11, v16
	v_mul_f32_e32 v8, v7, v18
	v_fma_f32 v9, -v17, v8, v7
	v_fmac_f32_e32 v8, v9, v18
	v_fma_f32 v7, -v17, v8, v7
	v_div_fmas_f32 v7, v7, v18, v8
	v_div_fixup_f32 v7, v7, v11, v16
	v_mul_f32_e32 v6, v6, v7
	v_cvt_pk_bf16_f32 v6, v6, s0
	global_store_short v[4:5], v6, off
	v_or_b32_e32 v4, 24, v72
	v_ashrrev_i32_e32 v5, 31, v4
	v_lshlrev_b64 v[4:5], 10, v[4:5]
	v_or_b32_e32 v4, v4, v73
	v_lshl_add_u64 v[6:7], s[12:13], 0, v[4:5]
	v_or_b32_e32 v8, 64, v4
	v_mov_b32_e32 v9, v5
	v_lshl_add_u64 v[10:11], s[12:13], 0, v[8:9]
	v_mov_b32_e32 v18, v157
	v_mov_b32_e32 v19, v158
	v_or_b32_e32 v6, 0x80, v4
	v_mov_b32_e32 v7, v5
	v_lshl_add_u64 v[10:11], s[12:13], 0, v[6:7]
	v_mov_b32_e32 v20, v159
	v_lshl_add_u64 v[10:11], s[14:15], 0, v[4:5]
	v_or_b32_e32 v4, 0xc0, v4
	v_lshl_add_u64 v[16:17], s[12:13], 0, v[4:5]
	v_mov_b32_e32 v16, v173
	v_mul_f32_e32 v22, v28, v0
	v_lshl_add_u64 v[8:9], s[14:15], 0, v[8:9]
	v_lshl_add_u64 v[6:7], s[14:15], 0, v[6:7]
	v_lshl_add_u64 v[4:5], s[14:15], 0, v[4:5]
	v_lshlrev_b32_e32 v17, 16, v18
	v_lshlrev_b32_e32 v18, 16, v19
	v_mul_f32_e32 v19, 0xbfb8aa3b, v17
	v_exp_f32_e32 v19, v19
	v_mul_f32_e32 v21, 0xbfb8aa3b, v18
	v_exp_f32_e32 v21, v21
	v_add_f32_e32 v19, 1.0, v19
	v_div_scale_f32 v23, s[0:1], v19, v19, v17
	v_add_f32_e32 v21, 1.0, v21
	v_rcp_f32_e32 v25, v23
	v_div_scale_f32 v24, s[0:1], v21, v21, v18
	v_rcp_f32_e32 v26, v24
	v_fma_f32 v28, -v23, v25, 1.0
	v_div_scale_f32 v27, vcc, v17, v19, v17
	v_fmac_f32_e32 v25, v28, v25
	v_fma_f32 v32, -v24, v26, 1.0
	v_mul_f32_e32 v28, v27, v25
	v_fmac_f32_e32 v26, v32, v26
	v_fma_f32 v32, -v23, v28, v27
	v_fmac_f32_e32 v28, v32, v25
	v_fma_f32 v23, -v23, v28, v27
	v_div_fmas_f32 v23, v23, v25, v28
	v_div_fixup_f32 v17, v23, v19, v17
	v_mul_f32_e32 v12, v12, v17
	v_cvt_pk_bf16_f32 v12, v12, s0
	global_store_short v[10:11], v12, off
	v_div_scale_f32 v10, vcc, v18, v21, v18
	v_mul_f32_e32 v11, v10, v26
	v_fma_f32 v12, -v24, v11, v10
	v_fmac_f32_e32 v11, v12, v26
	v_fma_f32 v10, -v24, v11, v10
	v_div_fmas_f32 v10, v10, v26, v11
	v_lshlrev_b32_e32 v11, 16, v20
	v_mul_f32_e32 v12, 0xbfb8aa3b, v11
	v_exp_f32_e32 v12, v12
	v_div_fixup_f32 v10, v10, v21, v18
	v_mul_f32_e32 v10, v22, v10
	v_cvt_pk_bf16_f32 v10, v10, s0
	v_add_f32_e32 v12, 1.0, v12
	v_div_scale_f32 v17, s[0:1], v12, v12, v11
	v_rcp_f32_e32 v18, v17
	global_store_short v[8:9], v10, off
	v_mul_f32_e32 v8, v44, v0
	v_mul_f32_e32 v0, v60, v0
	v_fma_f32 v9, -v17, v18, 1.0
	v_fmac_f32_e32 v18, v9, v18
	v_div_scale_f32 v9, vcc, v11, v12, v11
	v_mul_f32_e32 v10, v9, v18
	v_fma_f32 v19, -v17, v10, v9
	v_fmac_f32_e32 v10, v19, v18
	v_fma_f32 v9, -v17, v10, v9
	v_div_fmas_f32 v9, v9, v18, v10
	v_lshlrev_b32_e32 v10, 16, v16
	v_mul_f32_e32 v16, 0xbfb8aa3b, v10
	v_exp_f32_e32 v16, v16
	v_div_fixup_f32 v9, v9, v12, v11
	v_mul_f32_e32 v8, v8, v9
	v_cvt_pk_bf16_f32 v8, v8, s0
	v_add_f32_e32 v9, 1.0, v16
	v_div_scale_f32 v11, s[0:1], v9, v9, v10
	v_rcp_f32_e32 v12, v11
	global_store_short v[6:7], v8, off
	v_fma_f32 v6, -v11, v12, 1.0
	v_fmac_f32_e32 v12, v6, v12
	v_div_scale_f32 v6, vcc, v10, v9, v10
	v_mul_f32_e32 v7, v6, v12
	v_fma_f32 v8, -v11, v7, v6
	v_fmac_f32_e32 v7, v8, v12
	v_fma_f32 v6, -v11, v7, v6
	v_div_fmas_f32 v6, v6, v12, v7
	v_div_fixup_f32 v6, v6, v9, v10
	v_mul_f32_e32 v0, v0, v6
	v_cvt_pk_bf16_f32 v0, v0, s0
	global_store_short v[4:5], v0, off
	v_or_b32_e32 v4, 25, v72
	v_ashrrev_i32_e32 v5, 31, v4
	v_lshlrev_b64 v[4:5], 10, v[4:5]
	v_or_b32_e32 v4, v4, v73
	v_lshl_add_u64 v[6:7], s[12:13], 0, v[4:5]
	v_or_b32_e32 v8, 64, v4
	v_mov_b32_e32 v9, v5
	v_lshl_add_u64 v[10:11], s[12:13], 0, v[8:9]
	v_mov_b32_e32 v0, v174
	v_mov_b32_e32 v12, v175
	v_or_b32_e32 v6, 0x80, v4
	v_mov_b32_e32 v7, v5
	v_lshl_add_u64 v[10:11], s[12:13], 0, v[6:7]
	v_mov_b32_e32 v18, v176
	v_lshl_add_u64 v[10:11], s[14:15], 0, v[4:5]
	v_or_b32_e32 v4, 0xc0, v4
	v_lshl_add_u64 v[16:17], s[12:13], 0, v[4:5]
	v_mov_b32_e32 v16, v177
	v_rcp_f32_e32 v17, v1
	v_lshlrev_b32_e32 v0, 16, v0
	v_lshlrev_b32_e32 v1, 16, v12
	v_mul_f32_e32 v12, 0xbfb8aa3b, v0
	v_exp_f32_e32 v12, v12
	v_mul_f32_e32 v19, 0xbfb8aa3b, v1
	v_exp_f32_e32 v19, v19
	v_mul_f32_e32 v13, v13, v17
	v_add_f32_e32 v12, 1.0, v12
	v_div_scale_f32 v20, s[0:1], v12, v12, v0
	v_rcp_f32_e32 v22, v20
	v_div_scale_f32 v21, vcc, v0, v12, v0
	v_add_f32_e32 v19, 1.0, v19
	v_fma_f32 v25, -v20, v22, 1.0
	v_fmac_f32_e32 v22, v25, v22
	v_mul_f32_e32 v25, v21, v22
	v_fma_f32 v26, -v20, v25, v21
	v_fmac_f32_e32 v25, v26, v22
	v_div_scale_f32 v23, s[0:1], v19, v19, v1
	v_fma_f32 v20, -v20, v25, v21
	v_rcp_f32_e32 v24, v23
	v_div_fmas_f32 v20, v20, v22, v25
	v_div_fixup_f32 v0, v20, v12, v0
	v_mul_f32_e32 v0, v13, v0
	v_cvt_pk_bf16_f32 v0, v0, s0
	global_store_short v[10:11], v0, off
	v_fma_f32 v10, -v23, v24, 1.0
	v_fmac_f32_e32 v24, v10, v24
	v_div_scale_f32 v10, vcc, v1, v19, v1
	v_mul_f32_e32 v11, v10, v24
	v_fma_f32 v12, -v23, v11, v10
	v_fmac_f32_e32 v11, v12, v24
	v_fma_f32 v10, -v23, v11, v10
	v_div_fmas_f32 v10, v10, v24, v11
	v_lshlrev_b32_e32 v11, 16, v18
	v_mul_f32_e32 v12, 0xbfb8aa3b, v11
	v_exp_f32_e32 v12, v12
	v_mul_f32_e32 v0, v29, v17
	v_div_fixup_f32 v1, v10, v19, v1
	v_mul_f32_e32 v0, v0, v1
	v_add_f32_e32 v12, 1.0, v12
	v_cvt_pk_bf16_f32 v10, v0, s0
	v_div_scale_f32 v13, s[0:1], v12, v12, v11
	v_rcp_f32_e32 v18, v13
	v_lshl_add_u64 v[0:1], s[14:15], 0, v[8:9]
	global_store_short v[0:1], v10, off
	v_mul_f32_e32 v0, v45, v17
	v_fma_f32 v1, -v13, v18, 1.0
	v_fmac_f32_e32 v18, v1, v18
	v_div_scale_f32 v1, vcc, v11, v12, v11
	v_mul_f32_e32 v8, v1, v18
	v_fma_f32 v9, -v13, v8, v1
	v_fmac_f32_e32 v8, v9, v18
	v_fma_f32 v1, -v13, v8, v1
	v_div_fmas_f32 v1, v1, v18, v8
	v_lshlrev_b32_e32 v8, 16, v16
	v_mul_f32_e32 v9, 0xbfb8aa3b, v8
	v_exp_f32_e32 v9, v9
	v_div_fixup_f32 v1, v1, v12, v11
	v_mul_f32_e32 v0, v0, v1
	v_cvt_pk_bf16_f32 v10, v0, s0
	v_add_f32_e32 v9, 1.0, v9
	v_div_scale_f32 v11, s[0:1], v9, v9, v8
	v_rcp_f32_e32 v12, v11
	v_lshl_add_u64 v[0:1], s[14:15], 0, v[6:7]
	global_store_short v[0:1], v10, off
	v_mul_f32_e32 v0, v61, v17
	v_fma_f32 v1, -v11, v12, 1.0
	v_fmac_f32_e32 v12, v1, v12
	v_div_scale_f32 v1, vcc, v8, v9, v8
	v_mul_f32_e32 v6, v1, v12
	v_fma_f32 v7, -v11, v6, v1
	v_fmac_f32_e32 v6, v7, v12
	v_fma_f32 v1, -v11, v6, v1
	v_div_fmas_f32 v1, v1, v12, v6
	v_div_fixup_f32 v1, v1, v9, v8
	v_mul_f32_e32 v0, v0, v1
	v_cvt_pk_bf16_f32 v6, v0, s0
	v_lshl_add_u64 v[0:1], s[14:15], 0, v[4:5]
	global_store_short v[0:1], v6, off
	v_or_b32_e32 v0, 26, v72
	v_ashrrev_i32_e32 v1, 31, v0
	v_lshlrev_b64 v[0:1], 10, v[0:1]
	v_or_b32_e32 v0, v0, v73
	v_lshl_add_u64 v[4:5], s[12:13], 0, v[0:1]
	v_mov_b32_e32 v12, v178
	v_or_b32_e32 v4, 64, v0
	v_mov_b32_e32 v5, v1
	v_lshl_add_u64 v[6:7], s[12:13], 0, v[4:5]
	v_mov_b32_e32 v13, v179
	v_or_b32_e32 v6, 0x80, v0
	v_mov_b32_e32 v7, v1
	v_lshl_add_u64 v[8:9], s[12:13], 0, v[6:7]
	v_mov_b32_e32 v16, v180
	v_lshl_add_u64 v[8:9], s[14:15], 0, v[0:1]
	v_or_b32_e32 v0, 0xc0, v0
	v_lshl_add_u64 v[10:11], s[12:13], 0, v[0:1]
	v_mov_b32_e32 v10, v181
	v_lshl_add_u64 v[4:5], s[14:15], 0, v[4:5]
	v_lshl_add_u64 v[0:1], s[14:15], 0, v[0:1]
	v_lshlrev_b32_e32 v11, 16, v12
	v_mul_f32_e32 v12, 0xbfb8aa3b, v11
	v_exp_f32_e32 v12, v12
	v_lshlrev_b32_e32 v13, 16, v13
	v_mul_f32_e32 v17, 0xbfb8aa3b, v13
	v_add_f32_e32 v12, 1.0, v12
	v_div_scale_f32 v18, s[0:1], v12, v12, v11
	v_rcp_f32_e32 v19, v18
	v_div_scale_f32 v20, vcc, v11, v12, v11
	v_exp_f32_e32 v17, v17
	v_fma_f32 v21, -v18, v19, 1.0
	v_fmac_f32_e32 v19, v21, v19
	v_mul_f32_e32 v21, v20, v19
	v_fma_f32 v22, -v18, v21, v20
	v_fmac_f32_e32 v21, v22, v19
	v_fma_f32 v18, -v18, v21, v20
	v_div_fmas_f32 v18, v18, v19, v21
	v_div_fixup_f32 v11, v18, v12, v11
	v_add_f32_e32 v12, 1.0, v17
	v_mul_f32_e32 v11, v14, v11
	v_div_scale_f32 v14, s[0:1], v12, v12, v13
	v_rcp_f32_e32 v17, v14
	s_nop 0
	v_cvt_pk_bf16_f32 v11, v11, s0
	global_store_short v[8:9], v11, off
	v_mul_f32_e32 v8, v30, v2
	v_fma_f32 v9, -v14, v17, 1.0
	v_fmac_f32_e32 v17, v9, v17
	v_div_scale_f32 v9, vcc, v13, v12, v13
	v_mul_f32_e32 v11, v9, v17
	v_fma_f32 v18, -v14, v11, v9
	v_fmac_f32_e32 v11, v18, v17
	v_fma_f32 v9, -v14, v11, v9
	v_div_fmas_f32 v9, v9, v17, v11
	v_lshlrev_b32_e32 v11, 16, v16
	v_mul_f32_e32 v14, 0xbfb8aa3b, v11
	v_exp_f32_e32 v14, v14
	v_div_fixup_f32 v9, v9, v12, v13
	v_mul_f32_e32 v8, v8, v9
	v_cvt_pk_bf16_f32 v8, v8, s0
	v_add_f32_e32 v9, 1.0, v14
	v_div_scale_f32 v12, s[0:1], v9, v9, v11
	v_rcp_f32_e32 v13, v12
	global_store_short v[4:5], v8, off
	v_mul_f32_e32 v4, v46, v2
	v_mul_f32_e32 v2, v62, v2
	v_fma_f32 v5, -v12, v13, 1.0
	v_fmac_f32_e32 v13, v5, v13
	v_div_scale_f32 v5, vcc, v11, v9, v11
	v_mul_f32_e32 v8, v5, v13
	v_fma_f32 v14, -v12, v8, v5
	v_fmac_f32_e32 v8, v14, v13
	v_fma_f32 v5, -v12, v8, v5
	v_div_fmas_f32 v5, v5, v13, v8
	v_lshlrev_b32_e32 v8, 16, v10
	v_mul_f32_e32 v10, 0xbfb8aa3b, v8
	v_exp_f32_e32 v10, v10
	v_div_fixup_f32 v5, v5, v9, v11
	v_mul_f32_e32 v4, v4, v5
	v_cvt_pk_bf16_f32 v9, v4, s0
	v_add_f32_e32 v10, 1.0, v10
	v_div_scale_f32 v11, s[0:1], v10, v10, v8
	v_rcp_f32_e32 v12, v11
	v_lshl_add_u64 v[4:5], s[14:15], 0, v[6:7]
	global_store_short v[4:5], v9, off
	v_rcp_f32_e32 v14, v3
	v_fma_f32 v4, -v11, v12, 1.0
	v_fmac_f32_e32 v12, v4, v12
	v_div_scale_f32 v4, vcc, v8, v10, v8
	v_mul_f32_e32 v5, v4, v12
	v_fma_f32 v6, -v11, v5, v4
	v_fmac_f32_e32 v5, v6, v12
	v_fma_f32 v4, -v11, v5, v4
	v_div_fmas_f32 v4, v4, v12, v5
	v_div_fixup_f32 v4, v4, v10, v8
	v_mul_f32_e32 v2, v2, v4
	v_cvt_pk_bf16_f32 v2, v2, s0
	global_store_short v[0:1], v2, off
	v_or_b32_e32 v0, 27, v72
	v_ashrrev_i32_e32 v1, 31, v0
	v_lshlrev_b64 v[0:1], 10, v[0:1]
	v_or_b32_e32 v0, v0, v73
	v_lshl_add_u64 v[4:5], s[12:13], 0, v[0:1]
	v_mov_b32_e32 v2, v182
	v_or_b32_e32 v4, 64, v0
	v_mov_b32_e32 v5, v1
	v_lshl_add_u64 v[6:7], s[12:13], 0, v[4:5]
	v_mov_b32_e32 v12, v183
	v_or_b32_e32 v6, 0x80, v0
	v_mov_b32_e32 v7, v1
	v_lshl_add_u64 v[8:9], s[12:13], 0, v[6:7]
	v_mov_b32_e32 v13, v184
	v_lshl_add_u64 v[8:9], s[14:15], 0, v[0:1]
	v_or_b32_e32 v0, 0xc0, v0
	v_lshl_add_u64 v[10:11], s[12:13], 0, v[0:1]
	v_mov_b32_e32 v10, v185
	v_mul_f32_e32 v15, v15, v14
	v_lshl_add_u64 v[0:1], s[14:15], 0, v[0:1]
	v_lshlrev_b32_e32 v2, 16, v2
	v_mul_f32_e32 v11, 0xbfb8aa3b, v2
	v_exp_f32_e32 v11, v11
	v_lshlrev_b32_e32 v12, 16, v12
	v_add_f32_e32 v3, 1.0, v11
	v_div_scale_f32 v11, s[0:1], v3, v3, v2
	v_rcp_f32_e32 v16, v11
	v_div_scale_f32 v17, vcc, v2, v3, v2
	v_fma_f32 v18, -v11, v16, 1.0
	v_fmac_f32_e32 v16, v18, v16
	v_mul_f32_e32 v18, v17, v16
	v_fma_f32 v19, -v11, v18, v17
	v_fmac_f32_e32 v18, v19, v16
	v_fma_f32 v11, -v11, v18, v17
	v_mul_f32_e32 v17, 0xbfb8aa3b, v12
	v_exp_f32_e32 v17, v17
	v_div_fmas_f32 v11, v11, v16, v18
	v_div_fixup_f32 v2, v11, v3, v2
	v_mul_f32_e32 v2, v15, v2
	v_add_f32_e32 v3, 1.0, v17
	v_div_scale_f32 v11, s[0:1], v3, v3, v12
	v_rcp_f32_e32 v15, v11
	s_nop 0
	v_cvt_pk_bf16_f32 v2, v2, s0
	global_store_short v[8:9], v2, off
	v_mul_f32_e32 v2, v31, v14
	v_fma_f32 v8, -v11, v15, 1.0
	v_fmac_f32_e32 v15, v8, v15
	v_div_scale_f32 v8, vcc, v12, v3, v12
	v_mul_f32_e32 v9, v8, v15
	v_fma_f32 v16, -v11, v9, v8
	v_fmac_f32_e32 v9, v16, v15
	v_fma_f32 v8, -v11, v9, v8
	v_div_fmas_f32 v8, v8, v15, v9
	v_lshlrev_b32_e32 v9, 16, v13
	v_mul_f32_e32 v11, 0xbfb8aa3b, v9
	v_exp_f32_e32 v11, v11
	v_div_fixup_f32 v3, v8, v3, v12
	v_mul_f32_e32 v2, v2, v3
	v_cvt_pk_bf16_f32 v8, v2, s0
	v_add_f32_e32 v11, 1.0, v11
	v_div_scale_f32 v12, s[0:1], v11, v11, v9
	v_rcp_f32_e32 v13, v12
	v_lshl_add_u64 v[2:3], s[14:15], 0, v[4:5]
	global_store_short v[2:3], v8, off
	v_mul_f32_e32 v2, v47, v14
	v_fma_f32 v3, -v12, v13, 1.0
	v_fmac_f32_e32 v13, v3, v13
	v_div_scale_f32 v3, vcc, v9, v11, v9
	v_mul_f32_e32 v4, v3, v13
	v_fma_f32 v5, -v12, v4, v3
	v_fmac_f32_e32 v4, v5, v13
	v_fma_f32 v3, -v12, v4, v3
	v_div_fmas_f32 v3, v3, v13, v4
	v_lshlrev_b32_e32 v4, 16, v10
	v_mul_f32_e32 v5, 0xbfb8aa3b, v4
	v_exp_f32_e32 v5, v5
	v_div_fixup_f32 v3, v3, v11, v9
	v_mul_f32_e32 v2, v2, v3
	v_cvt_pk_bf16_f32 v8, v2, s0
	v_add_f32_e32 v5, 1.0, v5
	v_div_scale_f32 v9, s[0:1], v5, v5, v4
	v_rcp_f32_e32 v10, v9
	v_lshl_add_u64 v[2:3], s[14:15], 0, v[6:7]
	global_store_short v[2:3], v8, off
	v_mul_f32_e32 v2, v63, v14
	v_fma_f32 v3, -v9, v10, 1.0
	v_fmac_f32_e32 v10, v3, v10
	v_div_scale_f32 v3, vcc, v4, v5, v4
	v_mul_f32_e32 v6, v3, v10
	v_fma_f32 v7, -v9, v6, v3
	v_fmac_f32_e32 v6, v7, v10
	v_fma_f32 v3, -v9, v6, v3
	v_div_fmas_f32 v3, v3, v10, v6
	v_div_fixup_f32 v3, v3, v5, v4
	v_mul_f32_e32 v2, v2, v3
	v_cvt_pk_bf16_f32 v2, v2, s0
	global_store_short v[0:1], v2, off
	s_barrier
	s_cbranch_scc0 .LBB0_937
